# B1 RS-load hoist in z/gates/up GEMM epilogues; ph14 PP loads prefetched one unit ahead; redundant setprio/waitcnt trimmed
# speedup vs baseline: 1.0135x; 1.0135x over previous
; #define PG8_STAGE(bufoff, gbase, voff) do { _Pragma("unroll") for (int _i = 0; _i < 2; ++_i) \
;         __builtin_amdgcn_global_load_lds((const unsigned*)((const char*)(gbase) + (voff)[_i]), (LAS unsigned*)(lds + (bufoff) + ldsw + _i * 8192), 16, 0, 0); } while (0)
; #define PG8_LDA(dst, b, h) do { _Pragma("unroll") for (int m = 0; m < 4; ++m) _Pragma("unroll") for (int k = 0; k < 2; ++k) dst[m][k] = *(const LAS bf16x8*)(lds + PG8_SA(b, h) + aoff + m * 2048 + k * 1024); } while (0)
; #define PG8_LDB(dst, b, h) do { _Pragma("unroll") for (int n = 0; n < 2; ++n) _Pragma("unroll") for (int k = 0; k < 2; ++k) dst[n][k] = *(const LAS bf16x8*)(lds + PG8_SB(b, h) + boff + n * 2048 + k * 1024); } while (0)
; #define PG8_MMA(ai, bj, At, Bt) do { __builtin_amdgcn_s_setprio(1); _Pragma("unroll") for (int m = 0; m < 4; ++m) _Pragma("unroll") for (int n = 0; n < 2; ++n) _Pragma("unroll") for (int k = 0; k < 2; ++k) \
;         acc[ai][bj][m][n] = __builtin_amdgcn_mfma_f32_16x16x32_bf16(Bt[n][k], At[m][k], acc[ai][bj][m][n], 0, 0, 0); __builtin_amdgcn_s_setprio(0); } while (0)
; #define PG8_WAIT_V(n) asm volatile("s_waitcnt vmcnt(" #n ")" ::: "memory")
; #define PG8_WAIT_L(n) asm volatile("s_waitcnt lgkmcnt(" #n ")" ::: "memory")
; #define PG8_BAR __builtin_amdgcn_s_barrier()
; #define PG8_SCHED __builtin_amdgcn_sched_barrier(0)
; template <class Epi, class Sched>
; __device__ __forceinline__ void gemm_phase(LAS unsigned char* lds, const Gemm g, const Sched& S, const Epi& E, int wv) {
;     ...
;         const char* nA = has_next ? (const char*)g.A + (size_t)nxt.pm * tstepA + (size_t)nxt.ak * 2 : cA; const char* nB = has_next ? (const char*)g.Bt + (size_t)nxt.pn * tstepB : cB;
;         for (int t = 0; t < nt; t += 2) {
;             const bool last = (t == nt - 2);
;             const char* a1 = cA + (size_t)(t + 1) * kstep;
;             const char* a2 = last ? nA : cA + (size_t)(t + 2) * kstep; const char* b2 = last ? nB : cB + (size_t)(t + 2) * kstep;
;             const char* a3 = a2 + kstep; const char* b3 = b2 + kstep;
;             PG8_LDB(B0, 0, 0); PG8_LDB(B1, 0, 1); PG8_SCHED; PG8_LDA(At, 0, 0); PG8_STAGE(PG8_SA(1, 1), a1 + hstepA, voffA);
;             PG8_WAIT_V(8); PG8_WAIT_L(0); PG8_BAR; PG8_MMA(0, 0, At, B0); PG8_MMA(0, 1, At, B1); PG8_BAR; PG8_SCHED;
.LBB0_141:
	s_add_u32 s0, s78, 0xfffc0080
	s_addc_u32 s1, s79, -1
	s_add_i32 s20, 0, 0x10000
	s_cmp_eq_u32 s35, 12
	s_cselect_b32 s83, s5, s1
	s_cselect_b32 s82, s10, s0
	v_add_u32_e32 v0, s20, v185
	s_cselect_b32 s81, s11, s34
	s_cselect_b32 s80, s21, s31
	s_add_i32 s26, 0, 0x14000
	ds_read_b128 v[142:145], v0
	ds_read_b128 v[146:149], v0 offset:1024
	ds_read_b128 v[150:153], v0 offset:2048
	ds_read_b128 v[154:157], v0 offset:3072
	v_add_u32_e32 v0, s26, v185
	ds_read_b128 v[158:161], v0
	ds_read_b128 v[162:165], v0 offset:1024
	ds_read_b128 v[166:169], v0 offset:2048
	ds_read_b128 v[170:173], v0 offset:3072
	v_lshl_add_u64 v[182:183], s[78:79], 0, v[138:139]
	s_add_i32 m0, s92, 0xc000
	ds_read_b128 v[174:177], v189
	ds_read_b128 v[178:181], v189 offset:1024
	ds_read_b128 v[190:193], v189 offset:2048
	ds_read_b128 v[196:199], v189 offset:3072
	ds_read_b128 v[200:203], v189 offset:4096
	ds_read_b128 v[204:207], v189 offset:5120
	ds_read_b128 v[208:211], v189 offset:6144
	ds_read_b128 v[212:215], v189 offset:7168
	global_load_lds_dwordx4 v[182:183], off
	v_lshl_add_u64 v[182:183], s[78:79], 0, v[140:141]
	s_add_i32 m0, s92, 0xe000
	s_nop 0
	global_load_lds_dwordx4 v[182:183], off
	s_waitcnt vmcnt(8)
	s_waitcnt lgkmcnt(0)
	s_barrier
	s_setprio 1
	v_mfma_f32_16x16x32_bf16 v[126:129], v[142:145], v[174:177], v[126:129]
	v_mfma_f32_16x16x32_bf16 v[122:125], v[150:153], v[174:177], v[122:125]
	v_mfma_f32_16x16x32_bf16 v[110:113], v[142:145], v[190:193], v[110:113]
	v_mfma_f32_16x16x32_bf16 v[106:109], v[150:153], v[190:193], v[106:109]
	v_mfma_f32_16x16x32_bf16 v[94:97], v[142:145], v[200:203], v[94:97]
	v_mfma_f32_16x16x32_bf16 v[90:93], v[150:153], v[200:203], v[90:93]
	v_mfma_f32_16x16x32_bf16 v[78:81], v[142:145], v[208:211], v[78:81]
	v_mfma_f32_16x16x32_bf16 v[74:77], v[150:153], v[208:211], v[74:77]
	v_mfma_f32_16x16x32_bf16 v[126:129], v[146:149], v[178:181], v[126:129]
	v_mfma_f32_16x16x32_bf16 v[122:125], v[154:157], v[178:181], v[122:125]
	v_mfma_f32_16x16x32_bf16 v[110:113], v[146:149], v[196:199], v[110:113]
	v_mfma_f32_16x16x32_bf16 v[106:109], v[154:157], v[196:199], v[106:109]
	v_mfma_f32_16x16x32_bf16 v[94:97], v[146:149], v[204:207], v[94:97]
	v_mfma_f32_16x16x32_bf16 v[90:93], v[154:157], v[204:207], v[90:93]
	v_mfma_f32_16x16x32_bf16 v[78:81], v[146:149], v[212:215], v[78:81]
	v_mfma_f32_16x16x32_bf16 v[74:77], v[154:157], v[212:215], v[74:77]
	v_mfma_f32_16x16x32_bf16 v[118:121], v[158:161], v[174:177], v[118:121]
	v_mfma_f32_16x16x32_bf16 v[114:117], v[166:169], v[174:177], v[114:117]
	v_mfma_f32_16x16x32_bf16 v[102:105], v[158:161], v[190:193], v[102:105]
	v_mfma_f32_16x16x32_bf16 v[98:101], v[166:169], v[190:193], v[98:101]
	v_mfma_f32_16x16x32_bf16 v[86:89], v[158:161], v[200:203], v[86:89]
	v_mfma_f32_16x16x32_bf16 v[82:85], v[166:169], v[200:203], v[82:85]
	v_mfma_f32_16x16x32_bf16 v[70:73], v[158:161], v[208:211], v[70:73]
	v_mfma_f32_16x16x32_bf16 v[66:69], v[166:169], v[208:211], v[66:69]
	v_mfma_f32_16x16x32_bf16 v[118:121], v[162:165], v[178:181], v[118:121]
	v_mfma_f32_16x16x32_bf16 v[114:117], v[170:173], v[178:181], v[114:117]
	v_mfma_f32_16x16x32_bf16 v[102:105], v[162:165], v[196:199], v[102:105]
	v_mfma_f32_16x16x32_bf16 v[98:101], v[170:173], v[196:199], v[98:101]
	v_mfma_f32_16x16x32_bf16 v[86:89], v[162:165], v[204:207], v[86:89]
	v_mfma_f32_16x16x32_bf16 v[82:85], v[170:173], v[204:207], v[82:85]
	v_mfma_f32_16x16x32_bf16 v[70:73], v[162:165], v[212:215], v[70:73]
	v_mfma_f32_16x16x32_bf16 v[66:69], v[170:173], v[212:215], v[66:69]
	s_setprio 0
	s_barrier
	s_add_i32 s0, s20, s91
	v_lshl_add_u64 v[182:183], s[80:81], 0, v[132:133]
	s_mov_b32 m0, s0
	ds_read_b128 v[174:177], v189 offset:16384
	ds_read_b128 v[178:181], v189 offset:17408
	ds_read_b128 v[190:193], v189 offset:18432
	ds_read_b128 v[196:199], v189 offset:19456
	ds_read_b128 v[200:203], v189 offset:20480
	ds_read_b128 v[204:207], v189 offset:21504
	ds_read_b128 v[208:211], v189 offset:22528
	ds_read_b128 v[212:215], v189 offset:23552
	global_load_lds_dwordx4 v[182:183], off
	s_add_i32 m0, s0, 0x2000
	s_add_u32 s0, s80, 0x40000
	v_lshl_add_u64 v[186:187], s[80:81], 0, v[136:137]
	s_addc_u32 s1, s81, 0
	s_add_i32 s20, s26, s91
	global_load_lds_dwordx4 v[186:187], off
	v_lshl_add_u64 v[216:217], s[0:1], 0, v[132:133]
	s_mov_b32 m0, s20
	v_lshl_add_u64 v[218:219], s[82:83], 0, v[134:135]
	global_load_lds_dwordx4 v[216:217], off
	v_lshl_add_u64 v[216:217], s[0:1], 0, v[136:137]
	s_add_i32 m0, s20, 0x2000
	s_nop 0
	global_load_lds_dwordx4 v[216:217], off
	v_lshl_add_u64 v[216:217], s[82:83], 0, v[130:131]
	s_mov_b32 m0, s92
	s_nop 0
	global_load_lds_dwordx4 v[216:217], off
	s_mov_b32 m0, s93
	s_nop 0
	global_load_lds_dwordx4 v[218:219], off
	s_waitcnt vmcnt(8)
	s_waitcnt lgkmcnt(0)
	s_barrier
; #define PG8_STAGE(bufoff, gbase, voff) do { _Pragma("unroll") for (int _i = 0; _i < 2; ++_i) \
;         __builtin_amdgcn_global_load_lds((const unsigned*)((const char*)(gbase) + (voff)[_i]), (LAS unsigned*)(lds + (bufoff) + ldsw + _i * 8192), 16, 0, 0); } while (0)
; #define PG8_LDA(dst, b, h) do { _Pragma("unroll") for (int m = 0; m < 4; ++m) _Pragma("unroll") for (int k = 0; k < 2; ++k) dst[m][k] = *(const LAS bf16x8*)(lds + PG8_SA(b, h) + aoff + m * 2048 + k * 1024); } while (0)
; #define PG8_LDB(dst, b, h) do { _Pragma("unroll") for (int n = 0; n < 2; ++n) _Pragma("unroll") for (int k = 0; k < 2; ++k) dst[n][k] = *(const LAS bf16x8*)(lds + PG8_SB(b, h) + boff + n * 2048 + k * 1024); } while (0)
; #define PG8_MMA(ai, bj, At, Bt) do { __builtin_amdgcn_s_setprio(1); _Pragma("unroll") for (int m = 0; m < 4; ++m) _Pragma("unroll") for (int n = 0; n < 2; ++n) _Pragma("unroll") for (int k = 0; k < 2; ++k) \
;         acc[ai][bj][m][n] = __builtin_amdgcn_mfma_f32_16x16x32_bf16(Bt[n][k], At[m][k], acc[ai][bj][m][n], 0, 0, 0); __builtin_amdgcn_s_setprio(0); } while (0)
; #define PG8_WAIT_V(n) asm volatile("s_waitcnt vmcnt(" #n ")" ::: "memory")
; #define PG8_WAIT_L(n) asm volatile("s_waitcnt lgkmcnt(" #n ")" ::: "memory")
; #define PG8_BAR __builtin_amdgcn_s_barrier()
; #define PG8_SCHED __builtin_amdgcn_sched_barrier(0)
; template <class Epi, class Sched>
; __device__ __forceinline__ void gemm_phase(LAS unsigned char* lds, const Gemm g, const Sched& S, const Epi& E, int wv) {
;     ...
;             PG8_WAIT_V(8); PG8_WAIT_L(0); PG8_BAR; PG8_MMA(0, 0, At, B0); PG8_MMA(0, 1, At, B1); PG8_BAR; PG8_SCHED;
;             PG8_LDA(At, 0, 1); PG8_STAGE(PG8_SB(0, 0), b2, voffB); PG8_STAGE(PG8_SB(0, 1), b2 + hstepB, voffB); PG8_STAGE(PG8_SA(0, 0), a2, voffA);
;             PG8_WAIT_V(8); PG8_WAIT_L(0); PG8_BAR; PG8_MMA(1, 0, At, B0); PG8_MMA(1, 1, At, B1); PG8_BAR; PG8_SCHED;
;             PG8_LDB(B0, 1, 0); PG8_LDB(B1, 1, 1); PG8_SCHED; PG8_LDA(At, 1, 0); PG8_STAGE(PG8_SA(0, 1), a2 + hstepA, voffA);
;             PG8_WAIT_V(8); PG8_WAIT_L(0); PG8_BAR; PG8_MMA(0, 0, At, B0); PG8_MMA(0, 1, At, B1); PG8_BAR; PG8_SCHED;
	s_setprio 1
	v_mfma_f32_16x16x32_bf16 v[62:65], v[142:145], v[174:177], v[62:65]
	v_mfma_f32_16x16x32_bf16 v[58:61], v[150:153], v[174:177], v[58:61]
	v_mfma_f32_16x16x32_bf16 v[46:49], v[142:145], v[190:193], v[46:49]
	v_mfma_f32_16x16x32_bf16 v[42:45], v[150:153], v[190:193], v[42:45]
	v_mfma_f32_16x16x32_bf16 v[30:33], v[142:145], v[200:203], v[30:33]
	v_mfma_f32_16x16x32_bf16 v[26:29], v[150:153], v[200:203], v[26:29]
	v_mfma_f32_16x16x32_bf16 v[14:17], v[142:145], v[208:211], v[14:17]
	v_mfma_f32_16x16x32_bf16 v[10:13], v[150:153], v[208:211], v[10:13]
	v_mfma_f32_16x16x32_bf16 v[62:65], v[146:149], v[178:181], v[62:65]
	v_mfma_f32_16x16x32_bf16 v[58:61], v[154:157], v[178:181], v[58:61]
	v_mfma_f32_16x16x32_bf16 v[46:49], v[146:149], v[196:199], v[46:49]
	v_mfma_f32_16x16x32_bf16 v[42:45], v[154:157], v[196:199], v[42:45]
	v_mfma_f32_16x16x32_bf16 v[30:33], v[146:149], v[204:207], v[30:33]
	v_mfma_f32_16x16x32_bf16 v[26:29], v[154:157], v[204:207], v[26:29]
	v_mfma_f32_16x16x32_bf16 v[14:17], v[146:149], v[212:215], v[14:17]
	v_mfma_f32_16x16x32_bf16 v[10:13], v[154:157], v[212:215], v[10:13]
	v_mfma_f32_16x16x32_bf16 v[54:57], v[158:161], v[174:177], v[54:57]
	v_mfma_f32_16x16x32_bf16 v[50:53], v[166:169], v[174:177], v[50:53]
	v_mfma_f32_16x16x32_bf16 v[38:41], v[158:161], v[190:193], v[38:41]
	v_mfma_f32_16x16x32_bf16 v[34:37], v[166:169], v[190:193], v[34:37]
	v_mfma_f32_16x16x32_bf16 v[22:25], v[158:161], v[200:203], v[22:25]
	v_mfma_f32_16x16x32_bf16 v[18:21], v[166:169], v[200:203], v[18:21]
	v_mfma_f32_16x16x32_bf16 v[6:9], v[158:161], v[208:211], v[6:9]
	v_mfma_f32_16x16x32_bf16 v[2:5], v[166:169], v[208:211], v[2:5]
	v_mfma_f32_16x16x32_bf16 v[54:57], v[162:165], v[178:181], v[54:57]
	v_mfma_f32_16x16x32_bf16 v[50:53], v[170:173], v[178:181], v[50:53]
	v_mfma_f32_16x16x32_bf16 v[38:41], v[162:165], v[196:199], v[38:41]
	v_mfma_f32_16x16x32_bf16 v[34:37], v[170:173], v[196:199], v[34:37]
	v_mfma_f32_16x16x32_bf16 v[22:25], v[162:165], v[204:207], v[22:25]
	v_mfma_f32_16x16x32_bf16 v[18:21], v[170:173], v[204:207], v[18:21]
	v_mfma_f32_16x16x32_bf16 v[6:9], v[162:165], v[212:215], v[6:9]
	v_mfma_f32_16x16x32_bf16 v[2:5], v[170:173], v[212:215], v[2:5]
	s_setprio 0
	s_barrier
	s_add_i32 s20, 0, 0x18000
	v_add_u32_e32 v0, s20, v185
	s_add_i32 s26, 0, 0x1c000
	ds_read_b128 v[142:145], v0
	ds_read_b128 v[146:149], v0 offset:1024
	ds_read_b128 v[150:153], v0 offset:2048
	ds_read_b128 v[154:157], v0 offset:3072
	v_add_u32_e32 v0, s26, v185
	ds_read_b128 v[158:161], v0
	ds_read_b128 v[162:165], v0 offset:1024
	ds_read_b128 v[166:169], v0 offset:2048
	ds_read_b128 v[170:173], v0 offset:3072
	s_add_u32 s0, s82, 0x40000
	s_addc_u32 s1, s83, 0
	s_mov_b32 m0, s96
	v_lshl_add_u64 v[220:221], s[0:1], 0, v[130:131]
	ds_read_b128 v[174:177], v189 offset:32768
	ds_read_b128 v[178:181], v189 offset:33792
	ds_read_b128 v[190:193], v189 offset:34816
	ds_read_b128 v[196:199], v189 offset:35840
	ds_read_b128 v[200:203], v189 offset:36864
	ds_read_b128 v[204:207], v189 offset:37888
	ds_read_b128 v[208:211], v189 offset:38912
	ds_read_b128 v[212:215], v189 offset:39936
	global_load_lds_dwordx4 v[220:221], off
	v_lshl_add_u64 v[220:221], s[0:1], 0, v[134:135]
	s_mov_b32 m0, s50
	s_nop 0
	global_load_lds_dwordx4 v[220:221], off
	s_waitcnt vmcnt(8)
	s_waitcnt lgkmcnt(0)
	s_barrier
	s_setprio 1
	v_mfma_f32_16x16x32_bf16 v[126:129], v[142:145], v[174:177], v[126:129]
	v_mfma_f32_16x16x32_bf16 v[122:125], v[150:153], v[174:177], v[122:125]
	v_mfma_f32_16x16x32_bf16 v[110:113], v[142:145], v[190:193], v[110:113]
	v_mfma_f32_16x16x32_bf16 v[106:109], v[150:153], v[190:193], v[106:109]
	v_mfma_f32_16x16x32_bf16 v[94:97], v[142:145], v[200:203], v[94:97]
	v_mfma_f32_16x16x32_bf16 v[90:93], v[150:153], v[200:203], v[90:93]
	v_mfma_f32_16x16x32_bf16 v[78:81], v[142:145], v[208:211], v[78:81]
	v_mfma_f32_16x16x32_bf16 v[74:77], v[150:153], v[208:211], v[74:77]
	v_mfma_f32_16x16x32_bf16 v[126:129], v[146:149], v[178:181], v[126:129]
	v_mfma_f32_16x16x32_bf16 v[122:125], v[154:157], v[178:181], v[122:125]
	v_mfma_f32_16x16x32_bf16 v[110:113], v[146:149], v[196:199], v[110:113]
	v_mfma_f32_16x16x32_bf16 v[106:109], v[154:157], v[196:199], v[106:109]
	v_mfma_f32_16x16x32_bf16 v[94:97], v[146:149], v[204:207], v[94:97]
	v_mfma_f32_16x16x32_bf16 v[90:93], v[154:157], v[204:207], v[90:93]
	v_mfma_f32_16x16x32_bf16 v[78:81], v[146:149], v[212:215], v[78:81]
	v_mfma_f32_16x16x32_bf16 v[74:77], v[154:157], v[212:215], v[74:77]
	v_mfma_f32_16x16x32_bf16 v[118:121], v[158:161], v[174:177], v[118:121]
	v_mfma_f32_16x16x32_bf16 v[114:117], v[166:169], v[174:177], v[114:117]
	v_mfma_f32_16x16x32_bf16 v[102:105], v[158:161], v[190:193], v[102:105]
	v_mfma_f32_16x16x32_bf16 v[98:101], v[166:169], v[190:193], v[98:101]
	v_mfma_f32_16x16x32_bf16 v[86:89], v[158:161], v[200:203], v[86:89]
	v_mfma_f32_16x16x32_bf16 v[82:85], v[166:169], v[200:203], v[82:85]
	v_mfma_f32_16x16x32_bf16 v[70:73], v[158:161], v[208:211], v[70:73]
	v_mfma_f32_16x16x32_bf16 v[66:69], v[166:169], v[208:211], v[66:69]
	v_mfma_f32_16x16x32_bf16 v[118:121], v[162:165], v[178:181], v[118:121]
	v_mfma_f32_16x16x32_bf16 v[114:117], v[170:173], v[178:181], v[114:117]
	v_mfma_f32_16x16x32_bf16 v[102:105], v[162:165], v[196:199], v[102:105]
	v_mfma_f32_16x16x32_bf16 v[98:101], v[170:173], v[196:199], v[98:101]
	v_mfma_f32_16x16x32_bf16 v[86:89], v[162:165], v[204:207], v[86:89]
	v_mfma_f32_16x16x32_bf16 v[82:85], v[170:173], v[204:207], v[82:85]
	v_mfma_f32_16x16x32_bf16 v[70:73], v[162:165], v[212:215], v[70:73]
	v_mfma_f32_16x16x32_bf16 v[66:69], v[170:173], v[212:215], v[66:69]
	s_setprio 0
	s_barrier
; __device__ __forceinline__ int ltid(int wv) { unsigned z = 0u; asm volatile("" : "+v"(z)); return wv * 64 + (int)__builtin_amdgcn_mbcnt_hi(~0u, __builtin_amdgcn_mbcnt_lo(~0u, z)); }
; #define EPI_LOOP_ROWS for (int ai = 0; ai < 2; ++ai) _Pragma("unroll") for (int m = 0; m < 4; ++m)
; __device__ __forceinline__ float row_part(const float* RS, int row, int fq) { const f32x4 a = ((const f32x4*)(RS + (size_t)row * 16))[fq]; return (a.x + a.y) + (a.z + a.w); }
; #define PG8_STAGE(bufoff, gbase, voff) do { _Pragma("unroll") for (int _i = 0; _i < 2; ++_i) \
;         __builtin_amdgcn_global_load_lds((const unsigned*)((const char*)(gbase) + (voff)[_i]), (LAS unsigned*)(lds + (bufoff) + ldsw + _i * 8192), 16, 0, 0); } while (0)
; #define PG8_LDA(dst, b, h) do { _Pragma("unroll") for (int m = 0; m < 4; ++m) _Pragma("unroll") for (int k = 0; k < 2; ++k) dst[m][k] = *(const LAS bf16x8*)(lds + PG8_SA(b, h) + aoff + m * 2048 + k * 1024); } while (0)
; #define PG8_MMA(ai, bj, At, Bt) do { __builtin_amdgcn_s_setprio(1); _Pragma("unroll") for (int m = 0; m < 4; ++m) _Pragma("unroll") for (int n = 0; n < 2; ++n) _Pragma("unroll") for (int k = 0; k < 2; ++k) \
;         acc[ai][bj][m][n] = __builtin_amdgcn_mfma_f32_16x16x32_bf16(Bt[n][k], At[m][k], acc[ai][bj][m][n], 0, 0, 0); __builtin_amdgcn_s_setprio(0); } while (0)
; #define PG8_WAIT_V(n) asm volatile("s_waitcnt vmcnt(" #n ")" ::: "memory")
;     __device__ __forceinline__ void operator()(const f32x4 (&acc)[2][2][4][2], const Unit& u, int wv) const {
;         const int t_ = ltid(wv), wid_ = __builtin_amdgcn_readfirstlane(t_ >> 6), wr = wid_ >> 2, wc = wid_ & 3, fr = t_ & 15, fq = (t_ & 63) >> 4;
;         const int col0 = u.pn * BM + wc * 32 + 8 * fq, row0 = u.pm * BM + wr * 64 + fr;
;         float rs[2][4], sq[2][4];
; #pragma unroll
;         EPI_LOOP_ROWS rs[ai][m] = RSin ? row_part(RSin, row0 + ai * HALF + m * 16, fq) : 0.f;
; template <class Epi, class Sched>
; __device__ __forceinline__ void gemm_phase(LAS unsigned char* lds, const Gemm g, const Sched& S, const Epi& E, int wv) {
;     ...
;             PG8_LDA(At, 1, 1); PG8_STAGE(PG8_SB(1, 0), b3, voffB); PG8_STAGE(PG8_SB(1, 1), b3 + hstepB, voffB); PG8_STAGE(PG8_SA(1, 0), a3, voffA);
;             PG8_WAIT_V(8); PG8_WAIT_L(0); PG8_BAR; PG8_MMA(1, 0, At, B0); PG8_MMA(1, 1, At, B1); PG8_BAR; PG8_SCHED;
;         }
;         if (wr == 0) PG8_BAR;
;         E(acc, cur, wv);
	s_add_i32 s0, s20, s91
	v_lshl_add_u64 v[182:183], v[182:183], 0, s[24:25]
	s_mov_b32 m0, s0
	ds_read_b128 v[174:177], v189 offset:49152
	ds_read_b128 v[178:181], v189 offset:50176
	ds_read_b128 v[190:193], v189 offset:51200
	ds_read_b128 v[196:199], v189 offset:52224
	ds_read_b128 v[200:203], v189 offset:53248
	ds_read_b128 v[204:207], v189 offset:54272
	ds_read_b128 v[208:211], v189 offset:55296
	ds_read_b128 v[212:215], v189 offset:56320
	global_load_lds_dwordx4 v[182:183], off
	s_add_i32 m0, s0, 0x2000
	s_add_u32 s0, s80, 0x40080
	v_lshl_add_u64 v[182:183], v[186:187], 0, s[24:25]
	s_addc_u32 s1, s81, 0
	s_add_i32 s20, s26, s91
	global_load_lds_dwordx4 v[182:183], off
	v_lshl_add_u64 v[182:183], s[0:1], 0, v[132:133]
	s_mov_b32 m0, s20
	s_nop 0
	global_load_lds_dwordx4 v[182:183], off
	v_lshl_add_u64 v[182:183], s[0:1], 0, v[136:137]
	s_add_i32 m0, s20, 0x2000
	s_nop 0
	global_load_lds_dwordx4 v[182:183], off
	v_lshl_add_u64 v[182:183], v[216:217], 0, s[24:25]
	s_mov_b32 m0, s62
	s_nop 0
	global_load_lds_dwordx4 v[182:183], off
	v_lshl_add_u64 v[182:183], v[218:219], 0, s[24:25]
	s_mov_b32 m0, s46
	s_nop 0
	global_load_lds_dwordx4 v[182:183], off
	s_waitcnt vmcnt(8)
	s_waitcnt lgkmcnt(0)
	s_barrier
	s_setprio 1
	v_mfma_f32_16x16x32_bf16 v[62:65], v[142:145], v[174:177], v[62:65]
	v_mfma_f32_16x16x32_bf16 v[58:61], v[150:153], v[174:177], v[58:61]
	v_mfma_f32_16x16x32_bf16 v[46:49], v[142:145], v[190:193], v[46:49]
	v_mfma_f32_16x16x32_bf16 v[42:45], v[150:153], v[190:193], v[42:45]
	v_mfma_f32_16x16x32_bf16 v[30:33], v[142:145], v[200:203], v[30:33]
	v_mfma_f32_16x16x32_bf16 v[26:29], v[150:153], v[200:203], v[26:29]
	v_mfma_f32_16x16x32_bf16 v[14:17], v[142:145], v[208:211], v[14:17]
	v_mfma_f32_16x16x32_bf16 v[10:13], v[150:153], v[208:211], v[10:13]
	v_mfma_f32_16x16x32_bf16 v[62:65], v[146:149], v[178:181], v[62:65]
	v_mfma_f32_16x16x32_bf16 v[58:61], v[154:157], v[178:181], v[58:61]
	v_mfma_f32_16x16x32_bf16 v[46:49], v[146:149], v[196:199], v[46:49]
	v_mfma_f32_16x16x32_bf16 v[42:45], v[154:157], v[196:199], v[42:45]
	v_mfma_f32_16x16x32_bf16 v[30:33], v[146:149], v[204:207], v[30:33]
	v_mfma_f32_16x16x32_bf16 v[26:29], v[154:157], v[204:207], v[26:29]
	v_mfma_f32_16x16x32_bf16 v[14:17], v[146:149], v[212:215], v[14:17]
	v_mfma_f32_16x16x32_bf16 v[10:13], v[154:157], v[212:215], v[10:13]
	v_mfma_f32_16x16x32_bf16 v[54:57], v[158:161], v[174:177], v[54:57]
	v_mfma_f32_16x16x32_bf16 v[50:53], v[166:169], v[174:177], v[50:53]
	v_mfma_f32_16x16x32_bf16 v[38:41], v[158:161], v[190:193], v[38:41]
	v_mfma_f32_16x16x32_bf16 v[34:37], v[166:169], v[190:193], v[34:37]
	v_mfma_f32_16x16x32_bf16 v[22:25], v[158:161], v[200:203], v[22:25]
	v_mfma_f32_16x16x32_bf16 v[18:21], v[166:169], v[200:203], v[18:21]
	v_mfma_f32_16x16x32_bf16 v[6:9], v[158:161], v[208:211], v[6:9]
	v_mfma_f32_16x16x32_bf16 v[2:5], v[166:169], v[208:211], v[2:5]
	v_mfma_f32_16x16x32_bf16 v[54:57], v[162:165], v[178:181], v[54:57]
	v_mfma_f32_16x16x32_bf16 v[50:53], v[170:173], v[178:181], v[50:53]
	v_mfma_f32_16x16x32_bf16 v[38:41], v[162:165], v[196:199], v[38:41]
	v_mfma_f32_16x16x32_bf16 v[34:37], v[170:173], v[196:199], v[34:37]
	v_mfma_f32_16x16x32_bf16 v[22:25], v[162:165], v[204:207], v[22:25]
	v_mfma_f32_16x16x32_bf16 v[18:21], v[170:173], v[204:207], v[18:21]
	v_mfma_f32_16x16x32_bf16 v[6:9], v[162:165], v[212:215], v[6:9]
	v_mfma_f32_16x16x32_bf16 v[2:5], v[170:173], v[212:215], v[2:5]
	s_setprio 0
	s_barrier
	s_add_i32 s35, s35, 2
	s_add_u32 s78, s78, 0x100
	s_addc_u32 s79, s79, 0
	s_add_u32 s31, s31, 0x100
	s_addc_u32 s34, s34, 0
	s_cmp_gt_u32 s35, 13
	s_cbranch_scc0 .LBB0_141
	s_and_b64 vcc, exec, s[68:69]
	s_cbranch_vccz .LBB0_144
	s_barrier
.LBB0_144:
	v_mov_b32_e32 v0, v1
	s_lshl_b32 s1, s4, 8
	v_mbcnt_lo_u32_b32 v0, -1, v0
	v_mbcnt_hi_u32_b32 v0, -1, v0
	v_add_u32_e32 v142, s33, v0
	v_and_b32_e32 v214, 63, v0
	v_readfirstlane_b32 s0, v142
	s_bfe_u32 s49, s0, 0x20006
	s_ashr_i32 s0, s0, 2
	s_andn2_b32 s0, s0, 63
	s_add_i32 s0, s0, s1
	v_and_or_b32 v164, v0, 15, s0
	v_lshrrev_b32_e32 v196, 1, v0
	v_and_b32_e32 v0, 48, v0
	v_ashrrev_i32_e32 v165, 31, v164
	v_lshl_add_u64 v[190:191], s[64:65], 0, v[0:1]
	v_lshlrev_b64 v[142:143], 6, v[164:165]
	v_lshl_add_u64 v[144:145], v[190:191], 0, v[142:143]
	global_load_dwordx4 v[144:147], v[144:145], off
	v_or_b32_e32 v186, 16, v164
	v_ashrrev_i32_e32 v187, 31, v186
	v_or_b32_e32 v180, 32, v164
	v_ashrrev_i32_e32 v181, 31, v180
	v_or_b32_e32 v178, 48, v164
	v_ashrrev_i32_e32 v179, 31, v178
	v_add_u32_e32 v172, 0x80, v164
	v_ashrrev_i32_e32 v173, 31, v172
	v_add_u32_e32 v168, 0x90, v164
	v_ashrrev_i32_e32 v169, 31, v168
	v_add_u32_e32 v162, 0xa0, v164
	v_ashrrev_i32_e32 v163, 31, v162
	v_lshlrev_b32_e32 v0, 2, v214
	v_xor_b32_e32 v216, 64, v0
	v_xor_b32_e32 v215, 0x80, v0
	s_lshl_b32 s5, s49, 5
	s_lshl_b32 s0, s28, 8
	s_or_b32 s10, s5, s0
	s_mov_b32 s0, 0x358637bd
	v_and_or_b32 v196, v196, 24, s10
	v_ashrrev_i32_e32 v197, 31, v196
	v_lshlrev_b32_e32 v217, 11, v164
	v_lshl_add_u32 v217, v196, 1, v217
	global_load_dwordx4 v[220:223], v217, s[12:13]
	s_waitcnt vmcnt(0)
	v_mov_b32_e32 v148, v145
	v_mov_b32_e32 v149, v146
	v_mov_b32_e32 v145, v147
	v_pk_add_f32 v[160:161], v[148:149], v[144:145]
	v_lshlrev_b64 v[144:145], 6, v[186:187]
	v_lshl_add_u64 v[146:147], v[190:191], 0, v[144:145]
	global_load_dwordx4 v[146:149], v[146:147], off
	s_waitcnt vmcnt(0)
	v_mov_b32_e32 v150, v147
	v_mov_b32_e32 v151, v148
	v_mov_b32_e32 v147, v149
	v_pk_add_f32 v[182:183], v[150:151], v[146:147]
	v_lshlrev_b64 v[146:147], 6, v[180:181]
	v_lshl_add_u64 v[148:149], v[190:191], 0, v[146:147]
	global_load_dwordx4 v[148:151], v[148:149], off
	s_waitcnt vmcnt(0)
; __device__ __forceinline__ float sigmoidf_(float v) { return __builtin_amdgcn_rcpf(1.0f + __expf(-v)); }
; #define EPI_LOOP_ROWS for (int ai = 0; ai < 2; ++ai) _Pragma("unroll") for (int m = 0; m < 4; ++m)
; __device__ __forceinline__ float row_part(const float* RS, int row, int fq) { const f32x4 a = ((const f32x4*)(RS + (size_t)row * 16))[fq]; return (a.x + a.y) + (a.z + a.w); }
; __device__ __forceinline__ float row_rstd_fin(float s, int lane) { s += shx(s, 16, lane); s += shx(s, 32, lane); return rsqrtf(s * (1.0f / 1024.0f) + EPS); }
;     __device__ __forceinline__ void operator()(const f32x4 (&acc)[2][2][4][2], const Unit& u, int wv) const {
;     ...
;         EPI_LOOP_ROWS rs[ai][m] = RSin ? row_part(RSin, row0 + ai * HALF + m * 16, fq) : 0.f;
; #pragma unroll
;         EPI_LOOP_ROWS rs[ai][m] = RSin ? row_rstd_fin(rs[ai][m], t_ & 63) : 1.0f;
; #pragma unroll
;         EPI_LOOP_ROWS { const size_t row = (size_t)(row0 + ai * HALF + m * 16);
;             const float rstd = rs[ai][m]; float ssq = 0.f;
; #pragma unroll
;             for (int bj = 0; bj < 2; ++bj) { const int col = col0 + bj * HALF;
;                 f32x4 v0 = acc[ai][bj][m][0] * rstd, v1 = acc[ai][bj][m][1] * rstd;
;                 if (PP) { const u32x4 g = *(const u32x4*)(PP + row * 1024 + col);
;                     v0[0] = sigmoidf_(v0[0]) * __builtin_bit_cast(float, g.x << 16); v0[1] = sigmoidf_(v0[1]) * __builtin_bit_cast(float, g.x & 0xffff0000u);
	v_mov_b32_e32 v152, v149
	v_mov_b32_e32 v153, v150
	v_mov_b32_e32 v149, v151
	v_pk_add_f32 v[174:175], v[152:153], v[148:149]
	v_lshlrev_b64 v[148:149], 6, v[178:179]
	v_lshl_add_u64 v[150:151], v[190:191], 0, v[148:149]
	global_load_dwordx4 v[150:153], v[150:151], off
	s_waitcnt vmcnt(0)
	v_mov_b32_e32 v154, v151
	v_mov_b32_e32 v155, v152
	v_mov_b32_e32 v151, v153
	v_pk_add_f32 v[176:177], v[154:155], v[150:151]
	v_lshlrev_b64 v[150:151], 6, v[172:173]
	v_lshl_add_u64 v[152:153], v[190:191], 0, v[150:151]
	global_load_dwordx4 v[152:155], v[152:153], off
	s_waitcnt vmcnt(0)
	v_mov_b32_e32 v156, v153
	v_mov_b32_e32 v157, v154
	v_mov_b32_e32 v153, v155
	v_pk_add_f32 v[170:171], v[156:157], v[152:153]
	v_lshlrev_b64 v[152:153], 6, v[168:169]
	v_lshl_add_u64 v[154:155], v[190:191], 0, v[152:153]
	global_load_dwordx4 v[154:157], v[154:155], off
	s_waitcnt vmcnt(0)
	v_mov_b32_e32 v158, v155
	v_mov_b32_e32 v159, v156
	v_mov_b32_e32 v155, v157
	v_pk_add_f32 v[192:193], v[158:159], v[154:155]
	v_lshlrev_b64 v[154:155], 6, v[162:163]
	v_lshl_add_u64 v[156:157], v[190:191], 0, v[154:155]
	global_load_dwordx4 v[156:159], v[156:157], off
	s_waitcnt vmcnt(0)
	v_mov_b32_e32 v167, v158
	v_add_u32_e32 v158, 0xb0, v164
	v_mov_b32_e32 v166, v157
	v_mov_b32_e32 v157, v159
	v_ashrrev_i32_e32 v159, 31, v158
	v_pk_add_f32 v[166:167], v[166:167], v[156:157]
	v_lshlrev_b64 v[156:157], 6, v[158:159]
	v_lshl_add_u64 v[190:191], v[190:191], 0, v[156:157]
	global_load_dwordx4 v[198:201], v[190:191], off
	s_waitcnt vmcnt(0)
	v_mov_b32_e32 v190, v199
	v_mov_b32_e32 v191, v200
	v_mov_b32_e32 v199, v201
	v_pk_add_f32 v[190:191], v[190:191], v[198:199]
	v_mov_b32_e32 v198, v182
	v_mov_b32_e32 v199, v160
	v_mov_b32_e32 v160, v183
	v_pk_add_f32 v[160:161], v[198:199], v[160:161]
	ds_bpermute_b32 v183, v216, v161
	ds_bpermute_b32 v182, v216, v160
	v_mov_b64_e32 v[198:199], s[0:1]
	s_mov_b32 s0, 0x3a800000
	s_waitcnt lgkmcnt(0)
	v_pk_add_f32 v[160:161], v[160:161], v[182:183]
	ds_bpermute_b32 v183, v215, v161
	ds_bpermute_b32 v182, v215, v160
	s_waitcnt lgkmcnt(0)
	v_pk_add_f32 v[160:161], v[160:161], v[182:183]
	s_nop 0
	v_pk_fma_f32 v[160:161], v[160:161], s[0:1], v[198:199] op_sel_hi:[1,0,0]
	s_nop 0
	v_mul_f32_e32 v0, 0x4b800000, v161
	v_cmp_gt_f32_e64 s[4:5], s97, v161
	v_cmp_gt_f32_e32 vcc, s97, v160
	s_nop 0
	v_cndmask_b32_e64 v0, v161, v0, s[4:5]
	v_rsq_f32_e32 v0, v0
	s_nop 0
	v_mul_f32_e32 v161, 0x45800000, v0
	v_cndmask_b32_e64 v188, v0, v161, s[4:5]
	v_mul_f32_e32 v0, 0x4b800000, v160
	v_cndmask_b32_e32 v0, v160, v0, vcc
	v_rsq_f32_e32 v0, v0
	v_mov_b32_e32 v161, v174
	v_mov_b32_e32 v174, v177
	v_pk_mul_f32 v[204:205], v[122:123], v[188:189] op_sel_hi:[1,0]
	v_mul_f32_e32 v160, 0x45800000, v0
	v_cndmask_b32_e32 v184, v0, v160, vcc
	v_mov_b32_e32 v160, v176
	v_pk_add_f32 v[160:161], v[160:161], v[174:175]
	ds_bpermute_b32 v175, v216, v161
	ds_bpermute_b32 v174, v216, v160
	v_pk_mul_f32 v[210:211], v[124:125], v[188:189] op_sel_hi:[1,0]
	v_pk_mul_f32 v[128:129], v[128:129], v[188:189] op_sel_hi:[1,0]
	v_pk_mul_f32 v[126:127], v[126:127], v[188:189] op_sel_hi:[1,0]
	v_pk_mul_f32 v[120:121], v[120:121], v[188:189] op_sel_hi:[1,0]
	s_waitcnt lgkmcnt(0)
	v_pk_add_f32 v[160:161], v[160:161], v[174:175]
	ds_bpermute_b32 v175, v215, v161
	ds_bpermute_b32 v174, v215, v160
	v_mul_f32_e32 v126, 0xbfb8aa3b, v126
	v_exp_f32_e32 v126, v126
	v_pk_mul_f32 v[118:119], v[118:119], v[188:189] op_sel_hi:[1,0]
	v_pk_mul_f32 v[110:111], v[110:111], v[184:185] op_sel_hi:[1,0]
	s_waitcnt lgkmcnt(0)
	v_pk_add_f32 v[160:161], v[160:161], v[174:175]
	v_add_f32_e32 v126, 1.0, v126
	v_pk_fma_f32 v[160:161], v[160:161], s[0:1], v[198:199] op_sel_hi:[1,0,0]
	v_mul_f32_e32 v118, 0xbfb8aa3b, v118
	v_mul_f32_e32 v0, 0x4b800000, v161
	v_cmp_gt_f32_e64 s[4:5], s97, v161
	v_cmp_gt_f32_e32 vcc, s97, v160
	v_exp_f32_e32 v118, v118
	v_cndmask_b32_e64 v0, v161, v0, s[4:5]
	v_rsq_f32_e32 v0, v0
	v_pk_mul_f32 v[112:113], v[112:113], v[184:185] op_sel_hi:[1,0]
	v_add_f32_e32 v118, 1.0, v118
	v_mul_f32_e32 v112, 0xbfb8aa3b, v112
	v_mul_f32_e32 v161, 0x45800000, v0
	v_cndmask_b32_e64 v182, v0, v161, s[4:5]
	v_mul_f32_e32 v0, 0x4b800000, v160
	v_cndmask_b32_e32 v0, v160, v0, vcc
	v_rsq_f32_e32 v0, v0
	v_mov_b32_e32 v161, v170
	v_mov_b32_e32 v170, v193
	v_mul_f32_e32 v113, 0xbfb8aa3b, v113
	v_mul_f32_e32 v160, 0x45800000, v0
	v_cndmask_b32_e32 v176, v0, v160, vcc
	v_mov_b32_e32 v160, v192
	v_pk_add_f32 v[160:161], v[160:161], v[170:171]
	ds_bpermute_b32 v171, v216, v161
	ds_bpermute_b32 v170, v216, v160
	v_lshlrev_b64 v[192:193], 11, v[164:165]
	v_lshl_add_u64 v[122:123], s[12:13], 0, v[192:193]
	v_exp_f32_e32 v112, v112
	v_exp_f32_e32 v113, v113
	s_waitcnt lgkmcnt(0)
	v_pk_add_f32 v[160:161], v[160:161], v[170:171]
	ds_bpermute_b32 v171, v215, v161
	ds_bpermute_b32 v170, v215, v160
	v_add_f32_e32 v112, 1.0, v112
	v_add_f32_e32 v113, 1.0, v113
	v_rcp_f32_e32 v112, v112
	v_rcp_f32_e32 v113, v113
	s_waitcnt lgkmcnt(0)
	v_pk_add_f32 v[160:161], v[160:161], v[170:171]
	v_pk_mul_f32 v[104:105], v[104:105], v[184:185] op_sel_hi:[1,0]
	v_pk_fma_f32 v[160:161], v[160:161], s[0:1], v[198:199] op_sel_hi:[1,0,0]
	v_pk_mul_f32 v[102:103], v[102:103], v[184:185] op_sel_hi:[1,0]
	v_mul_f32_e32 v0, 0x4b800000, v161
	v_cmp_gt_f32_e64 s[4:5], s97, v161
	v_cmp_gt_f32_e32 vcc, s97, v160
	v_mul_f32_e32 v102, 0xbfb8aa3b, v102
	v_cndmask_b32_e64 v0, v161, v0, s[4:5]
	v_rsq_f32_e32 v0, v0
	v_exp_f32_e32 v102, v102
	v_pk_mul_f32 v[90:91], v[90:91], v[182:183] op_sel_hi:[1,0]
	v_pk_mul_f32 v[94:95], v[94:95], v[182:183] op_sel_hi:[1,0]
	v_mul_f32_e32 v161, 0x45800000, v0
	v_cndmask_b32_e64 v174, v0, v161, s[4:5]
	v_mul_f32_e32 v0, 0x4b800000, v160
	v_cndmask_b32_e32 v0, v160, v0, vcc
	v_rsq_f32_e32 v0, v0
	v_mov_b32_e32 v161, v166
	v_mov_b32_e32 v166, v191
	v_add_f32_e32 v102, 1.0, v102
	v_mul_f32_e32 v160, 0x45800000, v0
	v_cndmask_b32_e32 v170, v0, v160, vcc
	v_mov_b32_e32 v160, v190
	v_pk_add_f32 v[160:161], v[160:161], v[166:167]
	ds_bpermute_b32 v167, v216, v161
	ds_bpermute_b32 v166, v216, v160
	v_mul_f32_e32 v90, 0xbfb8aa3b, v90
	v_exp_f32_e32 v90, v90
	v_mul_f32_e32 v94, 0xbfb8aa3b, v94
	v_exp_f32_e32 v94, v94
	s_waitcnt lgkmcnt(0)
; __device__ __forceinline__ unsigned cvtpk(float lo, float hi) { f32x2 v = {lo, hi}; bf16x2_t b = __builtin_convertvector(v, bf16x2_t); return __builtin_bit_cast(unsigned, b); }
; __device__ __forceinline__ float sigmoidf_(float v) { return __builtin_amdgcn_rcpf(1.0f + __expf(-v)); }
; #define EPI_LOOP_ROWS for (int ai = 0; ai < 2; ++ai) _Pragma("unroll") for (int m = 0; m < 4; ++m)
;     __device__ __forceinline__ void operator()(const f32x4 (&acc)[2][2][4][2], const Unit& u, int wv) const {
;     ...
;         EPI_LOOP_ROWS { const size_t row = (size_t)(row0 + ai * HALF + m * 16);
;             const float rstd = rs[ai][m]; float ssq = 0.f;
; #pragma unroll
;             for (int bj = 0; bj < 2; ++bj) { const int col = col0 + bj * HALF;
;                 f32x4 v0 = acc[ai][bj][m][0] * rstd, v1 = acc[ai][bj][m][1] * rstd;
;                 if (PP) { const u32x4 g = *(const u32x4*)(PP + row * 1024 + col);
;                     v0[0] = sigmoidf_(v0[0]) * __builtin_bit_cast(float, g.x << 16); v0[1] = sigmoidf_(v0[1]) * __builtin_bit_cast(float, g.x & 0xffff0000u);
;                     v0[2] = sigmoidf_(v0[2]) * __builtin_bit_cast(float, g.y << 16); v0[3] = sigmoidf_(v0[3]) * __builtin_bit_cast(float, g.y & 0xffff0000u);
;                     v1[0] = sigmoidf_(v1[0]) * __builtin_bit_cast(float, g.z << 16); v1[1] = sigmoidf_(v1[1]) * __builtin_bit_cast(float, g.z & 0xffff0000u);
;                     v1[2] = sigmoidf_(v1[2]) * __builtin_bit_cast(float, g.w << 16); v1[3] = sigmoidf_(v1[3]) * __builtin_bit_cast(float, g.w & 0xffff0000u); }
;                 float* xp = X + row * 1024 + col;
;                 v0 += *(const f32x4*)xp; v1 += *(const f32x4*)(xp + 4);
;                 *(f32x4*)xp = v0; *(f32x4*)(xp + 4) = v1;
;                 u32x4 w; w.x = cvtpk(v0[0], v0[1]); w.y = cvtpk(v0[2], v0[3]); w.z = cvtpk(v1[0], v1[1]); w.w = cvtpk(v1[2], v1[3]);
;                 *(u32x4*)(XB + row * 1024 + col) = w;
;                 ssq += ((v0[0] * v0[0] + v0[1] * v0[1]) + (v0[2] * v0[2] + v0[3] * v0[3])) + ((v1[0] * v1[0] + v1[1] * v1[1]) + (v1[2] * v1[2] + v1[3] * v1[3])); }
	v_pk_add_f32 v[160:161], v[160:161], v[166:167]
	ds_bpermute_b32 v167, v215, v161
	ds_bpermute_b32 v166, v215, v160
	v_add_f32_e32 v90, 1.0, v90
	v_add_f32_e32 v94, 1.0, v94
	v_pk_mul_f32 v[92:93], v[92:93], v[182:183] op_sel_hi:[1,0]
	v_pk_mul_f32 v[96:97], v[96:97], v[182:183] op_sel_hi:[1,0]
	s_waitcnt lgkmcnt(0)
	v_pk_add_f32 v[160:161], v[160:161], v[166:167]
	v_pk_mul_f32 v[88:89], v[88:89], v[182:183] op_sel_hi:[1,0]
	v_pk_fma_f32 v[160:161], v[160:161], s[0:1], v[198:199] op_sel_hi:[1,0,0]
	v_rcp_f32_e32 v198, v126
	v_mul_f32_e32 v0, 0x4b800000, v161
	v_cmp_gt_f32_e64 s[4:5], s97, v161
	v_cmp_gt_f32_e32 vcc, s97, v160
	v_mul_f32_e32 v126, 0xbfb8aa3b, v127
	v_cndmask_b32_e64 v0, v161, v0, s[4:5]
	v_rsq_f32_e32 v0, v0
	v_exp_f32_e32 v126, v126
	v_pk_mul_f32 v[86:87], v[86:87], v[182:183] op_sel_hi:[1,0]
	v_pk_mul_f32 v[78:79], v[78:79], v[176:177] op_sel_hi:[1,0]
	v_mul_f32_e32 v161, 0x45800000, v0
	v_cndmask_b32_e64 v166, v0, v161, s[4:5]
	v_mul_f32_e32 v0, 0x4b800000, v160
	v_cndmask_b32_e32 v0, v160, v0, vcc
	v_rsq_f32_e32 v0, v0
	v_add_f32_e32 v126, 1.0, v126
	v_rcp_f32_e32 v199, v126
	v_mul_f32_e32 v86, 0xbfb8aa3b, v86
	v_mul_f32_e32 v160, 0x45800000, v0
	v_cndmask_b32_e32 v0, v0, v160, vcc
	v_lshlrev_b64 v[160:161], 1, v[196:197]
	v_lshl_add_u64 v[190:191], v[122:123], 0, v[160:161]
	v_mov_b32_e32 v122, v220
	v_mov_b32_e32 v123, v221
	v_mov_b32_e32 v124, v222
	v_mov_b32_e32 v125, v223
	v_exp_f32_e32 v86, v86
	v_pk_mul_f32 v[80:81], v[80:81], v[176:177] op_sel_hi:[1,0]
	v_pk_mul_f32 v[72:73], v[72:73], v[176:177] op_sel_hi:[1,0]
	v_mul_f32_e32 v80, 0xbfb8aa3b, v80
	v_add_f32_e32 v86, 1.0, v86
	v_mul_f32_e32 v81, 0xbfb8aa3b, v81
	v_exp_f32_e32 v80, v80
	v_exp_f32_e32 v81, v81
	v_pk_mul_f32 v[70:71], v[70:71], v[176:177] op_sel_hi:[1,0]
	v_pk_mul_f32 v[58:59], v[58:59], v[174:175] op_sel_hi:[1,0]
	v_add_f32_e32 v80, 1.0, v80
	v_add_f32_e32 v81, 1.0, v81
	v_rcp_f32_e32 v80, v80
	v_rcp_f32_e32 v81, v81
	v_mul_f32_e32 v70, 0xbfb8aa3b, v70
	v_exp_f32_e32 v70, v70
	v_mul_f32_e32 v58, 0xbfb8aa3b, v58
	v_exp_f32_e32 v58, v58
	v_pk_mul_f32 v[62:63], v[62:63], v[174:175] op_sel_hi:[1,0]
	v_add_f32_e32 v70, 1.0, v70
	v_mul_f32_e32 v62, 0xbfb8aa3b, v62
	v_exp_f32_e32 v62, v62
	v_add_f32_e32 v58, 1.0, v58
	v_pk_mul_f32 v[60:61], v[60:61], v[174:175] op_sel_hi:[1,0]
	v_pk_mul_f32 v[64:65], v[64:65], v[174:175] op_sel_hi:[1,0]
	v_add_f32_e32 v62, 1.0, v62
	v_pk_mul_f32 v[56:57], v[56:57], v[174:175] op_sel_hi:[1,0]
	v_pk_mul_f32 v[54:55], v[54:55], v[174:175] op_sel_hi:[1,0]
	v_pk_mul_f32 v[48:49], v[48:49], v[170:171] op_sel_hi:[1,0]
	v_mul_f32_e32 v54, 0xbfb8aa3b, v54
	v_exp_f32_e32 v54, v54
	v_pk_mul_f32 v[40:41], v[40:41], v[170:171] op_sel_hi:[1,0]
	v_pk_mul_f32 v[38:39], v[38:39], v[170:171] op_sel_hi:[1,0]
	v_pk_mul_f32 v[16:17], v[16:17], v[0:1] op_sel_hi:[1,0]
	v_add_f32_e32 v54, 1.0, v54
	v_mul_f32_e32 v38, 0xbfb8aa3b, v38
	v_exp_f32_e32 v38, v38
	v_pk_mul_f32 v[14:15], v[14:15], v[0:1] op_sel_hi:[1,0]
	v_pk_mul_f32 v[6:7], v[6:7], v[0:1] op_sel_hi:[1,0]
	v_cmp_gt_u32_e32 vcc, 16, v214
	v_add_f32_e32 v38, 1.0, v38
	s_waitcnt vmcnt(0)
	v_lshlrev_b32_e32 v200, 16, v122
	v_and_b32_e32 v201, 0xffff0000, v122
	v_mul_f32_e32 v122, 0xbfb8aa3b, v128
	v_exp_f32_e32 v122, v122
	v_lshlrev_b32_e32 v206, 16, v123
	v_and_b32_e32 v207, 0xffff0000, v123
	v_lshlrev_b32_e32 v208, 16, v124
	v_add_f32_e32 v122, 1.0, v122
	v_rcp_f32_e32 v202, v122
	v_mul_f32_e32 v122, 0xbfb8aa3b, v129
	v_exp_f32_e32 v122, v122
	v_and_b32_e32 v209, 0xffff0000, v124
	v_lshlrev_b32_e32 v212, 16, v125
	v_and_b32_e32 v213, 0xffff0000, v125
	v_add_f32_e32 v122, 1.0, v122
	v_rcp_f32_e32 v203, v122
	v_mul_f32_e32 v122, 0xbfb8aa3b, v204
	v_exp_f32_e32 v122, v122
	s_nop 0
	v_add_f32_e32 v122, 1.0, v122
	v_rcp_f32_e32 v204, v122
	v_mul_f32_e32 v122, 0xbfb8aa3b, v205
	v_exp_f32_e32 v122, v122
	s_nop 0
	v_add_f32_e32 v122, 1.0, v122
	v_rcp_f32_e32 v205, v122
	v_mul_f32_e32 v122, 0xbfb8aa3b, v210
	v_exp_f32_e32 v122, v122
	s_nop 0
	v_add_f32_e32 v122, 1.0, v122
	v_rcp_f32_e32 v210, v122
	v_mul_f32_e32 v122, 0xbfb8aa3b, v211
	v_exp_f32_e32 v122, v122
	s_nop 0
	v_add_f32_e32 v122, 1.0, v122
	v_rcp_f32_e32 v211, v122
	v_lshlrev_b64 v[122:123], 12, v[164:165]
	v_lshl_add_u64 v[122:123], s[6:7], 0, v[122:123]
	v_lshlrev_b64 v[164:165], 2, v[196:197]
	v_lshl_add_u64 v[196:197], v[122:123], 0, v[164:165]
	global_load_dwordx4 v[224:227], v217, s[12:13] offset:256
	global_load_dwordx4 v[122:125], v[196:197], off offset:16
	global_load_dwordx4 v[126:129], v[196:197], off
	s_waitcnt vmcnt(0)
	v_pk_fma_f32 v[128:129], v[202:203], v[206:207], v[128:129]
	v_pk_fma_f32 v[126:127], v[198:199], v[200:201], v[126:127]
	v_pk_fma_f32 v[200:201], v[210:211], v[212:213], v[124:125]
	v_mul_f32_e32 v124, v127, v127
	v_mul_f32_e32 v125, v129, v129
	v_pk_fma_f32 v[198:199], v[204:205], v[208:209], v[122:123]
	v_fmac_f32_e32 v124, v126, v126
	v_fmac_f32_e32 v125, v128, v128
	global_store_dwordx4 v[196:197], v[126:129], off
	global_store_dwordx4 v[196:197], v[198:201], off offset:16
	v_cvt_pk_bf16_f32 v202, v126, v127
	v_add_f32_e32 v124, v124, v125
	v_mul_f32_e32 v125, v199, v199
	v_mul_f32_e32 v126, v201, v201
	v_fmac_f32_e32 v125, v198, v198
	v_fmac_f32_e32 v126, v200, v200
	v_add_f32_e32 v125, v125, v126
	v_add_f32_e32 v167, v124, v125
	v_pk_mul_f32 v[124:125], v[116:117], v[188:189] op_sel_hi:[1,0]
	v_pk_mul_f32 v[126:127], v[114:115], v[188:189] op_sel_hi:[1,0]
	v_mov_b32_e32 v114, v224
	v_mov_b32_e32 v115, v225
	v_mov_b32_e32 v116, v226
	v_mov_b32_e32 v117, v227
	v_lshl_add_u64 v[122:123], s[66:67], 0, v[192:193]
	v_cvt_pk_bf16_f32 v203, v128, v129
	v_rcp_f32_e32 v128, v118
	v_mul_f32_e32 v118, 0xbfb8aa3b, v119
	v_exp_f32_e32 v118, v118
	v_cvt_pk_bf16_f32 v204, v198, v199
	v_cvt_pk_bf16_f32 v205, v200, v201
	v_lshl_add_u64 v[122:123], v[122:123], 0, v[160:161]
	global_store_dwordx4 v[122:123], v[202:205], off
	v_add_f32_e32 v118, 1.0, v118
	v_rcp_f32_e32 v129, v118
	v_pk_mul_f32 v[32:33], v[32:33], v[166:167] op_sel_hi:[1,0]
	v_pk_mul_f32 v[24:25], v[24:25], v[166:167] op_sel_hi:[1,0]
	v_pk_mul_f32 v[22:23], v[22:23], v[166:167] op_sel_hi:[1,0]
	s_waitcnt vmcnt(1)
; __device__ __forceinline__ unsigned cvtpk(float lo, float hi) { f32x2 v = {lo, hi}; bf16x2_t b = __builtin_convertvector(v, bf16x2_t); return __builtin_bit_cast(unsigned, b); }
; __device__ __forceinline__ float sigmoidf_(float v) { return __builtin_amdgcn_rcpf(1.0f + __expf(-v)); }
; #define EPI_LOOP_ROWS for (int ai = 0; ai < 2; ++ai) _Pragma("unroll") for (int m = 0; m < 4; ++m)
;     __device__ __forceinline__ void operator()(const f32x4 (&acc)[2][2][4][2], const Unit& u, int wv) const {
;     ...
;         EPI_LOOP_ROWS { const size_t row = (size_t)(row0 + ai * HALF + m * 16);
;             const float rstd = rs[ai][m]; float ssq = 0.f;
; #pragma unroll
;             for (int bj = 0; bj < 2; ++bj) { const int col = col0 + bj * HALF;
;                 f32x4 v0 = acc[ai][bj][m][0] * rstd, v1 = acc[ai][bj][m][1] * rstd;
;                 if (PP) { const u32x4 g = *(const u32x4*)(PP + row * 1024 + col);
;                     v0[0] = sigmoidf_(v0[0]) * __builtin_bit_cast(float, g.x << 16); v0[1] = sigmoidf_(v0[1]) * __builtin_bit_cast(float, g.x & 0xffff0000u);
;                     v0[2] = sigmoidf_(v0[2]) * __builtin_bit_cast(float, g.y << 16); v0[3] = sigmoidf_(v0[3]) * __builtin_bit_cast(float, g.y & 0xffff0000u);
;                     v1[0] = sigmoidf_(v1[0]) * __builtin_bit_cast(float, g.z << 16); v1[1] = sigmoidf_(v1[1]) * __builtin_bit_cast(float, g.z & 0xffff0000u);
;                     v1[2] = sigmoidf_(v1[2]) * __builtin_bit_cast(float, g.w << 16); v1[3] = sigmoidf_(v1[3]) * __builtin_bit_cast(float, g.w & 0xffff0000u); }
;                 float* xp = X + row * 1024 + col;
;                 v0 += *(const f32x4*)xp; v1 += *(const f32x4*)(xp + 4);
;                 *(f32x4*)xp = v0; *(f32x4*)(xp + 4) = v1;
;                 u32x4 w; w.x = cvtpk(v0[0], v0[1]); w.y = cvtpk(v0[2], v0[3]); w.z = cvtpk(v1[0], v1[1]); w.w = cvtpk(v1[2], v1[3]);
;                 *(u32x4*)(XB + row * 1024 + col) = w;
;                 ssq += ((v0[0] * v0[0] + v0[1] * v0[1]) + (v0[2] * v0[2] + v0[3] * v0[3])) + ((v1[0] * v1[0] + v1[1] * v1[1]) + (v1[2] * v1[2] + v1[3] * v1[3])); }
	v_lshlrev_b32_e32 v190, 16, v114
	v_and_b32_e32 v191, 0xffff0000, v114
	v_mul_f32_e32 v114, 0xbfb8aa3b, v120
	v_exp_f32_e32 v114, v114
	v_lshlrev_b32_e32 v198, 16, v115
	v_and_b32_e32 v199, 0xffff0000, v115
	v_lshlrev_b32_e32 v200, 16, v116
	v_add_f32_e32 v114, 1.0, v114
	v_rcp_f32_e32 v192, v114
	v_mul_f32_e32 v114, 0xbfb8aa3b, v121
	v_exp_f32_e32 v114, v114
	v_and_b32_e32 v201, 0xffff0000, v116
	v_lshlrev_b32_e32 v202, 16, v117
	v_and_b32_e32 v203, 0xffff0000, v117
	v_add_f32_e32 v114, 1.0, v114
	v_rcp_f32_e32 v193, v114
	v_mul_f32_e32 v114, 0xbfb8aa3b, v126
	v_exp_f32_e32 v114, v114
	v_mul_f32_e32 v22, 0xbfb8aa3b, v22
	v_exp_f32_e32 v22, v22
	v_add_f32_e32 v114, 1.0, v114
	v_rcp_f32_e32 v126, v114
	v_mul_f32_e32 v114, 0xbfb8aa3b, v127
	v_exp_f32_e32 v114, v114
	v_add_f32_e32 v22, 1.0, v22
	v_add_f32_e32 v114, 1.0, v114
	v_rcp_f32_e32 v127, v114
	v_mul_f32_e32 v114, 0xbfb8aa3b, v124
	v_exp_f32_e32 v114, v114
	s_nop 0
	v_add_f32_e32 v114, 1.0, v114
	v_rcp_f32_e32 v124, v114
	v_mul_f32_e32 v114, 0xbfb8aa3b, v125
	v_exp_f32_e32 v114, v114
	s_nop 0
	v_add_f32_e32 v114, 1.0, v114
	v_rcp_f32_e32 v125, v114
	v_add_u32_e32 v218, 0x8000, v217
	global_load_dwordx4 v[220:223], v218, s[12:13]
	global_load_dwordx4 v[114:117], v[196:197], off offset:528
	global_load_dwordx4 v[118:121], v[196:197], off offset:512
	s_waitcnt vmcnt(1)
	v_pk_fma_f32 v[114:115], v[126:127], v[200:201], v[114:115]
	s_waitcnt vmcnt(0)
	v_pk_fma_f32 v[120:121], v[192:193], v[198:199], v[120:121]
	v_pk_fma_f32 v[118:119], v[128:129], v[190:191], v[118:119]
	v_pk_fma_f32 v[116:117], v[124:125], v[202:203], v[116:117]
	global_store_dwordx4 v[196:197], v[118:121], off offset:512
	global_store_dwordx4 v[196:197], v[114:117], off offset:528
	v_cvt_pk_bf16_f32 v124, v118, v119
	v_cvt_pk_bf16_f32 v126, v114, v115
	v_mul_f32_e32 v119, v119, v119
	v_mul_f32_e32 v115, v115, v115
	v_fmac_f32_e32 v119, v118, v118
	v_mul_f32_e32 v118, v121, v121
	v_fmac_f32_e32 v115, v114, v114
	v_mul_f32_e32 v114, v117, v117
	v_fmac_f32_e32 v118, v120, v120
	v_fmac_f32_e32 v114, v116, v116
	v_add_f32_e32 v118, v119, v118
	v_add_f32_e32 v114, v115, v114
	v_add_f32_e32 v114, v118, v114
	v_add_f32_e32 v128, v167, v114
	v_lshlrev_b64 v[114:115], 11, v[186:187]
	v_cvt_pk_bf16_f32 v127, v116, v117
	v_pk_mul_f32 v[116:117], v[106:107], v[184:185] op_sel_hi:[1,0]
	v_lshl_add_u64 v[106:107], s[12:13], 0, v[114:115]
	v_cvt_pk_bf16_f32 v125, v120, v121
	v_lshl_add_u64 v[106:107], v[106:107], 0, v[160:161]
	global_store_dwordx4 v[122:123], v[124:127], off offset:256
	v_mov_b32_e32 v122, v220
	v_mov_b32_e32 v123, v221
	v_mov_b32_e32 v124, v222
	v_mov_b32_e32 v125, v223
	v_mul_f32_e32 v116, 0xbfb8aa3b, v116
	v_pk_mul_f32 v[126:127], v[108:109], v[184:185] op_sel_hi:[1,0]
	v_mul_f32_e32 v108, 0xbfb8aa3b, v110
	v_mul_f32_e32 v109, 0xbfb8aa3b, v111
	v_exp_f32_e32 v108, v108
	v_exp_f32_e32 v109, v109
	v_mul_f32_e32 v117, 0xbfb8aa3b, v117
	v_exp_f32_e32 v116, v116
	v_exp_f32_e32 v117, v117
	v_add_f32_e32 v108, 1.0, v108
	v_add_f32_e32 v109, 1.0, v109
	v_rcp_f32_e32 v108, v108
	v_rcp_f32_e32 v109, v109
	v_add_f32_e32 v116, 1.0, v116
	v_add_f32_e32 v117, 1.0, v117
	v_rcp_f32_e32 v116, v116
	v_rcp_f32_e32 v117, v117
	s_waitcnt vmcnt(0)
	v_lshlrev_b32_e32 v110, 16, v122
	v_and_b32_e32 v111, 0xffff0000, v122
	v_lshlrev_b32_e32 v118, 16, v123
	v_and_b32_e32 v119, 0xffff0000, v123
	v_mul_f32_e32 v122, 0xbfb8aa3b, v126
	v_mul_f32_e32 v123, 0xbfb8aa3b, v127
	v_lshlrev_b64 v[126:127], 12, v[186:187]
	v_lshl_add_u64 v[126:127], s[6:7], 0, v[126:127]
	v_lshl_add_u64 v[126:127], v[126:127], 0, v[164:165]
	v_add_u32_e32 v218, 0x8000, v217
	global_load_dwordx4 v[224:227], v218, s[12:13] offset:256
	global_load_dwordx4 v[190:193], v[126:127], off offset:16
	global_load_dwordx4 v[196:199], v[126:127], off
	v_exp_f32_e32 v122, v122
	v_exp_f32_e32 v123, v123
	v_lshlrev_b32_e32 v120, 16, v124
	v_and_b32_e32 v121, 0xffff0000, v124
	v_add_f32_e32 v122, 1.0, v122
	v_add_f32_e32 v123, 1.0, v123
	v_rcp_f32_e32 v122, v122
	v_rcp_f32_e32 v123, v123
	v_lshlrev_b32_e32 v124, 16, v125
	v_and_b32_e32 v125, 0xffff0000, v125
	s_waitcnt vmcnt(1)
	v_pk_fma_f32 v[116:117], v[116:117], v[120:121], v[190:191]
	s_waitcnt vmcnt(0)
	v_pk_fma_f32 v[112:113], v[112:113], v[118:119], v[198:199]
	v_pk_fma_f32 v[110:111], v[108:109], v[110:111], v[196:197]
	v_pk_fma_f32 v[118:119], v[122:123], v[124:125], v[192:193]
	global_store_dwordx4 v[126:127], v[110:113], off
	global_store_dwordx4 v[126:127], v[116:119], off offset:16
	v_cvt_pk_bf16_f32 v120, v110, v111
	v_mul_f32_e32 v111, v111, v111
	v_fmac_f32_e32 v111, v110, v110
	v_mul_f32_e32 v110, v113, v113
	v_fmac_f32_e32 v110, v112, v112
	v_cvt_pk_bf16_f32 v121, v112, v113
	v_add_f32_e32 v110, v111, v110
	v_mul_f32_e32 v111, v117, v117
	v_mul_f32_e32 v112, v119, v119
	v_fmac_f32_e32 v111, v116, v116
	v_fmac_f32_e32 v112, v118, v118
	v_add_f32_e32 v111, v111, v112
	v_add_f32_e32 v124, v110, v111
	v_pk_mul_f32 v[110:111], v[100:101], v[184:185] op_sel_hi:[1,0]
	v_pk_mul_f32 v[112:113], v[98:99], v[184:185] op_sel_hi:[1,0]
	v_mov_b32_e32 v98, v224
	v_mov_b32_e32 v99, v225
	v_mov_b32_e32 v100, v226
	v_mov_b32_e32 v101, v227
	v_lshl_add_u64 v[108:109], s[66:67], 0, v[114:115]
	v_cvt_pk_bf16_f32 v122, v116, v117
	v_rcp_f32_e32 v106, v102
	v_mul_f32_e32 v102, 0xbfb8aa3b, v103
	v_exp_f32_e32 v102, v102
	v_cvt_pk_bf16_f32 v123, v118, v119
	v_lshl_add_u64 v[108:109], v[108:109], 0, v[160:161]
	global_store_dwordx4 v[108:109], v[120:123], off
	v_add_f32_e32 v102, 1.0, v102
	v_rcp_f32_e32 v107, v102
	s_waitcnt vmcnt(1)
; __device__ __forceinline__ unsigned cvtpk(float lo, float hi) { f32x2 v = {lo, hi}; bf16x2_t b = __builtin_convertvector(v, bf16x2_t); return __builtin_bit_cast(unsigned, b); }
; __device__ __forceinline__ float sigmoidf_(float v) { return __builtin_amdgcn_rcpf(1.0f + __expf(-v)); }
; #define EPI_LOOP_ROWS for (int ai = 0; ai < 2; ++ai) _Pragma("unroll") for (int m = 0; m < 4; ++m)
;     __device__ __forceinline__ void operator()(const f32x4 (&acc)[2][2][4][2], const Unit& u, int wv) const {
;     ...
;         EPI_LOOP_ROWS { const size_t row = (size_t)(row0 + ai * HALF + m * 16);
;             const float rstd = rs[ai][m]; float ssq = 0.f;
; #pragma unroll
;             for (int bj = 0; bj < 2; ++bj) { const int col = col0 + bj * HALF;
;                 f32x4 v0 = acc[ai][bj][m][0] * rstd, v1 = acc[ai][bj][m][1] * rstd;
;                 if (PP) { const u32x4 g = *(const u32x4*)(PP + row * 1024 + col);
;                     v0[0] = sigmoidf_(v0[0]) * __builtin_bit_cast(float, g.x << 16); v0[1] = sigmoidf_(v0[1]) * __builtin_bit_cast(float, g.x & 0xffff0000u);
;                     v0[2] = sigmoidf_(v0[2]) * __builtin_bit_cast(float, g.y << 16); v0[3] = sigmoidf_(v0[3]) * __builtin_bit_cast(float, g.y & 0xffff0000u);
;                     v1[0] = sigmoidf_(v1[0]) * __builtin_bit_cast(float, g.z << 16); v1[1] = sigmoidf_(v1[1]) * __builtin_bit_cast(float, g.z & 0xffff0000u);
;                     v1[2] = sigmoidf_(v1[2]) * __builtin_bit_cast(float, g.w << 16); v1[3] = sigmoidf_(v1[3]) * __builtin_bit_cast(float, g.w & 0xffff0000u); }
;                 float* xp = X + row * 1024 + col;
;                 v0 += *(const f32x4*)xp; v1 += *(const f32x4*)(xp + 4);
;                 *(f32x4*)xp = v0; *(f32x4*)(xp + 4) = v1;
;                 u32x4 w; w.x = cvtpk(v0[0], v0[1]); w.y = cvtpk(v0[2], v0[3]); w.z = cvtpk(v1[0], v1[1]); w.w = cvtpk(v1[2], v1[3]);
;                 *(u32x4*)(XB + row * 1024 + col) = w;
;                 ssq += ((v0[0] * v0[0] + v0[1] * v0[1]) + (v0[2] * v0[2] + v0[3] * v0[3])) + ((v1[0] * v1[0] + v1[1] * v1[1]) + (v1[2] * v1[2] + v1[3] * v1[3])); }
	v_lshlrev_b32_e32 v114, 16, v98
	v_and_b32_e32 v115, 0xffff0000, v98
	v_mul_f32_e32 v98, 0xbfb8aa3b, v104
	v_exp_f32_e32 v98, v98
	v_lshlrev_b32_e32 v118, 16, v99
	v_and_b32_e32 v119, 0xffff0000, v99
	v_lshlrev_b32_e32 v120, 16, v100
	v_add_f32_e32 v98, 1.0, v98
	v_rcp_f32_e32 v116, v98
	v_mul_f32_e32 v98, 0xbfb8aa3b, v105
	v_exp_f32_e32 v98, v98
	v_and_b32_e32 v121, 0xffff0000, v100
	v_lshlrev_b32_e32 v122, 16, v101
	v_and_b32_e32 v123, 0xffff0000, v101
	v_add_f32_e32 v98, 1.0, v98
	v_rcp_f32_e32 v117, v98
	v_mul_f32_e32 v98, 0xbfb8aa3b, v112
	v_exp_f32_e32 v98, v98
	s_nop 0
	v_add_f32_e32 v98, 1.0, v98
	v_rcp_f32_e32 v112, v98
	v_mul_f32_e32 v98, 0xbfb8aa3b, v113
	v_exp_f32_e32 v98, v98
	s_nop 0
	v_add_f32_e32 v98, 1.0, v98
	v_rcp_f32_e32 v113, v98
	v_mul_f32_e32 v98, 0xbfb8aa3b, v110
	v_exp_f32_e32 v98, v98
	s_nop 0
	v_add_f32_e32 v98, 1.0, v98
	v_rcp_f32_e32 v110, v98
	v_mul_f32_e32 v98, 0xbfb8aa3b, v111
	v_exp_f32_e32 v98, v98
	s_nop 0
	v_add_f32_e32 v98, 1.0, v98
	v_rcp_f32_e32 v111, v98
	v_add_u32_e32 v218, 0x10000, v217
	global_load_dwordx4 v[220:223], v218, s[12:13]
	global_load_dwordx4 v[98:101], v[126:127], off offset:528
	global_load_dwordx4 v[102:105], v[126:127], off offset:512
	s_waitcnt vmcnt(1)
	v_pk_fma_f32 v[98:99], v[112:113], v[120:121], v[98:99]
	s_waitcnt vmcnt(0)
	v_pk_fma_f32 v[104:105], v[116:117], v[118:119], v[104:105]
	v_pk_fma_f32 v[102:103], v[106:107], v[114:115], v[102:103]
	v_pk_fma_f32 v[100:101], v[110:111], v[122:123], v[100:101]
	global_store_dwordx4 v[126:127], v[102:105], off offset:512
	global_store_dwordx4 v[126:127], v[98:101], off offset:528
	v_cvt_pk_bf16_f32 v110, v102, v103
	v_cvt_pk_bf16_f32 v112, v98, v99
	v_mul_f32_e32 v103, v103, v103
	v_mul_f32_e32 v99, v99, v99
	v_fmac_f32_e32 v103, v102, v102
	v_mul_f32_e32 v102, v105, v105
	v_fmac_f32_e32 v99, v98, v98
	v_mul_f32_e32 v98, v101, v101
	v_fmac_f32_e32 v102, v104, v104
	v_fmac_f32_e32 v98, v100, v100
	v_add_f32_e32 v102, v103, v102
	v_add_f32_e32 v98, v99, v98
	v_cvt_pk_bf16_f32 v111, v104, v105
	v_cvt_pk_bf16_f32 v113, v100, v101
	v_add_f32_e32 v98, v102, v98
	v_lshlrev_b64 v[100:101], 11, v[180:181]
	global_store_dwordx4 v[108:109], v[110:113], off offset:256
	v_add_f32_e32 v120, v124, v98
	v_lshl_add_u64 v[98:99], s[12:13], 0, v[100:101]
	v_lshl_add_u64 v[98:99], v[98:99], 0, v[160:161]
	v_mov_b32_e32 v116, v220
	v_mov_b32_e32 v117, v221
	v_mov_b32_e32 v118, v222
	v_mov_b32_e32 v119, v223
	v_rcp_f32_e32 v110, v90
	v_mul_f32_e32 v90, 0xbfb8aa3b, v91
	v_exp_f32_e32 v90, v90
	v_rcp_f32_e32 v104, v94
	v_mul_f32_e32 v94, 0xbfb8aa3b, v95
	v_exp_f32_e32 v94, v94
	v_add_f32_e32 v90, 1.0, v90
	v_rcp_f32_e32 v111, v90
	v_mul_f32_e32 v90, 0xbfb8aa3b, v92
	v_exp_f32_e32 v90, v90
	v_add_f32_e32 v94, 1.0, v94
	v_rcp_f32_e32 v105, v94
	v_mul_f32_e32 v94, 0xbfb8aa3b, v96
	v_exp_f32_e32 v94, v94
	v_add_f32_e32 v90, 1.0, v90
	v_add_f32_e32 v94, 1.0, v94
	v_rcp_f32_e32 v108, v94
	v_mul_f32_e32 v94, 0xbfb8aa3b, v97
	v_exp_f32_e32 v94, v94
	s_waitcnt vmcnt(0)
	v_lshlrev_b32_e32 v106, 16, v116
	v_and_b32_e32 v107, 0xffff0000, v116
	v_rcp_f32_e32 v116, v90
	v_mul_f32_e32 v90, 0xbfb8aa3b, v93
	v_exp_f32_e32 v90, v90
	v_lshlrev_b32_e32 v112, 16, v117
	v_and_b32_e32 v113, 0xffff0000, v117
	v_add_f32_e32 v94, 1.0, v94
	v_add_f32_e32 v90, 1.0, v90
	v_rcp_f32_e32 v117, v90
	v_lshlrev_b64 v[90:91], 12, v[180:181]
	v_lshl_add_u64 v[90:91], s[6:7], 0, v[90:91]
	v_lshl_add_u64 v[102:103], v[90:91], 0, v[164:165]
	v_rcp_f32_e32 v109, v94
	v_add_u32_e32 v218, 0x10000, v217
	global_load_dwordx4 v[224:227], v218, s[12:13] offset:256
	global_load_dwordx4 v[90:93], v[102:103], off offset:16
	global_load_dwordx4 v[94:97], v[102:103], off
	v_lshlrev_b32_e32 v114, 16, v118
	v_and_b32_e32 v115, 0xffff0000, v118
	v_lshlrev_b32_e32 v118, 16, v119
	v_and_b32_e32 v119, 0xffff0000, v119
	s_waitcnt vmcnt(0)
	v_pk_fma_f32 v[96:97], v[108:109], v[112:113], v[96:97]
	v_pk_fma_f32 v[94:95], v[104:105], v[106:107], v[94:95]
	v_pk_fma_f32 v[106:107], v[116:117], v[118:119], v[92:93]
	v_mul_f32_e32 v92, v95, v95
	v_mul_f32_e32 v93, v97, v97
	v_pk_fma_f32 v[104:105], v[110:111], v[114:115], v[90:91]
	v_fmac_f32_e32 v92, v94, v94
	v_fmac_f32_e32 v93, v96, v96
	global_store_dwordx4 v[102:103], v[94:97], off
	global_store_dwordx4 v[102:103], v[104:107], off offset:16
	v_cvt_pk_bf16_f32 v108, v94, v95
	v_add_f32_e32 v92, v92, v93
	v_mul_f32_e32 v93, v105, v105
	v_mul_f32_e32 v94, v107, v107
	v_lshl_add_u64 v[90:91], s[66:67], 0, v[100:101]
	v_fmac_f32_e32 v93, v104, v104
	v_fmac_f32_e32 v94, v106, v106
	v_cvt_pk_bf16_f32 v109, v96, v97
	v_cvt_pk_bf16_f32 v110, v104, v105
	v_cvt_pk_bf16_f32 v111, v106, v107
	v_lshl_add_u64 v[90:91], v[90:91], 0, v[160:161]
	v_add_f32_e32 v93, v93, v94
	global_store_dwordx4 v[90:91], v[108:111], off
	v_pk_mul_f32 v[94:95], v[82:83], v[182:183] op_sel_hi:[1,0]
	v_rcp_f32_e32 v96, v86
	v_add_f32_e32 v110, v92, v93
	v_pk_mul_f32 v[92:93], v[84:85], v[182:183] op_sel_hi:[1,0]
	v_mov_b32_e32 v82, v224
	v_mov_b32_e32 v83, v225
	v_mov_b32_e32 v84, v226
	v_mov_b32_e32 v85, v227
	v_mul_f32_e32 v86, 0xbfb8aa3b, v87
	v_exp_f32_e32 v86, v86
	s_waitcnt vmcnt(0)
; __device__ __forceinline__ unsigned cvtpk(float lo, float hi) { f32x2 v = {lo, hi}; bf16x2_t b = __builtin_convertvector(v, bf16x2_t); return __builtin_bit_cast(unsigned, b); }
; __device__ __forceinline__ float sigmoidf_(float v) { return __builtin_amdgcn_rcpf(1.0f + __expf(-v)); }
; #define EPI_LOOP_ROWS for (int ai = 0; ai < 2; ++ai) _Pragma("unroll") for (int m = 0; m < 4; ++m)
;     __device__ __forceinline__ void operator()(const f32x4 (&acc)[2][2][4][2], const Unit& u, int wv) const {
;     ...
;         EPI_LOOP_ROWS { const size_t row = (size_t)(row0 + ai * HALF + m * 16);
;             const float rstd = rs[ai][m]; float ssq = 0.f;
; #pragma unroll
;             for (int bj = 0; bj < 2; ++bj) { const int col = col0 + bj * HALF;
;                 f32x4 v0 = acc[ai][bj][m][0] * rstd, v1 = acc[ai][bj][m][1] * rstd;
;                 if (PP) { const u32x4 g = *(const u32x4*)(PP + row * 1024 + col);
;                     v0[0] = sigmoidf_(v0[0]) * __builtin_bit_cast(float, g.x << 16); v0[1] = sigmoidf_(v0[1]) * __builtin_bit_cast(float, g.x & 0xffff0000u);
;                     v0[2] = sigmoidf_(v0[2]) * __builtin_bit_cast(float, g.y << 16); v0[3] = sigmoidf_(v0[3]) * __builtin_bit_cast(float, g.y & 0xffff0000u);
;                     v1[0] = sigmoidf_(v1[0]) * __builtin_bit_cast(float, g.z << 16); v1[1] = sigmoidf_(v1[1]) * __builtin_bit_cast(float, g.z & 0xffff0000u);
;                     v1[2] = sigmoidf_(v1[2]) * __builtin_bit_cast(float, g.w << 16); v1[3] = sigmoidf_(v1[3]) * __builtin_bit_cast(float, g.w & 0xffff0000u); }
;                 float* xp = X + row * 1024 + col;
;                 v0 += *(const f32x4*)xp; v1 += *(const f32x4*)(xp + 4);
;                 *(f32x4*)xp = v0; *(f32x4*)(xp + 4) = v1;
;                 u32x4 w; w.x = cvtpk(v0[0], v0[1]); w.y = cvtpk(v0[2], v0[3]); w.z = cvtpk(v1[0], v1[1]); w.w = cvtpk(v1[2], v1[3]);
;                 *(u32x4*)(XB + row * 1024 + col) = w;
;                 ssq += ((v0[0] * v0[0] + v0[1] * v0[1]) + (v0[2] * v0[2] + v0[3] * v0[3])) + ((v1[0] * v1[0] + v1[1] * v1[1]) + (v1[2] * v1[2] + v1[3] * v1[3])); }
	v_lshlrev_b32_e32 v98, 16, v82
	v_and_b32_e32 v99, 0xffff0000, v82
	v_mul_f32_e32 v82, 0xbfb8aa3b, v88
	v_exp_f32_e32 v82, v82
	v_add_f32_e32 v86, 1.0, v86
	v_rcp_f32_e32 v97, v86
	v_lshlrev_b32_e32 v104, 16, v83
	v_add_f32_e32 v82, 1.0, v82
	v_rcp_f32_e32 v100, v82
	v_mul_f32_e32 v82, 0xbfb8aa3b, v89
	v_exp_f32_e32 v82, v82
	v_and_b32_e32 v105, 0xffff0000, v83
	v_lshlrev_b32_e32 v106, 16, v84
	v_and_b32_e32 v107, 0xffff0000, v84
	v_add_f32_e32 v82, 1.0, v82
	v_rcp_f32_e32 v101, v82
	v_mul_f32_e32 v82, 0xbfb8aa3b, v94
	v_exp_f32_e32 v82, v82
	v_lshlrev_b32_e32 v108, 16, v85
	v_and_b32_e32 v109, 0xffff0000, v85
	v_add_f32_e32 v82, 1.0, v82
	v_rcp_f32_e32 v94, v82
	v_mul_f32_e32 v82, 0xbfb8aa3b, v95
	v_exp_f32_e32 v82, v82
	s_nop 0
	v_add_f32_e32 v82, 1.0, v82
	v_rcp_f32_e32 v95, v82
	v_mul_f32_e32 v82, 0xbfb8aa3b, v92
	v_exp_f32_e32 v82, v82
	s_nop 0
	v_add_f32_e32 v82, 1.0, v82
	v_rcp_f32_e32 v92, v82
	v_mul_f32_e32 v82, 0xbfb8aa3b, v93
	v_exp_f32_e32 v82, v82
	s_nop 0
	v_add_f32_e32 v82, 1.0, v82
	v_rcp_f32_e32 v93, v82
	v_add_u32_e32 v218, 0x18000, v217
	global_load_dwordx4 v[220:223], v218, s[12:13]
	global_load_dwordx4 v[82:85], v[102:103], off offset:528
	global_load_dwordx4 v[86:89], v[102:103], off offset:512
	s_waitcnt vmcnt(1)
	v_pk_fma_f32 v[82:83], v[94:95], v[106:107], v[82:83]
	s_waitcnt vmcnt(0)
	v_pk_fma_f32 v[88:89], v[100:101], v[104:105], v[88:89]
	v_pk_fma_f32 v[86:87], v[96:97], v[98:99], v[86:87]
	v_pk_fma_f32 v[84:85], v[92:93], v[108:109], v[84:85]
	global_store_dwordx4 v[102:103], v[86:89], off offset:512
	global_store_dwordx4 v[102:103], v[82:85], off offset:528
	v_cvt_pk_bf16_f32 v92, v86, v87
	v_cvt_pk_bf16_f32 v94, v82, v83
	v_mul_f32_e32 v87, v87, v87
	v_mul_f32_e32 v83, v83, v83
	v_fmac_f32_e32 v87, v86, v86
	v_mul_f32_e32 v86, v89, v89
	v_fmac_f32_e32 v83, v82, v82
	v_mul_f32_e32 v82, v85, v85
	v_fmac_f32_e32 v86, v88, v88
	v_fmac_f32_e32 v82, v84, v84
	v_add_f32_e32 v86, v87, v86
	v_add_f32_e32 v82, v83, v82
	v_add_f32_e32 v82, v86, v82
	v_add_f32_e32 v96, v110, v82
	v_lshlrev_b64 v[82:83], 11, v[178:179]
	v_cvt_pk_bf16_f32 v95, v84, v85
	v_pk_mul_f32 v[84:85], v[74:75], v[176:177] op_sel_hi:[1,0]
	v_lshl_add_u64 v[74:75], s[12:13], 0, v[82:83]
	v_cvt_pk_bf16_f32 v93, v88, v89
	v_lshl_add_u64 v[74:75], v[74:75], 0, v[160:161]
	global_store_dwordx4 v[90:91], v[92:95], off offset:256
	v_mov_b32_e32 v90, v220
	v_mov_b32_e32 v91, v221
	v_mov_b32_e32 v92, v222
	v_mov_b32_e32 v93, v223
	v_mul_f32_e32 v84, 0xbfb8aa3b, v84
	v_pk_mul_f32 v[94:95], v[76:77], v[176:177] op_sel_hi:[1,0]
	v_mul_f32_e32 v76, 0xbfb8aa3b, v78
	v_mul_f32_e32 v77, 0xbfb8aa3b, v79
	v_exp_f32_e32 v76, v76
	v_exp_f32_e32 v77, v77
	v_mul_f32_e32 v85, 0xbfb8aa3b, v85
	v_exp_f32_e32 v84, v84
	v_exp_f32_e32 v85, v85
	v_add_f32_e32 v76, 1.0, v76
	v_add_f32_e32 v77, 1.0, v77
	v_rcp_f32_e32 v76, v76
	v_rcp_f32_e32 v77, v77
	v_add_f32_e32 v84, 1.0, v84
	v_add_f32_e32 v85, 1.0, v85
	v_rcp_f32_e32 v84, v84
	v_rcp_f32_e32 v85, v85
	s_waitcnt vmcnt(0)
	v_lshlrev_b32_e32 v78, 16, v90
	v_and_b32_e32 v79, 0xffff0000, v90
	v_lshlrev_b32_e32 v86, 16, v91
	v_and_b32_e32 v87, 0xffff0000, v91
	v_mul_f32_e32 v90, 0xbfb8aa3b, v94
	v_mul_f32_e32 v91, 0xbfb8aa3b, v95
	v_lshlrev_b64 v[94:95], 12, v[178:179]
	v_lshl_add_u64 v[94:95], s[6:7], 0, v[94:95]
	v_lshl_add_u64 v[94:95], v[94:95], 0, v[164:165]
	v_add_u32_e32 v218, 0x18000, v217
	global_load_dwordx4 v[224:227], v218, s[12:13] offset:256
	global_load_dwordx4 v[98:101], v[94:95], off offset:16
	global_load_dwordx4 v[102:105], v[94:95], off
	v_exp_f32_e32 v90, v90
	v_exp_f32_e32 v91, v91
	v_lshlrev_b32_e32 v88, 16, v92
	v_and_b32_e32 v89, 0xffff0000, v92
	v_add_f32_e32 v90, 1.0, v90
	v_add_f32_e32 v91, 1.0, v91
	v_rcp_f32_e32 v90, v90
	v_rcp_f32_e32 v91, v91
	v_lshlrev_b32_e32 v92, 16, v93
	v_and_b32_e32 v93, 0xffff0000, v93
	s_waitcnt vmcnt(1)
	v_pk_fma_f32 v[84:85], v[84:85], v[88:89], v[98:99]
	s_waitcnt vmcnt(0)
	v_pk_fma_f32 v[80:81], v[80:81], v[86:87], v[104:105]
	v_pk_fma_f32 v[78:79], v[76:77], v[78:79], v[102:103]
	v_pk_fma_f32 v[86:87], v[90:91], v[92:93], v[100:101]
	global_store_dwordx4 v[94:95], v[78:81], off
	global_store_dwordx4 v[94:95], v[84:87], off offset:16
	v_cvt_pk_bf16_f32 v88, v78, v79
	v_mul_f32_e32 v79, v79, v79
	v_fmac_f32_e32 v79, v78, v78
	v_mul_f32_e32 v78, v81, v81
	v_fmac_f32_e32 v78, v80, v80
	v_cvt_pk_bf16_f32 v89, v80, v81
	v_add_f32_e32 v78, v79, v78
	v_mul_f32_e32 v79, v85, v85
	v_mul_f32_e32 v80, v87, v87
	v_fmac_f32_e32 v79, v84, v84
	v_fmac_f32_e32 v80, v86, v86
	v_add_f32_e32 v79, v79, v80
	v_add_f32_e32 v92, v78, v79
	v_pk_mul_f32 v[78:79], v[68:69], v[176:177] op_sel_hi:[1,0]
	v_pk_mul_f32 v[80:81], v[66:67], v[176:177] op_sel_hi:[1,0]
	v_mov_b32_e32 v66, v224
	v_mov_b32_e32 v67, v225
	v_mov_b32_e32 v68, v226
	v_mov_b32_e32 v69, v227
	v_lshl_add_u64 v[76:77], s[66:67], 0, v[82:83]
	v_cvt_pk_bf16_f32 v90, v84, v85
	v_rcp_f32_e32 v74, v70
	v_mul_f32_e32 v70, 0xbfb8aa3b, v71
	v_exp_f32_e32 v70, v70
	v_cvt_pk_bf16_f32 v91, v86, v87
	v_lshl_add_u64 v[76:77], v[76:77], 0, v[160:161]
	global_store_dwordx4 v[76:77], v[88:91], off
	v_add_f32_e32 v70, 1.0, v70
	v_rcp_f32_e32 v75, v70
	s_waitcnt vmcnt(1)
; __device__ __forceinline__ unsigned cvtpk(float lo, float hi) { f32x2 v = {lo, hi}; bf16x2_t b = __builtin_convertvector(v, bf16x2_t); return __builtin_bit_cast(unsigned, b); }
; __device__ __forceinline__ float sigmoidf_(float v) { return __builtin_amdgcn_rcpf(1.0f + __expf(-v)); }
; #define EPI_LOOP_ROWS for (int ai = 0; ai < 2; ++ai) _Pragma("unroll") for (int m = 0; m < 4; ++m)
;     __device__ __forceinline__ void operator()(const f32x4 (&acc)[2][2][4][2], const Unit& u, int wv) const {
;     ...
;         EPI_LOOP_ROWS { const size_t row = (size_t)(row0 + ai * HALF + m * 16);
;             const float rstd = rs[ai][m]; float ssq = 0.f;
; #pragma unroll
;             for (int bj = 0; bj < 2; ++bj) { const int col = col0 + bj * HALF;
;                 f32x4 v0 = acc[ai][bj][m][0] * rstd, v1 = acc[ai][bj][m][1] * rstd;
;                 if (PP) { const u32x4 g = *(const u32x4*)(PP + row * 1024 + col);
;                     v0[0] = sigmoidf_(v0[0]) * __builtin_bit_cast(float, g.x << 16); v0[1] = sigmoidf_(v0[1]) * __builtin_bit_cast(float, g.x & 0xffff0000u);
;                     v0[2] = sigmoidf_(v0[2]) * __builtin_bit_cast(float, g.y << 16); v0[3] = sigmoidf_(v0[3]) * __builtin_bit_cast(float, g.y & 0xffff0000u);
;                     v1[0] = sigmoidf_(v1[0]) * __builtin_bit_cast(float, g.z << 16); v1[1] = sigmoidf_(v1[1]) * __builtin_bit_cast(float, g.z & 0xffff0000u);
;                     v1[2] = sigmoidf_(v1[2]) * __builtin_bit_cast(float, g.w << 16); v1[3] = sigmoidf_(v1[3]) * __builtin_bit_cast(float, g.w & 0xffff0000u); }
;                 float* xp = X + row * 1024 + col;
;                 v0 += *(const f32x4*)xp; v1 += *(const f32x4*)(xp + 4);
;                 *(f32x4*)xp = v0; *(f32x4*)(xp + 4) = v1;
;                 u32x4 w; w.x = cvtpk(v0[0], v0[1]); w.y = cvtpk(v0[2], v0[3]); w.z = cvtpk(v1[0], v1[1]); w.w = cvtpk(v1[2], v1[3]);
;                 *(u32x4*)(XB + row * 1024 + col) = w;
;                 ssq += ((v0[0] * v0[0] + v0[1] * v0[1]) + (v0[2] * v0[2] + v0[3] * v0[3])) + ((v1[0] * v1[0] + v1[1] * v1[1]) + (v1[2] * v1[2] + v1[3] * v1[3])); }
	v_lshlrev_b32_e32 v82, 16, v66
	v_and_b32_e32 v83, 0xffff0000, v66
	v_mul_f32_e32 v66, 0xbfb8aa3b, v72
	v_exp_f32_e32 v66, v66
	v_lshlrev_b32_e32 v86, 16, v67
	v_and_b32_e32 v87, 0xffff0000, v67
	v_lshlrev_b32_e32 v88, 16, v68
	v_add_f32_e32 v66, 1.0, v66
	v_rcp_f32_e32 v84, v66
	v_mul_f32_e32 v66, 0xbfb8aa3b, v73
	v_exp_f32_e32 v66, v66
	v_and_b32_e32 v89, 0xffff0000, v68
	v_lshlrev_b32_e32 v90, 16, v69
	v_and_b32_e32 v91, 0xffff0000, v69
	v_add_f32_e32 v66, 1.0, v66
	v_rcp_f32_e32 v85, v66
	v_mul_f32_e32 v66, 0xbfb8aa3b, v80
	v_exp_f32_e32 v66, v66
	s_nop 0
	v_add_f32_e32 v66, 1.0, v66
	v_rcp_f32_e32 v80, v66
	v_mul_f32_e32 v66, 0xbfb8aa3b, v81
	v_exp_f32_e32 v66, v66
	s_nop 0
	v_add_f32_e32 v66, 1.0, v66
	v_rcp_f32_e32 v81, v66
	v_mul_f32_e32 v66, 0xbfb8aa3b, v78
	v_exp_f32_e32 v66, v66
	s_nop 0
	v_add_f32_e32 v66, 1.0, v66
	v_rcp_f32_e32 v78, v66
	v_mul_f32_e32 v66, 0xbfb8aa3b, v79
	v_exp_f32_e32 v66, v66
	s_nop 0
	v_add_f32_e32 v66, 1.0, v66
	v_rcp_f32_e32 v79, v66
	v_add_u32_e32 v218, 0x40000, v217
	global_load_dwordx4 v[220:223], v218, s[12:13]
	global_load_dwordx4 v[66:69], v[94:95], off offset:528
	global_load_dwordx4 v[70:73], v[94:95], off offset:512
	s_waitcnt vmcnt(1)
	v_pk_fma_f32 v[66:67], v[80:81], v[88:89], v[66:67]
	s_waitcnt vmcnt(0)
	v_pk_fma_f32 v[72:73], v[84:85], v[86:87], v[72:73]
	v_pk_fma_f32 v[70:71], v[74:75], v[82:83], v[70:71]
	v_pk_fma_f32 v[68:69], v[78:79], v[90:91], v[68:69]
	global_store_dwordx4 v[94:95], v[70:73], off offset:512
	global_store_dwordx4 v[94:95], v[66:69], off offset:528
	v_cvt_pk_bf16_f32 v78, v70, v71
	v_cvt_pk_bf16_f32 v80, v66, v67
	v_mul_f32_e32 v71, v71, v71
	v_mul_f32_e32 v67, v67, v67
	v_fmac_f32_e32 v71, v70, v70
	v_mul_f32_e32 v70, v73, v73
	v_fmac_f32_e32 v67, v66, v66
	v_mul_f32_e32 v66, v69, v69
	v_fmac_f32_e32 v70, v72, v72
	v_fmac_f32_e32 v66, v68, v68
	v_add_f32_e32 v70, v71, v70
	v_add_f32_e32 v66, v67, v66
	v_cvt_pk_bf16_f32 v79, v72, v73
	v_cvt_pk_bf16_f32 v81, v68, v69
	v_add_f32_e32 v66, v70, v66
	v_lshlrev_b64 v[68:69], 11, v[172:173]
	global_store_dwordx4 v[76:77], v[78:81], off offset:256
	v_add_f32_e32 v88, v92, v66
	v_lshl_add_u64 v[66:67], s[12:13], 0, v[68:69]
	v_lshl_add_u64 v[66:67], v[66:67], 0, v[160:161]
	v_mov_b32_e32 v84, v220
	v_mov_b32_e32 v85, v221
	v_mov_b32_e32 v86, v222
	v_mov_b32_e32 v87, v223
	v_rcp_f32_e32 v78, v58
	v_mul_f32_e32 v58, 0xbfb8aa3b, v59
	v_exp_f32_e32 v58, v58
	v_rcp_f32_e32 v72, v62
	v_mul_f32_e32 v62, 0xbfb8aa3b, v63
	v_exp_f32_e32 v62, v62
	v_add_f32_e32 v58, 1.0, v58
	v_rcp_f32_e32 v79, v58
	v_mul_f32_e32 v58, 0xbfb8aa3b, v60
	v_exp_f32_e32 v58, v58
	v_add_f32_e32 v62, 1.0, v62
	v_rcp_f32_e32 v73, v62
	v_mul_f32_e32 v62, 0xbfb8aa3b, v64
	v_exp_f32_e32 v62, v62
	v_add_f32_e32 v58, 1.0, v58
	v_add_f32_e32 v62, 1.0, v62
	v_rcp_f32_e32 v76, v62
	v_mul_f32_e32 v62, 0xbfb8aa3b, v65
	v_exp_f32_e32 v62, v62
	s_waitcnt vmcnt(0)
	v_lshlrev_b32_e32 v74, 16, v84
	v_and_b32_e32 v75, 0xffff0000, v84
	v_rcp_f32_e32 v84, v58
	v_mul_f32_e32 v58, 0xbfb8aa3b, v61
	v_exp_f32_e32 v58, v58
	v_lshlrev_b32_e32 v80, 16, v85
	v_and_b32_e32 v81, 0xffff0000, v85
	v_add_f32_e32 v62, 1.0, v62
	v_add_f32_e32 v58, 1.0, v58
	v_rcp_f32_e32 v85, v58
	v_lshlrev_b64 v[58:59], 12, v[172:173]
	v_lshl_add_u64 v[58:59], s[6:7], 0, v[58:59]
	v_lshl_add_u64 v[70:71], v[58:59], 0, v[164:165]
	v_rcp_f32_e32 v77, v62
	v_add_u32_e32 v218, 0x40000, v217
	global_load_dwordx4 v[224:227], v218, s[12:13] offset:256
	global_load_dwordx4 v[58:61], v[70:71], off offset:16
	global_load_dwordx4 v[62:65], v[70:71], off
	v_lshlrev_b32_e32 v82, 16, v86
	v_and_b32_e32 v83, 0xffff0000, v86
	v_lshlrev_b32_e32 v86, 16, v87
	v_and_b32_e32 v87, 0xffff0000, v87
	s_waitcnt vmcnt(0)
	v_pk_fma_f32 v[64:65], v[76:77], v[80:81], v[64:65]
	v_pk_fma_f32 v[62:63], v[72:73], v[74:75], v[62:63]
	v_pk_fma_f32 v[74:75], v[84:85], v[86:87], v[60:61]
	v_mul_f32_e32 v60, v63, v63
	v_mul_f32_e32 v61, v65, v65
	v_pk_fma_f32 v[72:73], v[78:79], v[82:83], v[58:59]
	v_fmac_f32_e32 v60, v62, v62
	v_fmac_f32_e32 v61, v64, v64
	global_store_dwordx4 v[70:71], v[62:65], off
	global_store_dwordx4 v[70:71], v[72:75], off offset:16
	v_cvt_pk_bf16_f32 v76, v62, v63
	v_add_f32_e32 v60, v60, v61
	v_mul_f32_e32 v61, v73, v73
	v_mul_f32_e32 v62, v75, v75
	v_lshl_add_u64 v[58:59], s[66:67], 0, v[68:69]
	v_fmac_f32_e32 v61, v72, v72
	v_fmac_f32_e32 v62, v74, v74
	v_cvt_pk_bf16_f32 v77, v64, v65
	v_cvt_pk_bf16_f32 v78, v72, v73
	v_cvt_pk_bf16_f32 v79, v74, v75
	v_lshl_add_u64 v[58:59], v[58:59], 0, v[160:161]
	v_add_f32_e32 v61, v61, v62
	global_store_dwordx4 v[58:59], v[76:79], off
	v_pk_mul_f32 v[62:63], v[50:51], v[174:175] op_sel_hi:[1,0]
	v_rcp_f32_e32 v64, v54
	v_add_f32_e32 v78, v60, v61
	v_pk_mul_f32 v[60:61], v[52:53], v[174:175] op_sel_hi:[1,0]
	v_mov_b32_e32 v50, v224
	v_mov_b32_e32 v51, v225
	v_mov_b32_e32 v52, v226
	v_mov_b32_e32 v53, v227
	v_mul_f32_e32 v54, 0xbfb8aa3b, v55
	v_exp_f32_e32 v54, v54
	s_waitcnt vmcnt(0)
	v_lshlrev_b32_e32 v66, 16, v50
	v_and_b32_e32 v67, 0xffff0000, v50
	v_mul_f32_e32 v50, 0xbfb8aa3b, v56
	v_exp_f32_e32 v50, v50
	v_add_f32_e32 v54, 1.0, v54
	v_rcp_f32_e32 v65, v54
	v_lshlrev_b32_e32 v72, 16, v51
	v_add_f32_e32 v50, 1.0, v50
	v_rcp_f32_e32 v68, v50
	v_mul_f32_e32 v50, 0xbfb8aa3b, v57
	v_exp_f32_e32 v50, v50
	v_and_b32_e32 v73, 0xffff0000, v51
	v_lshlrev_b32_e32 v74, 16, v52
	v_and_b32_e32 v75, 0xffff0000, v52
	v_add_f32_e32 v50, 1.0, v50
	v_rcp_f32_e32 v69, v50
	v_mul_f32_e32 v50, 0xbfb8aa3b, v62
	v_exp_f32_e32 v50, v50
	v_lshlrev_b32_e32 v76, 16, v53
	v_and_b32_e32 v77, 0xffff0000, v53
	v_add_f32_e32 v50, 1.0, v50
	v_rcp_f32_e32 v62, v50
	v_mul_f32_e32 v50, 0xbfb8aa3b, v63
	v_exp_f32_e32 v50, v50
	s_nop 0
	v_add_f32_e32 v50, 1.0, v50
	v_rcp_f32_e32 v63, v50
	v_mul_f32_e32 v50, 0xbfb8aa3b, v60
	v_exp_f32_e32 v50, v50
	s_nop 0
	v_add_f32_e32 v50, 1.0, v50
	v_rcp_f32_e32 v60, v50
	v_mul_f32_e32 v50, 0xbfb8aa3b, v61
	v_exp_f32_e32 v50, v50
	s_nop 0
	v_add_f32_e32 v50, 1.0, v50
	v_rcp_f32_e32 v61, v50
	v_add_u32_e32 v218, 0x48000, v217
	global_load_dwordx4 v[220:223], v218, s[12:13]
	global_load_dwordx4 v[50:53], v[70:71], off offset:528
	global_load_dwordx4 v[54:57], v[70:71], off offset:512
	s_waitcnt vmcnt(1)
; __device__ __forceinline__ unsigned cvtpk(float lo, float hi) { f32x2 v = {lo, hi}; bf16x2_t b = __builtin_convertvector(v, bf16x2_t); return __builtin_bit_cast(unsigned, b); }
; __device__ __forceinline__ float sigmoidf_(float v) { return __builtin_amdgcn_rcpf(1.0f + __expf(-v)); }
; #define EPI_LOOP_ROWS for (int ai = 0; ai < 2; ++ai) _Pragma("unroll") for (int m = 0; m < 4; ++m)
;     __device__ __forceinline__ void operator()(const f32x4 (&acc)[2][2][4][2], const Unit& u, int wv) const {
;     ...
;         EPI_LOOP_ROWS { const size_t row = (size_t)(row0 + ai * HALF + m * 16);
;             const float rstd = rs[ai][m]; float ssq = 0.f;
; #pragma unroll
;             for (int bj = 0; bj < 2; ++bj) { const int col = col0 + bj * HALF;
;                 f32x4 v0 = acc[ai][bj][m][0] * rstd, v1 = acc[ai][bj][m][1] * rstd;
;                 if (PP) { const u32x4 g = *(const u32x4*)(PP + row * 1024 + col);
;                     v0[0] = sigmoidf_(v0[0]) * __builtin_bit_cast(float, g.x << 16); v0[1] = sigmoidf_(v0[1]) * __builtin_bit_cast(float, g.x & 0xffff0000u);
;                     v0[2] = sigmoidf_(v0[2]) * __builtin_bit_cast(float, g.y << 16); v0[3] = sigmoidf_(v0[3]) * __builtin_bit_cast(float, g.y & 0xffff0000u);
;                     v1[0] = sigmoidf_(v1[0]) * __builtin_bit_cast(float, g.z << 16); v1[1] = sigmoidf_(v1[1]) * __builtin_bit_cast(float, g.z & 0xffff0000u);
;                     v1[2] = sigmoidf_(v1[2]) * __builtin_bit_cast(float, g.w << 16); v1[3] = sigmoidf_(v1[3]) * __builtin_bit_cast(float, g.w & 0xffff0000u); }
;                 float* xp = X + row * 1024 + col;
;                 v0 += *(const f32x4*)xp; v1 += *(const f32x4*)(xp + 4);
;                 *(f32x4*)xp = v0; *(f32x4*)(xp + 4) = v1;
;                 u32x4 w; w.x = cvtpk(v0[0], v0[1]); w.y = cvtpk(v0[2], v0[3]); w.z = cvtpk(v1[0], v1[1]); w.w = cvtpk(v1[2], v1[3]);
;                 *(u32x4*)(XB + row * 1024 + col) = w;
;                 ssq += ((v0[0] * v0[0] + v0[1] * v0[1]) + (v0[2] * v0[2] + v0[3] * v0[3])) + ((v1[0] * v1[0] + v1[1] * v1[1]) + (v1[2] * v1[2] + v1[3] * v1[3])); }
	v_pk_fma_f32 v[50:51], v[62:63], v[74:75], v[50:51]
	s_waitcnt vmcnt(0)
	v_pk_fma_f32 v[56:57], v[68:69], v[72:73], v[56:57]
	v_pk_fma_f32 v[54:55], v[64:65], v[66:67], v[54:55]
	v_pk_fma_f32 v[52:53], v[60:61], v[76:77], v[52:53]
	global_store_dwordx4 v[70:71], v[54:57], off offset:512
	global_store_dwordx4 v[70:71], v[50:53], off offset:528
	v_cvt_pk_bf16_f32 v60, v54, v55
	v_cvt_pk_bf16_f32 v62, v50, v51
	v_mul_f32_e32 v55, v55, v55
	v_mul_f32_e32 v51, v51, v51
	v_fmac_f32_e32 v55, v54, v54
	v_mul_f32_e32 v54, v57, v57
	v_fmac_f32_e32 v51, v50, v50
	v_mul_f32_e32 v50, v53, v53
	v_fmac_f32_e32 v54, v56, v56
	v_fmac_f32_e32 v50, v52, v52
	v_add_f32_e32 v54, v55, v54
	v_add_f32_e32 v50, v51, v50
	v_add_f32_e32 v50, v54, v50
	v_cvt_pk_bf16_f32 v61, v56, v57
	v_cvt_pk_bf16_f32 v63, v52, v53
	v_add_f32_e32 v52, v78, v50
	v_lshlrev_b64 v[50:51], 11, v[168:169]
	global_store_dwordx4 v[58:59], v[60:63], off offset:256
	v_pk_mul_f32 v[58:59], v[42:43], v[170:171] op_sel_hi:[1,0]
	v_lshl_add_u64 v[42:43], s[12:13], 0, v[50:51]
	v_lshl_add_u64 v[42:43], v[42:43], 0, v[160:161]
	v_pk_mul_f32 v[54:55], v[46:47], v[170:171] op_sel_hi:[1,0]
	v_pk_mul_f32 v[56:57], v[44:45], v[170:171] op_sel_hi:[1,0]
	v_mov_b32_e32 v44, v220
	v_mov_b32_e32 v45, v221
	v_mov_b32_e32 v46, v222
	v_mov_b32_e32 v47, v223
	v_mul_f32_e32 v53, 0xbfb8aa3b, v54
	v_exp_f32_e32 v53, v53
	s_waitcnt vmcnt(0)
	v_lshlrev_b32_e32 v62, 16, v44
	v_and_b32_e32 v63, 0xffff0000, v44
	v_mul_f32_e32 v44, 0xbfb8aa3b, v48
	v_exp_f32_e32 v44, v44
	v_lshlrev_b32_e32 v64, 16, v45
	v_and_b32_e32 v65, 0xffff0000, v45
	v_add_f32_e32 v53, 1.0, v53
	v_add_f32_e32 v44, 1.0, v44
	v_rcp_f32_e32 v48, v44
	v_mul_f32_e32 v44, 0xbfb8aa3b, v49
	v_exp_f32_e32 v44, v44
	v_rcp_f32_e32 v60, v53
	v_mul_f32_e32 v53, 0xbfb8aa3b, v55
	v_lshlrev_b32_e32 v66, 16, v46
	v_add_f32_e32 v44, 1.0, v44
	v_rcp_f32_e32 v49, v44
	v_mul_f32_e32 v44, 0xbfb8aa3b, v58
	v_exp_f32_e32 v44, v44
	v_and_b32_e32 v67, 0xffff0000, v46
	v_lshlrev_b32_e32 v70, 16, v47
	v_and_b32_e32 v71, 0xffff0000, v47
	v_add_f32_e32 v44, 1.0, v44
	v_rcp_f32_e32 v58, v44
	v_mul_f32_e32 v44, 0xbfb8aa3b, v59
	v_exp_f32_e32 v44, v44
	v_exp_f32_e32 v53, v53
	v_add_f32_e32 v44, 1.0, v44
	v_rcp_f32_e32 v59, v44
	v_mul_f32_e32 v44, 0xbfb8aa3b, v56
	v_exp_f32_e32 v44, v44
	v_add_f32_e32 v53, 1.0, v53
	v_rcp_f32_e32 v61, v53
	v_add_f32_e32 v44, 1.0, v44
	v_rcp_f32_e32 v68, v44
	v_mul_f32_e32 v44, 0xbfb8aa3b, v57
	v_exp_f32_e32 v44, v44
	s_nop 0
	v_add_f32_e32 v44, 1.0, v44
	v_rcp_f32_e32 v69, v44
	v_lshlrev_b64 v[44:45], 12, v[168:169]
	v_lshl_add_u64 v[44:45], s[6:7], 0, v[44:45]
	v_lshl_add_u64 v[72:73], v[44:45], 0, v[164:165]
	v_add_u32_e32 v218, 0x48000, v217
	global_load_dwordx4 v[224:227], v218, s[12:13] offset:256
	global_load_dwordx4 v[44:47], v[72:73], off offset:16
	global_load_dwordx4 v[54:57], v[72:73], off
	s_waitcnt vmcnt(1)
	v_pk_fma_f32 v[44:45], v[58:59], v[66:67], v[44:45]
	s_waitcnt vmcnt(0)
	v_pk_fma_f32 v[56:57], v[48:49], v[64:65], v[56:57]
	v_pk_fma_f32 v[54:55], v[60:61], v[62:63], v[54:55]
	v_pk_fma_f32 v[46:47], v[68:69], v[70:71], v[46:47]
	global_store_dwordx4 v[72:73], v[54:57], off
	global_store_dwordx4 v[72:73], v[44:47], off offset:16
	v_cvt_pk_bf16_f32 v60, v44, v45
	v_lshl_add_u64 v[48:49], s[66:67], 0, v[50:51]
	v_mul_f32_e32 v45, v45, v45
	v_mul_f32_e32 v50, v55, v55
	v_mul_f32_e32 v51, v57, v57
	v_fmac_f32_e32 v45, v44, v44
	v_mul_f32_e32 v44, v47, v47
	v_fmac_f32_e32 v50, v54, v54
	v_fmac_f32_e32 v51, v56, v56
	v_fmac_f32_e32 v44, v46, v46
	v_add_f32_e32 v50, v50, v51
	v_add_f32_e32 v44, v45, v44
	v_cvt_pk_bf16_f32 v61, v46, v47
	v_add_f32_e32 v53, v50, v44
	v_pk_mul_f32 v[44:45], v[36:37], v[170:171] op_sel_hi:[1,0]
	v_pk_mul_f32 v[46:47], v[34:35], v[170:171] op_sel_hi:[1,0]
	v_mov_b32_e32 v34, v224
	v_mov_b32_e32 v35, v225
	v_mov_b32_e32 v36, v226
	v_mov_b32_e32 v37, v227
	v_cvt_pk_bf16_f32 v58, v54, v55
	v_rcp_f32_e32 v42, v38
	v_mul_f32_e32 v38, 0xbfb8aa3b, v39
	v_exp_f32_e32 v38, v38
	v_cvt_pk_bf16_f32 v59, v56, v57
	v_lshl_add_u64 v[48:49], v[48:49], 0, v[160:161]
	global_store_dwordx4 v[48:49], v[58:61], off
	v_add_f32_e32 v38, 1.0, v38
	v_rcp_f32_e32 v43, v38
	s_waitcnt vmcnt(1)
	v_lshlrev_b32_e32 v50, 16, v34
	v_and_b32_e32 v51, 0xffff0000, v34
	v_mul_f32_e32 v34, 0xbfb8aa3b, v40
	v_exp_f32_e32 v34, v34
	v_lshlrev_b32_e32 v56, 16, v35
	v_and_b32_e32 v57, 0xffff0000, v35
	v_lshlrev_b32_e32 v58, 16, v36
	v_add_f32_e32 v34, 1.0, v34
	v_rcp_f32_e32 v54, v34
	v_mul_f32_e32 v34, 0xbfb8aa3b, v41
	v_exp_f32_e32 v34, v34
	v_and_b32_e32 v59, 0xffff0000, v36
	v_lshlrev_b32_e32 v60, 16, v37
	v_and_b32_e32 v61, 0xffff0000, v37
	v_add_f32_e32 v34, 1.0, v34
	v_rcp_f32_e32 v55, v34
	v_mul_f32_e32 v34, 0xbfb8aa3b, v46
	v_exp_f32_e32 v34, v34
	s_nop 0
	v_add_f32_e32 v34, 1.0, v34
	v_rcp_f32_e32 v46, v34
	v_mul_f32_e32 v34, 0xbfb8aa3b, v47
	v_exp_f32_e32 v34, v34
	s_nop 0
	v_add_f32_e32 v34, 1.0, v34
	v_rcp_f32_e32 v47, v34
	v_mul_f32_e32 v34, 0xbfb8aa3b, v44
	v_exp_f32_e32 v34, v34
	s_nop 0
	v_add_f32_e32 v34, 1.0, v34
	v_rcp_f32_e32 v44, v34
	v_mul_f32_e32 v34, 0xbfb8aa3b, v45
	v_exp_f32_e32 v34, v34
	s_nop 0
	v_add_f32_e32 v34, 1.0, v34
	v_rcp_f32_e32 v45, v34
	v_add_u32_e32 v218, 0x50000, v217
	global_load_dwordx4 v[220:223], v218, s[12:13]
	global_load_dwordx4 v[34:37], v[72:73], off offset:528
	global_load_dwordx4 v[38:41], v[72:73], off offset:512
	s_waitcnt vmcnt(1)
	v_pk_fma_f32 v[34:35], v[46:47], v[58:59], v[34:35]
	s_waitcnt vmcnt(0)
; __device__ __forceinline__ unsigned cvtpk(float lo, float hi) { f32x2 v = {lo, hi}; bf16x2_t b = __builtin_convertvector(v, bf16x2_t); return __builtin_bit_cast(unsigned, b); }
; __device__ __forceinline__ float sigmoidf_(float v) { return __builtin_amdgcn_rcpf(1.0f + __expf(-v)); }
; #define EPI_LOOP_ROWS for (int ai = 0; ai < 2; ++ai) _Pragma("unroll") for (int m = 0; m < 4; ++m)
;     __device__ __forceinline__ void operator()(const f32x4 (&acc)[2][2][4][2], const Unit& u, int wv) const {
;     ...
;         EPI_LOOP_ROWS { const size_t row = (size_t)(row0 + ai * HALF + m * 16);
;             const float rstd = rs[ai][m]; float ssq = 0.f;
; #pragma unroll
;             for (int bj = 0; bj < 2; ++bj) { const int col = col0 + bj * HALF;
;                 f32x4 v0 = acc[ai][bj][m][0] * rstd, v1 = acc[ai][bj][m][1] * rstd;
;                 if (PP) { const u32x4 g = *(const u32x4*)(PP + row * 1024 + col);
;                     v0[0] = sigmoidf_(v0[0]) * __builtin_bit_cast(float, g.x << 16); v0[1] = sigmoidf_(v0[1]) * __builtin_bit_cast(float, g.x & 0xffff0000u);
;                     v0[2] = sigmoidf_(v0[2]) * __builtin_bit_cast(float, g.y << 16); v0[3] = sigmoidf_(v0[3]) * __builtin_bit_cast(float, g.y & 0xffff0000u);
;                     v1[0] = sigmoidf_(v1[0]) * __builtin_bit_cast(float, g.z << 16); v1[1] = sigmoidf_(v1[1]) * __builtin_bit_cast(float, g.z & 0xffff0000u);
;                     v1[2] = sigmoidf_(v1[2]) * __builtin_bit_cast(float, g.w << 16); v1[3] = sigmoidf_(v1[3]) * __builtin_bit_cast(float, g.w & 0xffff0000u); }
;                 float* xp = X + row * 1024 + col;
;                 v0 += *(const f32x4*)xp; v1 += *(const f32x4*)(xp + 4);
;                 *(f32x4*)xp = v0; *(f32x4*)(xp + 4) = v1;
;                 u32x4 w; w.x = cvtpk(v0[0], v0[1]); w.y = cvtpk(v0[2], v0[3]); w.z = cvtpk(v1[0], v1[1]); w.w = cvtpk(v1[2], v1[3]);
;                 *(u32x4*)(XB + row * 1024 + col) = w;
;                 ssq += ((v0[0] * v0[0] + v0[1] * v0[1]) + (v0[2] * v0[2] + v0[3] * v0[3])) + ((v1[0] * v1[0] + v1[1] * v1[1]) + (v1[2] * v1[2] + v1[3] * v1[3])); }
	v_pk_fma_f32 v[40:41], v[54:55], v[56:57], v[40:41]
	v_pk_fma_f32 v[38:39], v[42:43], v[50:51], v[38:39]
	v_pk_fma_f32 v[36:37], v[44:45], v[60:61], v[36:37]
	global_store_dwordx4 v[72:73], v[38:41], off offset:512
	global_store_dwordx4 v[72:73], v[34:37], off offset:528
	v_cvt_pk_bf16_f32 v42, v38, v39
	v_cvt_pk_bf16_f32 v44, v34, v35
	v_mul_f32_e32 v39, v39, v39
	v_mul_f32_e32 v35, v35, v35
	v_fmac_f32_e32 v39, v38, v38
	v_mul_f32_e32 v38, v41, v41
	v_fmac_f32_e32 v35, v34, v34
	v_mul_f32_e32 v34, v37, v37
	v_fmac_f32_e32 v38, v40, v40
	v_fmac_f32_e32 v34, v36, v36
	v_add_f32_e32 v38, v39, v38
	v_add_f32_e32 v34, v35, v34
	v_add_f32_e32 v34, v38, v34
	v_cvt_pk_bf16_f32 v43, v40, v41
	v_cvt_pk_bf16_f32 v45, v36, v37
	v_add_f32_e32 v36, v53, v34
	v_lshlrev_b64 v[34:35], 11, v[162:163]
	global_store_dwordx4 v[48:49], v[42:45], off offset:256
	v_pk_mul_f32 v[38:39], v[30:31], v[166:167] op_sel_hi:[1,0]
	v_pk_mul_f32 v[40:41], v[28:29], v[166:167] op_sel_hi:[1,0]
	v_pk_mul_f32 v[42:43], v[26:27], v[166:167] op_sel_hi:[1,0]
	v_lshl_add_u64 v[26:27], s[12:13], 0, v[34:35]
	v_lshl_add_u64 v[26:27], v[26:27], 0, v[160:161]
	v_mov_b32_e32 v28, v220
	v_mov_b32_e32 v29, v221
	v_mov_b32_e32 v30, v222
	v_mov_b32_e32 v31, v223
	v_mul_f32_e32 v37, 0xbfb8aa3b, v38
	v_exp_f32_e32 v37, v37
	s_waitcnt vmcnt(0)
	v_lshlrev_b32_e32 v46, 16, v28
	v_and_b32_e32 v47, 0xffff0000, v28
	v_mul_f32_e32 v28, 0xbfb8aa3b, v32
	v_exp_f32_e32 v28, v28
	v_lshlrev_b32_e32 v48, 16, v29
	v_and_b32_e32 v49, 0xffff0000, v29
	v_add_f32_e32 v37, 1.0, v37
	v_add_f32_e32 v28, 1.0, v28
	v_rcp_f32_e32 v32, v28
	v_mul_f32_e32 v28, 0xbfb8aa3b, v33
	v_exp_f32_e32 v28, v28
	v_rcp_f32_e32 v44, v37
	v_mul_f32_e32 v37, 0xbfb8aa3b, v39
	v_lshlrev_b32_e32 v50, 16, v30
	v_add_f32_e32 v28, 1.0, v28
	v_rcp_f32_e32 v33, v28
	v_mul_f32_e32 v28, 0xbfb8aa3b, v42
	v_exp_f32_e32 v28, v28
	v_and_b32_e32 v51, 0xffff0000, v30
	v_lshlrev_b32_e32 v56, 16, v31
	v_and_b32_e32 v57, 0xffff0000, v31
	v_add_f32_e32 v28, 1.0, v28
	v_rcp_f32_e32 v42, v28
	v_mul_f32_e32 v28, 0xbfb8aa3b, v43
	v_exp_f32_e32 v28, v28
	v_exp_f32_e32 v37, v37
	v_add_f32_e32 v28, 1.0, v28
	v_rcp_f32_e32 v43, v28
	v_mul_f32_e32 v28, 0xbfb8aa3b, v40
	v_exp_f32_e32 v28, v28
	v_add_f32_e32 v37, 1.0, v37
	v_rcp_f32_e32 v45, v37
	v_add_f32_e32 v28, 1.0, v28
	v_rcp_f32_e32 v54, v28
	v_mul_f32_e32 v28, 0xbfb8aa3b, v41
	v_exp_f32_e32 v28, v28
	s_nop 0
	v_add_f32_e32 v28, 1.0, v28
	v_rcp_f32_e32 v55, v28
	v_lshlrev_b64 v[28:29], 12, v[162:163]
	v_lshl_add_u64 v[28:29], s[6:7], 0, v[28:29]
	v_lshl_add_u64 v[58:59], v[28:29], 0, v[164:165]
	v_add_u32_e32 v218, 0x50000, v217
	global_load_dwordx4 v[224:227], v218, s[12:13] offset:256
	global_load_dwordx4 v[28:31], v[58:59], off offset:16
	global_load_dwordx4 v[38:41], v[58:59], off
	s_waitcnt vmcnt(1)
	v_pk_fma_f32 v[28:29], v[42:43], v[50:51], v[28:29]
	s_waitcnt vmcnt(0)
	v_pk_fma_f32 v[40:41], v[32:33], v[48:49], v[40:41]
	v_pk_fma_f32 v[38:39], v[44:45], v[46:47], v[38:39]
	v_pk_fma_f32 v[30:31], v[54:55], v[56:57], v[30:31]
	global_store_dwordx4 v[58:59], v[38:41], off
	global_store_dwordx4 v[58:59], v[28:31], off offset:16
	v_cvt_pk_bf16_f32 v44, v28, v29
	v_lshl_add_u64 v[32:33], s[66:67], 0, v[34:35]
	v_mul_f32_e32 v29, v29, v29
	v_mul_f32_e32 v34, v39, v39
	v_mul_f32_e32 v35, v41, v41
	v_fmac_f32_e32 v29, v28, v28
	v_mul_f32_e32 v28, v31, v31
	v_fmac_f32_e32 v34, v38, v38
	v_fmac_f32_e32 v35, v40, v40
	v_fmac_f32_e32 v28, v30, v30
	v_add_f32_e32 v34, v34, v35
	v_add_f32_e32 v28, v29, v28
	v_cvt_pk_bf16_f32 v45, v30, v31
	v_add_f32_e32 v37, v34, v28
	v_pk_mul_f32 v[28:29], v[20:21], v[166:167] op_sel_hi:[1,0]
	v_pk_mul_f32 v[30:31], v[18:19], v[166:167] op_sel_hi:[1,0]
	v_mov_b32_e32 v18, v224
	v_mov_b32_e32 v19, v225
	v_mov_b32_e32 v20, v226
	v_mov_b32_e32 v21, v227
	v_cvt_pk_bf16_f32 v42, v38, v39
	v_rcp_f32_e32 v26, v22
	v_mul_f32_e32 v22, 0xbfb8aa3b, v23
	v_exp_f32_e32 v22, v22
	v_cvt_pk_bf16_f32 v43, v40, v41
	v_lshl_add_u64 v[32:33], v[32:33], 0, v[160:161]
	global_store_dwordx4 v[32:33], v[42:45], off
	v_add_f32_e32 v22, 1.0, v22
	v_rcp_f32_e32 v27, v22
	s_waitcnt vmcnt(1)
	v_lshlrev_b32_e32 v34, 16, v18
	v_and_b32_e32 v35, 0xffff0000, v18
	v_mul_f32_e32 v18, 0xbfb8aa3b, v24
	v_exp_f32_e32 v18, v18
	v_lshlrev_b32_e32 v40, 16, v19
	v_and_b32_e32 v41, 0xffff0000, v19
	v_lshlrev_b32_e32 v42, 16, v20
	v_add_f32_e32 v18, 1.0, v18
	v_rcp_f32_e32 v38, v18
	v_mul_f32_e32 v18, 0xbfb8aa3b, v25
	v_exp_f32_e32 v18, v18
	v_and_b32_e32 v43, 0xffff0000, v20
	v_lshlrev_b32_e32 v44, 16, v21
	v_and_b32_e32 v45, 0xffff0000, v21
	v_add_f32_e32 v18, 1.0, v18
	v_rcp_f32_e32 v39, v18
	v_mul_f32_e32 v18, 0xbfb8aa3b, v30
	v_exp_f32_e32 v18, v18
	s_nop 0
	v_add_f32_e32 v18, 1.0, v18
	v_rcp_f32_e32 v30, v18
	v_mul_f32_e32 v18, 0xbfb8aa3b, v31
	v_exp_f32_e32 v18, v18
	s_nop 0
	v_add_f32_e32 v18, 1.0, v18
	v_rcp_f32_e32 v31, v18
	v_mul_f32_e32 v18, 0xbfb8aa3b, v28
	v_exp_f32_e32 v18, v18
	s_nop 0
	v_add_f32_e32 v18, 1.0, v18
	v_rcp_f32_e32 v28, v18
	v_mul_f32_e32 v18, 0xbfb8aa3b, v29
	v_exp_f32_e32 v18, v18
	s_nop 0
	v_add_f32_e32 v18, 1.0, v18
	v_rcp_f32_e32 v29, v18
	v_add_u32_e32 v218, 0x58000, v217
	global_load_dwordx4 v[220:223], v218, s[12:13]
	global_load_dwordx4 v[18:21], v[58:59], off offset:528
	global_load_dwordx4 v[22:25], v[58:59], off offset:512
	s_waitcnt vmcnt(1)
	v_pk_fma_f32 v[18:19], v[30:31], v[42:43], v[18:19]
	s_waitcnt vmcnt(0)
; __device__ __forceinline__ unsigned cvtpk(float lo, float hi) { f32x2 v = {lo, hi}; bf16x2_t b = __builtin_convertvector(v, bf16x2_t); return __builtin_bit_cast(unsigned, b); }
; __device__ __forceinline__ float shx(float v, int o, int lane) { return __builtin_bit_cast(float, __builtin_amdgcn_ds_bpermute((lane ^ o) << 2, __builtin_bit_cast(int, v))); }
; __device__ __forceinline__ float sigmoidf_(float v) { return __builtin_amdgcn_rcpf(1.0f + __expf(-v)); }
; #define EPI_LOOP_ROWS for (int ai = 0; ai < 2; ++ai) _Pragma("unroll") for (int m = 0; m < 4; ++m)
;     __device__ __forceinline__ void operator()(const f32x4 (&acc)[2][2][4][2], const Unit& u, int wv) const {
;     ...
;             for (int bj = 0; bj < 2; ++bj) { const int col = col0 + bj * HALF;
;                 f32x4 v0 = acc[ai][bj][m][0] * rstd, v1 = acc[ai][bj][m][1] * rstd;
;                 if (PP) { const u32x4 g = *(const u32x4*)(PP + row * 1024 + col);
;                     v0[0] = sigmoidf_(v0[0]) * __builtin_bit_cast(float, g.x << 16); v0[1] = sigmoidf_(v0[1]) * __builtin_bit_cast(float, g.x & 0xffff0000u);
;                     v0[2] = sigmoidf_(v0[2]) * __builtin_bit_cast(float, g.y << 16); v0[3] = sigmoidf_(v0[3]) * __builtin_bit_cast(float, g.y & 0xffff0000u);
;                     v1[0] = sigmoidf_(v1[0]) * __builtin_bit_cast(float, g.z << 16); v1[1] = sigmoidf_(v1[1]) * __builtin_bit_cast(float, g.z & 0xffff0000u);
;                     v1[2] = sigmoidf_(v1[2]) * __builtin_bit_cast(float, g.w << 16); v1[3] = sigmoidf_(v1[3]) * __builtin_bit_cast(float, g.w & 0xffff0000u); }
;                 float* xp = X + row * 1024 + col;
;                 v0 += *(const f32x4*)xp; v1 += *(const f32x4*)(xp + 4);
;                 *(f32x4*)xp = v0; *(f32x4*)(xp + 4) = v1;
;                 u32x4 w; w.x = cvtpk(v0[0], v0[1]); w.y = cvtpk(v0[2], v0[3]); w.z = cvtpk(v1[0], v1[1]); w.w = cvtpk(v1[2], v1[3]);
;                 *(u32x4*)(XB + row * 1024 + col) = w;
;                 ssq += ((v0[0] * v0[0] + v0[1] * v0[1]) + (v0[2] * v0[2] + v0[3] * v0[3])) + ((v1[0] * v1[0] + v1[1] * v1[1]) + (v1[2] * v1[2] + v1[3] * v1[3])); }
;             sq[ai][m] = ssq;
;             if (m & 1) asm volatile("" ::: "memory"); }
; #pragma unroll
;         EPI_LOOP_ROWS sq[ai][m] += shx(sq[ai][m], 16, t_ & 63);
; #pragma unroll
;         EPI_LOOP_ROWS sq[ai][m] += shx(sq[ai][m], 32, t_ & 63);
;         if (fq == 0) {
	v_pk_fma_f32 v[24:25], v[38:39], v[40:41], v[24:25]
	v_pk_fma_f32 v[22:23], v[26:27], v[34:35], v[22:23]
	v_pk_fma_f32 v[20:21], v[28:29], v[44:45], v[20:21]
	global_store_dwordx4 v[58:59], v[22:25], off offset:512
	global_store_dwordx4 v[58:59], v[18:21], off offset:528
	v_cvt_pk_bf16_f32 v26, v22, v23
	v_cvt_pk_bf16_f32 v28, v18, v19
	v_mul_f32_e32 v23, v23, v23
	v_mul_f32_e32 v19, v19, v19
	v_fmac_f32_e32 v23, v22, v22
	v_mul_f32_e32 v22, v25, v25
	v_fmac_f32_e32 v19, v18, v18
	v_mul_f32_e32 v18, v21, v21
	v_fmac_f32_e32 v22, v24, v24
	v_fmac_f32_e32 v18, v20, v20
	v_cvt_pk_bf16_f32 v27, v24, v25
	v_cvt_pk_bf16_f32 v29, v20, v21
	v_add_f32_e32 v22, v23, v22
	v_add_f32_e32 v18, v19, v18
	global_store_dwordx4 v[32:33], v[26:29], off offset:256
	v_add_f32_e32 v18, v22, v18
	v_pk_mul_f32 v[30:31], v[12:13], v[0:1] op_sel_hi:[1,0]
	v_lshlrev_b64 v[26:27], 11, v[158:159]
	v_add_f32_e32 v28, v37, v18
	v_pk_mul_f32 v[18:19], v[10:11], v[0:1] op_sel_hi:[1,0]
	v_lshl_add_u64 v[10:11], s[12:13], 0, v[26:27]
	v_lshl_add_u64 v[24:25], v[10:11], 0, v[160:161]
	v_mov_b32_e32 v20, v220
	v_mov_b32_e32 v21, v221
	v_mov_b32_e32 v22, v222
	v_mov_b32_e32 v23, v223
	v_mul_f32_e32 v10, 0xbfb8aa3b, v14
	v_mul_f32_e32 v11, 0xbfb8aa3b, v15
	v_mul_f32_e32 v14, 0xbfb8aa3b, v16
	v_mul_f32_e32 v15, 0xbfb8aa3b, v17
	v_mul_f32_e32 v18, 0xbfb8aa3b, v18
	v_mul_f32_e32 v19, 0xbfb8aa3b, v19
	v_exp_f32_e32 v10, v10
	v_exp_f32_e32 v11, v11
	v_exp_f32_e32 v14, v14
	v_exp_f32_e32 v15, v15
	v_exp_f32_e32 v18, v18
	v_exp_f32_e32 v19, v19
	v_add_f32_e32 v10, 1.0, v10
	v_add_f32_e32 v11, 1.0, v11
	v_add_f32_e32 v14, 1.0, v14
	v_add_f32_e32 v15, 1.0, v15
	v_add_f32_e32 v18, 1.0, v18
	v_add_f32_e32 v19, 1.0, v19
	v_rcp_f32_e32 v10, v10
	v_rcp_f32_e32 v11, v11
	v_rcp_f32_e32 v14, v14
	v_rcp_f32_e32 v15, v15
	v_rcp_f32_e32 v18, v18
	v_rcp_f32_e32 v19, v19
	v_lshl_add_u64 v[26:27], s[66:67], 0, v[26:27]
	v_lshl_add_u64 v[26:27], v[26:27], 0, v[160:161]
	s_waitcnt vmcnt(0)
	v_lshlrev_b32_e32 v12, 16, v20
	v_and_b32_e32 v13, 0xffff0000, v20
	v_lshlrev_b32_e32 v16, 16, v21
	v_and_b32_e32 v17, 0xffff0000, v21
	v_lshlrev_b32_e32 v20, 16, v22
	v_and_b32_e32 v21, 0xffff0000, v22
	v_mul_f32_e32 v22, 0xbfb8aa3b, v30
	v_exp_f32_e32 v22, v22
	v_lshlrev_b32_e32 v42, 16, v23
	v_and_b32_e32 v43, 0xffff0000, v23
	v_add_f32_e32 v22, 1.0, v22
	v_rcp_f32_e32 v34, v22
	v_mul_f32_e32 v22, 0xbfb8aa3b, v31
	v_exp_f32_e32 v22, v22
	s_nop 0
	v_add_f32_e32 v22, 1.0, v22
	v_rcp_f32_e32 v35, v22
	v_lshlrev_b64 v[22:23], 12, v[158:159]
	v_lshl_add_u64 v[22:23], s[6:7], 0, v[22:23]
	v_lshl_add_u64 v[22:23], v[22:23], 0, v[164:165]
	v_add_u32_e32 v218, 0x58000, v217
	global_load_dwordx4 v[224:227], v218, s[12:13] offset:256
	global_load_dwordx4 v[30:33], v[22:23], off offset:16
	global_load_dwordx4 v[38:41], v[22:23], off
	s_waitcnt vmcnt(0)
	v_pk_fma_f32 v[16:17], v[14:15], v[16:17], v[40:41]
	v_pk_fma_f32 v[14:15], v[10:11], v[12:13], v[38:39]
	v_pk_fma_f32 v[10:11], v[18:19], v[20:21], v[30:31]
	v_pk_fma_f32 v[12:13], v[34:35], v[42:43], v[32:33]
	global_store_dwordx4 v[22:23], v[14:17], off
	global_store_dwordx4 v[22:23], v[10:13], off offset:16
	v_cvt_pk_bf16_f32 v18, v14, v15
	v_cvt_pk_bf16_f32 v20, v10, v11
	v_mul_f32_e32 v15, v15, v15
	v_mul_f32_e32 v11, v11, v11
	v_fmac_f32_e32 v15, v14, v14
	v_mul_f32_e32 v14, v17, v17
	v_fmac_f32_e32 v11, v10, v10
	v_mul_f32_e32 v10, v13, v13
	v_fmac_f32_e32 v14, v16, v16
	v_fmac_f32_e32 v10, v12, v12
	v_cvt_pk_bf16_f32 v19, v16, v17
	v_cvt_pk_bf16_f32 v21, v12, v13
	v_add_f32_e32 v14, v15, v14
	v_add_f32_e32 v10, v11, v10
	global_store_dwordx4 v[26:27], v[18:21], off
	v_pk_mul_f32 v[12:13], v[4:5], v[0:1] op_sel_hi:[1,0]
	s_nop 0
	v_add_f32_e32 v18, v14, v10
	v_pk_mul_f32 v[14:15], v[2:3], v[0:1] op_sel_hi:[1,0]
	v_mov_b32_e32 v2, v224
	v_mov_b32_e32 v3, v225
	v_mov_b32_e32 v4, v226
	v_mov_b32_e32 v5, v227
	global_load_dwordx4 v[30:33], v[22:23], off offset:528
	global_load_dwordx4 v[38:41], v[22:23], off offset:512
	v_pk_mul_f32 v[10:11], v[8:9], v[0:1] op_sel_hi:[1,0]
	v_mul_f32_e32 v0, 0xbfb8aa3b, v6
	v_exp_f32_e32 v0, v0
	s_waitcnt vmcnt(2)
	v_lshlrev_b32_e32 v8, 16, v2
	v_add_f32_e32 v0, 1.0, v0
	v_rcp_f32_e32 v6, v0
	v_mul_f32_e32 v0, 0xbfb8aa3b, v7
	v_exp_f32_e32 v0, v0
	v_and_b32_e32 v9, 0xffff0000, v2
	v_lshlrev_b32_e32 v2, 16, v3
	v_and_b32_e32 v3, 0xffff0000, v3
	v_add_f32_e32 v0, 1.0, v0
	v_rcp_f32_e32 v7, v0
	v_mul_f32_e32 v0, 0xbfb8aa3b, v10
	v_exp_f32_e32 v0, v0
	v_lshlrev_b32_e32 v16, 16, v4
	v_and_b32_e32 v17, 0xffff0000, v4
	v_lshlrev_b32_e32 v20, 16, v5
	v_add_f32_e32 v0, 1.0, v0
	v_rcp_f32_e32 v10, v0
	v_mul_f32_e32 v0, 0xbfb8aa3b, v11
	v_exp_f32_e32 v0, v0
	v_and_b32_e32 v21, 0xffff0000, v5
	v_add_f32_e32 v0, 1.0, v0
	v_rcp_f32_e32 v11, v0
	v_mul_f32_e32 v0, 0xbfb8aa3b, v14
	v_exp_f32_e32 v0, v0
	s_waitcnt vmcnt(0)
	v_pk_fma_f32 v[4:5], v[10:11], v[2:3], v[40:41]
	v_pk_fma_f32 v[2:3], v[6:7], v[8:9], v[38:39]
	v_add_f32_e32 v0, 1.0, v0
	v_rcp_f32_e32 v14, v0
	v_mul_f32_e32 v0, 0xbfb8aa3b, v15
	v_exp_f32_e32 v0, v0
	v_cvt_pk_bf16_f32 v10, v2, v3
	v_cvt_pk_bf16_f32 v11, v4, v5
	v_add_f32_e32 v0, 1.0, v0
	v_rcp_f32_e32 v15, v0
	v_mul_f32_e32 v0, 0xbfb8aa3b, v12
	v_exp_f32_e32 v0, v0
	v_pk_fma_f32 v[6:7], v[14:15], v[16:17], v[30:31]
	v_add_f32_e32 v0, 1.0, v0
	v_rcp_f32_e32 v12, v0
	v_mul_f32_e32 v0, 0xbfb8aa3b, v13
	v_exp_f32_e32 v0, v0
	s_nop 0
	v_add_f32_e32 v0, 1.0, v0
	v_rcp_f32_e32 v13, v0
	v_mul_f32_e32 v0, v3, v3
	v_fmac_f32_e32 v0, v2, v2
	v_pk_fma_f32 v[8:9], v[12:13], v[20:21], v[32:33]
	global_store_dwordx4 v[22:23], v[2:5], off offset:512
	global_store_dwordx4 v[22:23], v[6:9], off offset:528
	v_cvt_pk_bf16_f32 v13, v8, v9
	v_mul_f32_e32 v2, v5, v5
	v_fmac_f32_e32 v2, v4, v4
	v_add_f32_e32 v0, v0, v2
	v_mul_f32_e32 v2, v7, v7
	v_mul_f32_e32 v3, v9, v9
	v_fmac_f32_e32 v2, v6, v6
	v_fmac_f32_e32 v3, v8, v8
	v_add_f32_e32 v2, v2, v3
	v_add_f32_e32 v0, v0, v2
	v_add_f32_e32 v8, v18, v0
	v_cvt_pk_bf16_f32 v12, v6, v7
	ds_bpermute_b32 v0, v216, v128
	ds_bpermute_b32 v2, v216, v120
	ds_bpermute_b32 v3, v216, v96
	ds_bpermute_b32 v4, v216, v88
	ds_bpermute_b32 v5, v216, v52
	ds_bpermute_b32 v6, v216, v36
	ds_bpermute_b32 v7, v216, v28
	ds_bpermute_b32 v9, v216, v8
	s_waitcnt lgkmcnt(7)
	v_add_f32_e32 v0, v128, v0
	s_waitcnt lgkmcnt(6)
	v_add_f32_e32 v2, v120, v2
	s_waitcnt lgkmcnt(5)
	v_add_f32_e32 v3, v96, v3
	s_waitcnt lgkmcnt(4)
	v_add_f32_e32 v4, v88, v4
	s_waitcnt lgkmcnt(3)
	v_add_f32_e32 v5, v52, v5
	s_waitcnt lgkmcnt(2)
	v_add_f32_e32 v6, v36, v6
	s_waitcnt lgkmcnt(1)
	v_add_f32_e32 v7, v28, v7
	s_waitcnt lgkmcnt(0)
	v_add_f32_e32 v8, v8, v9
	global_store_dwordx4 v[26:27], v[10:13], off offset:256
	ds_bpermute_b32 v9, v215, v0
	ds_bpermute_b32 v10, v215, v2
	ds_bpermute_b32 v11, v215, v3
	ds_bpermute_b32 v12, v215, v4
	ds_bpermute_b32 v13, v215, v5
	ds_bpermute_b32 v14, v215, v6
	ds_bpermute_b32 v15, v215, v7
	ds_bpermute_b32 v16, v215, v8
	s_and_saveexec_b64 s[4:5], vcc
	s_cbranch_execz .LBB0_146
; #define EPI_LOOP_ROWS for (int ai = 0; ai < 2; ++ai) _Pragma("unroll") for (int m = 0; m < 4; ++m)
;     __device__ __forceinline__ void operator()(const f32x4 (&acc)[2][2][4][2], const Unit& u, int wv) const {
;     ...
;         if (fq == 0) {
; #pragma unroll
;             EPI_LOOP_ROWS RSout[(size_t)(row0 + ai * HALF + m * 16) * 16 + u.pn * 4 + wc] = sq[ai][m]; }
	s_lshl_b32 s0, s28, 2
	s_ashr_i32 s1, s0, 31
	s_lshl_b64 s[0:1], s[0:1], 2
	s_add_u32 s0, s60, s0
	s_addc_u32 s1, s61, s1
	s_lshl_b32 s10, s49, 2
	s_add_u32 s0, s0, s10
	s_addc_u32 s1, s1, 0
	s_waitcnt lgkmcnt(5)
	v_add_f32_e32 v11, v3, v11
	v_add_f32_e32 v10, v2, v10
	v_add_f32_e32 v0, v0, v9
	v_lshl_add_u64 v[2:3], s[0:1], 0, v[142:143]
	global_store_dword v[2:3], v0, off
	v_lshl_add_u64 v[2:3], s[0:1], 0, v[144:145]
	global_store_dword v[2:3], v10, off
	v_lshl_add_u64 v[2:3], s[0:1], 0, v[146:147]
	s_waitcnt lgkmcnt(4)
	v_add_f32_e32 v4, v4, v12
	global_store_dword v[2:3], v11, off
	v_lshl_add_u64 v[2:3], s[0:1], 0, v[148:149]
	s_waitcnt lgkmcnt(3)
	v_add_f32_e32 v5, v5, v13
	global_store_dword v[2:3], v4, off
	v_lshl_add_u64 v[2:3], s[0:1], 0, v[150:151]
	s_waitcnt lgkmcnt(2)
	v_add_f32_e32 v6, v6, v14
	global_store_dword v[2:3], v5, off
	v_lshl_add_u64 v[2:3], s[0:1], 0, v[152:153]
	s_waitcnt lgkmcnt(1)
	v_add_f32_e32 v7, v7, v15
	global_store_dword v[2:3], v6, off
	v_lshl_add_u64 v[2:3], s[0:1], 0, v[154:155]
	s_waitcnt lgkmcnt(0)
	v_add_f32_e32 v8, v8, v16
	global_store_dword v[2:3], v7, off
	v_lshl_add_u64 v[2:3], s[0:1], 0, v[156:157]
	global_store_dword v[2:3], v8, off

; #define PG8_STAGE(bufoff, gbase, voff) do { _Pragma("unroll") for (int _i = 0; _i < 2; ++_i) \
;         __builtin_amdgcn_global_load_lds((const unsigned*)((const char*)(gbase) + (voff)[_i]), (LAS unsigned*)(lds + (bufoff) + ldsw + _i * 8192), 16, 0, 0); } while (0)
; #define PG8_LDA(dst, b, h) do { _Pragma("unroll") for (int m = 0; m < 4; ++m) _Pragma("unroll") for (int k = 0; k < 2; ++k) dst[m][k] = *(const LAS bf16x8*)(lds + PG8_SA(b, h) + aoff + m * 2048 + k * 1024); } while (0)
; #define PG8_LDB(dst, b, h) do { _Pragma("unroll") for (int n = 0; n < 2; ++n) _Pragma("unroll") for (int k = 0; k < 2; ++k) dst[n][k] = *(const LAS bf16x8*)(lds + PG8_SB(b, h) + boff + n * 2048 + k * 1024); } while (0)
; #define PG8_MMA(ai, bj, At, Bt) do { __builtin_amdgcn_s_setprio(1); _Pragma("unroll") for (int m = 0; m < 4; ++m) _Pragma("unroll") for (int n = 0; n < 2; ++n) _Pragma("unroll") for (int k = 0; k < 2; ++k) \
;         acc[ai][bj][m][n] = __builtin_amdgcn_mfma_f32_16x16x32_bf16(Bt[n][k], At[m][k], acc[ai][bj][m][n], 0, 0, 0); __builtin_amdgcn_s_setprio(0); } while (0)
; #define PG8_WAIT_V(n) asm volatile("s_waitcnt vmcnt(" #n ")" ::: "memory")
; #define PG8_WAIT_L(n) asm volatile("s_waitcnt lgkmcnt(" #n ")" ::: "memory")
; #define PG8_BAR __builtin_amdgcn_s_barrier()
; #define PG8_SCHED __builtin_amdgcn_sched_barrier(0)
; template <class Epi, class Sched>
; __device__ __forceinline__ void gemm_phase(LAS unsigned char* lds, const Gemm g, const Sched& S, const Epi& E, int wv) {
;     ...
;             const char* a1 = cA + (size_t)(t + 1) * kstep;
;             const char* a2 = last ? nA : cA + (size_t)(t + 2) * kstep; const char* b2 = last ? nB : cB + (size_t)(t + 2) * kstep;
;             const char* a3 = a2 + kstep; const char* b3 = b2 + kstep;
;             PG8_LDB(B0, 0, 0); PG8_LDB(B1, 0, 1); PG8_SCHED; PG8_LDA(At, 0, 0); PG8_STAGE(PG8_SA(1, 1), a1 + hstepA, voffA);
;             PG8_WAIT_V(8); PG8_WAIT_L(0); PG8_BAR; PG8_MMA(0, 0, At, B0); PG8_MMA(0, 1, At, B1); PG8_BAR; PG8_SCHED;
.LBB0_174:
	s_add_u32 s70, s68, 0x100
	s_addc_u32 s71, s69, 0
	s_add_i32 s0, 0, 0x10000
	s_cmp_eq_u32 s31, 40
	s_cselect_b32 s75, s5, s71
	s_cselect_b32 s74, s4, s70
	v_add_u32_e32 v144, s0, v146
	s_cselect_b32 s73, s67, s21
	s_cselect_b32 s72, s66, s11
	s_add_i32 s20, 0, 0x14000
	ds_read_b128 v[140:143], v144
	ds_read_b128 v[148:151], v144 offset:1024
	ds_read_b128 v[152:155], v144 offset:2048
	ds_read_b128 v[156:159], v144 offset:3072
	v_add_u32_e32 v144, s20, v146
	ds_read_b128 v[160:163], v144
	ds_read_b128 v[164:167], v144 offset:1024
	ds_read_b128 v[168:171], v144 offset:2048
	ds_read_b128 v[172:175], v144 offset:3072
	v_lshl_add_u64 v[144:145], s[68:69], 0, v[136:137]
	s_add_i32 m0, s62, 0xc000
	ds_read_b128 v[176:179], v147
	ds_read_b128 v[180:183], v147 offset:1024
	ds_read_b128 v[184:187], v147 offset:2048
	ds_read_b128 v[188:191], v147 offset:3072
	ds_read_b128 v[196:199], v147 offset:4096
	ds_read_b128 v[200:203], v147 offset:5120
	ds_read_b128 v[204:207], v147 offset:6144
	ds_read_b128 v[208:211], v147 offset:7168
	global_load_lds_dwordx4 v[144:145], off
	v_lshl_add_u64 v[144:145], s[68:69], 0, v[138:139]
	s_add_i32 m0, s62, 0xe000
	s_nop 0
	global_load_lds_dwordx4 v[144:145], off
	s_waitcnt vmcnt(8)
	s_waitcnt lgkmcnt(0)
	s_barrier
	s_setprio 1
	v_mfma_f32_16x16x32_bf16 v[126:129], v[140:143], v[176:179], v[126:129]
	v_mfma_f32_16x16x32_bf16 v[122:125], v[152:155], v[176:179], v[122:125]
	v_mfma_f32_16x16x32_bf16 v[110:113], v[140:143], v[184:187], v[110:113]
	v_mfma_f32_16x16x32_bf16 v[106:109], v[152:155], v[184:187], v[106:109]
	v_mfma_f32_16x16x32_bf16 v[94:97], v[140:143], v[196:199], v[94:97]
	v_mfma_f32_16x16x32_bf16 v[90:93], v[152:155], v[196:199], v[90:93]
	v_mfma_f32_16x16x32_bf16 v[78:81], v[140:143], v[204:207], v[78:81]
	v_mfma_f32_16x16x32_bf16 v[74:77], v[152:155], v[204:207], v[74:77]
	v_mfma_f32_16x16x32_bf16 v[126:129], v[148:151], v[180:183], v[126:129]
	v_mfma_f32_16x16x32_bf16 v[122:125], v[156:159], v[180:183], v[122:125]
	v_mfma_f32_16x16x32_bf16 v[110:113], v[148:151], v[188:191], v[110:113]
	v_mfma_f32_16x16x32_bf16 v[106:109], v[156:159], v[188:191], v[106:109]
	v_mfma_f32_16x16x32_bf16 v[94:97], v[148:151], v[200:203], v[94:97]
	v_mfma_f32_16x16x32_bf16 v[90:93], v[156:159], v[200:203], v[90:93]
	v_mfma_f32_16x16x32_bf16 v[78:81], v[148:151], v[208:211], v[78:81]
	v_mfma_f32_16x16x32_bf16 v[74:77], v[156:159], v[208:211], v[74:77]
	v_mfma_f32_16x16x32_bf16 v[118:121], v[160:163], v[176:179], v[118:121]
	v_mfma_f32_16x16x32_bf16 v[114:117], v[168:171], v[176:179], v[114:117]
	v_mfma_f32_16x16x32_bf16 v[102:105], v[160:163], v[184:187], v[102:105]
	v_mfma_f32_16x16x32_bf16 v[98:101], v[168:171], v[184:187], v[98:101]
	v_mfma_f32_16x16x32_bf16 v[86:89], v[160:163], v[196:199], v[86:89]
	v_mfma_f32_16x16x32_bf16 v[82:85], v[168:171], v[196:199], v[82:85]
	v_mfma_f32_16x16x32_bf16 v[70:73], v[160:163], v[204:207], v[70:73]
	v_mfma_f32_16x16x32_bf16 v[66:69], v[168:171], v[204:207], v[66:69]
	v_mfma_f32_16x16x32_bf16 v[118:121], v[164:167], v[180:183], v[118:121]
	v_mfma_f32_16x16x32_bf16 v[114:117], v[172:175], v[180:183], v[114:117]
	v_mfma_f32_16x16x32_bf16 v[102:105], v[164:167], v[188:191], v[102:105]
	v_mfma_f32_16x16x32_bf16 v[98:101], v[172:175], v[188:191], v[98:101]
	v_mfma_f32_16x16x32_bf16 v[86:89], v[164:167], v[200:203], v[86:89]
	v_mfma_f32_16x16x32_bf16 v[82:85], v[172:175], v[200:203], v[82:85]
	v_mfma_f32_16x16x32_bf16 v[70:73], v[164:167], v[208:211], v[70:73]
	v_mfma_f32_16x16x32_bf16 v[66:69], v[172:175], v[208:211], v[66:69]
	s_setprio 0
	s_barrier
	s_add_i32 s0, s0, s61
	v_lshl_add_u64 v[144:145], s[72:73], 0, v[0:1]
	s_mov_b32 m0, s0
	ds_read_b128 v[176:179], v147 offset:16384
	ds_read_b128 v[180:183], v147 offset:17408
	ds_read_b128 v[184:187], v147 offset:18432
	ds_read_b128 v[188:191], v147 offset:19456
	ds_read_b128 v[196:199], v147 offset:20480
	ds_read_b128 v[200:203], v147 offset:21504
	ds_read_b128 v[204:207], v147 offset:22528
	ds_read_b128 v[208:211], v147 offset:23552
	global_load_lds_dwordx4 v[144:145], off
	s_add_i32 m0, s0, 0x2000
	s_add_u32 s0, s72, 0xb0000
	v_lshl_add_u64 v[192:193], s[72:73], 0, v[134:135]
	s_addc_u32 s1, s73, 0
	s_add_i32 s20, s20, s61
	global_load_lds_dwordx4 v[192:193], off
	v_lshl_add_u64 v[212:213], s[0:1], 0, v[0:1]
	s_mov_b32 m0, s20
	v_lshl_add_u64 v[214:215], s[74:75], 0, v[132:133]
	global_load_lds_dwordx4 v[212:213], off
	v_lshl_add_u64 v[212:213], s[0:1], 0, v[134:135]
	s_add_i32 m0, s20, 0x2000
	s_nop 0
	global_load_lds_dwordx4 v[212:213], off
	v_lshl_add_u64 v[212:213], s[74:75], 0, v[130:131]
	s_mov_b32 m0, s62
	s_nop 0
	global_load_lds_dwordx4 v[212:213], off
	s_mov_b32 m0, s76
	s_nop 0
	global_load_lds_dwordx4 v[214:215], off
	s_waitcnt vmcnt(8)
	s_waitcnt lgkmcnt(0)
	s_barrier
; #define PG8_STAGE(bufoff, gbase, voff) do { _Pragma("unroll") for (int _i = 0; _i < 2; ++_i) \
;         __builtin_amdgcn_global_load_lds((const unsigned*)((const char*)(gbase) + (voff)[_i]), (LAS unsigned*)(lds + (bufoff) + ldsw + _i * 8192), 16, 0, 0); } while (0)
; #define PG8_LDA(dst, b, h) do { _Pragma("unroll") for (int m = 0; m < 4; ++m) _Pragma("unroll") for (int k = 0; k < 2; ++k) dst[m][k] = *(const LAS bf16x8*)(lds + PG8_SA(b, h) + aoff + m * 2048 + k * 1024); } while (0)
; #define PG8_LDB(dst, b, h) do { _Pragma("unroll") for (int n = 0; n < 2; ++n) _Pragma("unroll") for (int k = 0; k < 2; ++k) dst[n][k] = *(const LAS bf16x8*)(lds + PG8_SB(b, h) + boff + n * 2048 + k * 1024); } while (0)
; #define PG8_MMA(ai, bj, At, Bt) do { __builtin_amdgcn_s_setprio(1); _Pragma("unroll") for (int m = 0; m < 4; ++m) _Pragma("unroll") for (int n = 0; n < 2; ++n) _Pragma("unroll") for (int k = 0; k < 2; ++k) \
;         acc[ai][bj][m][n] = __builtin_amdgcn_mfma_f32_16x16x32_bf16(Bt[n][k], At[m][k], acc[ai][bj][m][n], 0, 0, 0); __builtin_amdgcn_s_setprio(0); } while (0)
; #define PG8_WAIT_V(n) asm volatile("s_waitcnt vmcnt(" #n ")" ::: "memory")
; #define PG8_WAIT_L(n) asm volatile("s_waitcnt lgkmcnt(" #n ")" ::: "memory")
; #define PG8_BAR __builtin_amdgcn_s_barrier()
; #define PG8_SCHED __builtin_amdgcn_sched_barrier(0)
; template <class Epi, class Sched>
; __device__ __forceinline__ void gemm_phase(LAS unsigned char* lds, const Gemm g, const Sched& S, const Epi& E, int wv) {
;     ...
;             PG8_WAIT_V(8); PG8_WAIT_L(0); PG8_BAR; PG8_MMA(0, 0, At, B0); PG8_MMA(0, 1, At, B1); PG8_BAR; PG8_SCHED;
;             PG8_LDA(At, 0, 1); PG8_STAGE(PG8_SB(0, 0), b2, voffB); PG8_STAGE(PG8_SB(0, 1), b2 + hstepB, voffB); PG8_STAGE(PG8_SA(0, 0), a2, voffA);
;             PG8_WAIT_V(8); PG8_WAIT_L(0); PG8_BAR; PG8_MMA(1, 0, At, B0); PG8_MMA(1, 1, At, B1); PG8_BAR; PG8_SCHED;
;             PG8_LDB(B0, 1, 0); PG8_LDB(B1, 1, 1); PG8_SCHED; PG8_LDA(At, 1, 0); PG8_STAGE(PG8_SA(0, 1), a2 + hstepA, voffA);
;             PG8_WAIT_V(8); PG8_WAIT_L(0); PG8_BAR; PG8_MMA(0, 0, At, B0); PG8_MMA(0, 1, At, B1); PG8_BAR; PG8_SCHED;
	s_setprio 1
	v_mfma_f32_16x16x32_bf16 v[62:65], v[140:143], v[176:179], v[62:65]
	v_mfma_f32_16x16x32_bf16 v[58:61], v[152:155], v[176:179], v[58:61]
	v_mfma_f32_16x16x32_bf16 v[46:49], v[140:143], v[184:187], v[46:49]
	v_mfma_f32_16x16x32_bf16 v[42:45], v[152:155], v[184:187], v[42:45]
	v_mfma_f32_16x16x32_bf16 v[30:33], v[140:143], v[196:199], v[30:33]
	v_mfma_f32_16x16x32_bf16 v[26:29], v[152:155], v[196:199], v[26:29]
	v_mfma_f32_16x16x32_bf16 v[14:17], v[140:143], v[204:207], v[14:17]
	v_mfma_f32_16x16x32_bf16 v[10:13], v[152:155], v[204:207], v[10:13]
	v_mfma_f32_16x16x32_bf16 v[62:65], v[148:151], v[180:183], v[62:65]
	v_mfma_f32_16x16x32_bf16 v[58:61], v[156:159], v[180:183], v[58:61]
	v_mfma_f32_16x16x32_bf16 v[46:49], v[148:151], v[188:191], v[46:49]
	v_mfma_f32_16x16x32_bf16 v[42:45], v[156:159], v[188:191], v[42:45]
	v_mfma_f32_16x16x32_bf16 v[30:33], v[148:151], v[200:203], v[30:33]
	v_mfma_f32_16x16x32_bf16 v[26:29], v[156:159], v[200:203], v[26:29]
	v_mfma_f32_16x16x32_bf16 v[14:17], v[148:151], v[208:211], v[14:17]
	v_mfma_f32_16x16x32_bf16 v[10:13], v[156:159], v[208:211], v[10:13]
	v_mfma_f32_16x16x32_bf16 v[54:57], v[160:163], v[176:179], v[54:57]
	v_mfma_f32_16x16x32_bf16 v[50:53], v[168:171], v[176:179], v[50:53]
	v_mfma_f32_16x16x32_bf16 v[38:41], v[160:163], v[184:187], v[38:41]
	v_mfma_f32_16x16x32_bf16 v[34:37], v[168:171], v[184:187], v[34:37]
	v_mfma_f32_16x16x32_bf16 v[22:25], v[160:163], v[196:199], v[22:25]
	v_mfma_f32_16x16x32_bf16 v[18:21], v[168:171], v[196:199], v[18:21]
	v_mfma_f32_16x16x32_bf16 v[6:9], v[160:163], v[204:207], v[6:9]
	v_mfma_f32_16x16x32_bf16 v[2:5], v[168:171], v[204:207], v[2:5]
	v_mfma_f32_16x16x32_bf16 v[54:57], v[164:167], v[180:183], v[54:57]
	v_mfma_f32_16x16x32_bf16 v[50:53], v[172:175], v[180:183], v[50:53]
	v_mfma_f32_16x16x32_bf16 v[38:41], v[164:167], v[188:191], v[38:41]
	v_mfma_f32_16x16x32_bf16 v[34:37], v[172:175], v[188:191], v[34:37]
	v_mfma_f32_16x16x32_bf16 v[22:25], v[164:167], v[200:203], v[22:25]
	v_mfma_f32_16x16x32_bf16 v[18:21], v[172:175], v[200:203], v[18:21]
	v_mfma_f32_16x16x32_bf16 v[6:9], v[164:167], v[208:211], v[6:9]
	v_mfma_f32_16x16x32_bf16 v[2:5], v[172:175], v[208:211], v[2:5]
	s_setprio 0
	s_barrier
	s_add_i32 s20, 0, 0x18000
	s_add_i32 s26, 0, 0x1c000
	v_add_u32_e32 v156, s20, v146
	v_add_u32_e32 v172, s26, v146
	ds_read_b128 v[140:143], v156
	ds_read_b128 v[148:151], v156 offset:1024
	ds_read_b128 v[152:155], v156 offset:2048
	ds_read_b128 v[156:159], v156 offset:3072
	ds_read_b128 v[160:163], v172
	ds_read_b128 v[164:167], v172 offset:1024
	ds_read_b128 v[168:171], v172 offset:2048
	ds_read_b128 v[172:175], v172 offset:3072
	s_add_u32 s0, s74, 0xb0000
	s_addc_u32 s1, s75, 0
	s_mov_b32 m0, s77
	v_lshl_add_u64 v[216:217], s[0:1], 0, v[130:131]
	ds_read_b128 v[176:179], v147 offset:32768
	ds_read_b128 v[180:183], v147 offset:33792
	ds_read_b128 v[184:187], v147 offset:34816
	ds_read_b128 v[188:191], v147 offset:35840
	ds_read_b128 v[196:199], v147 offset:36864
	ds_read_b128 v[200:203], v147 offset:37888
	ds_read_b128 v[204:207], v147 offset:38912
	ds_read_b128 v[208:211], v147 offset:39936
	global_load_lds_dwordx4 v[216:217], off
	v_lshl_add_u64 v[216:217], s[0:1], 0, v[132:133]
	s_mov_b32 m0, s78
	s_nop 0
	global_load_lds_dwordx4 v[216:217], off
	s_waitcnt vmcnt(8)
	s_waitcnt lgkmcnt(0)
	s_barrier
	s_setprio 1
	v_mfma_f32_16x16x32_bf16 v[126:129], v[140:143], v[176:179], v[126:129]
	v_mfma_f32_16x16x32_bf16 v[122:125], v[152:155], v[176:179], v[122:125]
	v_mfma_f32_16x16x32_bf16 v[110:113], v[140:143], v[184:187], v[110:113]
	v_mfma_f32_16x16x32_bf16 v[106:109], v[152:155], v[184:187], v[106:109]
	v_mfma_f32_16x16x32_bf16 v[94:97], v[140:143], v[196:199], v[94:97]
	v_mfma_f32_16x16x32_bf16 v[90:93], v[152:155], v[196:199], v[90:93]
	v_mfma_f32_16x16x32_bf16 v[78:81], v[140:143], v[204:207], v[78:81]
	v_mfma_f32_16x16x32_bf16 v[74:77], v[152:155], v[204:207], v[74:77]
	v_mfma_f32_16x16x32_bf16 v[126:129], v[148:151], v[180:183], v[126:129]
	v_mfma_f32_16x16x32_bf16 v[122:125], v[156:159], v[180:183], v[122:125]
	v_mfma_f32_16x16x32_bf16 v[110:113], v[148:151], v[188:191], v[110:113]
	v_mfma_f32_16x16x32_bf16 v[106:109], v[156:159], v[188:191], v[106:109]
	v_mfma_f32_16x16x32_bf16 v[94:97], v[148:151], v[200:203], v[94:97]
	v_mfma_f32_16x16x32_bf16 v[90:93], v[156:159], v[200:203], v[90:93]
	v_mfma_f32_16x16x32_bf16 v[78:81], v[148:151], v[208:211], v[78:81]
	v_mfma_f32_16x16x32_bf16 v[74:77], v[156:159], v[208:211], v[74:77]
	v_mfma_f32_16x16x32_bf16 v[118:121], v[160:163], v[176:179], v[118:121]
	v_mfma_f32_16x16x32_bf16 v[114:117], v[168:171], v[176:179], v[114:117]
	v_mfma_f32_16x16x32_bf16 v[102:105], v[160:163], v[184:187], v[102:105]
	v_mfma_f32_16x16x32_bf16 v[98:101], v[168:171], v[184:187], v[98:101]
	v_mfma_f32_16x16x32_bf16 v[86:89], v[160:163], v[196:199], v[86:89]
	v_mfma_f32_16x16x32_bf16 v[82:85], v[168:171], v[196:199], v[82:85]
	v_mfma_f32_16x16x32_bf16 v[70:73], v[160:163], v[204:207], v[70:73]
	v_mfma_f32_16x16x32_bf16 v[66:69], v[168:171], v[204:207], v[66:69]
	v_mfma_f32_16x16x32_bf16 v[118:121], v[164:167], v[180:183], v[118:121]
	v_mfma_f32_16x16x32_bf16 v[114:117], v[172:175], v[180:183], v[114:117]
	v_mfma_f32_16x16x32_bf16 v[102:105], v[164:167], v[188:191], v[102:105]
	v_mfma_f32_16x16x32_bf16 v[98:101], v[172:175], v[188:191], v[98:101]
	v_mfma_f32_16x16x32_bf16 v[86:89], v[164:167], v[200:203], v[86:89]
	v_mfma_f32_16x16x32_bf16 v[82:85], v[172:175], v[200:203], v[82:85]
	v_mfma_f32_16x16x32_bf16 v[70:73], v[164:167], v[208:211], v[70:73]
	v_mfma_f32_16x16x32_bf16 v[66:69], v[172:175], v[208:211], v[66:69]
	s_setprio 0
	s_barrier
; #define PG8_STAGE(bufoff, gbase, voff) do { _Pragma("unroll") for (int _i = 0; _i < 2; ++_i) \
;         __builtin_amdgcn_global_load_lds((const unsigned*)((const char*)(gbase) + (voff)[_i]), (LAS unsigned*)(lds + (bufoff) + ldsw + _i * 8192), 16, 0, 0); } while (0)
; #define PG8_LDA(dst, b, h) do { _Pragma("unroll") for (int m = 0; m < 4; ++m) _Pragma("unroll") for (int k = 0; k < 2; ++k) dst[m][k] = *(const LAS bf16x8*)(lds + PG8_SA(b, h) + aoff + m * 2048 + k * 1024); } while (0)
; #define PG8_MMA(ai, bj, At, Bt) do { __builtin_amdgcn_s_setprio(1); _Pragma("unroll") for (int m = 0; m < 4; ++m) _Pragma("unroll") for (int n = 0; n < 2; ++n) _Pragma("unroll") for (int k = 0; k < 2; ++k) \
;         acc[ai][bj][m][n] = __builtin_amdgcn_mfma_f32_16x16x32_bf16(Bt[n][k], At[m][k], acc[ai][bj][m][n], 0, 0, 0); __builtin_amdgcn_s_setprio(0); } while (0)
; #define PG8_WAIT_V(n) asm volatile("s_waitcnt vmcnt(" #n ")" ::: "memory")
; #define PG8_WAIT_L(n) asm volatile("s_waitcnt lgkmcnt(" #n ")" ::: "memory")
; #define PG8_BAR __builtin_amdgcn_s_barrier()
; #define PG8_SCHED __builtin_amdgcn_sched_barrier(0)
; template <class Epi, class Sched>
; __device__ __forceinline__ void gemm_phase(LAS unsigned char* lds, const Gemm g, const Sched& S, const Epi& E, int wv) {
;     ...
;             PG8_LDA(At, 1, 1); PG8_STAGE(PG8_SB(1, 0), b3, voffB); PG8_STAGE(PG8_SB(1, 1), b3 + hstepB, voffB); PG8_STAGE(PG8_SA(1, 0), a3, voffA);
;             PG8_WAIT_V(8); PG8_WAIT_L(0); PG8_BAR; PG8_MMA(1, 0, At, B0); PG8_MMA(1, 1, At, B1); PG8_BAR; PG8_SCHED;
;         }
;         if (wr == 0) PG8_BAR;
	s_add_i32 s0, s20, s61
	v_lshl_add_u64 v[144:145], v[144:145], 0, s[24:25]
	s_mov_b32 m0, s0
	ds_read_b128 v[176:179], v147 offset:49152
	ds_read_b128 v[180:183], v147 offset:50176
	ds_read_b128 v[184:187], v147 offset:51200
	ds_read_b128 v[188:191], v147 offset:52224
	ds_read_b128 v[196:199], v147 offset:53248
	ds_read_b128 v[200:203], v147 offset:54272
	ds_read_b128 v[204:207], v147 offset:55296
	ds_read_b128 v[208:211], v147 offset:56320
	global_load_lds_dwordx4 v[144:145], off
	s_add_i32 m0, s0, 0x2000
	s_add_u32 s0, s72, 0xb0080
	v_lshl_add_u64 v[144:145], v[192:193], 0, s[24:25]
	s_addc_u32 s1, s73, 0
	s_add_i32 s20, s26, s61
	global_load_lds_dwordx4 v[144:145], off
	v_lshl_add_u64 v[144:145], s[0:1], 0, v[0:1]
	s_mov_b32 m0, s20
	s_nop 0
	global_load_lds_dwordx4 v[144:145], off
	v_lshl_add_u64 v[144:145], s[0:1], 0, v[134:135]
	s_add_i32 m0, s20, 0x2000
	s_nop 0
	global_load_lds_dwordx4 v[144:145], off
	v_lshl_add_u64 v[144:145], v[212:213], 0, s[24:25]
	s_mov_b32 m0, s82
	s_nop 0
	global_load_lds_dwordx4 v[144:145], off
	v_lshl_add_u64 v[144:145], v[214:215], 0, s[24:25]
	s_mov_b32 m0, s83
	s_nop 0
	global_load_lds_dwordx4 v[144:145], off
	s_waitcnt vmcnt(8)
	s_waitcnt lgkmcnt(0)
	s_barrier
	s_setprio 1
	v_mfma_f32_16x16x32_bf16 v[62:65], v[140:143], v[176:179], v[62:65]
	v_mfma_f32_16x16x32_bf16 v[58:61], v[152:155], v[176:179], v[58:61]
	v_mfma_f32_16x16x32_bf16 v[46:49], v[140:143], v[184:187], v[46:49]
	v_mfma_f32_16x16x32_bf16 v[42:45], v[152:155], v[184:187], v[42:45]
	v_mfma_f32_16x16x32_bf16 v[30:33], v[140:143], v[196:199], v[30:33]
	v_mfma_f32_16x16x32_bf16 v[26:29], v[152:155], v[196:199], v[26:29]
	v_mfma_f32_16x16x32_bf16 v[14:17], v[140:143], v[204:207], v[14:17]
	v_mfma_f32_16x16x32_bf16 v[10:13], v[152:155], v[204:207], v[10:13]
	v_mfma_f32_16x16x32_bf16 v[62:65], v[148:151], v[180:183], v[62:65]
	v_mfma_f32_16x16x32_bf16 v[58:61], v[156:159], v[180:183], v[58:61]
	v_mfma_f32_16x16x32_bf16 v[46:49], v[148:151], v[188:191], v[46:49]
	v_mfma_f32_16x16x32_bf16 v[42:45], v[156:159], v[188:191], v[42:45]
	v_mfma_f32_16x16x32_bf16 v[30:33], v[148:151], v[200:203], v[30:33]
	v_mfma_f32_16x16x32_bf16 v[26:29], v[156:159], v[200:203], v[26:29]
	v_mfma_f32_16x16x32_bf16 v[14:17], v[148:151], v[208:211], v[14:17]
	v_mfma_f32_16x16x32_bf16 v[10:13], v[156:159], v[208:211], v[10:13]
	v_mfma_f32_16x16x32_bf16 v[54:57], v[160:163], v[176:179], v[54:57]
	v_mfma_f32_16x16x32_bf16 v[50:53], v[168:171], v[176:179], v[50:53]
	v_mfma_f32_16x16x32_bf16 v[38:41], v[160:163], v[184:187], v[38:41]
	v_mfma_f32_16x16x32_bf16 v[34:37], v[168:171], v[184:187], v[34:37]
	v_mfma_f32_16x16x32_bf16 v[22:25], v[160:163], v[196:199], v[22:25]
	v_mfma_f32_16x16x32_bf16 v[18:21], v[168:171], v[196:199], v[18:21]
	v_mfma_f32_16x16x32_bf16 v[6:9], v[160:163], v[204:207], v[6:9]
	v_mfma_f32_16x16x32_bf16 v[2:5], v[168:171], v[204:207], v[2:5]
	v_mfma_f32_16x16x32_bf16 v[54:57], v[164:167], v[180:183], v[54:57]
	v_mfma_f32_16x16x32_bf16 v[50:53], v[172:175], v[180:183], v[50:53]
	v_mfma_f32_16x16x32_bf16 v[38:41], v[164:167], v[188:191], v[38:41]
	v_mfma_f32_16x16x32_bf16 v[34:37], v[172:175], v[188:191], v[34:37]
	v_mfma_f32_16x16x32_bf16 v[22:25], v[164:167], v[200:203], v[22:25]
	v_mfma_f32_16x16x32_bf16 v[18:21], v[172:175], v[200:203], v[18:21]
	v_mfma_f32_16x16x32_bf16 v[6:9], v[164:167], v[208:211], v[6:9]
	v_mfma_f32_16x16x32_bf16 v[2:5], v[172:175], v[208:211], v[2:5]
	s_setprio 0
	s_barrier
	s_add_i32 s31, s31, 2
	s_add_u32 s11, s11, 0x100
	s_addc_u32 s21, s21, 0
	s_cmp_gt_u32 s31, 41
	s_mov_b64 s[68:69], s[70:71]
	s_cbranch_scc0 .LBB0_174
	s_and_b64 vcc, exec, s[64:65]
	s_cbranch_vccz .LBB0_177
	s_barrier

; #define PG8_STAGE(bufoff, gbase, voff) do { _Pragma("unroll") for (int _i = 0; _i < 2; ++_i) \
;         __builtin_amdgcn_global_load_lds((const unsigned*)((const char*)(gbase) + (voff)[_i]), (LAS unsigned*)(lds + (bufoff) + ldsw + _i * 8192), 16, 0, 0); } while (0)
; #define PG8_LDA(dst, b, h) do { _Pragma("unroll") for (int m = 0; m < 4; ++m) _Pragma("unroll") for (int k = 0; k < 2; ++k) dst[m][k] = *(const LAS bf16x8*)(lds + PG8_SA(b, h) + aoff + m * 2048 + k * 1024); } while (0)
; #define PG8_LDB(dst, b, h) do { _Pragma("unroll") for (int n = 0; n < 2; ++n) _Pragma("unroll") for (int k = 0; k < 2; ++k) dst[n][k] = *(const LAS bf16x8*)(lds + PG8_SB(b, h) + boff + n * 2048 + k * 1024); } while (0)
; #define PG8_MMA(ai, bj, At, Bt) do { __builtin_amdgcn_s_setprio(1); _Pragma("unroll") for (int m = 0; m < 4; ++m) _Pragma("unroll") for (int n = 0; n < 2; ++n) _Pragma("unroll") for (int k = 0; k < 2; ++k) \
;         acc[ai][bj][m][n] = __builtin_amdgcn_mfma_f32_16x16x32_bf16(Bt[n][k], At[m][k], acc[ai][bj][m][n], 0, 0, 0); __builtin_amdgcn_s_setprio(0); } while (0)
; #define PG8_WAIT_V(n) asm volatile("s_waitcnt vmcnt(" #n ")" ::: "memory")
; #define PG8_WAIT_L(n) asm volatile("s_waitcnt lgkmcnt(" #n ")" ::: "memory")
; #define PG8_BAR __builtin_amdgcn_s_barrier()
; #define PG8_SCHED __builtin_amdgcn_sched_barrier(0)
; template <class Epi, class Sched>
; __device__ __forceinline__ void gemm_phase(LAS unsigned char* lds, const Gemm g, const Sched& S, const Epi& E, int wv) {
;     ...
;             const char* a1 = cA + (size_t)(t + 1) * kstep;
;             const char* a2 = last ? nA : cA + (size_t)(t + 2) * kstep; const char* b2 = last ? nB : cB + (size_t)(t + 2) * kstep;
;             const char* a3 = a2 + kstep; const char* b3 = b2 + kstep;
;             PG8_LDB(B0, 0, 0); PG8_LDB(B1, 0, 1); PG8_SCHED; PG8_LDA(At, 0, 0); PG8_STAGE(PG8_SA(1, 1), a1 + hstepA, voffA);
;             PG8_WAIT_V(8); PG8_WAIT_L(0); PG8_BAR; PG8_MMA(0, 0, At, B0); PG8_MMA(0, 1, At, B1); PG8_BAR; PG8_SCHED;
.LBB0_201:
	s_add_u32 s0, s76, 0xfffc0080
	s_addc_u32 s1, s77, -1
	s_add_i32 s20, 0, 0x10000
	s_cmp_eq_u32 s56, 12
	s_cselect_b32 s81, s10, s1
	s_cselect_b32 s80, s11, s0
	v_add_u32_e32 v0, s20, v161
	s_cselect_b32 s79, s21, s35
	s_cselect_b32 s78, s31, s34
	s_add_i32 s26, 0, 0x14000
	ds_read_b128 v[142:145], v0
	ds_read_b128 v[146:149], v0 offset:1024
	ds_read_b128 v[150:153], v0 offset:2048
	ds_read_b128 v[154:157], v0 offset:3072
	v_add_u32_e32 v0, s26, v161
	ds_read_b128 v[162:165], v0
	ds_read_b128 v[166:169], v0 offset:1024
	ds_read_b128 v[170:173], v0 offset:2048
	ds_read_b128 v[176:179], v0 offset:3072
	v_lshl_add_u64 v[158:159], s[76:77], 0, v[138:139]
	s_add_i32 m0, s82, 0xc000
	ds_read_b128 v[180:183], v175
	ds_read_b128 v[184:187], v175 offset:1024
	ds_read_b128 v[188:191], v175 offset:2048
	ds_read_b128 v[196:199], v175 offset:3072
	ds_read_b128 v[200:203], v175 offset:4096
	ds_read_b128 v[204:207], v175 offset:5120
	ds_read_b128 v[208:211], v175 offset:6144
	ds_read_b128 v[212:215], v175 offset:7168
	global_load_lds_dwordx4 v[158:159], off
	v_lshl_add_u64 v[158:159], s[76:77], 0, v[140:141]
	s_add_i32 m0, s82, 0xe000
	s_nop 0
	global_load_lds_dwordx4 v[158:159], off
	s_waitcnt vmcnt(8)
	s_waitcnt lgkmcnt(0)
	s_barrier
	s_setprio 1
	v_mfma_f32_16x16x32_bf16 v[126:129], v[142:145], v[180:183], v[126:129]
	v_mfma_f32_16x16x32_bf16 v[122:125], v[150:153], v[180:183], v[122:125]
	v_mfma_f32_16x16x32_bf16 v[118:121], v[142:145], v[188:191], v[118:121]
	v_mfma_f32_16x16x32_bf16 v[114:117], v[150:153], v[188:191], v[114:117]
	v_mfma_f32_16x16x32_bf16 v[102:105], v[142:145], v[200:203], v[102:105]
	v_mfma_f32_16x16x32_bf16 v[98:101], v[150:153], v[200:203], v[98:101]
	v_mfma_f32_16x16x32_bf16 v[86:89], v[142:145], v[208:211], v[86:89]
	v_mfma_f32_16x16x32_bf16 v[82:85], v[150:153], v[208:211], v[82:85]
	v_mfma_f32_16x16x32_bf16 v[126:129], v[146:149], v[184:187], v[126:129]
	v_mfma_f32_16x16x32_bf16 v[122:125], v[154:157], v[184:187], v[122:125]
	v_mfma_f32_16x16x32_bf16 v[118:121], v[146:149], v[196:199], v[118:121]
	v_mfma_f32_16x16x32_bf16 v[114:117], v[154:157], v[196:199], v[114:117]
	v_mfma_f32_16x16x32_bf16 v[102:105], v[146:149], v[204:207], v[102:105]
	v_mfma_f32_16x16x32_bf16 v[98:101], v[154:157], v[204:207], v[98:101]
	v_mfma_f32_16x16x32_bf16 v[86:89], v[146:149], v[212:215], v[86:89]
	v_mfma_f32_16x16x32_bf16 v[82:85], v[154:157], v[212:215], v[82:85]
	v_mfma_f32_16x16x32_bf16 v[110:113], v[162:165], v[180:183], v[110:113]
	v_mfma_f32_16x16x32_bf16 v[106:109], v[170:173], v[180:183], v[106:109]
	v_mfma_f32_16x16x32_bf16 v[94:97], v[162:165], v[188:191], v[94:97]
	v_mfma_f32_16x16x32_bf16 v[90:93], v[170:173], v[188:191], v[90:93]
	v_mfma_f32_16x16x32_bf16 v[78:81], v[162:165], v[200:203], v[78:81]
	v_mfma_f32_16x16x32_bf16 v[74:77], v[170:173], v[200:203], v[74:77]
	v_mfma_f32_16x16x32_bf16 v[70:73], v[162:165], v[208:211], v[70:73]
	v_mfma_f32_16x16x32_bf16 v[66:69], v[170:173], v[208:211], v[66:69]
	v_mfma_f32_16x16x32_bf16 v[110:113], v[166:169], v[184:187], v[110:113]
	v_mfma_f32_16x16x32_bf16 v[106:109], v[176:179], v[184:187], v[106:109]
	v_mfma_f32_16x16x32_bf16 v[94:97], v[166:169], v[196:199], v[94:97]
	v_mfma_f32_16x16x32_bf16 v[90:93], v[176:179], v[196:199], v[90:93]
	v_mfma_f32_16x16x32_bf16 v[78:81], v[166:169], v[204:207], v[78:81]
	v_mfma_f32_16x16x32_bf16 v[74:77], v[176:179], v[204:207], v[74:77]
	v_mfma_f32_16x16x32_bf16 v[70:73], v[166:169], v[212:215], v[70:73]
	v_mfma_f32_16x16x32_bf16 v[66:69], v[176:179], v[212:215], v[66:69]
	s_setprio 0
	s_barrier
	s_add_i32 s0, s20, s60
	v_lshl_add_u64 v[158:159], s[78:79], 0, v[134:135]
	s_mov_b32 m0, s0
	ds_read_b128 v[180:183], v175 offset:16384
	ds_read_b128 v[184:187], v175 offset:17408
	ds_read_b128 v[188:191], v175 offset:18432
	ds_read_b128 v[196:199], v175 offset:19456
	ds_read_b128 v[200:203], v175 offset:20480
	ds_read_b128 v[204:207], v175 offset:21504
	ds_read_b128 v[208:211], v175 offset:22528
	ds_read_b128 v[212:215], v175 offset:23552
	global_load_lds_dwordx4 v[158:159], off
	s_add_i32 m0, s0, 0x2000
	s_add_u32 s0, s78, 0x40000
	v_lshl_add_u64 v[192:193], s[78:79], 0, v[130:131]
	s_addc_u32 s1, s79, 0
	s_add_i32 s20, s26, s60
	global_load_lds_dwordx4 v[192:193], off
	v_lshl_add_u64 v[216:217], s[0:1], 0, v[134:135]
	s_mov_b32 m0, s20
	v_lshl_add_u64 v[218:219], s[80:81], 0, v[132:133]
	global_load_lds_dwordx4 v[216:217], off
	v_lshl_add_u64 v[216:217], s[0:1], 0, v[130:131]
	s_add_i32 m0, s20, 0x2000
	s_nop 0
	global_load_lds_dwordx4 v[216:217], off
	v_lshl_add_u64 v[216:217], s[80:81], 0, v[136:137]
	s_mov_b32 m0, s82
	s_nop 0
	global_load_lds_dwordx4 v[216:217], off
	s_mov_b32 m0, s83
	s_nop 0
	global_load_lds_dwordx4 v[218:219], off
	s_waitcnt vmcnt(8)
	s_waitcnt lgkmcnt(0)
	s_barrier
; #define PG8_STAGE(bufoff, gbase, voff) do { _Pragma("unroll") for (int _i = 0; _i < 2; ++_i) \
;         __builtin_amdgcn_global_load_lds((const unsigned*)((const char*)(gbase) + (voff)[_i]), (LAS unsigned*)(lds + (bufoff) + ldsw + _i * 8192), 16, 0, 0); } while (0)
; #define PG8_LDA(dst, b, h) do { _Pragma("unroll") for (int m = 0; m < 4; ++m) _Pragma("unroll") for (int k = 0; k < 2; ++k) dst[m][k] = *(const LAS bf16x8*)(lds + PG8_SA(b, h) + aoff + m * 2048 + k * 1024); } while (0)
; #define PG8_LDB(dst, b, h) do { _Pragma("unroll") for (int n = 0; n < 2; ++n) _Pragma("unroll") for (int k = 0; k < 2; ++k) dst[n][k] = *(const LAS bf16x8*)(lds + PG8_SB(b, h) + boff + n * 2048 + k * 1024); } while (0)
; #define PG8_MMA(ai, bj, At, Bt) do { __builtin_amdgcn_s_setprio(1); _Pragma("unroll") for (int m = 0; m < 4; ++m) _Pragma("unroll") for (int n = 0; n < 2; ++n) _Pragma("unroll") for (int k = 0; k < 2; ++k) \
;         acc[ai][bj][m][n] = __builtin_amdgcn_mfma_f32_16x16x32_bf16(Bt[n][k], At[m][k], acc[ai][bj][m][n], 0, 0, 0); __builtin_amdgcn_s_setprio(0); } while (0)
; #define PG8_WAIT_V(n) asm volatile("s_waitcnt vmcnt(" #n ")" ::: "memory")
; #define PG8_WAIT_L(n) asm volatile("s_waitcnt lgkmcnt(" #n ")" ::: "memory")
; #define PG8_BAR __builtin_amdgcn_s_barrier()
; #define PG8_SCHED __builtin_amdgcn_sched_barrier(0)
; template <class Epi, class Sched>
; __device__ __forceinline__ void gemm_phase(LAS unsigned char* lds, const Gemm g, const Sched& S, const Epi& E, int wv) {
;     ...
;             PG8_WAIT_V(8); PG8_WAIT_L(0); PG8_BAR; PG8_MMA(0, 0, At, B0); PG8_MMA(0, 1, At, B1); PG8_BAR; PG8_SCHED;
;             PG8_LDA(At, 0, 1); PG8_STAGE(PG8_SB(0, 0), b2, voffB); PG8_STAGE(PG8_SB(0, 1), b2 + hstepB, voffB); PG8_STAGE(PG8_SA(0, 0), a2, voffA);
;             PG8_WAIT_V(8); PG8_WAIT_L(0); PG8_BAR; PG8_MMA(1, 0, At, B0); PG8_MMA(1, 1, At, B1); PG8_BAR; PG8_SCHED;
;             PG8_LDB(B0, 1, 0); PG8_LDB(B1, 1, 1); PG8_SCHED; PG8_LDA(At, 1, 0); PG8_STAGE(PG8_SA(0, 1), a2 + hstepA, voffA);
;             PG8_WAIT_V(8); PG8_WAIT_L(0); PG8_BAR; PG8_MMA(0, 0, At, B0); PG8_MMA(0, 1, At, B1); PG8_BAR; PG8_SCHED;
	s_setprio 1
	v_mfma_f32_16x16x32_bf16 v[62:65], v[142:145], v[180:183], v[62:65]
	v_mfma_f32_16x16x32_bf16 v[58:61], v[150:153], v[180:183], v[58:61]
	v_mfma_f32_16x16x32_bf16 v[54:57], v[142:145], v[188:191], v[54:57]
	v_mfma_f32_16x16x32_bf16 v[50:53], v[150:153], v[188:191], v[50:53]
	v_mfma_f32_16x16x32_bf16 v[38:41], v[142:145], v[200:203], v[38:41]
	v_mfma_f32_16x16x32_bf16 v[34:37], v[150:153], v[200:203], v[34:37]
	v_mfma_f32_16x16x32_bf16 v[22:25], v[142:145], v[208:211], v[22:25]
	v_mfma_f32_16x16x32_bf16 v[18:21], v[150:153], v[208:211], v[18:21]
	v_mfma_f32_16x16x32_bf16 v[62:65], v[146:149], v[184:187], v[62:65]
	v_mfma_f32_16x16x32_bf16 v[58:61], v[154:157], v[184:187], v[58:61]
	v_mfma_f32_16x16x32_bf16 v[54:57], v[146:149], v[196:199], v[54:57]
	v_mfma_f32_16x16x32_bf16 v[50:53], v[154:157], v[196:199], v[50:53]
	v_mfma_f32_16x16x32_bf16 v[38:41], v[146:149], v[204:207], v[38:41]
	v_mfma_f32_16x16x32_bf16 v[34:37], v[154:157], v[204:207], v[34:37]
	v_mfma_f32_16x16x32_bf16 v[22:25], v[146:149], v[212:215], v[22:25]
	v_mfma_f32_16x16x32_bf16 v[18:21], v[154:157], v[212:215], v[18:21]
	v_mfma_f32_16x16x32_bf16 v[46:49], v[162:165], v[180:183], v[46:49]
	v_mfma_f32_16x16x32_bf16 v[42:45], v[170:173], v[180:183], v[42:45]
	v_mfma_f32_16x16x32_bf16 v[30:33], v[162:165], v[188:191], v[30:33]
	v_mfma_f32_16x16x32_bf16 v[26:29], v[170:173], v[188:191], v[26:29]
	v_mfma_f32_16x16x32_bf16 v[14:17], v[162:165], v[200:203], v[14:17]
	v_mfma_f32_16x16x32_bf16 v[10:13], v[170:173], v[200:203], v[10:13]
	v_mfma_f32_16x16x32_bf16 v[6:9], v[162:165], v[208:211], v[6:9]
	v_mfma_f32_16x16x32_bf16 v[2:5], v[170:173], v[208:211], v[2:5]
	v_mfma_f32_16x16x32_bf16 v[46:49], v[166:169], v[184:187], v[46:49]
	v_mfma_f32_16x16x32_bf16 v[42:45], v[176:179], v[184:187], v[42:45]
	v_mfma_f32_16x16x32_bf16 v[30:33], v[166:169], v[196:199], v[30:33]
	v_mfma_f32_16x16x32_bf16 v[26:29], v[176:179], v[196:199], v[26:29]
	v_mfma_f32_16x16x32_bf16 v[14:17], v[166:169], v[204:207], v[14:17]
	v_mfma_f32_16x16x32_bf16 v[10:13], v[176:179], v[204:207], v[10:13]
	v_mfma_f32_16x16x32_bf16 v[6:9], v[166:169], v[212:215], v[6:9]
	v_mfma_f32_16x16x32_bf16 v[2:5], v[176:179], v[212:215], v[2:5]
	s_setprio 0
	s_barrier
	s_add_i32 s20, 0, 0x18000
	v_add_u32_e32 v0, s20, v161
	s_add_i32 s26, 0, 0x1c000
	ds_read_b128 v[142:145], v0
	ds_read_b128 v[146:149], v0 offset:1024
	ds_read_b128 v[150:153], v0 offset:2048
	ds_read_b128 v[154:157], v0 offset:3072
	v_add_u32_e32 v0, s26, v161
	ds_read_b128 v[162:165], v0
	ds_read_b128 v[166:169], v0 offset:1024
	ds_read_b128 v[170:173], v0 offset:2048
	ds_read_b128 v[176:179], v0 offset:3072
	s_add_u32 s0, s80, 0x40000
	s_addc_u32 s1, s81, 0
	s_mov_b32 m0, s84
	v_lshl_add_u64 v[220:221], s[0:1], 0, v[136:137]
	ds_read_b128 v[180:183], v175 offset:32768
	ds_read_b128 v[184:187], v175 offset:33792
	ds_read_b128 v[188:191], v175 offset:34816
	ds_read_b128 v[196:199], v175 offset:35840
	ds_read_b128 v[200:203], v175 offset:36864
	ds_read_b128 v[204:207], v175 offset:37888
	ds_read_b128 v[208:211], v175 offset:38912
	ds_read_b128 v[212:215], v175 offset:39936
	global_load_lds_dwordx4 v[220:221], off
	v_lshl_add_u64 v[220:221], s[0:1], 0, v[132:133]
	s_mov_b32 m0, s85
	s_nop 0
	global_load_lds_dwordx4 v[220:221], off
	s_waitcnt vmcnt(8)
	s_waitcnt lgkmcnt(0)
	s_barrier
	s_setprio 1
	v_mfma_f32_16x16x32_bf16 v[126:129], v[142:145], v[180:183], v[126:129]
	v_mfma_f32_16x16x32_bf16 v[122:125], v[150:153], v[180:183], v[122:125]
	v_mfma_f32_16x16x32_bf16 v[118:121], v[142:145], v[188:191], v[118:121]
	v_mfma_f32_16x16x32_bf16 v[114:117], v[150:153], v[188:191], v[114:117]
	v_mfma_f32_16x16x32_bf16 v[102:105], v[142:145], v[200:203], v[102:105]
	v_mfma_f32_16x16x32_bf16 v[98:101], v[150:153], v[200:203], v[98:101]
	v_mfma_f32_16x16x32_bf16 v[86:89], v[142:145], v[208:211], v[86:89]
	v_mfma_f32_16x16x32_bf16 v[82:85], v[150:153], v[208:211], v[82:85]
	v_mfma_f32_16x16x32_bf16 v[126:129], v[146:149], v[184:187], v[126:129]
	v_mfma_f32_16x16x32_bf16 v[122:125], v[154:157], v[184:187], v[122:125]
	v_mfma_f32_16x16x32_bf16 v[118:121], v[146:149], v[196:199], v[118:121]
	v_mfma_f32_16x16x32_bf16 v[114:117], v[154:157], v[196:199], v[114:117]
	v_mfma_f32_16x16x32_bf16 v[102:105], v[146:149], v[204:207], v[102:105]
	v_mfma_f32_16x16x32_bf16 v[98:101], v[154:157], v[204:207], v[98:101]
	v_mfma_f32_16x16x32_bf16 v[86:89], v[146:149], v[212:215], v[86:89]
	v_mfma_f32_16x16x32_bf16 v[82:85], v[154:157], v[212:215], v[82:85]
	v_mfma_f32_16x16x32_bf16 v[110:113], v[162:165], v[180:183], v[110:113]
	v_mfma_f32_16x16x32_bf16 v[106:109], v[170:173], v[180:183], v[106:109]
	v_mfma_f32_16x16x32_bf16 v[94:97], v[162:165], v[188:191], v[94:97]
	v_mfma_f32_16x16x32_bf16 v[90:93], v[170:173], v[188:191], v[90:93]
	v_mfma_f32_16x16x32_bf16 v[78:81], v[162:165], v[200:203], v[78:81]
	v_mfma_f32_16x16x32_bf16 v[74:77], v[170:173], v[200:203], v[74:77]
	v_mfma_f32_16x16x32_bf16 v[70:73], v[162:165], v[208:211], v[70:73]
	v_mfma_f32_16x16x32_bf16 v[66:69], v[170:173], v[208:211], v[66:69]
	v_mfma_f32_16x16x32_bf16 v[110:113], v[166:169], v[184:187], v[110:113]
	v_mfma_f32_16x16x32_bf16 v[106:109], v[176:179], v[184:187], v[106:109]
	v_mfma_f32_16x16x32_bf16 v[94:97], v[166:169], v[196:199], v[94:97]
	v_mfma_f32_16x16x32_bf16 v[90:93], v[176:179], v[196:199], v[90:93]
	v_mfma_f32_16x16x32_bf16 v[78:81], v[166:169], v[204:207], v[78:81]
	v_mfma_f32_16x16x32_bf16 v[74:77], v[176:179], v[204:207], v[74:77]
	v_mfma_f32_16x16x32_bf16 v[70:73], v[166:169], v[212:215], v[70:73]
	v_mfma_f32_16x16x32_bf16 v[66:69], v[176:179], v[212:215], v[66:69]
	s_setprio 0
	s_barrier
; __device__ __forceinline__ int ltid(int wv) { unsigned z = 0u; asm volatile("" : "+v"(z)); return wv * 64 + (int)__builtin_amdgcn_mbcnt_hi(~0u, __builtin_amdgcn_mbcnt_lo(~0u, z)); }
; #define EPI_LOOP_ROWS for (int ai = 0; ai < 2; ++ai) _Pragma("unroll") for (int m = 0; m < 4; ++m)
; __device__ __forceinline__ float row_part(const float* RS, int row, int fq) { const f32x4 a = ((const f32x4*)(RS + (size_t)row * 16))[fq]; return (a.x + a.y) + (a.z + a.w); }
; #define PG8_STAGE(bufoff, gbase, voff) do { _Pragma("unroll") for (int _i = 0; _i < 2; ++_i) \
;         __builtin_amdgcn_global_load_lds((const unsigned*)((const char*)(gbase) + (voff)[_i]), (LAS unsigned*)(lds + (bufoff) + ldsw + _i * 8192), 16, 0, 0); } while (0)
; #define PG8_LDA(dst, b, h) do { _Pragma("unroll") for (int m = 0; m < 4; ++m) _Pragma("unroll") for (int k = 0; k < 2; ++k) dst[m][k] = *(const LAS bf16x8*)(lds + PG8_SA(b, h) + aoff + m * 2048 + k * 1024); } while (0)
; #define PG8_WAIT_V(n) asm volatile("s_waitcnt vmcnt(" #n ")" ::: "memory")
; #define PG8_WAIT_L(n) asm volatile("s_waitcnt lgkmcnt(" #n ")" ::: "memory")
; #define PG8_BAR __builtin_amdgcn_s_barrier()
; #define PG8_SCHED __builtin_amdgcn_sched_barrier(0)
;     __device__ __forceinline__ void operator()(const f32x4 (&acc)[2][2][4][2], const Unit& u, int wv) const {
;         const int t_ = ltid(wv), wid_ = __builtin_amdgcn_readfirstlane(t_ >> 6), wr = wid_ >> 2, wc = wid_ & 3, fr = t_ & 15, fq = (t_ & 63) >> 4;
;         const bool gate = u.pn >= split_pn;
;         bf16_t* base = gate ? O1 : O0;
;         const int col0 = (gate ? (u.pn - split_pn) : u.pn) * BM + wc * 32 + 8 * fq;
;         const int row0 = u.pm * BM + wr * 64 + fr;
;         float rs[2][4];
; #pragma unroll
;         EPI_LOOP_ROWS rs[ai][m] = RS ? row_part(RS, row0 + ai * HALF + m * 16, fq) : 0.f;
; template <class Epi, class Sched>
; __device__ __forceinline__ void gemm_phase(LAS unsigned char* lds, const Gemm g, const Sched& S, const Epi& E, int wv) {
;     ...
;             PG8_LDA(At, 1, 1); PG8_STAGE(PG8_SB(1, 0), b3, voffB); PG8_STAGE(PG8_SB(1, 1), b3 + hstepB, voffB); PG8_STAGE(PG8_SA(1, 0), a3, voffA);
;             PG8_WAIT_V(8); PG8_WAIT_L(0); PG8_BAR; PG8_MMA(1, 0, At, B0); PG8_MMA(1, 1, At, B1); PG8_BAR; PG8_SCHED;
;         }
;         if (wr == 0) PG8_BAR;
;         E(acc, cur, wv);
	s_add_i32 s0, s20, s60
	v_lshl_add_u64 v[158:159], v[158:159], 0, s[24:25]
	s_mov_b32 m0, s0
	ds_read_b128 v[180:183], v175 offset:49152
	ds_read_b128 v[184:187], v175 offset:50176
	ds_read_b128 v[188:191], v175 offset:51200
	ds_read_b128 v[196:199], v175 offset:52224
	ds_read_b128 v[200:203], v175 offset:53248
	ds_read_b128 v[204:207], v175 offset:54272
	ds_read_b128 v[208:211], v175 offset:55296
	ds_read_b128 v[212:215], v175 offset:56320
	global_load_lds_dwordx4 v[158:159], off
	s_add_i32 m0, s0, 0x2000
	s_add_u32 s0, s78, 0x40080
	v_lshl_add_u64 v[158:159], v[192:193], 0, s[24:25]
	s_addc_u32 s1, s79, 0
	s_add_i32 s20, s26, s60
	global_load_lds_dwordx4 v[158:159], off
	v_lshl_add_u64 v[158:159], s[0:1], 0, v[134:135]
	s_mov_b32 m0, s20
	s_nop 0
	global_load_lds_dwordx4 v[158:159], off
	v_lshl_add_u64 v[158:159], s[0:1], 0, v[130:131]
	s_add_i32 m0, s20, 0x2000
	s_nop 0
	global_load_lds_dwordx4 v[158:159], off
	v_lshl_add_u64 v[158:159], v[216:217], 0, s[24:25]
	s_mov_b32 m0, s86
	s_nop 0
	global_load_lds_dwordx4 v[158:159], off
	v_lshl_add_u64 v[158:159], v[218:219], 0, s[24:25]
	s_mov_b32 m0, s87
	s_nop 0
	global_load_lds_dwordx4 v[158:159], off
	s_waitcnt vmcnt(8)
	s_waitcnt lgkmcnt(0)
	s_barrier
	s_setprio 1
	v_mfma_f32_16x16x32_bf16 v[62:65], v[142:145], v[180:183], v[62:65]
	v_mfma_f32_16x16x32_bf16 v[58:61], v[150:153], v[180:183], v[58:61]
	v_mfma_f32_16x16x32_bf16 v[54:57], v[142:145], v[188:191], v[54:57]
	v_mfma_f32_16x16x32_bf16 v[50:53], v[150:153], v[188:191], v[50:53]
	v_mfma_f32_16x16x32_bf16 v[38:41], v[142:145], v[200:203], v[38:41]
	v_mfma_f32_16x16x32_bf16 v[34:37], v[150:153], v[200:203], v[34:37]
	v_mfma_f32_16x16x32_bf16 v[22:25], v[142:145], v[208:211], v[22:25]
	v_mfma_f32_16x16x32_bf16 v[18:21], v[150:153], v[208:211], v[18:21]
	v_mfma_f32_16x16x32_bf16 v[62:65], v[146:149], v[184:187], v[62:65]
	v_mfma_f32_16x16x32_bf16 v[58:61], v[154:157], v[184:187], v[58:61]
	v_mfma_f32_16x16x32_bf16 v[54:57], v[146:149], v[196:199], v[54:57]
	v_mfma_f32_16x16x32_bf16 v[50:53], v[154:157], v[196:199], v[50:53]
	v_mfma_f32_16x16x32_bf16 v[38:41], v[146:149], v[204:207], v[38:41]
	v_mfma_f32_16x16x32_bf16 v[34:37], v[154:157], v[204:207], v[34:37]
	v_mfma_f32_16x16x32_bf16 v[22:25], v[146:149], v[212:215], v[22:25]
	v_mfma_f32_16x16x32_bf16 v[18:21], v[154:157], v[212:215], v[18:21]
	v_mfma_f32_16x16x32_bf16 v[46:49], v[162:165], v[180:183], v[46:49]
	v_mfma_f32_16x16x32_bf16 v[42:45], v[170:173], v[180:183], v[42:45]
	v_mfma_f32_16x16x32_bf16 v[30:33], v[162:165], v[188:191], v[30:33]
	v_mfma_f32_16x16x32_bf16 v[26:29], v[170:173], v[188:191], v[26:29]
	v_mfma_f32_16x16x32_bf16 v[14:17], v[162:165], v[200:203], v[14:17]
	v_mfma_f32_16x16x32_bf16 v[10:13], v[170:173], v[200:203], v[10:13]
	v_mfma_f32_16x16x32_bf16 v[6:9], v[162:165], v[208:211], v[6:9]
	v_mfma_f32_16x16x32_bf16 v[2:5], v[170:173], v[208:211], v[2:5]
	v_mfma_f32_16x16x32_bf16 v[46:49], v[166:169], v[184:187], v[46:49]
	v_mfma_f32_16x16x32_bf16 v[42:45], v[176:179], v[184:187], v[42:45]
	v_mfma_f32_16x16x32_bf16 v[30:33], v[166:169], v[196:199], v[30:33]
	v_mfma_f32_16x16x32_bf16 v[26:29], v[176:179], v[196:199], v[26:29]
	v_mfma_f32_16x16x32_bf16 v[14:17], v[166:169], v[204:207], v[14:17]
	v_mfma_f32_16x16x32_bf16 v[10:13], v[176:179], v[204:207], v[10:13]
	v_mfma_f32_16x16x32_bf16 v[6:9], v[166:169], v[212:215], v[6:9]
	v_mfma_f32_16x16x32_bf16 v[2:5], v[176:179], v[212:215], v[2:5]
	s_setprio 0
	s_barrier
	s_add_i32 s56, s56, 2
	s_add_u32 s76, s76, 0x100
	s_addc_u32 s77, s77, 0
	s_add_u32 s34, s34, 0x100
	s_addc_u32 s35, s35, 0
	s_cmp_gt_u32 s56, 13
	s_cbranch_scc0 .LBB0_201
	s_and_b64 vcc, exec, s[66:67]
	s_cbranch_vccz .LBB0_204
	s_barrier
.LBB0_204:
	v_mov_b32_e32 v0, v1
	s_nop 0
	v_mbcnt_lo_u32_b32 v0, -1, v0
	v_mbcnt_hi_u32_b32 v0, -1, v0
	v_add_u32_e32 v142, s33, v0
	v_and_b32_e32 v160, 63, v0
	v_readfirstlane_b32 s0, v142
	s_lshr_b32 s1, s0, 1
	s_ashr_i32 s0, s0, 2
	s_and_b32 s10, s1, 0x60
	s_lshl_b32 s1, s4, 8
	s_andn2_b32 s0, s0, 63
	s_add_i32 s0, s0, s1
	v_and_or_b32 v158, v0, 15, s0
	v_lshrrev_b32_e32 v176, 1, v0
	v_and_b32_e32 v0, 48, v0
	v_ashrrev_i32_e32 v159, 31, v158
	v_lshl_add_u64 v[162:163], s[64:65], 0, v[0:1]
	v_lshlrev_b64 v[188:189], 6, v[158:159]
	v_lshl_add_u64 v[188:189], v[162:163], 0, v[188:189]
	global_load_dwordx4 v[196:199], v[188:189], off
	v_or_b32_e32 v154, 16, v158
	v_ashrrev_i32_e32 v155, 31, v154
	v_lshlrev_b64 v[188:189], 6, v[154:155]
	v_lshl_add_u64 v[188:189], v[162:163], 0, v[188:189]
	global_load_dwordx4 v[200:203], v[188:189], off
	v_or_b32_e32 v152, 32, v158
	v_ashrrev_i32_e32 v153, 31, v152
	v_lshlrev_b64 v[188:189], 6, v[152:153]
	v_lshl_add_u64 v[188:189], v[162:163], 0, v[188:189]
	global_load_dwordx4 v[204:207], v[188:189], off
	v_or_b32_e32 v150, 48, v158
	v_ashrrev_i32_e32 v151, 31, v150
	v_lshlrev_b64 v[188:189], 6, v[150:151]
	v_lshl_add_u64 v[188:189], v[162:163], 0, v[188:189]
	global_load_dwordx4 v[208:211], v[188:189], off
	v_add_u32_e32 v148, 0x80, v158
	v_ashrrev_i32_e32 v149, 31, v148
	v_lshlrev_b64 v[188:189], 6, v[148:149]
	v_lshl_add_u64 v[188:189], v[162:163], 0, v[188:189]
	global_load_dwordx4 v[212:215], v[188:189], off
	v_add_u32_e32 v146, 0x90, v158
	v_ashrrev_i32_e32 v147, 31, v146
	v_lshlrev_b64 v[188:189], 6, v[146:147]
	v_lshl_add_u64 v[188:189], v[162:163], 0, v[188:189]
	global_load_dwordx4 v[216:219], v[188:189], off
	v_add_u32_e32 v144, 0xa0, v158
	v_ashrrev_i32_e32 v145, 31, v144
	v_lshlrev_b64 v[188:189], 6, v[144:145]
	v_lshl_add_u64 v[188:189], v[162:163], 0, v[188:189]
	global_load_dwordx4 v[220:223], v[188:189], off
	v_add_u32_e32 v142, 0xb0, v158
	v_ashrrev_i32_e32 v143, 31, v142
	v_lshlrev_b64 v[188:189], 6, v[142:143]
	v_lshl_add_u64 v[188:189], v[162:163], 0, v[188:189]
	global_load_dwordx4 v[224:227], v[188:189], off
	v_lshlrev_b32_e32 v0, 2, v160
	s_lshl_b32 s0, s5, 8
	s_or_b32 s10, s10, s0
	s_mov_b32 s0, 0x358637bd
	s_waitcnt vmcnt(0)
; __device__ __forceinline__ float shx(float v, int o, int lane) { return __builtin_bit_cast(float, __builtin_amdgcn_ds_bpermute((lane ^ o) << 2, __builtin_bit_cast(int, v))); }
; __device__ __forceinline__ int ltid(int wv) { unsigned z = 0u; asm volatile("" : "+v"(z)); return wv * 64 + (int)__builtin_amdgcn_mbcnt_hi(~0u, __builtin_amdgcn_mbcnt_lo(~0u, z)); }
; #define EPI_LOOP_ROWS for (int ai = 0; ai < 2; ++ai) _Pragma("unroll") for (int m = 0; m < 4; ++m)
; __device__ __forceinline__ float row_part(const float* RS, int row, int fq) { const f32x4 a = ((const f32x4*)(RS + (size_t)row * 16))[fq]; return (a.x + a.y) + (a.z + a.w); }
; __device__ __forceinline__ float row_rstd_fin(float s, int lane) { s += shx(s, 16, lane); s += shx(s, 32, lane); return rsqrtf(s * (1.0f / 1024.0f) + EPS); }
;     __device__ __forceinline__ void operator()(const f32x4 (&acc)[2][2][4][2], const Unit& u, int wv) const {
;         const int t_ = ltid(wv), wid_ = __builtin_amdgcn_readfirstlane(t_ >> 6), wr = wid_ >> 2, wc = wid_ & 3, fr = t_ & 15, fq = (t_ & 63) >> 4;
;         const bool gate = u.pn >= split_pn;
;         bf16_t* base = gate ? O1 : O0;
;         const int col0 = (gate ? (u.pn - split_pn) : u.pn) * BM + wc * 32 + 8 * fq;
;         const int row0 = u.pm * BM + wr * 64 + fr;
;         float rs[2][4];
; #pragma unroll
;         EPI_LOOP_ROWS rs[ai][m] = RS ? row_part(RS, row0 + ai * HALF + m * 16, fq) : 0.f;
; #pragma unroll
;         EPI_LOOP_ROWS rs[ai][m] = RS ? row_rstd_fin(rs[ai][m], t_ & 63) : 1.0f;
	v_add_f32_e32 v156, v197, v196
	v_add_f32_e32 v157, v198, v199
	v_add_f32_e32 v182, v201, v200
	v_add_f32_e32 v183, v202, v203
	v_add_f32_e32 v184, v205, v204
	v_add_f32_e32 v185, v206, v207
	v_add_f32_e32 v170, v209, v208
	v_add_f32_e32 v171, v210, v211
	v_add_f32_e32 v172, v213, v212
	v_add_f32_e32 v173, v214, v215
	v_add_f32_e32 v164, v217, v216
	v_add_f32_e32 v165, v218, v219
	v_xor_b32_e32 v145, 64, v0
	v_add_f32_e32 v168, v221, v220
	v_add_f32_e32 v169, v222, v223
	v_mov_b32_e32 v166, v184
	v_mov_b32_e32 v167, v182
	v_mov_b32_e32 v182, v185
	v_pk_add_f32 v[166:167], v[166:167], v[182:183]
	v_xor_b32_e32 v143, 0x80, v0
	v_add_f32_e32 v162, v225, v224
	v_add_f32_e32 v163, v226, v227
	ds_bpermute_b32 v179, v145, v167
	ds_bpermute_b32 v178, v145, v166
	v_mov_b32_e32 v177, v162
	v_mov_b32_e32 v162, v157
	s_waitcnt lgkmcnt(0)
	v_pk_add_f32 v[166:167], v[166:167], v[178:179]
	ds_bpermute_b32 v179, v143, v167
	ds_bpermute_b32 v178, v143, v166
	s_waitcnt lgkmcnt(0)
	v_pk_add_f32 v[178:179], v[166:167], v[178:179]
	v_mov_b64_e32 v[166:167], s[0:1]
	v_pk_fma_f32 v[178:179], v[178:179], s[92:93], v[166:167] op_sel_hi:[1,0,0]
	s_nop 0
	v_mul_f32_e32 v0, 0x4b800000, v179
	v_cmp_gt_f32_e64 s[4:5], s97, v179
	v_cmp_gt_f32_e32 vcc, s97, v178
	s_nop 0
	v_cndmask_b32_e64 v0, v179, v0, s[4:5]
	v_rsq_f32_e32 v0, v0
	v_mov_b32_e32 v179, v170
	v_mov_b32_e32 v170, v173
	v_mul_f32_e32 v147, 0x45800000, v0
	v_cndmask_b32_e64 v160, v0, v147, s[4:5]
	v_mul_f32_e32 v0, 0x4b800000, v178
	v_cndmask_b32_e32 v0, v178, v0, vcc
	v_mov_b32_e32 v178, v172
	v_pk_add_f32 v[170:171], v[178:179], v[170:171]
	ds_bpermute_b32 v173, v145, v171
	ds_bpermute_b32 v172, v145, v170
	v_rsq_f32_e32 v0, v0
	v_mov_b32_e32 v178, v168
	v_mov_b32_e32 v179, v164
	v_mov_b32_e32 v164, v169
	s_waitcnt lgkmcnt(0)
	v_pk_add_f32 v[170:171], v[170:171], v[172:173]
	ds_bpermute_b32 v173, v143, v171
	ds_bpermute_b32 v172, v143, v170
	v_mul_f32_e32 v147, 0x45800000, v0
	v_cndmask_b32_e32 v0, v0, v147, vcc
	v_pk_add_f32 v[164:165], v[178:179], v[164:165]
	ds_bpermute_b32 v169, v145, v165
	s_waitcnt lgkmcnt(1)
	v_pk_add_f32 v[170:171], v[170:171], v[172:173]
	ds_bpermute_b32 v168, v145, v164
	v_pk_fma_f32 v[170:171], v[170:171], s[92:93], v[166:167] op_sel_hi:[1,0,0]
	v_pk_mul_f32 v[96:97], v[96:97], v[160:161] op_sel_hi:[1,0]
	v_mul_f32_e32 v147, 0x4b800000, v171
	v_cmp_gt_f32_e64 s[4:5], s97, v171
	s_waitcnt lgkmcnt(0)
	v_pk_add_f32 v[164:165], v[164:165], v[168:169]
	v_cmp_gt_f32_e32 vcc, s97, v170
	v_cndmask_b32_e64 v147, v171, v147, s[4:5]
	v_rsq_f32_e32 v147, v147
	ds_bpermute_b32 v169, v143, v165
	ds_bpermute_b32 v168, v143, v164
	v_pk_mul_f32 v[80:81], v[80:81], v[0:1] op_sel_hi:[1,0]
	v_mul_f32_e32 v149, 0x45800000, v147
	v_cndmask_b32_e64 v172, v147, v149, s[4:5]
	v_mul_f32_e32 v147, 0x4b800000, v170
	v_cndmask_b32_e32 v147, v170, v147, vcc
	v_rsq_f32_e32 v147, v147
	s_waitcnt lgkmcnt(0)
	v_pk_add_f32 v[164:165], v[164:165], v[168:169]
	v_pk_mul_f32 v[72:73], v[72:73], v[172:173] op_sel_hi:[1,0]
	v_pk_fma_f32 v[164:165], v[164:165], s[92:93], v[166:167] op_sel_hi:[1,0,0]
	v_mul_f32_e32 v149, 0x45800000, v147
	v_cndmask_b32_e32 v170, v147, v149, vcc
	v_mul_f32_e32 v147, 0x4b800000, v165
	v_cmp_gt_f32_e64 s[4:5], s97, v165
	v_cmp_gt_f32_e32 vcc, s97, v164
	v_pk_mul_f32 v[64:65], v[64:65], v[170:171] op_sel_hi:[1,0]
	v_cndmask_b32_e64 v147, v165, v147, s[4:5]
	v_rsq_f32_e32 v147, v147
	v_pk_mul_f32 v[48:49], v[48:49], v[170:171] op_sel_hi:[1,0]
	v_mul_f32_e32 v149, 0x45800000, v147
	v_cndmask_b32_e64 v174, v147, v149, s[4:5]
	v_mul_f32_e32 v147, 0x4b800000, v164
	v_cndmask_b32_e32 v147, v164, v147, vcc
	v_and_or_b32 v164, v176, 24, s10
	v_mov_b32_e32 v176, v156
	v_pk_add_f32 v[156:157], v[176:177], v[162:163]
	ds_bpermute_b32 v162, v145, v156
	ds_bpermute_b32 v163, v145, v157
	v_rsq_f32_e32 v147, v147
	v_ashrrev_i32_e32 v165, 31, v164
	v_lshl_add_u64 v[164:165], v[164:165], 1, s[12:13]
	v_mad_i64_i32 v[158:159], s[0:1], v158, s95, v[164:165]
	s_waitcnt lgkmcnt(0)
	v_pk_add_f32 v[156:157], v[156:157], v[162:163]
	ds_bpermute_b32 v162, v143, v156
	ds_bpermute_b32 v163, v143, v157
	v_mul_f32_e32 v149, 0x45800000, v147
	v_cndmask_b32_e32 v168, v147, v149, vcc
	v_pk_mul_f32 v[32:33], v[32:33], v[174:175] op_sel_hi:[1,0]
	v_pk_mul_f32 v[16:17], v[16:17], v[168:169] op_sel_hi:[1,0]
	s_waitcnt lgkmcnt(0)
; __device__ __forceinline__ unsigned cvtpk(float lo, float hi) { f32x2 v = {lo, hi}; bf16x2_t b = __builtin_convertvector(v, bf16x2_t); return __builtin_bit_cast(unsigned, b); }
; __device__ __forceinline__ float sigmoidf_(float v) { return __builtin_amdgcn_rcpf(1.0f + __expf(-v)); }
; __device__ __forceinline__ void st16_wt(void* p, u32x4 v) { asm volatile("global_store_dwordx4 %0, %1, off sc1\n\ts_nop 2" :: "v"(p), "v"(v) : "memory"); }
; #define EPI_LOOP_ROWS for (int ai = 0; ai < 2; ++ai) _Pragma("unroll") for (int m = 0; m < 4; ++m)
;     __device__ __forceinline__ void operator()(const f32x4 (&acc)[2][2][4][2], const Unit& u, int wv) const {
;     ...
;         EPI_LOOP_ROWS { bf16_t* rowp = base + (size_t)(row0 + ai * HALF + m * 16) * ldc + col0;
;             const float rstd = rs[ai][m];
;             float ssm = 0.f;
; #pragma unroll
;             for (int bj = 0; bj < 2; ++bj) { f32x4 v0 = acc[ai][bj][m][0] * rstd, v1 = acc[ai][bj][m][1] * rstd;
;                 if (RSM && (u.pn == 0 || (u.pn == 1 && bj == 0))) ssm += ((v0[0] * v0[0] + v0[1] * v0[1]) + (v0[2] * v0[2] + v0[3] * v0[3])) + ((v1[0] * v1[0] + v1[1] * v1[1]) + (v1[2] * v1[2] + v1[3] * v1[3]));
;                 if (gate) {
; #pragma unroll
;                     for (int e = 0; e < 4; ++e) { v0[e] = sigmoidf_(v0[e]); v1[e] = sigmoidf_(v1[e]); } }
;                 u32x4 w; w.x = cvtpk(v0[0], v0[1]); w.y = cvtpk(v0[2], v0[3]); w.z = cvtpk(v1[0], v1[1]); w.w = cvtpk(v1[2], v1[3]);
;                 st16_wt(rowp + bj * HALF, w); }
	v_pk_add_f32 v[156:157], v[156:157], v[162:163]
	s_nop 0
	v_pk_fma_f32 v[162:163], v[156:157], s[92:93], v[166:167] op_sel_hi:[1,0,0]
	s_nop 0
	v_mul_f32_e32 v143, 0x4b800000, v163
	v_cmp_gt_f32_e64 s[4:5], s97, v163
	v_cmp_gt_f32_e32 vcc, s97, v162
	s_nop 0
	v_cndmask_b32_e64 v143, v163, v143, s[4:5]
	v_rsq_f32_e32 v143, v143
	s_nop 0
	v_mul_f32_e32 v145, 0x45800000, v143
	v_cndmask_b32_e64 v156, v143, v145, s[4:5]
	v_mul_f32_e32 v143, 0x4b800000, v162
	v_cndmask_b32_e32 v143, v162, v143, vcc
	v_rsq_f32_e32 v143, v143
	s_mov_b64 s[4:5], 0x100
	v_pk_mul_f32 v[8:9], v[8:9], v[156:157] op_sel_hi:[1,0]
	v_mul_f32_e32 v145, 0x45800000, v143
	v_cndmask_b32_e32 v162, v143, v145, vcc
	v_pk_mul_f32 v[166:167], v[124:125], v[162:163] op_sel_hi:[1,0]
	v_pk_mul_f32 v[124:125], v[122:123], v[162:163] op_sel_hi:[1,0]
	v_pk_mul_f32 v[128:129], v[128:129], v[162:163] op_sel_hi:[1,0]
	v_pk_mul_f32 v[122:123], v[126:127], v[162:163] op_sel_hi:[1,0]
	v_cvt_pk_bf16_f32 v124, v124, v125
	v_cvt_pk_bf16_f32 v122, v122, v123
	v_cvt_pk_bf16_f32 v123, v128, v129
	v_cvt_pk_bf16_f32 v125, v166, v167
	global_store_dwordx4 v[158:159], v[122:125], off sc1
	s_nop 2
	v_pk_mul_f32 v[122:123], v[108:109], v[162:163] op_sel_hi:[1,0]
	v_pk_mul_f32 v[108:109], v[106:107], v[162:163] op_sel_hi:[1,0]
	v_pk_mul_f32 v[112:113], v[112:113], v[162:163] op_sel_hi:[1,0]
	v_pk_mul_f32 v[106:107], v[110:111], v[162:163] op_sel_hi:[1,0]
	v_cvt_pk_bf16_f32 v108, v108, v109
	v_cvt_pk_bf16_f32 v106, v106, v107
	v_cvt_pk_bf16_f32 v107, v112, v113
	v_cvt_pk_bf16_f32 v109, v122, v123
	v_lshl_add_u64 v[110:111], v[158:159], 0, s[4:5]
	global_store_dwordx4 v[110:111], v[106:109], off sc1
	s_nop 2
	v_pk_mul_f32 v[108:109], v[114:115], v[160:161] op_sel_hi:[1,0]
	v_pk_mul_f32 v[114:115], v[120:121], v[160:161] op_sel_hi:[1,0]
	v_pk_mul_f32 v[106:107], v[118:119], v[160:161] op_sel_hi:[1,0]
	v_pk_mul_f32 v[112:113], v[116:117], v[160:161] op_sel_hi:[1,0]
	v_cvt_pk_bf16_f32 v106, v106, v107
	v_cvt_pk_bf16_f32 v107, v114, v115
	v_mad_i64_i32 v[110:111], s[0:1], v154, s95, v[164:165]
	v_cvt_pk_bf16_f32 v108, v108, v109
	v_cvt_pk_bf16_f32 v109, v112, v113
	global_store_dwordx4 v[110:111], v[106:109], off sc1
	s_nop 2
	v_pk_mul_f32 v[106:107], v[92:93], v[160:161] op_sel_hi:[1,0]
	v_pk_mul_f32 v[92:93], v[90:91], v[160:161] op_sel_hi:[1,0]
	v_pk_mul_f32 v[90:91], v[94:95], v[160:161] op_sel_hi:[1,0]
	v_cvt_pk_bf16_f32 v92, v92, v93
	v_cvt_pk_bf16_f32 v90, v90, v91
	v_cvt_pk_bf16_f32 v91, v96, v97
	v_cvt_pk_bf16_f32 v93, v106, v107
	v_lshl_add_u64 v[94:95], v[110:111], 0, s[4:5]
	global_store_dwordx4 v[94:95], v[90:93], off sc1
	s_nop 2
	v_pk_mul_f32 v[92:93], v[98:99], v[0:1] op_sel_hi:[1,0]
	v_pk_mul_f32 v[98:99], v[104:105], v[0:1] op_sel_hi:[1,0]
	v_pk_mul_f32 v[90:91], v[102:103], v[0:1] op_sel_hi:[1,0]
	v_pk_mul_f32 v[96:97], v[100:101], v[0:1] op_sel_hi:[1,0]
	v_cvt_pk_bf16_f32 v90, v90, v91
	v_cvt_pk_bf16_f32 v91, v98, v99
	v_mad_i64_i32 v[94:95], s[0:1], v152, s95, v[164:165]
	v_cvt_pk_bf16_f32 v92, v92, v93
	v_cvt_pk_bf16_f32 v93, v96, v97
	global_store_dwordx4 v[94:95], v[90:93], off sc1
	s_nop 2
	v_pk_mul_f32 v[90:91], v[76:77], v[0:1] op_sel_hi:[1,0]
	v_pk_mul_f32 v[76:77], v[74:75], v[0:1] op_sel_hi:[1,0]
	v_pk_mul_f32 v[74:75], v[78:79], v[0:1] op_sel_hi:[1,0]
	v_cvt_pk_bf16_f32 v76, v76, v77
	v_cvt_pk_bf16_f32 v74, v74, v75
	v_cvt_pk_bf16_f32 v75, v80, v81
	v_cvt_pk_bf16_f32 v77, v90, v91
	v_lshl_add_u64 v[78:79], v[94:95], 0, s[4:5]
	global_store_dwordx4 v[78:79], v[74:77], off sc1
	s_nop 2
	v_pk_mul_f32 v[76:77], v[82:83], v[172:173] op_sel_hi:[1,0]
	v_pk_mul_f32 v[82:83], v[88:89], v[172:173] op_sel_hi:[1,0]
	v_pk_mul_f32 v[74:75], v[86:87], v[172:173] op_sel_hi:[1,0]
	v_pk_mul_f32 v[80:81], v[84:85], v[172:173] op_sel_hi:[1,0]
	v_cvt_pk_bf16_f32 v74, v74, v75
	v_cvt_pk_bf16_f32 v75, v82, v83
	v_mad_i64_i32 v[78:79], s[0:1], v150, s95, v[164:165]
	v_cvt_pk_bf16_f32 v76, v76, v77
	v_cvt_pk_bf16_f32 v77, v80, v81
	global_store_dwordx4 v[78:79], v[74:77], off sc1
	s_nop 2
	v_pk_mul_f32 v[74:75], v[68:69], v[172:173] op_sel_hi:[1,0]
; __device__ __forceinline__ unsigned cvtpk(float lo, float hi) { f32x2 v = {lo, hi}; bf16x2_t b = __builtin_convertvector(v, bf16x2_t); return __builtin_bit_cast(unsigned, b); }
; __device__ __forceinline__ float sigmoidf_(float v) { return __builtin_amdgcn_rcpf(1.0f + __expf(-v)); }
; __device__ __forceinline__ void st16_wt(void* p, u32x4 v) { asm volatile("global_store_dwordx4 %0, %1, off sc1\n\ts_nop 2" :: "v"(p), "v"(v) : "memory"); }
; #define EPI_LOOP_ROWS for (int ai = 0; ai < 2; ++ai) _Pragma("unroll") for (int m = 0; m < 4; ++m)
; #define PG8_BAR __builtin_amdgcn_s_barrier()
;     __device__ __forceinline__ void operator()(const f32x4 (&acc)[2][2][4][2], const Unit& u, int wv) const {
;     ...
;         EPI_LOOP_ROWS { bf16_t* rowp = base + (size_t)(row0 + ai * HALF + m * 16) * ldc + col0;
;             const float rstd = rs[ai][m];
;             float ssm = 0.f;
; #pragma unroll
;             for (int bj = 0; bj < 2; ++bj) { f32x4 v0 = acc[ai][bj][m][0] * rstd, v1 = acc[ai][bj][m][1] * rstd;
;                 if (RSM && (u.pn == 0 || (u.pn == 1 && bj == 0))) ssm += ((v0[0] * v0[0] + v0[1] * v0[1]) + (v0[2] * v0[2] + v0[3] * v0[3])) + ((v1[0] * v1[0] + v1[1] * v1[1]) + (v1[2] * v1[2] + v1[3] * v1[3]));
;                 if (gate) {
; #pragma unroll
;                     for (int e = 0; e < 4; ++e) { v0[e] = sigmoidf_(v0[e]); v1[e] = sigmoidf_(v1[e]); } }
;                 u32x4 w; w.x = cvtpk(v0[0], v0[1]); w.y = cvtpk(v0[2], v0[3]); w.z = cvtpk(v1[0], v1[1]); w.w = cvtpk(v1[2], v1[3]);
;                 st16_wt(rowp + bj * HALF, w); }
; template <class Epi, class Sched>
; __device__ __forceinline__ void gemm_phase(LAS unsigned char* lds, const Gemm g, const Sched& S, const Epi& E, int wv) {
;     ...
;         if (!has_next) break;
; #pragma unroll
;         for (int a = 0; a < 2; ++a)
; #pragma unroll
;             for (int b = 0; b < 2; ++b)
; #pragma unroll
;                 for (int m = 0; m < 4; ++m)
; #pragma unroll
;                     for (int n = 0; n < 2; ++n) acc[a][b][m][n] = (f32x4){0.f, 0.f, 0.f, 0.f};
;         cur = nxt; cA = nA; cB = nB; ++ui;
;         if (wr == 1) PG8_BAR;
	v_pk_mul_f32 v[68:69], v[66:67], v[172:173] op_sel_hi:[1,0]
	v_pk_mul_f32 v[66:67], v[70:71], v[172:173] op_sel_hi:[1,0]
	v_cvt_pk_bf16_f32 v68, v68, v69
	v_cvt_pk_bf16_f32 v69, v74, v75
	v_cvt_pk_bf16_f32 v66, v66, v67
	v_cvt_pk_bf16_f32 v67, v72, v73
	v_lshl_add_u64 v[70:71], v[78:79], 0, s[4:5]
	global_store_dwordx4 v[70:71], v[66:69], off sc1
	s_nop 2
	v_pk_mul_f32 v[68:69], v[60:61], v[170:171] op_sel_hi:[1,0]
	v_pk_mul_f32 v[60:61], v[58:59], v[170:171] op_sel_hi:[1,0]
	v_pk_mul_f32 v[58:59], v[62:63], v[170:171] op_sel_hi:[1,0]
	v_mad_i64_i32 v[66:67], s[0:1], v148, s95, v[164:165]
	v_cvt_pk_bf16_f32 v58, v58, v59
	v_cvt_pk_bf16_f32 v59, v64, v65
	v_cvt_pk_bf16_f32 v60, v60, v61
	v_cvt_pk_bf16_f32 v61, v68, v69
	global_store_dwordx4 v[66:67], v[58:61], off sc1
	s_nop 2
	v_pk_mul_f32 v[58:59], v[44:45], v[170:171] op_sel_hi:[1,0]
	v_pk_mul_f32 v[44:45], v[42:43], v[170:171] op_sel_hi:[1,0]
	v_pk_mul_f32 v[42:43], v[46:47], v[170:171] op_sel_hi:[1,0]
	v_cvt_pk_bf16_f32 v44, v44, v45
	v_cvt_pk_bf16_f32 v42, v42, v43
	v_cvt_pk_bf16_f32 v43, v48, v49
	v_cvt_pk_bf16_f32 v45, v58, v59
	v_lshl_add_u64 v[46:47], v[66:67], 0, s[4:5]
	global_store_dwordx4 v[46:47], v[42:45], off sc1
	s_nop 2
	v_pk_mul_f32 v[44:45], v[50:51], v[174:175] op_sel_hi:[1,0]
	v_pk_mul_f32 v[50:51], v[56:57], v[174:175] op_sel_hi:[1,0]
	v_pk_mul_f32 v[42:43], v[54:55], v[174:175] op_sel_hi:[1,0]
	v_pk_mul_f32 v[48:49], v[52:53], v[174:175] op_sel_hi:[1,0]
	v_cvt_pk_bf16_f32 v42, v42, v43
	v_cvt_pk_bf16_f32 v43, v50, v51
	v_mad_i64_i32 v[46:47], s[0:1], v146, s95, v[164:165]
	v_cvt_pk_bf16_f32 v44, v44, v45
	v_cvt_pk_bf16_f32 v45, v48, v49
	global_store_dwordx4 v[46:47], v[42:45], off sc1
	s_nop 2
	v_pk_mul_f32 v[42:43], v[28:29], v[174:175] op_sel_hi:[1,0]
	v_pk_mul_f32 v[28:29], v[26:27], v[174:175] op_sel_hi:[1,0]
	v_pk_mul_f32 v[26:27], v[30:31], v[174:175] op_sel_hi:[1,0]
	v_cvt_pk_bf16_f32 v28, v28, v29
	v_cvt_pk_bf16_f32 v26, v26, v27
	v_cvt_pk_bf16_f32 v27, v32, v33
	v_cvt_pk_bf16_f32 v29, v42, v43
	v_lshl_add_u64 v[30:31], v[46:47], 0, s[4:5]
	global_store_dwordx4 v[30:31], v[26:29], off sc1
	s_nop 2
	v_pk_mul_f32 v[28:29], v[34:35], v[168:169] op_sel_hi:[1,0]
	v_pk_mul_f32 v[34:35], v[40:41], v[168:169] op_sel_hi:[1,0]
	v_pk_mul_f32 v[26:27], v[38:39], v[168:169] op_sel_hi:[1,0]
	v_pk_mul_f32 v[32:33], v[36:37], v[168:169] op_sel_hi:[1,0]
	v_cvt_pk_bf16_f32 v26, v26, v27
	v_cvt_pk_bf16_f32 v27, v34, v35
	v_mad_i64_i32 v[30:31], s[0:1], v144, s95, v[164:165]
	v_cvt_pk_bf16_f32 v28, v28, v29
	v_cvt_pk_bf16_f32 v29, v32, v33
	global_store_dwordx4 v[30:31], v[26:29], off sc1
	s_nop 2
	v_pk_mul_f32 v[26:27], v[12:13], v[168:169] op_sel_hi:[1,0]
	v_pk_mul_f32 v[12:13], v[10:11], v[168:169] op_sel_hi:[1,0]
	v_pk_mul_f32 v[10:11], v[14:15], v[168:169] op_sel_hi:[1,0]
	v_cvt_pk_bf16_f32 v12, v12, v13
	v_cvt_pk_bf16_f32 v10, v10, v11
	v_cvt_pk_bf16_f32 v11, v16, v17
	v_cvt_pk_bf16_f32 v13, v26, v27
	v_lshl_add_u64 v[14:15], v[30:31], 0, s[4:5]
	global_store_dwordx4 v[14:15], v[10:13], off sc1
	s_nop 2
	v_pk_mul_f32 v[12:13], v[18:19], v[156:157] op_sel_hi:[1,0]
	v_pk_mul_f32 v[18:19], v[24:25], v[156:157] op_sel_hi:[1,0]
	v_pk_mul_f32 v[10:11], v[22:23], v[156:157] op_sel_hi:[1,0]
	v_pk_mul_f32 v[16:17], v[20:21], v[156:157] op_sel_hi:[1,0]
	v_cvt_pk_bf16_f32 v10, v10, v11
	v_cvt_pk_bf16_f32 v11, v18, v19
	v_mad_i64_i32 v[14:15], s[0:1], v142, s95, v[164:165]
	v_cvt_pk_bf16_f32 v12, v12, v13
	v_cvt_pk_bf16_f32 v13, v16, v17
	global_store_dwordx4 v[14:15], v[10:13], off sc1
	s_nop 2
	v_pk_mul_f32 v[10:11], v[4:5], v[156:157] op_sel_hi:[1,0]
	v_pk_mul_f32 v[4:5], v[2:3], v[156:157] op_sel_hi:[1,0]
	v_pk_mul_f32 v[2:3], v[6:7], v[156:157] op_sel_hi:[1,0]
	v_cvt_pk_bf16_f32 v4, v4, v5
	v_cvt_pk_bf16_f32 v2, v2, v3
	v_cvt_pk_bf16_f32 v3, v8, v9
	v_cvt_pk_bf16_f32 v5, v10, v11
	v_lshl_add_u64 v[6:7], v[14:15], 0, s[4:5]
	global_store_dwordx4 v[6:7], v[2:5], off sc1
	s_nop 2
	s_mov_b64 s[4:5], -1
	s_andn2_b64 vcc, exec, s[2:3]
	s_cbranch_vccnz .LBB0_197
	s_andn2_b64 vcc, exec, s[8:9]
	s_cbranch_vccnz .LBB0_196
	s_barrier
	s_branch .LBB0_196

; #define PG8_STAGE(bufoff, gbase, voff) do { _Pragma("unroll") for (int _i = 0; _i < 2; ++_i) \
;         __builtin_amdgcn_global_load_lds((const unsigned*)((const char*)(gbase) + (voff)[_i]), (LAS unsigned*)(lds + (bufoff) + ldsw + _i * 8192), 16, 0, 0); } while (0)
; #define PG8_LDA(dst, b, h) do { _Pragma("unroll") for (int m = 0; m < 4; ++m) _Pragma("unroll") for (int k = 0; k < 2; ++k) dst[m][k] = *(const LAS bf16x8*)(lds + PG8_SA(b, h) + aoff + m * 2048 + k * 1024); } while (0)
; #define PG8_LDB(dst, b, h) do { _Pragma("unroll") for (int n = 0; n < 2; ++n) _Pragma("unroll") for (int k = 0; k < 2; ++k) dst[n][k] = *(const LAS bf16x8*)(lds + PG8_SB(b, h) + boff + n * 2048 + k * 1024); } while (0)
; #define PG8_MMA(ai, bj, At, Bt) do { __builtin_amdgcn_s_setprio(1); _Pragma("unroll") for (int m = 0; m < 4; ++m) _Pragma("unroll") for (int n = 0; n < 2; ++n) _Pragma("unroll") for (int k = 0; k < 2; ++k) \
;         acc[ai][bj][m][n] = __builtin_amdgcn_mfma_f32_16x16x32_bf16(Bt[n][k], At[m][k], acc[ai][bj][m][n], 0, 0, 0); __builtin_amdgcn_s_setprio(0); } while (0)
; #define PG8_WAIT_V(n) asm volatile("s_waitcnt vmcnt(" #n ")" ::: "memory")
; #define PG8_WAIT_L(n) asm volatile("s_waitcnt lgkmcnt(" #n ")" ::: "memory")
; #define PG8_BAR __builtin_amdgcn_s_barrier()
; #define PG8_SCHED __builtin_amdgcn_sched_barrier(0)
; template <class Epi, class Sched>
; __device__ __forceinline__ void gemm_phase(LAS unsigned char* lds, const Gemm g, const Sched& S, const Epi& E, int wv) {
;     ...
;         const bool has_next = S.next(ui + 1, nxt);
;         const char* nA = has_next ? (const char*)g.A + (size_t)nxt.pm * tstepA + (size_t)nxt.ak * 2 : cA; const char* nB = has_next ? (const char*)g.Bt + (size_t)nxt.pn * tstepB : cB;
;         for (int t = 0; t < nt; t += 2) {
;             const bool last = (t == nt - 2);
;             const char* a1 = cA + (size_t)(t + 1) * kstep;
;             const char* a2 = last ? nA : cA + (size_t)(t + 2) * kstep; const char* b2 = last ? nB : cB + (size_t)(t + 2) * kstep;
;             const char* a3 = a2 + kstep; const char* b3 = b2 + kstep;
;             PG8_LDB(B0, 0, 0); PG8_LDB(B1, 0, 1); PG8_SCHED; PG8_LDA(At, 0, 0); PG8_STAGE(PG8_SA(1, 1), a1 + hstepA, voffA);
;             PG8_WAIT_V(8); PG8_WAIT_L(0); PG8_BAR; PG8_MMA(0, 0, At, B0); PG8_MMA(0, 1, At, B1); PG8_BAR; PG8_SCHED;
.LBB0_225:
	s_add_u32 s20, s70, s35
	s_addc_u32 s26, s71, 0
	s_add_u32 s27, s20, 0x100
	s_addc_u32 s33, s26, 0
	s_and_b64 s[0:1], s[82:83], exec
	s_cselect_b32 s87, s75, s33
	s_cselect_b32 s86, s31, s27
	s_add_u32 s0, s68, s35
	s_addc_u32 s1, s69, 0
	s_add_u32 s27, s0, 0x100
	s_addc_u32 s33, s1, 0
	s_add_i32 s58, 0, 0x10000
	s_and_b64 s[0:1], s[82:83], exec
	s_cselect_b32 s89, s73, s33
	s_cselect_b32 s88, s34, s27
	s_add_i32 s27, 0, 0x14000
	s_add_u32 s92, s20, 0x10080
	s_addc_u32 s93, s26, 0
	s_add_i32 s1, s58, s61
	s_add_i32 m0, s62, 0xc000
	s_add_i32 s59, s62, 0xe000
	s_add_i32 s53, s1, 0x2000
	s_add_u32 s90, s88, 0x10000
	v_add_u32_e32 v150, s58, v136
	v_add_u32_e32 v166, s27, v136
	s_addc_u32 s91, s89, 0
	s_add_i32 s0, s27, s61
	ds_read_b128 v[138:141], v150
	ds_read_b128 v[142:145], v150 offset:1024
	ds_read_b128 v[146:149], v150 offset:2048
	ds_read_b128 v[150:153], v150 offset:3072
	ds_read_b128 v[154:157], v166
	ds_read_b128 v[158:161], v166 offset:1024
	ds_read_b128 v[162:165], v166 offset:2048
	ds_read_b128 v[166:169], v166 offset:3072
	s_add_i32 s20, s0, 0x2000
	s_add_i32 vcc_lo, 0, 0x18000
	s_add_i32 vcc_hi, 0, 0x1c000
	s_add_u32 s84, s86, 0x10000
	s_addc_u32 s85, s87, 0
	s_add_i32 s35, vcc_lo, s61
	s_add_i32 s95, s35, 0x2000
	s_add_u32 s82, s88, 0x10080
	s_addc_u32 s83, s89, 0
	s_add_i32 s33, vcc_hi, s61
	s_add_i32 s26, s33, 0x2000
	v_lshl_add_u64 v[204:205], s[92:93], 0, v[130:131]
	ds_read_b128 v[170:173], v137
	ds_read_b128 v[174:177], v137 offset:1024
	ds_read_b128 v[178:181], v137 offset:2048
	ds_read_b128 v[182:185], v137 offset:3072
	ds_read_b128 v[186:189], v137 offset:4096
	ds_read_b128 v[190:193], v137 offset:5120
	ds_read_b128 v[196:199], v137 offset:6144
	ds_read_b128 v[200:203], v137 offset:7168
	global_load_lds_dwordx4 v[204:205], off
	v_lshl_add_u64 v[204:205], s[92:93], 0, v[132:133]
	s_mov_b32 m0, s59
	s_nop 0
	global_load_lds_dwordx4 v[204:205], off
	s_waitcnt vmcnt(8)
	s_waitcnt lgkmcnt(0)
	s_barrier
	s_setprio 1
	v_mfma_f32_16x16x32_bf16 v[126:129], v[138:141], v[170:173], v[126:129]
	v_mfma_f32_16x16x32_bf16 v[122:125], v[146:149], v[170:173], v[122:125]
	v_mfma_f32_16x16x32_bf16 v[118:121], v[138:141], v[178:181], v[118:121]
	v_mfma_f32_16x16x32_bf16 v[114:117], v[146:149], v[178:181], v[114:117]
	v_mfma_f32_16x16x32_bf16 v[102:105], v[138:141], v[186:189], v[102:105]
	v_mfma_f32_16x16x32_bf16 v[98:101], v[146:149], v[186:189], v[98:101]
	v_mfma_f32_16x16x32_bf16 v[86:89], v[138:141], v[196:199], v[86:89]
	v_mfma_f32_16x16x32_bf16 v[82:85], v[146:149], v[196:199], v[82:85]
	v_mfma_f32_16x16x32_bf16 v[126:129], v[142:145], v[174:177], v[126:129]
	v_mfma_f32_16x16x32_bf16 v[122:125], v[150:153], v[174:177], v[122:125]
	v_mfma_f32_16x16x32_bf16 v[118:121], v[142:145], v[182:185], v[118:121]
	v_mfma_f32_16x16x32_bf16 v[114:117], v[150:153], v[182:185], v[114:117]
	v_mfma_f32_16x16x32_bf16 v[102:105], v[142:145], v[190:193], v[102:105]
	v_mfma_f32_16x16x32_bf16 v[98:101], v[150:153], v[190:193], v[98:101]
	v_mfma_f32_16x16x32_bf16 v[86:89], v[142:145], v[200:203], v[86:89]
	v_mfma_f32_16x16x32_bf16 v[82:85], v[150:153], v[200:203], v[82:85]
	v_mfma_f32_16x16x32_bf16 v[110:113], v[154:157], v[170:173], v[110:113]
	v_mfma_f32_16x16x32_bf16 v[106:109], v[162:165], v[170:173], v[106:109]
	v_mfma_f32_16x16x32_bf16 v[94:97], v[154:157], v[178:181], v[94:97]
	v_mfma_f32_16x16x32_bf16 v[90:93], v[162:165], v[178:181], v[90:93]
	v_mfma_f32_16x16x32_bf16 v[78:81], v[154:157], v[186:189], v[78:81]
	v_mfma_f32_16x16x32_bf16 v[74:77], v[162:165], v[186:189], v[74:77]
	v_mfma_f32_16x16x32_bf16 v[70:73], v[154:157], v[196:199], v[70:73]
	v_mfma_f32_16x16x32_bf16 v[66:69], v[162:165], v[196:199], v[66:69]
	v_mfma_f32_16x16x32_bf16 v[110:113], v[158:161], v[174:177], v[110:113]
	v_mfma_f32_16x16x32_bf16 v[106:109], v[166:169], v[174:177], v[106:109]
	v_mfma_f32_16x16x32_bf16 v[94:97], v[158:161], v[182:185], v[94:97]
	v_mfma_f32_16x16x32_bf16 v[90:93], v[166:169], v[182:185], v[90:93]
	v_mfma_f32_16x16x32_bf16 v[78:81], v[158:161], v[190:193], v[78:81]
	v_mfma_f32_16x16x32_bf16 v[74:77], v[166:169], v[190:193], v[74:77]
	v_mfma_f32_16x16x32_bf16 v[70:73], v[158:161], v[200:203], v[70:73]
	v_mfma_f32_16x16x32_bf16 v[66:69], v[166:169], v[200:203], v[66:69]
	s_setprio 0
	s_barrier
	s_mov_b32 m0, s1
	v_lshl_add_u64 v[204:205], s[88:89], 0, v[0:1]
	ds_read_b128 v[170:173], v137 offset:16384
	ds_read_b128 v[174:177], v137 offset:17408
	ds_read_b128 v[178:181], v137 offset:18432
	ds_read_b128 v[182:185], v137 offset:19456
	ds_read_b128 v[186:189], v137 offset:20480
	ds_read_b128 v[190:193], v137 offset:21504
	ds_read_b128 v[196:199], v137 offset:22528
	ds_read_b128 v[200:203], v137 offset:23552
	global_load_lds_dwordx4 v[204:205], off
	v_lshl_add_u64 v[206:207], s[88:89], 0, v[134:135]
	s_mov_b32 m0, s53
	v_lshl_add_u64 v[208:209], s[90:91], 0, v[0:1]
	global_load_lds_dwordx4 v[206:207], off
	s_mov_b32 m0, s0
	v_lshl_add_u64 v[210:211], s[86:87], 0, v[132:133]
	global_load_lds_dwordx4 v[208:209], off
	v_lshl_add_u64 v[208:209], s[90:91], 0, v[134:135]
	s_mov_b32 m0, s20
	s_nop 0
	global_load_lds_dwordx4 v[208:209], off
	v_lshl_add_u64 v[208:209], s[86:87], 0, v[130:131]
	s_mov_b32 m0, s62
	s_nop 0
	global_load_lds_dwordx4 v[208:209], off
	s_mov_b32 m0, s65
	s_nop 0
	global_load_lds_dwordx4 v[210:211], off
	s_waitcnt vmcnt(8)
	s_waitcnt lgkmcnt(0)
	s_barrier
; #define PG8_STAGE(bufoff, gbase, voff) do { _Pragma("unroll") for (int _i = 0; _i < 2; ++_i) \
;         __builtin_amdgcn_global_load_lds((const unsigned*)((const char*)(gbase) + (voff)[_i]), (LAS unsigned*)(lds + (bufoff) + ldsw + _i * 8192), 16, 0, 0); } while (0)
; #define PG8_LDA(dst, b, h) do { _Pragma("unroll") for (int m = 0; m < 4; ++m) _Pragma("unroll") for (int k = 0; k < 2; ++k) dst[m][k] = *(const LAS bf16x8*)(lds + PG8_SA(b, h) + aoff + m * 2048 + k * 1024); } while (0)
; #define PG8_LDB(dst, b, h) do { _Pragma("unroll") for (int n = 0; n < 2; ++n) _Pragma("unroll") for (int k = 0; k < 2; ++k) dst[n][k] = *(const LAS bf16x8*)(lds + PG8_SB(b, h) + boff + n * 2048 + k * 1024); } while (0)
; #define PG8_MMA(ai, bj, At, Bt) do { __builtin_amdgcn_s_setprio(1); _Pragma("unroll") for (int m = 0; m < 4; ++m) _Pragma("unroll") for (int n = 0; n < 2; ++n) _Pragma("unroll") for (int k = 0; k < 2; ++k) \
;         acc[ai][bj][m][n] = __builtin_amdgcn_mfma_f32_16x16x32_bf16(Bt[n][k], At[m][k], acc[ai][bj][m][n], 0, 0, 0); __builtin_amdgcn_s_setprio(0); } while (0)
; #define PG8_WAIT_V(n) asm volatile("s_waitcnt vmcnt(" #n ")" ::: "memory")
; #define PG8_BAR __builtin_amdgcn_s_barrier()
; template <class Epi, class Sched>
; __device__ __forceinline__ void gemm_phase(LAS unsigned char* lds, const Gemm g, const Sched& S, const Epi& E, int wv) {
;     ...
;             PG8_LDB(B0, 0, 0); PG8_LDB(B1, 0, 1); PG8_SCHED; PG8_LDA(At, 0, 0); PG8_STAGE(PG8_SA(1, 1), a1 + hstepA, voffA);
;             PG8_WAIT_V(8); PG8_WAIT_L(0); PG8_BAR; PG8_MMA(0, 0, At, B0); PG8_MMA(0, 1, At, B1); PG8_BAR; PG8_SCHED;
;             PG8_LDA(At, 0, 1); PG8_STAGE(PG8_SB(0, 0), b2, voffB); PG8_STAGE(PG8_SB(0, 1), b2 + hstepB, voffB); PG8_STAGE(PG8_SA(0, 0), a2, voffA);
;             PG8_WAIT_V(8); PG8_WAIT_L(0); PG8_BAR; PG8_MMA(1, 0, At, B0); PG8_MMA(1, 1, At, B1); PG8_BAR; PG8_SCHED;
;             PG8_LDB(B0, 1, 0); PG8_LDB(B1, 1, 1); PG8_SCHED; PG8_LDA(At, 1, 0); PG8_STAGE(PG8_SA(0, 1), a2 + hstepA, voffA);
;             PG8_WAIT_V(8); PG8_WAIT_L(0); PG8_BAR; PG8_MMA(0, 0, At, B0); PG8_MMA(0, 1, At, B1); PG8_BAR; PG8_SCHED;
;             PG8_LDA(At, 1, 1); PG8_STAGE(PG8_SB(1, 0), b3, voffB); PG8_STAGE(PG8_SB(1, 1), b3 + hstepB, voffB); PG8_STAGE(PG8_SA(1, 0), a3, voffA);
;             PG8_WAIT_V(8); PG8_WAIT_L(0); PG8_BAR; PG8_MMA(1, 0, At, B0); PG8_MMA(1, 1, At, B1); PG8_BAR; PG8_SCHED;
	s_setprio 1
	v_mfma_f32_16x16x32_bf16 v[62:65], v[138:141], v[170:173], v[62:65]
	v_mfma_f32_16x16x32_bf16 v[58:61], v[146:149], v[170:173], v[58:61]
	v_mfma_f32_16x16x32_bf16 v[54:57], v[138:141], v[178:181], v[54:57]
	v_mfma_f32_16x16x32_bf16 v[50:53], v[146:149], v[178:181], v[50:53]
	v_mfma_f32_16x16x32_bf16 v[38:41], v[138:141], v[186:189], v[38:41]
	v_mfma_f32_16x16x32_bf16 v[34:37], v[146:149], v[186:189], v[34:37]
	v_mfma_f32_16x16x32_bf16 v[22:25], v[138:141], v[196:199], v[22:25]
	v_mfma_f32_16x16x32_bf16 v[18:21], v[146:149], v[196:199], v[18:21]
	v_mfma_f32_16x16x32_bf16 v[62:65], v[142:145], v[174:177], v[62:65]
	v_mfma_f32_16x16x32_bf16 v[58:61], v[150:153], v[174:177], v[58:61]
	v_mfma_f32_16x16x32_bf16 v[54:57], v[142:145], v[182:185], v[54:57]
	v_mfma_f32_16x16x32_bf16 v[50:53], v[150:153], v[182:185], v[50:53]
	v_mfma_f32_16x16x32_bf16 v[38:41], v[142:145], v[190:193], v[38:41]
	v_mfma_f32_16x16x32_bf16 v[34:37], v[150:153], v[190:193], v[34:37]
	v_mfma_f32_16x16x32_bf16 v[22:25], v[142:145], v[200:203], v[22:25]
	v_mfma_f32_16x16x32_bf16 v[18:21], v[150:153], v[200:203], v[18:21]
	v_mfma_f32_16x16x32_bf16 v[46:49], v[154:157], v[170:173], v[46:49]
	v_mfma_f32_16x16x32_bf16 v[42:45], v[162:165], v[170:173], v[42:45]
	v_mfma_f32_16x16x32_bf16 v[30:33], v[154:157], v[178:181], v[30:33]
	v_mfma_f32_16x16x32_bf16 v[26:29], v[162:165], v[178:181], v[26:29]
	v_mfma_f32_16x16x32_bf16 v[14:17], v[154:157], v[186:189], v[14:17]
	v_mfma_f32_16x16x32_bf16 v[10:13], v[162:165], v[186:189], v[10:13]
	v_mfma_f32_16x16x32_bf16 v[6:9], v[154:157], v[196:199], v[6:9]
	v_mfma_f32_16x16x32_bf16 v[2:5], v[162:165], v[196:199], v[2:5]
	v_mfma_f32_16x16x32_bf16 v[46:49], v[158:161], v[174:177], v[46:49]
	v_mfma_f32_16x16x32_bf16 v[42:45], v[166:169], v[174:177], v[42:45]
	v_mfma_f32_16x16x32_bf16 v[30:33], v[158:161], v[182:185], v[30:33]
	v_mfma_f32_16x16x32_bf16 v[26:29], v[166:169], v[182:185], v[26:29]
	v_mfma_f32_16x16x32_bf16 v[14:17], v[158:161], v[190:193], v[14:17]
	v_mfma_f32_16x16x32_bf16 v[10:13], v[166:169], v[190:193], v[10:13]
	v_mfma_f32_16x16x32_bf16 v[6:9], v[158:161], v[200:203], v[6:9]
	v_mfma_f32_16x16x32_bf16 v[2:5], v[166:169], v[200:203], v[2:5]
	s_setprio 0
	s_barrier
	v_add_u32_e32 v150, vcc_lo, v136
	v_add_u32_e32 v166, vcc_hi, v136
	ds_read_b128 v[138:141], v150
	ds_read_b128 v[142:145], v150 offset:1024
	ds_read_b128 v[146:149], v150 offset:2048
	ds_read_b128 v[150:153], v150 offset:3072
	ds_read_b128 v[154:157], v166
	ds_read_b128 v[158:161], v166 offset:1024
	ds_read_b128 v[162:165], v166 offset:2048
	ds_read_b128 v[166:169], v166 offset:3072
	s_mov_b32 m0, s67
	v_lshl_add_u64 v[212:213], s[84:85], 0, v[130:131]
	ds_read_b128 v[170:173], v137 offset:32768
	ds_read_b128 v[174:177], v137 offset:33792
	ds_read_b128 v[178:181], v137 offset:34816
	ds_read_b128 v[182:185], v137 offset:35840
	ds_read_b128 v[186:189], v137 offset:36864
	ds_read_b128 v[190:193], v137 offset:37888
	ds_read_b128 v[196:199], v137 offset:38912
	ds_read_b128 v[200:203], v137 offset:39936
	global_load_lds_dwordx4 v[212:213], off
	v_lshl_add_u64 v[212:213], s[84:85], 0, v[132:133]
	s_mov_b32 m0, s96
	s_nop 0
	global_load_lds_dwordx4 v[212:213], off
	s_waitcnt vmcnt(8)
	s_waitcnt lgkmcnt(0)
	s_barrier
	s_setprio 1
	v_mfma_f32_16x16x32_bf16 v[126:129], v[138:141], v[170:173], v[126:129]
	v_mfma_f32_16x16x32_bf16 v[122:125], v[146:149], v[170:173], v[122:125]
	v_mfma_f32_16x16x32_bf16 v[118:121], v[138:141], v[178:181], v[118:121]
	v_mfma_f32_16x16x32_bf16 v[114:117], v[146:149], v[178:181], v[114:117]
	v_mfma_f32_16x16x32_bf16 v[102:105], v[138:141], v[186:189], v[102:105]
	v_mfma_f32_16x16x32_bf16 v[98:101], v[146:149], v[186:189], v[98:101]
	v_mfma_f32_16x16x32_bf16 v[86:89], v[138:141], v[196:199], v[86:89]
	v_mfma_f32_16x16x32_bf16 v[82:85], v[146:149], v[196:199], v[82:85]
	v_mfma_f32_16x16x32_bf16 v[126:129], v[142:145], v[174:177], v[126:129]
	v_mfma_f32_16x16x32_bf16 v[122:125], v[150:153], v[174:177], v[122:125]
	v_mfma_f32_16x16x32_bf16 v[118:121], v[142:145], v[182:185], v[118:121]
	v_mfma_f32_16x16x32_bf16 v[114:117], v[150:153], v[182:185], v[114:117]
	v_mfma_f32_16x16x32_bf16 v[102:105], v[142:145], v[190:193], v[102:105]
	v_mfma_f32_16x16x32_bf16 v[98:101], v[150:153], v[190:193], v[98:101]
	v_mfma_f32_16x16x32_bf16 v[86:89], v[142:145], v[200:203], v[86:89]
	v_mfma_f32_16x16x32_bf16 v[82:85], v[150:153], v[200:203], v[82:85]
	v_mfma_f32_16x16x32_bf16 v[110:113], v[154:157], v[170:173], v[110:113]
	v_mfma_f32_16x16x32_bf16 v[106:109], v[162:165], v[170:173], v[106:109]
	v_mfma_f32_16x16x32_bf16 v[94:97], v[154:157], v[178:181], v[94:97]
	v_mfma_f32_16x16x32_bf16 v[90:93], v[162:165], v[178:181], v[90:93]
	v_mfma_f32_16x16x32_bf16 v[78:81], v[154:157], v[186:189], v[78:81]
	v_mfma_f32_16x16x32_bf16 v[74:77], v[162:165], v[186:189], v[74:77]
	v_mfma_f32_16x16x32_bf16 v[70:73], v[154:157], v[196:199], v[70:73]
	v_mfma_f32_16x16x32_bf16 v[66:69], v[162:165], v[196:199], v[66:69]
	v_mfma_f32_16x16x32_bf16 v[110:113], v[158:161], v[174:177], v[110:113]
	v_mfma_f32_16x16x32_bf16 v[106:109], v[166:169], v[174:177], v[106:109]
	v_mfma_f32_16x16x32_bf16 v[94:97], v[158:161], v[182:185], v[94:97]
	v_mfma_f32_16x16x32_bf16 v[90:93], v[166:169], v[182:185], v[90:93]
	v_mfma_f32_16x16x32_bf16 v[78:81], v[158:161], v[190:193], v[78:81]
	v_mfma_f32_16x16x32_bf16 v[74:77], v[166:169], v[190:193], v[74:77]
	v_mfma_f32_16x16x32_bf16 v[70:73], v[158:161], v[200:203], v[70:73]
	v_mfma_f32_16x16x32_bf16 v[66:69], v[166:169], v[200:203], v[66:69]
	s_setprio 0
	s_barrier
; #define PG8_STAGE(bufoff, gbase, voff) do { _Pragma("unroll") for (int _i = 0; _i < 2; ++_i) \
;         __builtin_amdgcn_global_load_lds((const unsigned*)((const char*)(gbase) + (voff)[_i]), (LAS unsigned*)(lds + (bufoff) + ldsw + _i * 8192), 16, 0, 0); } while (0)
; #define PG8_LDA(dst, b, h) do { _Pragma("unroll") for (int m = 0; m < 4; ++m) _Pragma("unroll") for (int k = 0; k < 2; ++k) dst[m][k] = *(const LAS bf16x8*)(lds + PG8_SA(b, h) + aoff + m * 2048 + k * 1024); } while (0)
; #define PG8_MMA(ai, bj, At, Bt) do { __builtin_amdgcn_s_setprio(1); _Pragma("unroll") for (int m = 0; m < 4; ++m) _Pragma("unroll") for (int n = 0; n < 2; ++n) _Pragma("unroll") for (int k = 0; k < 2; ++k) \
;         acc[ai][bj][m][n] = __builtin_amdgcn_mfma_f32_16x16x32_bf16(Bt[n][k], At[m][k], acc[ai][bj][m][n], 0, 0, 0); __builtin_amdgcn_s_setprio(0); } while (0)
; #define PG8_WAIT_V(n) asm volatile("s_waitcnt vmcnt(" #n ")" ::: "memory")
; #define PG8_WAIT_L(n) asm volatile("s_waitcnt lgkmcnt(" #n ")" ::: "memory")
; #define PG8_BAR __builtin_amdgcn_s_barrier()
; #define PG8_SCHED __builtin_amdgcn_sched_barrier(0)
; template <class Epi, class Sched>
; __device__ __forceinline__ void gemm_phase(LAS unsigned char* lds, const Gemm g, const Sched& S, const Epi& E, int wv) {
;     ...
;             PG8_LDA(At, 1, 1); PG8_STAGE(PG8_SB(1, 0), b3, voffB); PG8_STAGE(PG8_SB(1, 1), b3 + hstepB, voffB); PG8_STAGE(PG8_SA(1, 0), a3, voffA);
;             PG8_WAIT_V(8); PG8_WAIT_L(0); PG8_BAR; PG8_MMA(1, 0, At, B0); PG8_MMA(1, 1, At, B1); PG8_BAR; PG8_SCHED;
;         }
;         if (wr == 0) PG8_BAR;
	s_mov_b32 m0, s35
	v_lshl_add_u64 v[204:205], v[204:205], 0, s[24:25]
	ds_read_b128 v[170:173], v137 offset:49152
	ds_read_b128 v[174:177], v137 offset:50176
	ds_read_b128 v[178:181], v137 offset:51200
	ds_read_b128 v[182:185], v137 offset:52224
	ds_read_b128 v[186:189], v137 offset:53248
	ds_read_b128 v[190:193], v137 offset:54272
	ds_read_b128 v[196:199], v137 offset:55296
	ds_read_b128 v[200:203], v137 offset:56320
	global_load_lds_dwordx4 v[204:205], off
	v_lshl_add_u64 v[204:205], v[206:207], 0, s[24:25]
	s_mov_b32 m0, s95
	s_nop 0
	global_load_lds_dwordx4 v[204:205], off
	v_lshl_add_u64 v[204:205], s[82:83], 0, v[0:1]
	s_mov_b32 m0, s33
	s_nop 0
	global_load_lds_dwordx4 v[204:205], off
	v_lshl_add_u64 v[204:205], s[82:83], 0, v[134:135]
	s_mov_b32 m0, s26
	s_nop 0
	global_load_lds_dwordx4 v[204:205], off
	v_lshl_add_u64 v[204:205], v[208:209], 0, s[24:25]
	s_mov_b32 m0, s94
	s_nop 0
	global_load_lds_dwordx4 v[204:205], off
	v_lshl_add_u64 v[204:205], v[210:211], 0, s[24:25]
	s_mov_b32 m0, s10
	s_nop 0
	global_load_lds_dwordx4 v[204:205], off
	s_waitcnt vmcnt(8)
	s_waitcnt lgkmcnt(0)
	s_barrier
	s_setprio 1
	v_mfma_f32_16x16x32_bf16 v[62:65], v[138:141], v[170:173], v[62:65]
	v_mfma_f32_16x16x32_bf16 v[58:61], v[146:149], v[170:173], v[58:61]
	v_mfma_f32_16x16x32_bf16 v[54:57], v[138:141], v[178:181], v[54:57]
	v_mfma_f32_16x16x32_bf16 v[50:53], v[146:149], v[178:181], v[50:53]
	v_mfma_f32_16x16x32_bf16 v[38:41], v[138:141], v[186:189], v[38:41]
	v_mfma_f32_16x16x32_bf16 v[34:37], v[146:149], v[186:189], v[34:37]
	v_mfma_f32_16x16x32_bf16 v[22:25], v[138:141], v[196:199], v[22:25]
	v_mfma_f32_16x16x32_bf16 v[18:21], v[146:149], v[196:199], v[18:21]
	v_mfma_f32_16x16x32_bf16 v[62:65], v[142:145], v[174:177], v[62:65]
	v_mfma_f32_16x16x32_bf16 v[58:61], v[150:153], v[174:177], v[58:61]
	v_mfma_f32_16x16x32_bf16 v[54:57], v[142:145], v[182:185], v[54:57]
	v_mfma_f32_16x16x32_bf16 v[50:53], v[150:153], v[182:185], v[50:53]
	v_mfma_f32_16x16x32_bf16 v[38:41], v[142:145], v[190:193], v[38:41]
	v_mfma_f32_16x16x32_bf16 v[34:37], v[150:153], v[190:193], v[34:37]
	v_mfma_f32_16x16x32_bf16 v[22:25], v[142:145], v[200:203], v[22:25]
	v_mfma_f32_16x16x32_bf16 v[18:21], v[150:153], v[200:203], v[18:21]
	v_mfma_f32_16x16x32_bf16 v[46:49], v[154:157], v[170:173], v[46:49]
	v_mfma_f32_16x16x32_bf16 v[42:45], v[162:165], v[170:173], v[42:45]
	v_mfma_f32_16x16x32_bf16 v[30:33], v[154:157], v[178:181], v[30:33]
	v_mfma_f32_16x16x32_bf16 v[26:29], v[162:165], v[178:181], v[26:29]
	v_mfma_f32_16x16x32_bf16 v[14:17], v[154:157], v[186:189], v[14:17]
	v_mfma_f32_16x16x32_bf16 v[10:13], v[162:165], v[186:189], v[10:13]
	v_mfma_f32_16x16x32_bf16 v[6:9], v[154:157], v[196:199], v[6:9]
	v_mfma_f32_16x16x32_bf16 v[2:5], v[162:165], v[196:199], v[2:5]
	v_mfma_f32_16x16x32_bf16 v[46:49], v[158:161], v[174:177], v[46:49]
	v_mfma_f32_16x16x32_bf16 v[42:45], v[166:169], v[174:177], v[42:45]
	v_mfma_f32_16x16x32_bf16 v[30:33], v[158:161], v[182:185], v[30:33]
	v_mfma_f32_16x16x32_bf16 v[26:29], v[166:169], v[182:185], v[26:29]
	v_mfma_f32_16x16x32_bf16 v[14:17], v[158:161], v[190:193], v[14:17]
	v_mfma_f32_16x16x32_bf16 v[10:13], v[166:169], v[190:193], v[10:13]
	v_mfma_f32_16x16x32_bf16 v[6:9], v[158:161], v[200:203], v[6:9]
	v_mfma_f32_16x16x32_bf16 v[2:5], v[166:169], v[200:203], v[2:5]
	s_setprio 0
	s_barrier
	s_movk_i32 s35, 0x100
	s_andn2_b64 vcc, exec, s[80:81]
	s_mov_b64 s[82:83], -1
	s_mov_b64 s[80:81], 0
	s_cbranch_vccz .LBB0_225
	s_and_b64 vcc, exec, s[12:13]
	s_cbranch_vccz .LBB0_228
	s_barrier

; #define PG8_STAGE(bufoff, gbase, voff) do { _Pragma("unroll") for (int _i = 0; _i < 2; ++_i) \
;         __builtin_amdgcn_global_load_lds((const unsigned*)((const char*)(gbase) + (voff)[_i]), (LAS unsigned*)(lds + (bufoff) + ldsw + _i * 8192), 16, 0, 0); } while (0)
; #define PG8_LDA(dst, b, h) do { _Pragma("unroll") for (int m = 0; m < 4; ++m) _Pragma("unroll") for (int k = 0; k < 2; ++k) dst[m][k] = *(const LAS bf16x8*)(lds + PG8_SA(b, h) + aoff + m * 2048 + k * 1024); } while (0)
; #define PG8_LDB(dst, b, h) do { _Pragma("unroll") for (int n = 0; n < 2; ++n) _Pragma("unroll") for (int k = 0; k < 2; ++k) dst[n][k] = *(const LAS bf16x8*)(lds + PG8_SB(b, h) + boff + n * 2048 + k * 1024); } while (0)
; #define PG8_MMA(ai, bj, At, Bt) do { __builtin_amdgcn_s_setprio(1); _Pragma("unroll") for (int m = 0; m < 4; ++m) _Pragma("unroll") for (int n = 0; n < 2; ++n) _Pragma("unroll") for (int k = 0; k < 2; ++k) \
;         acc[ai][bj][m][n] = __builtin_amdgcn_mfma_f32_16x16x32_bf16(Bt[n][k], At[m][k], acc[ai][bj][m][n], 0, 0, 0); __builtin_amdgcn_s_setprio(0); } while (0)
; #define PG8_WAIT_V(n) asm volatile("s_waitcnt vmcnt(" #n ")" ::: "memory")
; template <class Epi, class Sched>
; __device__ __forceinline__ void gemm_phase(LAS unsigned char* lds, const Gemm g, const Sched& S, const Epi& E, int wv) {
;     ...
;         const char* nA = has_next ? (const char*)g.A + (size_t)nxt.pm * tstepA + (size_t)nxt.ak * 2 : cA; const char* nB = has_next ? (const char*)g.Bt + (size_t)nxt.pn * tstepB : cB;
;         for (int t = 0; t < nt; t += 2) {
;             const bool last = (t == nt - 2);
;             const char* a1 = cA + (size_t)(t + 1) * kstep;
;             const char* a2 = last ? nA : cA + (size_t)(t + 2) * kstep; const char* b2 = last ? nB : cB + (size_t)(t + 2) * kstep;
;             const char* a3 = a2 + kstep; const char* b3 = b2 + kstep;
;             PG8_LDB(B0, 0, 0); PG8_LDB(B1, 0, 1); PG8_SCHED; PG8_LDA(At, 0, 0); PG8_STAGE(PG8_SA(1, 1), a1 + hstepA, voffA);
;             PG8_WAIT_V(8); PG8_WAIT_L(0); PG8_BAR; PG8_MMA(0, 0, At, B0); PG8_MMA(0, 1, At, B1); PG8_BAR; PG8_SCHED;
;             PG8_LDA(At, 0, 1); PG8_STAGE(PG8_SB(0, 0), b2, voffB); PG8_STAGE(PG8_SB(0, 1), b2 + hstepB, voffB); PG8_STAGE(PG8_SA(0, 0), a2, voffA);
;             PG8_WAIT_V(8); PG8_WAIT_L(0); PG8_BAR; PG8_MMA(1, 0, At, B0); PG8_MMA(1, 1, At, B1); PG8_BAR; PG8_SCHED;
.LBB0_252:
	s_add_u32 s0, s74, 0xfffc0080
	s_addc_u32 s1, s75, -1
	s_add_i32 s20, 0, 0x10000
	s_cmp_eq_u32 s56, 12
	s_cselect_b32 s79, s10, s1
	s_cselect_b32 s78, s11, s0
	v_add_u32_e32 v144, s20, v146
	s_cselect_b32 s77, s21, s35
	s_cselect_b32 s76, s31, s34
	s_add_i32 s26, 0, 0x14000
	ds_read_b128 v[140:143], v144
	ds_read_b128 v[148:151], v144 offset:1024
	ds_read_b128 v[152:155], v144 offset:2048
	ds_read_b128 v[156:159], v144 offset:3072
	v_add_u32_e32 v144, s26, v146
	ds_read_b128 v[160:163], v144
	ds_read_b128 v[164:167], v144 offset:1024
	ds_read_b128 v[168:171], v144 offset:2048
	ds_read_b128 v[172:175], v144 offset:3072
	v_lshl_add_u64 v[144:145], s[74:75], 0, v[136:137]
	s_add_i32 m0, s62, 0xc000
	ds_read_b128 v[176:179], v147
	ds_read_b128 v[180:183], v147 offset:1024
	ds_read_b128 v[184:187], v147 offset:2048
	ds_read_b128 v[188:191], v147 offset:3072
	ds_read_b128 v[196:199], v147 offset:4096
	ds_read_b128 v[200:203], v147 offset:5120
	ds_read_b128 v[204:207], v147 offset:6144
	ds_read_b128 v[208:211], v147 offset:7168
	global_load_lds_dwordx4 v[144:145], off
	v_lshl_add_u64 v[144:145], s[74:75], 0, v[138:139]
	s_add_i32 m0, s62, 0xe000
	s_nop 0
	global_load_lds_dwordx4 v[144:145], off
	s_waitcnt vmcnt(8)
	s_waitcnt lgkmcnt(0)
	s_barrier
	s_setprio 1
	v_mfma_f32_16x16x32_bf16 v[126:129], v[140:143], v[176:179], v[126:129]
	v_mfma_f32_16x16x32_bf16 v[122:125], v[152:155], v[176:179], v[122:125]
	v_mfma_f32_16x16x32_bf16 v[110:113], v[140:143], v[184:187], v[110:113]
	v_mfma_f32_16x16x32_bf16 v[106:109], v[152:155], v[184:187], v[106:109]
	v_mfma_f32_16x16x32_bf16 v[94:97], v[140:143], v[196:199], v[94:97]
	v_mfma_f32_16x16x32_bf16 v[90:93], v[152:155], v[196:199], v[90:93]
	v_mfma_f32_16x16x32_bf16 v[78:81], v[140:143], v[204:207], v[78:81]
	v_mfma_f32_16x16x32_bf16 v[74:77], v[152:155], v[204:207], v[74:77]
	v_mfma_f32_16x16x32_bf16 v[126:129], v[148:151], v[180:183], v[126:129]
	v_mfma_f32_16x16x32_bf16 v[122:125], v[156:159], v[180:183], v[122:125]
	v_mfma_f32_16x16x32_bf16 v[110:113], v[148:151], v[188:191], v[110:113]
	v_mfma_f32_16x16x32_bf16 v[106:109], v[156:159], v[188:191], v[106:109]
	v_mfma_f32_16x16x32_bf16 v[94:97], v[148:151], v[200:203], v[94:97]
	v_mfma_f32_16x16x32_bf16 v[90:93], v[156:159], v[200:203], v[90:93]
	v_mfma_f32_16x16x32_bf16 v[78:81], v[148:151], v[208:211], v[78:81]
	v_mfma_f32_16x16x32_bf16 v[74:77], v[156:159], v[208:211], v[74:77]
	v_mfma_f32_16x16x32_bf16 v[118:121], v[160:163], v[176:179], v[118:121]
	v_mfma_f32_16x16x32_bf16 v[114:117], v[168:171], v[176:179], v[114:117]
	v_mfma_f32_16x16x32_bf16 v[102:105], v[160:163], v[184:187], v[102:105]
	v_mfma_f32_16x16x32_bf16 v[98:101], v[168:171], v[184:187], v[98:101]
	v_mfma_f32_16x16x32_bf16 v[86:89], v[160:163], v[196:199], v[86:89]
	v_mfma_f32_16x16x32_bf16 v[82:85], v[168:171], v[196:199], v[82:85]
	v_mfma_f32_16x16x32_bf16 v[70:73], v[160:163], v[204:207], v[70:73]
	v_mfma_f32_16x16x32_bf16 v[66:69], v[168:171], v[204:207], v[66:69]
	v_mfma_f32_16x16x32_bf16 v[118:121], v[164:167], v[180:183], v[118:121]
	v_mfma_f32_16x16x32_bf16 v[114:117], v[172:175], v[180:183], v[114:117]
	v_mfma_f32_16x16x32_bf16 v[102:105], v[164:167], v[188:191], v[102:105]
	v_mfma_f32_16x16x32_bf16 v[98:101], v[172:175], v[188:191], v[98:101]
	v_mfma_f32_16x16x32_bf16 v[86:89], v[164:167], v[200:203], v[86:89]
	v_mfma_f32_16x16x32_bf16 v[82:85], v[172:175], v[200:203], v[82:85]
	v_mfma_f32_16x16x32_bf16 v[70:73], v[164:167], v[208:211], v[70:73]
	v_mfma_f32_16x16x32_bf16 v[66:69], v[172:175], v[208:211], v[66:69]
	s_setprio 0
	s_barrier
	s_add_i32 s0, s20, s61
	v_lshl_add_u64 v[144:145], s[76:77], 0, v[0:1]
	s_mov_b32 m0, s0
	ds_read_b128 v[176:179], v147 offset:16384
	ds_read_b128 v[180:183], v147 offset:17408
	ds_read_b128 v[184:187], v147 offset:18432
	ds_read_b128 v[188:191], v147 offset:19456
	ds_read_b128 v[196:199], v147 offset:20480
	ds_read_b128 v[200:203], v147 offset:21504
	ds_read_b128 v[204:207], v147 offset:22528
	ds_read_b128 v[208:211], v147 offset:23552
	global_load_lds_dwordx4 v[144:145], off
	s_add_i32 m0, s0, 0x2000
	s_add_u32 s0, s76, 0x40000
	v_lshl_add_u64 v[192:193], s[76:77], 0, v[134:135]
	s_addc_u32 s1, s77, 0
	s_add_i32 s20, s26, s61
	global_load_lds_dwordx4 v[192:193], off
	v_lshl_add_u64 v[212:213], s[0:1], 0, v[0:1]
	s_mov_b32 m0, s20
	v_lshl_add_u64 v[214:215], s[78:79], 0, v[132:133]
	global_load_lds_dwordx4 v[212:213], off
	v_lshl_add_u64 v[212:213], s[0:1], 0, v[134:135]
	s_add_i32 m0, s20, 0x2000
	s_nop 0
	global_load_lds_dwordx4 v[212:213], off
	v_lshl_add_u64 v[212:213], s[78:79], 0, v[130:131]
	s_mov_b32 m0, s62
	s_nop 0
	global_load_lds_dwordx4 v[212:213], off
	s_mov_b32 m0, s80
	s_nop 0
	global_load_lds_dwordx4 v[214:215], off
	s_waitcnt vmcnt(8)
	s_waitcnt lgkmcnt(0)
	s_barrier
; #define PG8_STAGE(bufoff, gbase, voff) do { _Pragma("unroll") for (int _i = 0; _i < 2; ++_i) \
;         __builtin_amdgcn_global_load_lds((const unsigned*)((const char*)(gbase) + (voff)[_i]), (LAS unsigned*)(lds + (bufoff) + ldsw + _i * 8192), 16, 0, 0); } while (0)
; #define PG8_LDA(dst, b, h) do { _Pragma("unroll") for (int m = 0; m < 4; ++m) _Pragma("unroll") for (int k = 0; k < 2; ++k) dst[m][k] = *(const LAS bf16x8*)(lds + PG8_SA(b, h) + aoff + m * 2048 + k * 1024); } while (0)
; #define PG8_LDB(dst, b, h) do { _Pragma("unroll") for (int n = 0; n < 2; ++n) _Pragma("unroll") for (int k = 0; k < 2; ++k) dst[n][k] = *(const LAS bf16x8*)(lds + PG8_SB(b, h) + boff + n * 2048 + k * 1024); } while (0)
; #define PG8_MMA(ai, bj, At, Bt) do { __builtin_amdgcn_s_setprio(1); _Pragma("unroll") for (int m = 0; m < 4; ++m) _Pragma("unroll") for (int n = 0; n < 2; ++n) _Pragma("unroll") for (int k = 0; k < 2; ++k) \
;         acc[ai][bj][m][n] = __builtin_amdgcn_mfma_f32_16x16x32_bf16(Bt[n][k], At[m][k], acc[ai][bj][m][n], 0, 0, 0); __builtin_amdgcn_s_setprio(0); } while (0)
; #define PG8_WAIT_V(n) asm volatile("s_waitcnt vmcnt(" #n ")" ::: "memory")
; #define PG8_WAIT_L(n) asm volatile("s_waitcnt lgkmcnt(" #n ")" ::: "memory")
; #define PG8_BAR __builtin_amdgcn_s_barrier()
; #define PG8_SCHED __builtin_amdgcn_sched_barrier(0)
; template <class Epi, class Sched>
; __device__ __forceinline__ void gemm_phase(LAS unsigned char* lds, const Gemm g, const Sched& S, const Epi& E, int wv) {
;     ...
;             PG8_WAIT_V(8); PG8_WAIT_L(0); PG8_BAR; PG8_MMA(1, 0, At, B0); PG8_MMA(1, 1, At, B1); PG8_BAR; PG8_SCHED;
;             PG8_LDB(B0, 1, 0); PG8_LDB(B1, 1, 1); PG8_SCHED; PG8_LDA(At, 1, 0); PG8_STAGE(PG8_SA(0, 1), a2 + hstepA, voffA);
;             PG8_WAIT_V(8); PG8_WAIT_L(0); PG8_BAR; PG8_MMA(0, 0, At, B0); PG8_MMA(0, 1, At, B1); PG8_BAR; PG8_SCHED;
	s_setprio 1
	v_mfma_f32_16x16x32_bf16 v[62:65], v[140:143], v[176:179], v[62:65]
	v_mfma_f32_16x16x32_bf16 v[58:61], v[152:155], v[176:179], v[58:61]
	v_mfma_f32_16x16x32_bf16 v[46:49], v[140:143], v[184:187], v[46:49]
	v_mfma_f32_16x16x32_bf16 v[42:45], v[152:155], v[184:187], v[42:45]
	v_mfma_f32_16x16x32_bf16 v[30:33], v[140:143], v[196:199], v[30:33]
	v_mfma_f32_16x16x32_bf16 v[26:29], v[152:155], v[196:199], v[26:29]
	v_mfma_f32_16x16x32_bf16 v[14:17], v[140:143], v[204:207], v[14:17]
	v_mfma_f32_16x16x32_bf16 v[10:13], v[152:155], v[204:207], v[10:13]
	v_mfma_f32_16x16x32_bf16 v[62:65], v[148:151], v[180:183], v[62:65]
	v_mfma_f32_16x16x32_bf16 v[58:61], v[156:159], v[180:183], v[58:61]
	v_mfma_f32_16x16x32_bf16 v[46:49], v[148:151], v[188:191], v[46:49]
	v_mfma_f32_16x16x32_bf16 v[42:45], v[156:159], v[188:191], v[42:45]
	v_mfma_f32_16x16x32_bf16 v[30:33], v[148:151], v[200:203], v[30:33]
	v_mfma_f32_16x16x32_bf16 v[26:29], v[156:159], v[200:203], v[26:29]
	v_mfma_f32_16x16x32_bf16 v[14:17], v[148:151], v[208:211], v[14:17]
	v_mfma_f32_16x16x32_bf16 v[10:13], v[156:159], v[208:211], v[10:13]
	v_mfma_f32_16x16x32_bf16 v[54:57], v[160:163], v[176:179], v[54:57]
	v_mfma_f32_16x16x32_bf16 v[50:53], v[168:171], v[176:179], v[50:53]
	v_mfma_f32_16x16x32_bf16 v[38:41], v[160:163], v[184:187], v[38:41]
	v_mfma_f32_16x16x32_bf16 v[34:37], v[168:171], v[184:187], v[34:37]
	v_mfma_f32_16x16x32_bf16 v[22:25], v[160:163], v[196:199], v[22:25]
	v_mfma_f32_16x16x32_bf16 v[18:21], v[168:171], v[196:199], v[18:21]
	v_mfma_f32_16x16x32_bf16 v[6:9], v[160:163], v[204:207], v[6:9]
	v_mfma_f32_16x16x32_bf16 v[2:5], v[168:171], v[204:207], v[2:5]
	v_mfma_f32_16x16x32_bf16 v[54:57], v[164:167], v[180:183], v[54:57]
	v_mfma_f32_16x16x32_bf16 v[50:53], v[172:175], v[180:183], v[50:53]
	v_mfma_f32_16x16x32_bf16 v[38:41], v[164:167], v[188:191], v[38:41]
	v_mfma_f32_16x16x32_bf16 v[34:37], v[172:175], v[188:191], v[34:37]
	v_mfma_f32_16x16x32_bf16 v[22:25], v[164:167], v[200:203], v[22:25]
	v_mfma_f32_16x16x32_bf16 v[18:21], v[172:175], v[200:203], v[18:21]
	v_mfma_f32_16x16x32_bf16 v[6:9], v[164:167], v[208:211], v[6:9]
	v_mfma_f32_16x16x32_bf16 v[2:5], v[172:175], v[208:211], v[2:5]
	s_setprio 0
	s_barrier
	s_add_i32 s20, 0, 0x18000
	s_add_i32 s26, 0, 0x1c000
	v_add_u32_e32 v156, s20, v146
	v_add_u32_e32 v172, s26, v146
	ds_read_b128 v[140:143], v156
	ds_read_b128 v[148:151], v156 offset:1024
	ds_read_b128 v[152:155], v156 offset:2048
	ds_read_b128 v[156:159], v156 offset:3072
	ds_read_b128 v[160:163], v172
	ds_read_b128 v[164:167], v172 offset:1024
	ds_read_b128 v[168:171], v172 offset:2048
	ds_read_b128 v[172:175], v172 offset:3072
	s_add_u32 s0, s78, 0x40000
	s_addc_u32 s1, s79, 0
	s_mov_b32 m0, s81
	v_lshl_add_u64 v[216:217], s[0:1], 0, v[130:131]
	ds_read_b128 v[176:179], v147 offset:32768
	ds_read_b128 v[180:183], v147 offset:33792
	ds_read_b128 v[184:187], v147 offset:34816
	ds_read_b128 v[188:191], v147 offset:35840
	ds_read_b128 v[196:199], v147 offset:36864
	ds_read_b128 v[200:203], v147 offset:37888
	ds_read_b128 v[204:207], v147 offset:38912
	ds_read_b128 v[208:211], v147 offset:39936
	global_load_lds_dwordx4 v[216:217], off
	v_lshl_add_u64 v[216:217], s[0:1], 0, v[132:133]
	s_mov_b32 m0, s82
	s_nop 0
	global_load_lds_dwordx4 v[216:217], off
	s_waitcnt vmcnt(8)
	s_waitcnt lgkmcnt(0)
	s_barrier
	s_setprio 1
	v_mfma_f32_16x16x32_bf16 v[126:129], v[140:143], v[176:179], v[126:129]
	v_mfma_f32_16x16x32_bf16 v[122:125], v[152:155], v[176:179], v[122:125]
	v_mfma_f32_16x16x32_bf16 v[110:113], v[140:143], v[184:187], v[110:113]
	v_mfma_f32_16x16x32_bf16 v[106:109], v[152:155], v[184:187], v[106:109]
	v_mfma_f32_16x16x32_bf16 v[94:97], v[140:143], v[196:199], v[94:97]
	v_mfma_f32_16x16x32_bf16 v[90:93], v[152:155], v[196:199], v[90:93]
	v_mfma_f32_16x16x32_bf16 v[78:81], v[140:143], v[204:207], v[78:81]
	v_mfma_f32_16x16x32_bf16 v[74:77], v[152:155], v[204:207], v[74:77]
	v_mfma_f32_16x16x32_bf16 v[126:129], v[148:151], v[180:183], v[126:129]
	v_mfma_f32_16x16x32_bf16 v[122:125], v[156:159], v[180:183], v[122:125]
	v_mfma_f32_16x16x32_bf16 v[110:113], v[148:151], v[188:191], v[110:113]
	v_mfma_f32_16x16x32_bf16 v[106:109], v[156:159], v[188:191], v[106:109]
	v_mfma_f32_16x16x32_bf16 v[94:97], v[148:151], v[200:203], v[94:97]
	v_mfma_f32_16x16x32_bf16 v[90:93], v[156:159], v[200:203], v[90:93]
	v_mfma_f32_16x16x32_bf16 v[78:81], v[148:151], v[208:211], v[78:81]
	v_mfma_f32_16x16x32_bf16 v[74:77], v[156:159], v[208:211], v[74:77]
	v_mfma_f32_16x16x32_bf16 v[118:121], v[160:163], v[176:179], v[118:121]
	v_mfma_f32_16x16x32_bf16 v[114:117], v[168:171], v[176:179], v[114:117]
	v_mfma_f32_16x16x32_bf16 v[102:105], v[160:163], v[184:187], v[102:105]
	v_mfma_f32_16x16x32_bf16 v[98:101], v[168:171], v[184:187], v[98:101]
	v_mfma_f32_16x16x32_bf16 v[86:89], v[160:163], v[196:199], v[86:89]
	v_mfma_f32_16x16x32_bf16 v[82:85], v[168:171], v[196:199], v[82:85]
	v_mfma_f32_16x16x32_bf16 v[70:73], v[160:163], v[204:207], v[70:73]
	v_mfma_f32_16x16x32_bf16 v[66:69], v[168:171], v[204:207], v[66:69]
	v_mfma_f32_16x16x32_bf16 v[118:121], v[164:167], v[180:183], v[118:121]
	v_mfma_f32_16x16x32_bf16 v[114:117], v[172:175], v[180:183], v[114:117]
	v_mfma_f32_16x16x32_bf16 v[102:105], v[164:167], v[188:191], v[102:105]
	v_mfma_f32_16x16x32_bf16 v[98:101], v[172:175], v[188:191], v[98:101]
	v_mfma_f32_16x16x32_bf16 v[86:89], v[164:167], v[200:203], v[86:89]
	v_mfma_f32_16x16x32_bf16 v[82:85], v[172:175], v[200:203], v[82:85]
	v_mfma_f32_16x16x32_bf16 v[70:73], v[164:167], v[208:211], v[70:73]
	v_mfma_f32_16x16x32_bf16 v[66:69], v[172:175], v[208:211], v[66:69]
	s_setprio 0
	s_barrier
; #define PG8_STAGE(bufoff, gbase, voff) do { _Pragma("unroll") for (int _i = 0; _i < 2; ++_i) \
;         __builtin_amdgcn_global_load_lds((const unsigned*)((const char*)(gbase) + (voff)[_i]), (LAS unsigned*)(lds + (bufoff) + ldsw + _i * 8192), 16, 0, 0); } while (0)
; #define PG8_LDA(dst, b, h) do { _Pragma("unroll") for (int m = 0; m < 4; ++m) _Pragma("unroll") for (int k = 0; k < 2; ++k) dst[m][k] = *(const LAS bf16x8*)(lds + PG8_SA(b, h) + aoff + m * 2048 + k * 1024); } while (0)
; #define PG8_MMA(ai, bj, At, Bt) do { __builtin_amdgcn_s_setprio(1); _Pragma("unroll") for (int m = 0; m < 4; ++m) _Pragma("unroll") for (int n = 0; n < 2; ++n) _Pragma("unroll") for (int k = 0; k < 2; ++k) \
;         acc[ai][bj][m][n] = __builtin_amdgcn_mfma_f32_16x16x32_bf16(Bt[n][k], At[m][k], acc[ai][bj][m][n], 0, 0, 0); __builtin_amdgcn_s_setprio(0); } while (0)
; #define PG8_WAIT_V(n) asm volatile("s_waitcnt vmcnt(" #n ")" ::: "memory")
; #define PG8_WAIT_L(n) asm volatile("s_waitcnt lgkmcnt(" #n ")" ::: "memory")
; #define PG8_BAR __builtin_amdgcn_s_barrier()
; #define PG8_SCHED __builtin_amdgcn_sched_barrier(0)
; template <class Epi, class Sched>
; __device__ __forceinline__ void gemm_phase(LAS unsigned char* lds, const Gemm g, const Sched& S, const Epi& E, int wv) {
;     ...
;             PG8_LDA(At, 1, 1); PG8_STAGE(PG8_SB(1, 0), b3, voffB); PG8_STAGE(PG8_SB(1, 1), b3 + hstepB, voffB); PG8_STAGE(PG8_SA(1, 0), a3, voffA);
;             PG8_WAIT_V(8); PG8_WAIT_L(0); PG8_BAR; PG8_MMA(1, 0, At, B0); PG8_MMA(1, 1, At, B1); PG8_BAR; PG8_SCHED;
;         }
;         if (wr == 0) PG8_BAR;
	s_add_i32 s0, s20, s61
	v_lshl_add_u64 v[144:145], v[144:145], 0, s[24:25]
	s_mov_b32 m0, s0
	ds_read_b128 v[176:179], v147 offset:49152
	ds_read_b128 v[180:183], v147 offset:50176
	ds_read_b128 v[184:187], v147 offset:51200
	ds_read_b128 v[188:191], v147 offset:52224
	ds_read_b128 v[196:199], v147 offset:53248
	ds_read_b128 v[200:203], v147 offset:54272
	ds_read_b128 v[204:207], v147 offset:55296
	ds_read_b128 v[208:211], v147 offset:56320
	global_load_lds_dwordx4 v[144:145], off
	s_add_i32 m0, s0, 0x2000
	s_add_u32 s0, s76, 0x40080
	v_lshl_add_u64 v[144:145], v[192:193], 0, s[24:25]
	s_addc_u32 s1, s77, 0
	s_add_i32 s20, s26, s61
	global_load_lds_dwordx4 v[144:145], off
	v_lshl_add_u64 v[144:145], s[0:1], 0, v[0:1]
	s_mov_b32 m0, s20
	s_nop 0
	global_load_lds_dwordx4 v[144:145], off
	v_lshl_add_u64 v[144:145], s[0:1], 0, v[134:135]
	s_add_i32 m0, s20, 0x2000
	s_nop 0
	global_load_lds_dwordx4 v[144:145], off
	v_lshl_add_u64 v[144:145], v[212:213], 0, s[24:25]
	s_mov_b32 m0, s86
	s_nop 0
	global_load_lds_dwordx4 v[144:145], off
	v_lshl_add_u64 v[144:145], v[214:215], 0, s[24:25]
	s_mov_b32 m0, s87
	s_nop 0
	global_load_lds_dwordx4 v[144:145], off
	s_waitcnt vmcnt(8)
	s_waitcnt lgkmcnt(0)
	s_barrier
	s_setprio 1
	v_mfma_f32_16x16x32_bf16 v[62:65], v[140:143], v[176:179], v[62:65]
	v_mfma_f32_16x16x32_bf16 v[58:61], v[152:155], v[176:179], v[58:61]
	v_mfma_f32_16x16x32_bf16 v[46:49], v[140:143], v[184:187], v[46:49]
	v_mfma_f32_16x16x32_bf16 v[42:45], v[152:155], v[184:187], v[42:45]
	v_mfma_f32_16x16x32_bf16 v[30:33], v[140:143], v[196:199], v[30:33]
	v_mfma_f32_16x16x32_bf16 v[26:29], v[152:155], v[196:199], v[26:29]
	v_mfma_f32_16x16x32_bf16 v[14:17], v[140:143], v[204:207], v[14:17]
	v_mfma_f32_16x16x32_bf16 v[10:13], v[152:155], v[204:207], v[10:13]
	v_mfma_f32_16x16x32_bf16 v[62:65], v[148:151], v[180:183], v[62:65]
	v_mfma_f32_16x16x32_bf16 v[58:61], v[156:159], v[180:183], v[58:61]
	v_mfma_f32_16x16x32_bf16 v[46:49], v[148:151], v[188:191], v[46:49]
	v_mfma_f32_16x16x32_bf16 v[42:45], v[156:159], v[188:191], v[42:45]
	v_mfma_f32_16x16x32_bf16 v[30:33], v[148:151], v[200:203], v[30:33]
	v_mfma_f32_16x16x32_bf16 v[26:29], v[156:159], v[200:203], v[26:29]
	v_mfma_f32_16x16x32_bf16 v[14:17], v[148:151], v[208:211], v[14:17]
	v_mfma_f32_16x16x32_bf16 v[10:13], v[156:159], v[208:211], v[10:13]
	v_mfma_f32_16x16x32_bf16 v[54:57], v[160:163], v[176:179], v[54:57]
	v_mfma_f32_16x16x32_bf16 v[50:53], v[168:171], v[176:179], v[50:53]
	v_mfma_f32_16x16x32_bf16 v[38:41], v[160:163], v[184:187], v[38:41]
	v_mfma_f32_16x16x32_bf16 v[34:37], v[168:171], v[184:187], v[34:37]
	v_mfma_f32_16x16x32_bf16 v[22:25], v[160:163], v[196:199], v[22:25]
	v_mfma_f32_16x16x32_bf16 v[18:21], v[168:171], v[196:199], v[18:21]
	v_mfma_f32_16x16x32_bf16 v[6:9], v[160:163], v[204:207], v[6:9]
	v_mfma_f32_16x16x32_bf16 v[2:5], v[168:171], v[204:207], v[2:5]
	v_mfma_f32_16x16x32_bf16 v[54:57], v[164:167], v[180:183], v[54:57]
	v_mfma_f32_16x16x32_bf16 v[50:53], v[172:175], v[180:183], v[50:53]
	v_mfma_f32_16x16x32_bf16 v[38:41], v[164:167], v[188:191], v[38:41]
	v_mfma_f32_16x16x32_bf16 v[34:37], v[172:175], v[188:191], v[34:37]
	v_mfma_f32_16x16x32_bf16 v[22:25], v[164:167], v[200:203], v[22:25]
	v_mfma_f32_16x16x32_bf16 v[18:21], v[172:175], v[200:203], v[18:21]
	v_mfma_f32_16x16x32_bf16 v[6:9], v[164:167], v[208:211], v[6:9]
	v_mfma_f32_16x16x32_bf16 v[2:5], v[172:175], v[208:211], v[2:5]
	s_setprio 0
	s_barrier
	s_add_i32 s56, s56, 2
	s_add_u32 s74, s74, 0x100
	s_addc_u32 s75, s75, 0
	s_add_u32 s34, s34, 0x100
	s_addc_u32 s35, s35, 0
	s_cmp_gt_u32 s56, 13
	s_cbranch_scc0 .LBB0_252
	s_and_b64 vcc, exec, s[12:13]
	s_cbranch_vccz .LBB0_255
	s_barrier

; #define PG8_STAGE(bufoff, gbase, voff) do { _Pragma("unroll") for (int _i = 0; _i < 2; ++_i) \
;         __builtin_amdgcn_global_load_lds((const unsigned*)((const char*)(gbase) + (voff)[_i]), (LAS unsigned*)(lds + (bufoff) + ldsw + _i * 8192), 16, 0, 0); } while (0)
; #define PG8_LDA(dst, b, h) do { _Pragma("unroll") for (int m = 0; m < 4; ++m) _Pragma("unroll") for (int k = 0; k < 2; ++k) dst[m][k] = *(const LAS bf16x8*)(lds + PG8_SA(b, h) + aoff + m * 2048 + k * 1024); } while (0)
; #define PG8_LDB(dst, b, h) do { _Pragma("unroll") for (int n = 0; n < 2; ++n) _Pragma("unroll") for (int k = 0; k < 2; ++k) dst[n][k] = *(const LAS bf16x8*)(lds + PG8_SB(b, h) + boff + n * 2048 + k * 1024); } while (0)
; #define PG8_MMA(ai, bj, At, Bt) do { __builtin_amdgcn_s_setprio(1); _Pragma("unroll") for (int m = 0; m < 4; ++m) _Pragma("unroll") for (int n = 0; n < 2; ++n) _Pragma("unroll") for (int k = 0; k < 2; ++k) \
;         acc[ai][bj][m][n] = __builtin_amdgcn_mfma_f32_16x16x32_bf16(Bt[n][k], At[m][k], acc[ai][bj][m][n], 0, 0, 0); __builtin_amdgcn_s_setprio(0); } while (0)
; #define PG8_WAIT_V(n) asm volatile("s_waitcnt vmcnt(" #n ")" ::: "memory")
; template <class Epi, class Sched>
; __device__ __forceinline__ void gemm_phase(LAS unsigned char* lds, const Gemm g, const Sched& S, const Epi& E, int wv) {
;     ...
;         const char* nA = has_next ? (const char*)g.A + (size_t)nxt.pm * tstepA + (size_t)nxt.ak * 2 : cA; const char* nB = has_next ? (const char*)g.Bt + (size_t)nxt.pn * tstepB : cB;
;         for (int t = 0; t < nt; t += 2) {
;             const bool last = (t == nt - 2);
;             const char* a1 = cA + (size_t)(t + 1) * kstep;
;             const char* a2 = last ? nA : cA + (size_t)(t + 2) * kstep; const char* b2 = last ? nB : cB + (size_t)(t + 2) * kstep;
;             const char* a3 = a2 + kstep; const char* b3 = b2 + kstep;
;             PG8_LDB(B0, 0, 0); PG8_LDB(B1, 0, 1); PG8_SCHED; PG8_LDA(At, 0, 0); PG8_STAGE(PG8_SA(1, 1), a1 + hstepA, voffA);
;             PG8_WAIT_V(8); PG8_WAIT_L(0); PG8_BAR; PG8_MMA(0, 0, At, B0); PG8_MMA(0, 1, At, B1); PG8_BAR; PG8_SCHED;
;             PG8_LDA(At, 0, 1); PG8_STAGE(PG8_SB(0, 0), b2, voffB); PG8_STAGE(PG8_SB(0, 1), b2 + hstepB, voffB); PG8_STAGE(PG8_SA(0, 0), a2, voffA);
;             PG8_WAIT_V(8); PG8_WAIT_L(0); PG8_BAR; PG8_MMA(1, 0, At, B0); PG8_MMA(1, 1, At, B1); PG8_BAR; PG8_SCHED;
.LBB0_304:
	s_add_u32 s0, s74, 0xfffc0080
	s_addc_u32 s1, s75, -1
	s_add_i32 s20, 0, 0x10000
	s_cmp_eq_u32 s35, 12
	s_cselect_b32 s81, s5, s1
	s_cselect_b32 s80, s10, s0
	v_add_u32_e32 v0, s20, v184
	s_cselect_b32 s79, s11, s34
	s_cselect_b32 s78, s21, s31
	s_add_i32 s26, 0, 0x14000
	ds_read_b128 v[130:133], v0
	ds_read_b128 v[134:137], v0 offset:1024
	ds_read_b128 v[150:153], v0 offset:2048
	ds_read_b128 v[154:157], v0 offset:3072
	v_add_u32_e32 v0, s26, v184
	ds_read_b128 v[158:161], v0
	ds_read_b128 v[162:165], v0 offset:1024
	ds_read_b128 v[166:169], v0 offset:2048
	ds_read_b128 v[170:173], v0 offset:3072
	v_lshl_add_u64 v[182:183], s[74:75], 0, v[146:147]
	s_add_i32 m0, s61, 0xc000
	ds_read_b128 v[174:177], v185
	ds_read_b128 v[178:181], v185 offset:1024
	ds_read_b128 v[186:189], v185 offset:2048
	ds_read_b128 v[190:193], v185 offset:3072
	ds_read_b128 v[196:199], v185 offset:4096
	ds_read_b128 v[200:203], v185 offset:5120
	ds_read_b128 v[204:207], v185 offset:6144
	ds_read_b128 v[208:211], v185 offset:7168
	global_load_lds_dwordx4 v[182:183], off
	v_lshl_add_u64 v[182:183], s[74:75], 0, v[148:149]
	s_add_i32 m0, s61, 0xe000
	s_nop 0
	global_load_lds_dwordx4 v[182:183], off
	s_waitcnt vmcnt(8)
	s_waitcnt lgkmcnt(0)
	s_barrier
	s_setprio 1
	v_mfma_f32_16x16x32_bf16 v[126:129], v[130:133], v[174:177], v[126:129]
	v_mfma_f32_16x16x32_bf16 v[122:125], v[150:153], v[174:177], v[122:125]
	v_mfma_f32_16x16x32_bf16 v[110:113], v[130:133], v[186:189], v[110:113]
	v_mfma_f32_16x16x32_bf16 v[106:109], v[150:153], v[186:189], v[106:109]
	v_mfma_f32_16x16x32_bf16 v[94:97], v[130:133], v[196:199], v[94:97]
	v_mfma_f32_16x16x32_bf16 v[90:93], v[150:153], v[196:199], v[90:93]
	v_mfma_f32_16x16x32_bf16 v[78:81], v[130:133], v[204:207], v[78:81]
	v_mfma_f32_16x16x32_bf16 v[74:77], v[150:153], v[204:207], v[74:77]
	v_mfma_f32_16x16x32_bf16 v[126:129], v[134:137], v[178:181], v[126:129]
	v_mfma_f32_16x16x32_bf16 v[122:125], v[154:157], v[178:181], v[122:125]
	v_mfma_f32_16x16x32_bf16 v[110:113], v[134:137], v[190:193], v[110:113]
	v_mfma_f32_16x16x32_bf16 v[106:109], v[154:157], v[190:193], v[106:109]
	v_mfma_f32_16x16x32_bf16 v[94:97], v[134:137], v[200:203], v[94:97]
	v_mfma_f32_16x16x32_bf16 v[90:93], v[154:157], v[200:203], v[90:93]
	v_mfma_f32_16x16x32_bf16 v[78:81], v[134:137], v[208:211], v[78:81]
	v_mfma_f32_16x16x32_bf16 v[74:77], v[154:157], v[208:211], v[74:77]
	v_mfma_f32_16x16x32_bf16 v[118:121], v[158:161], v[174:177], v[118:121]
	v_mfma_f32_16x16x32_bf16 v[114:117], v[166:169], v[174:177], v[114:117]
	v_mfma_f32_16x16x32_bf16 v[102:105], v[158:161], v[186:189], v[102:105]
	v_mfma_f32_16x16x32_bf16 v[98:101], v[166:169], v[186:189], v[98:101]
	v_mfma_f32_16x16x32_bf16 v[86:89], v[158:161], v[196:199], v[86:89]
	v_mfma_f32_16x16x32_bf16 v[82:85], v[166:169], v[196:199], v[82:85]
	v_mfma_f32_16x16x32_bf16 v[70:73], v[158:161], v[204:207], v[70:73]
	v_mfma_f32_16x16x32_bf16 v[66:69], v[166:169], v[204:207], v[66:69]
	v_mfma_f32_16x16x32_bf16 v[118:121], v[162:165], v[178:181], v[118:121]
	v_mfma_f32_16x16x32_bf16 v[114:117], v[170:173], v[178:181], v[114:117]
	v_mfma_f32_16x16x32_bf16 v[102:105], v[162:165], v[190:193], v[102:105]
	v_mfma_f32_16x16x32_bf16 v[98:101], v[170:173], v[190:193], v[98:101]
	v_mfma_f32_16x16x32_bf16 v[86:89], v[162:165], v[200:203], v[86:89]
	v_mfma_f32_16x16x32_bf16 v[82:85], v[170:173], v[200:203], v[82:85]
	v_mfma_f32_16x16x32_bf16 v[70:73], v[162:165], v[208:211], v[70:73]
	v_mfma_f32_16x16x32_bf16 v[66:69], v[170:173], v[208:211], v[66:69]
	s_setprio 0
	s_barrier
	s_add_i32 s0, s20, s60
	v_lshl_add_u64 v[182:183], s[78:79], 0, v[140:141]
	s_mov_b32 m0, s0
	ds_read_b128 v[174:177], v185 offset:16384
	ds_read_b128 v[178:181], v185 offset:17408
	ds_read_b128 v[186:189], v185 offset:18432
	ds_read_b128 v[190:193], v185 offset:19456
	ds_read_b128 v[196:199], v185 offset:20480
	ds_read_b128 v[200:203], v185 offset:21504
	ds_read_b128 v[204:207], v185 offset:22528
	ds_read_b128 v[208:211], v185 offset:23552
	global_load_lds_dwordx4 v[182:183], off
	s_add_i32 m0, s0, 0x2000
	s_add_u32 s0, s78, 0x40000
	v_lshl_add_u64 v[212:213], s[78:79], 0, v[144:145]
	s_addc_u32 s1, s79, 0
	s_add_i32 s20, s26, s60
	global_load_lds_dwordx4 v[212:213], off
	v_lshl_add_u64 v[214:215], s[0:1], 0, v[140:141]
	s_mov_b32 m0, s20
	v_lshl_add_u64 v[216:217], s[80:81], 0, v[142:143]
	global_load_lds_dwordx4 v[214:215], off
	v_lshl_add_u64 v[214:215], s[0:1], 0, v[144:145]
	s_add_i32 m0, s20, 0x2000
	s_nop 0
	global_load_lds_dwordx4 v[214:215], off
	v_lshl_add_u64 v[214:215], s[80:81], 0, v[138:139]
	s_mov_b32 m0, s61
	s_nop 0
	global_load_lds_dwordx4 v[214:215], off
	s_mov_b32 m0, s62
	s_nop 0
	global_load_lds_dwordx4 v[216:217], off
	s_waitcnt vmcnt(8)
	s_waitcnt lgkmcnt(0)
	s_barrier
; #define PG8_STAGE(bufoff, gbase, voff) do { _Pragma("unroll") for (int _i = 0; _i < 2; ++_i) \
;         __builtin_amdgcn_global_load_lds((const unsigned*)((const char*)(gbase) + (voff)[_i]), (LAS unsigned*)(lds + (bufoff) + ldsw + _i * 8192), 16, 0, 0); } while (0)
; #define PG8_LDA(dst, b, h) do { _Pragma("unroll") for (int m = 0; m < 4; ++m) _Pragma("unroll") for (int k = 0; k < 2; ++k) dst[m][k] = *(const LAS bf16x8*)(lds + PG8_SA(b, h) + aoff + m * 2048 + k * 1024); } while (0)
; #define PG8_LDB(dst, b, h) do { _Pragma("unroll") for (int n = 0; n < 2; ++n) _Pragma("unroll") for (int k = 0; k < 2; ++k) dst[n][k] = *(const LAS bf16x8*)(lds + PG8_SB(b, h) + boff + n * 2048 + k * 1024); } while (0)
; #define PG8_MMA(ai, bj, At, Bt) do { __builtin_amdgcn_s_setprio(1); _Pragma("unroll") for (int m = 0; m < 4; ++m) _Pragma("unroll") for (int n = 0; n < 2; ++n) _Pragma("unroll") for (int k = 0; k < 2; ++k) \
;         acc[ai][bj][m][n] = __builtin_amdgcn_mfma_f32_16x16x32_bf16(Bt[n][k], At[m][k], acc[ai][bj][m][n], 0, 0, 0); __builtin_amdgcn_s_setprio(0); } while (0)
; #define PG8_WAIT_V(n) asm volatile("s_waitcnt vmcnt(" #n ")" ::: "memory")
; #define PG8_WAIT_L(n) asm volatile("s_waitcnt lgkmcnt(" #n ")" ::: "memory")
; #define PG8_BAR __builtin_amdgcn_s_barrier()
; #define PG8_SCHED __builtin_amdgcn_sched_barrier(0)
; template <class Epi, class Sched>
; __device__ __forceinline__ void gemm_phase(LAS unsigned char* lds, const Gemm g, const Sched& S, const Epi& E, int wv) {
;     ...
;             PG8_WAIT_V(8); PG8_WAIT_L(0); PG8_BAR; PG8_MMA(1, 0, At, B0); PG8_MMA(1, 1, At, B1); PG8_BAR; PG8_SCHED;
;             PG8_LDB(B0, 1, 0); PG8_LDB(B1, 1, 1); PG8_SCHED; PG8_LDA(At, 1, 0); PG8_STAGE(PG8_SA(0, 1), a2 + hstepA, voffA);
;             PG8_WAIT_V(8); PG8_WAIT_L(0); PG8_BAR; PG8_MMA(0, 0, At, B0); PG8_MMA(0, 1, At, B1); PG8_BAR; PG8_SCHED;
	s_setprio 1
	v_mfma_f32_16x16x32_bf16 v[62:65], v[130:133], v[174:177], v[62:65]
	v_mfma_f32_16x16x32_bf16 v[58:61], v[150:153], v[174:177], v[58:61]
	v_mfma_f32_16x16x32_bf16 v[46:49], v[130:133], v[186:189], v[46:49]
	v_mfma_f32_16x16x32_bf16 v[42:45], v[150:153], v[186:189], v[42:45]
	v_mfma_f32_16x16x32_bf16 v[30:33], v[130:133], v[196:199], v[30:33]
	v_mfma_f32_16x16x32_bf16 v[26:29], v[150:153], v[196:199], v[26:29]
	v_mfma_f32_16x16x32_bf16 v[14:17], v[130:133], v[204:207], v[14:17]
	v_mfma_f32_16x16x32_bf16 v[10:13], v[150:153], v[204:207], v[10:13]
	v_mfma_f32_16x16x32_bf16 v[62:65], v[134:137], v[178:181], v[62:65]
	v_mfma_f32_16x16x32_bf16 v[58:61], v[154:157], v[178:181], v[58:61]
	v_mfma_f32_16x16x32_bf16 v[46:49], v[134:137], v[190:193], v[46:49]
	v_mfma_f32_16x16x32_bf16 v[42:45], v[154:157], v[190:193], v[42:45]
	v_mfma_f32_16x16x32_bf16 v[30:33], v[134:137], v[200:203], v[30:33]
	v_mfma_f32_16x16x32_bf16 v[26:29], v[154:157], v[200:203], v[26:29]
	v_mfma_f32_16x16x32_bf16 v[14:17], v[134:137], v[208:211], v[14:17]
	v_mfma_f32_16x16x32_bf16 v[10:13], v[154:157], v[208:211], v[10:13]
	v_mfma_f32_16x16x32_bf16 v[54:57], v[158:161], v[174:177], v[54:57]
	v_mfma_f32_16x16x32_bf16 v[50:53], v[166:169], v[174:177], v[50:53]
	v_mfma_f32_16x16x32_bf16 v[38:41], v[158:161], v[186:189], v[38:41]
	v_mfma_f32_16x16x32_bf16 v[34:37], v[166:169], v[186:189], v[34:37]
	v_mfma_f32_16x16x32_bf16 v[22:25], v[158:161], v[196:199], v[22:25]
	v_mfma_f32_16x16x32_bf16 v[18:21], v[166:169], v[196:199], v[18:21]
	v_mfma_f32_16x16x32_bf16 v[6:9], v[158:161], v[204:207], v[6:9]
	v_mfma_f32_16x16x32_bf16 v[2:5], v[166:169], v[204:207], v[2:5]
	v_mfma_f32_16x16x32_bf16 v[54:57], v[162:165], v[178:181], v[54:57]
	v_mfma_f32_16x16x32_bf16 v[50:53], v[170:173], v[178:181], v[50:53]
	v_mfma_f32_16x16x32_bf16 v[38:41], v[162:165], v[190:193], v[38:41]
	v_mfma_f32_16x16x32_bf16 v[34:37], v[170:173], v[190:193], v[34:37]
	v_mfma_f32_16x16x32_bf16 v[22:25], v[162:165], v[200:203], v[22:25]
	v_mfma_f32_16x16x32_bf16 v[18:21], v[170:173], v[200:203], v[18:21]
	v_mfma_f32_16x16x32_bf16 v[6:9], v[162:165], v[208:211], v[6:9]
	v_mfma_f32_16x16x32_bf16 v[2:5], v[170:173], v[208:211], v[2:5]
	s_setprio 0
	s_barrier
	s_add_i32 s20, 0, 0x18000
	v_add_u32_e32 v0, s20, v184
	s_add_i32 s26, 0, 0x1c000
	ds_read_b128 v[130:133], v0
	ds_read_b128 v[134:137], v0 offset:1024
	ds_read_b128 v[150:153], v0 offset:2048
	ds_read_b128 v[154:157], v0 offset:3072
	v_add_u32_e32 v0, s26, v184
	ds_read_b128 v[158:161], v0
	ds_read_b128 v[162:165], v0 offset:1024
	ds_read_b128 v[166:169], v0 offset:2048
	ds_read_b128 v[170:173], v0 offset:3072
	s_add_u32 s0, s80, 0x40000
	s_addc_u32 s1, s81, 0
	s_mov_b32 m0, s82
	v_lshl_add_u64 v[218:219], s[0:1], 0, v[138:139]
	ds_read_b128 v[174:177], v185 offset:32768
	ds_read_b128 v[178:181], v185 offset:33792
	ds_read_b128 v[186:189], v185 offset:34816
	ds_read_b128 v[190:193], v185 offset:35840
	ds_read_b128 v[196:199], v185 offset:36864
	ds_read_b128 v[200:203], v185 offset:37888
	ds_read_b128 v[204:207], v185 offset:38912
	ds_read_b128 v[208:211], v185 offset:39936
	global_load_lds_dwordx4 v[218:219], off
	v_lshl_add_u64 v[218:219], s[0:1], 0, v[142:143]
	s_mov_b32 m0, s83
	s_nop 0
	global_load_lds_dwordx4 v[218:219], off
	s_waitcnt vmcnt(8)
	s_waitcnt lgkmcnt(0)
	s_barrier
	s_setprio 1
	v_mfma_f32_16x16x32_bf16 v[126:129], v[130:133], v[174:177], v[126:129]
	v_mfma_f32_16x16x32_bf16 v[122:125], v[150:153], v[174:177], v[122:125]
	v_mfma_f32_16x16x32_bf16 v[110:113], v[130:133], v[186:189], v[110:113]
	v_mfma_f32_16x16x32_bf16 v[106:109], v[150:153], v[186:189], v[106:109]
	v_mfma_f32_16x16x32_bf16 v[94:97], v[130:133], v[196:199], v[94:97]
	v_mfma_f32_16x16x32_bf16 v[90:93], v[150:153], v[196:199], v[90:93]
	v_mfma_f32_16x16x32_bf16 v[78:81], v[130:133], v[204:207], v[78:81]
	v_mfma_f32_16x16x32_bf16 v[74:77], v[150:153], v[204:207], v[74:77]
	v_mfma_f32_16x16x32_bf16 v[126:129], v[134:137], v[178:181], v[126:129]
	v_mfma_f32_16x16x32_bf16 v[122:125], v[154:157], v[178:181], v[122:125]
	v_mfma_f32_16x16x32_bf16 v[110:113], v[134:137], v[190:193], v[110:113]
	v_mfma_f32_16x16x32_bf16 v[106:109], v[154:157], v[190:193], v[106:109]
	v_mfma_f32_16x16x32_bf16 v[94:97], v[134:137], v[200:203], v[94:97]
	v_mfma_f32_16x16x32_bf16 v[90:93], v[154:157], v[200:203], v[90:93]
	v_mfma_f32_16x16x32_bf16 v[78:81], v[134:137], v[208:211], v[78:81]
	v_mfma_f32_16x16x32_bf16 v[74:77], v[154:157], v[208:211], v[74:77]
	v_mfma_f32_16x16x32_bf16 v[118:121], v[158:161], v[174:177], v[118:121]
	v_mfma_f32_16x16x32_bf16 v[114:117], v[166:169], v[174:177], v[114:117]
	v_mfma_f32_16x16x32_bf16 v[102:105], v[158:161], v[186:189], v[102:105]
	v_mfma_f32_16x16x32_bf16 v[98:101], v[166:169], v[186:189], v[98:101]
	v_mfma_f32_16x16x32_bf16 v[86:89], v[158:161], v[196:199], v[86:89]
	v_mfma_f32_16x16x32_bf16 v[82:85], v[166:169], v[196:199], v[82:85]
	v_mfma_f32_16x16x32_bf16 v[70:73], v[158:161], v[204:207], v[70:73]
	v_mfma_f32_16x16x32_bf16 v[66:69], v[166:169], v[204:207], v[66:69]
	v_mfma_f32_16x16x32_bf16 v[118:121], v[162:165], v[178:181], v[118:121]
	v_mfma_f32_16x16x32_bf16 v[114:117], v[170:173], v[178:181], v[114:117]
	v_mfma_f32_16x16x32_bf16 v[102:105], v[162:165], v[190:193], v[102:105]
	v_mfma_f32_16x16x32_bf16 v[98:101], v[170:173], v[190:193], v[98:101]
	v_mfma_f32_16x16x32_bf16 v[86:89], v[162:165], v[200:203], v[86:89]
	v_mfma_f32_16x16x32_bf16 v[82:85], v[170:173], v[200:203], v[82:85]
	v_mfma_f32_16x16x32_bf16 v[70:73], v[162:165], v[208:211], v[70:73]
	v_mfma_f32_16x16x32_bf16 v[66:69], v[170:173], v[208:211], v[66:69]
	s_setprio 0
	s_barrier
; #define PG8_STAGE(bufoff, gbase, voff) do { _Pragma("unroll") for (int _i = 0; _i < 2; ++_i) \
;         __builtin_amdgcn_global_load_lds((const unsigned*)((const char*)(gbase) + (voff)[_i]), (LAS unsigned*)(lds + (bufoff) + ldsw + _i * 8192), 16, 0, 0); } while (0)
; #define PG8_LDA(dst, b, h) do { _Pragma("unroll") for (int m = 0; m < 4; ++m) _Pragma("unroll") for (int k = 0; k < 2; ++k) dst[m][k] = *(const LAS bf16x8*)(lds + PG8_SA(b, h) + aoff + m * 2048 + k * 1024); } while (0)
; #define PG8_MMA(ai, bj, At, Bt) do { __builtin_amdgcn_s_setprio(1); _Pragma("unroll") for (int m = 0; m < 4; ++m) _Pragma("unroll") for (int n = 0; n < 2; ++n) _Pragma("unroll") for (int k = 0; k < 2; ++k) \
;         acc[ai][bj][m][n] = __builtin_amdgcn_mfma_f32_16x16x32_bf16(Bt[n][k], At[m][k], acc[ai][bj][m][n], 0, 0, 0); __builtin_amdgcn_s_setprio(0); } while (0)
; #define PG8_WAIT_V(n) asm volatile("s_waitcnt vmcnt(" #n ")" ::: "memory")
; #define PG8_WAIT_L(n) asm volatile("s_waitcnt lgkmcnt(" #n ")" ::: "memory")
; #define PG8_BAR __builtin_amdgcn_s_barrier()
; #define PG8_SCHED __builtin_amdgcn_sched_barrier(0)
; template <class Epi, class Sched>
; __device__ __forceinline__ void gemm_phase(LAS unsigned char* lds, const Gemm g, const Sched& S, const Epi& E, int wv) {
;     ...
;             PG8_LDA(At, 1, 1); PG8_STAGE(PG8_SB(1, 0), b3, voffB); PG8_STAGE(PG8_SB(1, 1), b3 + hstepB, voffB); PG8_STAGE(PG8_SA(1, 0), a3, voffA);
;             PG8_WAIT_V(8); PG8_WAIT_L(0); PG8_BAR; PG8_MMA(1, 0, At, B0); PG8_MMA(1, 1, At, B1); PG8_BAR; PG8_SCHED;
;         }
;         if (wr == 0) PG8_BAR;
	s_add_i32 s0, s20, s60
	v_lshl_add_u64 v[182:183], v[182:183], 0, s[24:25]
	s_mov_b32 m0, s0
	ds_read_b128 v[174:177], v185 offset:49152
	ds_read_b128 v[178:181], v185 offset:50176
	ds_read_b128 v[186:189], v185 offset:51200
	ds_read_b128 v[190:193], v185 offset:52224
	ds_read_b128 v[196:199], v185 offset:53248
	ds_read_b128 v[200:203], v185 offset:54272
	ds_read_b128 v[204:207], v185 offset:55296
	ds_read_b128 v[208:211], v185 offset:56320
	global_load_lds_dwordx4 v[182:183], off
	s_add_i32 m0, s0, 0x2000
	s_add_u32 s0, s78, 0x40080
	v_lshl_add_u64 v[182:183], v[212:213], 0, s[24:25]
	s_addc_u32 s1, s79, 0
	s_add_i32 s20, s26, s60
	global_load_lds_dwordx4 v[182:183], off
	v_lshl_add_u64 v[182:183], s[0:1], 0, v[140:141]
	s_mov_b32 m0, s20
	s_nop 0
	global_load_lds_dwordx4 v[182:183], off
	v_lshl_add_u64 v[182:183], s[0:1], 0, v[144:145]
	s_add_i32 m0, s20, 0x2000
	s_nop 0
	global_load_lds_dwordx4 v[182:183], off
	v_lshl_add_u64 v[182:183], v[214:215], 0, s[24:25]
	s_mov_b32 m0, s84
	s_nop 0
	global_load_lds_dwordx4 v[182:183], off
	v_lshl_add_u64 v[182:183], v[216:217], 0, s[24:25]
	s_mov_b32 m0, s85
	s_nop 0
	global_load_lds_dwordx4 v[182:183], off
	s_waitcnt vmcnt(8)
	s_waitcnt lgkmcnt(0)
	s_barrier
	s_setprio 1
	v_mfma_f32_16x16x32_bf16 v[62:65], v[130:133], v[174:177], v[62:65]
	v_mfma_f32_16x16x32_bf16 v[58:61], v[150:153], v[174:177], v[58:61]
	v_mfma_f32_16x16x32_bf16 v[46:49], v[130:133], v[186:189], v[46:49]
	v_mfma_f32_16x16x32_bf16 v[42:45], v[150:153], v[186:189], v[42:45]
	v_mfma_f32_16x16x32_bf16 v[30:33], v[130:133], v[196:199], v[30:33]
	v_mfma_f32_16x16x32_bf16 v[26:29], v[150:153], v[196:199], v[26:29]
	v_mfma_f32_16x16x32_bf16 v[14:17], v[130:133], v[204:207], v[14:17]
	v_mfma_f32_16x16x32_bf16 v[10:13], v[150:153], v[204:207], v[10:13]
	v_mfma_f32_16x16x32_bf16 v[62:65], v[134:137], v[178:181], v[62:65]
	v_mfma_f32_16x16x32_bf16 v[58:61], v[154:157], v[178:181], v[58:61]
	v_mfma_f32_16x16x32_bf16 v[46:49], v[134:137], v[190:193], v[46:49]
	v_mfma_f32_16x16x32_bf16 v[42:45], v[154:157], v[190:193], v[42:45]
	v_mfma_f32_16x16x32_bf16 v[30:33], v[134:137], v[200:203], v[30:33]
	v_mfma_f32_16x16x32_bf16 v[26:29], v[154:157], v[200:203], v[26:29]
	v_mfma_f32_16x16x32_bf16 v[14:17], v[134:137], v[208:211], v[14:17]
	v_mfma_f32_16x16x32_bf16 v[10:13], v[154:157], v[208:211], v[10:13]
	v_mfma_f32_16x16x32_bf16 v[54:57], v[158:161], v[174:177], v[54:57]
	v_mfma_f32_16x16x32_bf16 v[50:53], v[166:169], v[174:177], v[50:53]
	v_mfma_f32_16x16x32_bf16 v[38:41], v[158:161], v[186:189], v[38:41]
	v_mfma_f32_16x16x32_bf16 v[34:37], v[166:169], v[186:189], v[34:37]
	v_mfma_f32_16x16x32_bf16 v[22:25], v[158:161], v[196:199], v[22:25]
	v_mfma_f32_16x16x32_bf16 v[18:21], v[166:169], v[196:199], v[18:21]
	v_mfma_f32_16x16x32_bf16 v[6:9], v[158:161], v[204:207], v[6:9]
	v_mfma_f32_16x16x32_bf16 v[2:5], v[166:169], v[204:207], v[2:5]
	v_mfma_f32_16x16x32_bf16 v[54:57], v[162:165], v[178:181], v[54:57]
	v_mfma_f32_16x16x32_bf16 v[50:53], v[170:173], v[178:181], v[50:53]
	v_mfma_f32_16x16x32_bf16 v[38:41], v[162:165], v[190:193], v[38:41]
	v_mfma_f32_16x16x32_bf16 v[34:37], v[170:173], v[190:193], v[34:37]
	v_mfma_f32_16x16x32_bf16 v[22:25], v[162:165], v[200:203], v[22:25]
	v_mfma_f32_16x16x32_bf16 v[18:21], v[170:173], v[200:203], v[18:21]
	v_mfma_f32_16x16x32_bf16 v[6:9], v[162:165], v[208:211], v[6:9]
	v_mfma_f32_16x16x32_bf16 v[2:5], v[170:173], v[208:211], v[2:5]
	s_setprio 0
	s_barrier
	s_add_i32 s35, s35, 2
	s_add_u32 s74, s74, 0x100
	s_addc_u32 s75, s75, 0
	s_add_u32 s31, s31, 0x100
	s_addc_u32 s34, s34, 0
	s_cmp_gt_u32 s35, 13
	s_cbranch_scc0 .LBB0_304
	s_and_b64 vcc, exec, s[64:65]
	s_cbranch_vccz .LBB0_307
	s_barrier
; __device__ __forceinline__ float shx(float v, int o, int lane) { return __builtin_bit_cast(float, __builtin_amdgcn_ds_bpermute((lane ^ o) << 2, __builtin_bit_cast(int, v))); }
; __device__ __forceinline__ int ltid(int wv) { unsigned z = 0u; asm volatile("" : "+v"(z)); return wv * 64 + (int)__builtin_amdgcn_mbcnt_hi(~0u, __builtin_amdgcn_mbcnt_lo(~0u, z)); }
; #define EPI_LOOP_ROWS for (int ai = 0; ai < 2; ++ai) _Pragma("unroll") for (int m = 0; m < 4; ++m)
; __device__ __forceinline__ float row_part(const float* RS, int row, int fq) { const f32x4 a = ((const f32x4*)(RS + (size_t)row * 16))[fq]; return (a.x + a.y) + (a.z + a.w); }
; __device__ __forceinline__ float row_rstd_fin(float s, int lane) { s += shx(s, 16, lane); s += shx(s, 32, lane); return rsqrtf(s * (1.0f / 1024.0f) + EPS); }
;     __device__ __forceinline__ void operator()(const f32x4 (&acc)[2][2][4][2], const Unit& u, int wv) const {
;         const int t_ = ltid(wv), wid_ = __builtin_amdgcn_readfirstlane(t_ >> 6), wr = wid_ >> 2, wc = wid_ & 3, fr = t_ & 15, fq = (t_ & 63) >> 4;
;         const bool gate = u.pn >= split_pn;
;         bf16_t* base = gate ? O1 : O0;
;         const int col0 = (gate ? (u.pn - split_pn) : u.pn) * BM + wc * 32 + 8 * fq;
;         const int row0 = u.pm * BM + wr * 64 + fr;
;         float rs[2][4];
; #pragma unroll
;         EPI_LOOP_ROWS rs[ai][m] = RS ? row_part(RS, row0 + ai * HALF + m * 16, fq) : 0.f;
; #pragma unroll
;         EPI_LOOP_ROWS rs[ai][m] = RS ? row_rstd_fin(rs[ai][m], t_ & 63) : 1.0f;
.LBB0_307:
	v_mov_b32_e32 v0, v1
	s_cmp_gt_i32 s76, -1
	v_mbcnt_lo_u32_b32 v0, -1, v0
	v_mbcnt_hi_u32_b32 v183, -1, v0
	v_add_u32_e32 v0, s33, v183
	s_cselect_b64 s[74:75], -1, 0
	v_readfirstlane_b32 s10, v0
	s_ashr_i32 s1, s10, 2
	s_lshl_b32 s0, s4, 8
	s_andn2_b32 s1, s1, 63
	s_add_i32 s1, s1, s0
	v_and_or_b32 v174, v183, 15, s1
	v_and_b32_e32 v0, 48, v183
	v_ashrrev_i32_e32 v175, 31, v174
	v_lshl_add_u64 v[136:137], s[12:13], 0, v[0:1]
	v_lshlrev_b64 v[188:189], 6, v[174:175]
	v_lshl_add_u64 v[188:189], v[136:137], 0, v[188:189]
	global_load_dwordx4 v[196:199], v[188:189], off
	v_or_b32_e32 v172, 16, v174
	v_ashrrev_i32_e32 v173, 31, v172
	v_lshlrev_b64 v[188:189], 6, v[172:173]
	v_lshl_add_u64 v[188:189], v[136:137], 0, v[188:189]
	global_load_dwordx4 v[200:203], v[188:189], off
	v_or_b32_e32 v166, 32, v174
	v_ashrrev_i32_e32 v167, 31, v166
	v_lshlrev_b64 v[188:189], 6, v[166:167]
	v_lshl_add_u64 v[188:189], v[136:137], 0, v[188:189]
	global_load_dwordx4 v[204:207], v[188:189], off
	v_or_b32_e32 v164, 48, v174
	v_ashrrev_i32_e32 v165, 31, v164
	v_lshlrev_b64 v[188:189], 6, v[164:165]
	v_lshl_add_u64 v[188:189], v[136:137], 0, v[188:189]
	global_load_dwordx4 v[208:211], v[188:189], off
	v_add_u32_e32 v158, 0x80, v174
	v_ashrrev_i32_e32 v159, 31, v158
	v_lshlrev_b64 v[188:189], 6, v[158:159]
	v_lshl_add_u64 v[188:189], v[136:137], 0, v[188:189]
	global_load_dwordx4 v[212:215], v[188:189], off
	v_add_u32_e32 v154, 0x90, v174
	v_ashrrev_i32_e32 v155, 31, v154
	v_lshlrev_b64 v[188:189], 6, v[154:155]
	v_lshl_add_u64 v[188:189], v[136:137], 0, v[188:189]
	global_load_dwordx4 v[216:219], v[188:189], off
	v_add_u32_e32 v152, 0xa0, v174
	v_ashrrev_i32_e32 v153, 31, v152
	v_lshlrev_b64 v[188:189], 6, v[152:153]
	v_lshl_add_u64 v[188:189], v[136:137], 0, v[188:189]
	global_load_dwordx4 v[220:223], v[188:189], off
	v_add_u32_e32 v150, 0xb0, v174
	v_ashrrev_i32_e32 v151, 31, v150
	v_lshlrev_b64 v[188:189], 6, v[150:151]
	v_lshl_add_u64 v[188:189], v[136:137], 0, v[188:189]
	global_load_dwordx4 v[224:227], v[188:189], off
	v_and_b32_e32 v180, 63, v183
	v_lshlrev_b32_e32 v0, 2, v180
	v_xor_b32_e32 v186, 64, v0
	v_xor_b32_e32 v0, 0x80, v0
	s_mov_b64 s[78:79], -1
	s_waitcnt vmcnt(0)
	v_add_f32_e32 v156, v197, v196
	v_add_f32_e32 v157, v198, v199
	v_add_f32_e32 v168, v201, v200
	v_add_f32_e32 v169, v202, v203
	v_add_f32_e32 v134, v205, v204
	v_add_f32_e32 v135, v206, v207
	v_add_f32_e32 v160, v209, v208
	v_add_f32_e32 v161, v210, v211
	v_add_f32_e32 v130, v213, v212
	v_add_f32_e32 v131, v214, v215
	v_add_f32_e32 v162, v217, v216
	v_add_f32_e32 v163, v218, v219
	v_mov_b32_e32 v170, v168
	v_mov_b32_e32 v171, v156
	v_mov_b32_e32 v156, v169
	v_pk_add_f32 v[156:157], v[170:171], v[156:157]
	ds_bpermute_b32 v169, v186, v157
	ds_bpermute_b32 v168, v186, v156
	s_waitcnt lgkmcnt(0)
	v_pk_add_f32 v[156:157], v[156:157], v[168:169]
	ds_bpermute_b32 v169, v0, v157
	ds_bpermute_b32 v168, v0, v156
	s_waitcnt lgkmcnt(0)
	v_pk_add_f32 v[156:157], v[156:157], v[168:169]
	s_nop 0
	v_pk_fma_f32 v[180:181], v[156:157], s[92:93], v[194:195] op_sel_hi:[1,0,0]
	v_add_f32_e32 v132, v221, v220
	v_add_f32_e32 v133, v222, v223
	v_mul_f32_e32 v156, 0x4b800000, v181
	v_cmp_gt_f32_e32 vcc, s97, v181
	v_cmp_gt_f32_e64 s[4:5], s97, v180
	v_add_f32_e32 v136, v225, v224
	v_cndmask_b32_e32 v156, v181, v156, vcc
	v_rsq_f32_e32 v156, v156
	v_add_f32_e32 v137, v226, v227
	v_mul_f32_e32 v157, 0x45800000, v156
	v_cndmask_b32_e32 v182, v156, v157, vcc
	v_mov_b32_e32 v156, v160
	v_mov_b32_e32 v157, v134
	v_mov_b32_e32 v134, v161
	v_pk_add_f32 v[134:135], v[156:157], v[134:135]
	ds_bpermute_b32 v157, v186, v135
	ds_bpermute_b32 v156, v186, v134
	v_pk_mul_f32 v[128:129], v[128:129], v[182:183] op_sel_hi:[1,0]
	v_pk_mul_f32 v[126:127], v[126:127], v[182:183] op_sel_hi:[1,0]
	v_pk_mul_f32 v[124:125], v[124:125], v[182:183] op_sel_hi:[1,0]
	v_pk_mul_f32 v[122:123], v[122:123], v[182:183] op_sel_hi:[1,0]
	s_waitcnt lgkmcnt(0)
	v_pk_add_f32 v[176:177], v[134:135], v[156:157]
	v_mov_b32_e32 v134, v162
	v_mov_b32_e32 v135, v130
	v_mov_b32_e32 v130, v163
	v_pk_add_f32 v[130:131], v[134:135], v[130:131]
	ds_bpermute_b32 v135, v186, v131
	ds_bpermute_b32 v134, v186, v130
	ds_bpermute_b32 v179, v0, v177
	ds_bpermute_b32 v178, v0, v176
	s_and_b64 vcc, exec, s[74:75]
	s_waitcnt lgkmcnt(2)
	v_pk_add_f32 v[168:169], v[130:131], v[134:135]
	v_mov_b32_e32 v130, v136
	v_mov_b32_e32 v131, v132
	v_mov_b32_e32 v132, v137
	v_pk_add_f32 v[130:131], v[130:131], v[132:133]
	ds_bpermute_b32 v133, v186, v131
	ds_bpermute_b32 v132, v186, v130
	ds_bpermute_b32 v171, v0, v169
	ds_bpermute_b32 v170, v0, v168
	s_waitcnt lgkmcnt(2)
	v_pk_add_f32 v[160:161], v[130:131], v[132:133]
	ds_bpermute_b32 v163, v0, v161
	ds_bpermute_b32 v162, v0, v160
	s_cbranch_vccz .LBB0_309
	v_mul_f32_e32 v0, 0xbfb8aa3b, v126
	v_exp_f32_e32 v0, v0
	v_mul_f32_e32 v130, 0xbfb8aa3b, v122
	v_exp_f32_e32 v130, v130
	v_mul_f32_e32 v132, 0xbfb8aa3b, v123
	v_add_f32_e32 v0, 1.0, v0
	v_exp_f32_e32 v132, v132
	v_add_f32_e32 v131, 1.0, v130
	v_rcp_f32_e32 v130, v0
	v_mul_f32_e32 v0, 0xbfb8aa3b, v127
	v_exp_f32_e32 v0, v0
	v_rcp_f32_e32 v134, v131
	v_mul_f32_e32 v133, 0xbfb8aa3b, v124
	v_exp_f32_e32 v133, v133
	v_add_f32_e32 v0, 1.0, v0
	v_rcp_f32_e32 v131, v0
	v_add_f32_e32 v0, 1.0, v132
	v_mul_f32_e32 v132, 0xbfb8aa3b, v128
	v_exp_f32_e32 v132, v132
	v_rcp_f32_e32 v135, v0
	v_mul_f32_e32 v136, 0xbfb8aa3b, v125
	v_exp_f32_e32 v137, v136
	v_add_f32_e32 v0, 1.0, v132
	v_rcp_f32_e32 v132, v0
	v_add_f32_e32 v0, 1.0, v133
	v_mul_f32_e32 v133, 0xbfb8aa3b, v129
	v_exp_f32_e32 v133, v133
	v_rcp_f32_e32 v136, v0
	s_mov_b64 s[78:79], 0
	v_add_f32_e32 v0, 1.0, v133
	v_rcp_f32_e32 v133, v0
	v_add_f32_e32 v0, 1.0, v137
	v_rcp_f32_e32 v137, v0

; #define LAS __attribute__((address_space(3)))
; __device__ __forceinline__ unsigned cvtpk(float lo, float hi) { f32x2 v = {lo, hi}; bf16x2_t b = __builtin_convertvector(v, bf16x2_t); return __builtin_bit_cast(unsigned, b); }
; __device__ __forceinline__ float xhalf_max(float v) { float a = v, b = v; xhalf_swap(a, b); return fmaxf(a, b); }
; __device__ __forceinline__ void softmax_pv(WaveAttn& st, f32x16 s, LAS const unsigned char* vb, int lane) {
;     float mx = s[0];
; #pragma unroll
;     for (int r = 1; r < 16; ++r) mx = fmaxf(mx, s[r]);
;     mx = xhalf_max(mx);
;     if (__builtin_amdgcn_ballot_w64(mx > st.m + 8.0f) != 0ull) {
;         const float mn = fmaxf(st.m, mx);
;         const float alpha = __builtin_amdgcn_exp2f(st.m - mn);
;         st.m = mn; st.l *= alpha;
; #pragma unroll
;         for (int r = 0; r < 16; ++r) { st.o0[r] *= alpha; st.o1[r] *= alpha; }
;     }
;     const float mn = st.m;
;     float ps = 0.f;
; #pragma unroll
;     for (int r = 0; r < 16; ++r) { s[r] = __builtin_amdgcn_exp2f(s[r] - mn); ps += s[r]; }
;     st.l += ps;
;     u32x4 p0, p1;
;     p0.x = cvtpk(s[0], s[1]); p0.y = cvtpk(s[2], s[3]); p0.z = cvtpk(s[4], s[5]); p0.w = cvtpk(s[6], s[7]);
;     p1.x = cvtpk(s[8], s[9]); p1.y = cvtpk(s[10], s[11]); p1.z = cvtpk(s[12], s[13]); p1.w = cvtpk(s[14], s[15]);
;     const bf16x8 pb0 = __builtin_bit_cast(bf16x8, p0), pb1 = __builtin_bit_cast(bf16x8, p1);
;     ...
;     { const bf16x8 v00 = VFRAG(0), v01 = VFRAG(1024), v10 = VFRAG(2048), v11 = VFRAG(2048 + 1024);
;       st.o0 = __builtin_amdgcn_mfma_f32_32x32x16_bf16(v00, pb0, st.o0, 0, 0, 0);
;       st.o0 = __builtin_amdgcn_mfma_f32_32x32x16_bf16(v01, pb1, st.o0, 0, 0, 0);
;       st.o1 = __builtin_amdgcn_mfma_f32_32x32x16_bf16(v10, pb0, st.o1, 0, 0, 0);
;       st.o1 = __builtin_amdgcn_mfma_f32_32x32x16_bf16(v11, pb1, st.o1, 0, 0, 0); }
; __device__ __forceinline__ void mla_phase(const bf16_t* QKV, bf16_t* O, LAS unsigned char* lds, int nseq, int wv) {
;     ...
;                 LAS const unsigned char* kp = kb + (sub * 32 + r32) * MLA_KP + hi * 16;
; #pragma unroll
;                 for (int ds = 0; ds < 6; ++ds) { const bf16x8 kf = *(LAS const bf16x8*)(kp + ds * 32); s = __builtin_amdgcn_mfma_f32_32x32x16_bf16(kf, q[ds], s, 0, 0, 0); }
;                 softmax_pv(st, s, vbuf + sub * 4096 + voff, lane);
.LBB0_409:
	s_bitcmp1_b32 s0, 0
	s_cselect_b32 s0, 0xa800, 0
	s_add_i32 s0, s0, 0
	v_add_u32_e32 v34, s0, v119
	v_add_u32_e32 v122, v34, v120
	ds_read_b128 v[34:37], v122
	ds_read_b128 v[124:127], v122 offset:32
	s_waitcnt lgkmcnt(0)
	v_mfma_f32_32x32x16_bf16 v[34:49], v[34:37], v[50:53], 0
	v_mfma_f32_32x32x16_bf16 v[34:49], v[124:127], v[54:57], v[34:49]
	ds_read_b128 v[124:127], v122 offset:64
	s_waitcnt lgkmcnt(0)
	v_mfma_f32_32x32x16_bf16 v[34:49], v[124:127], v[58:61], v[34:49]
	ds_read_b128 v[124:127], v122 offset:96
	s_waitcnt lgkmcnt(0)
	v_mfma_f32_32x32x16_bf16 v[34:49], v[124:127], v[62:65], v[34:49]
	ds_read_b128 v[124:127], v122 offset:128
	s_waitcnt lgkmcnt(0)
	v_mfma_f32_32x32x16_bf16 v[34:49], v[124:127], v[66:69], v[34:49]
	ds_read_b128 v[124:127], v122 offset:160
	s_waitcnt lgkmcnt(0)
	v_mfma_f32_32x32x16_bf16 v[34:49], v[124:127], v[70:73], v[34:49]
	s_nop 11
	v_max_f32_e32 v124, v34, v35
	v_max3_f32 v124, v124, v36, v37
	v_max3_f32 v124, v124, v38, v39
	v_max3_f32 v124, v124, v40, v41
	v_max3_f32 v124, v124, v42, v43
	v_max3_f32 v124, v124, v44, v45
	v_max3_f32 v124, v124, v46, v47
	v_max3_f32 v124, v124, v48, v49
	v_mov_b32_e32 v125, v124
	s_nop 1
	v_permlane32_swap_b32 v125, v124
	s_nop 1
	s_nop 0
	v_max_f32_e32 v125, v125, v124
	v_add_f32_e32 v124, 0x41000000, v121
	v_cmp_gt_f32_e32 vcc, v125, v124
	s_cbranch_vccz .LBB0_411
	v_max_f32_e32 v125, v121, v125
	v_sub_f32_e32 v121, v121, v125
	v_exp_f32_e32 v124, v121
	v_mov_b32_e32 v121, v125
	v_mul_f32_e32 v123, v123, v124
	v_pk_mul_f32 v[32:33], v[32:33], v[124:125] op_sel_hi:[1,0]
	v_pk_mul_f32 v[30:31], v[30:31], v[124:125] op_sel_hi:[1,0]
	v_pk_mul_f32 v[28:29], v[28:29], v[124:125] op_sel_hi:[1,0]
	v_pk_mul_f32 v[26:27], v[26:27], v[124:125] op_sel_hi:[1,0]
	v_pk_mul_f32 v[24:25], v[24:25], v[124:125] op_sel_hi:[1,0]
	v_pk_mul_f32 v[22:23], v[22:23], v[124:125] op_sel_hi:[1,0]
	v_pk_mul_f32 v[20:21], v[20:21], v[124:125] op_sel_hi:[1,0]
	v_pk_mul_f32 v[18:19], v[18:19], v[124:125] op_sel_hi:[1,0]
	v_pk_mul_f32 v[16:17], v[16:17], v[124:125] op_sel_hi:[1,0]
	v_pk_mul_f32 v[14:15], v[14:15], v[124:125] op_sel_hi:[1,0]
	v_pk_mul_f32 v[12:13], v[12:13], v[124:125] op_sel_hi:[1,0]
	v_pk_mul_f32 v[10:11], v[10:11], v[124:125] op_sel_hi:[1,0]
	v_pk_mul_f32 v[8:9], v[8:9], v[124:125] op_sel_hi:[1,0]
	v_pk_mul_f32 v[6:7], v[6:7], v[124:125] op_sel_hi:[1,0]
	v_pk_mul_f32 v[4:5], v[4:5], v[124:125] op_sel_hi:[1,0]
	v_pk_mul_f32 v[2:3], v[2:3], v[124:125] op_sel_hi:[1,0]
	v_add_f32_e32 v124, 0x41000000, v125
.LBB0_411:
	v_sub_f32_e32 v34, v34, v121
	v_exp_f32_e32 v34, v34
	v_sub_f32_e32 v35, v35, v121
	v_exp_f32_e32 v35, v35
	v_sub_f32_e32 v36, v36, v121
	v_exp_f32_e32 v36, v36
	v_sub_f32_e32 v37, v37, v121
	v_exp_f32_e32 v37, v37
	v_sub_f32_e32 v38, v38, v121
	v_add_f32_e32 v125, 0, v34
	v_exp_f32_e32 v38, v38
	v_sub_f32_e32 v39, v39, v121
	v_add_f32_e32 v125, v35, v125
	v_exp_f32_e32 v39, v39
	v_sub_f32_e32 v40, v40, v121
	v_add_f32_e32 v125, v36, v125
	v_exp_f32_e32 v40, v40
	v_sub_f32_e32 v41, v41, v121
	v_add_f32_e32 v125, v37, v125
	v_exp_f32_e32 v41, v41
	v_sub_f32_e32 v42, v42, v121
	v_add_f32_e32 v125, v38, v125
	v_exp_f32_e32 v42, v42
	v_sub_f32_e32 v43, v43, v121
	v_add_f32_e32 v125, v39, v125
	v_exp_f32_e32 v43, v43
	v_sub_f32_e32 v44, v44, v121
	v_add_f32_e32 v125, v40, v125
	v_exp_f32_e32 v44, v44
	v_sub_f32_e32 v45, v45, v121
	v_add_f32_e32 v125, v41, v125
	v_exp_f32_e32 v45, v45
	v_sub_f32_e32 v46, v46, v121
	v_add_f32_e32 v125, v42, v125
	v_exp_f32_e32 v46, v46
	v_sub_f32_e32 v47, v47, v121
	v_add_f32_e32 v125, v43, v125
	v_exp_f32_e32 v47, v47
	v_sub_f32_e32 v48, v48, v121
	v_add_f32_e32 v125, v44, v125
	v_exp_f32_e32 v48, v48
	v_sub_f32_e32 v49, v49, v121
	v_add_f32_e32 v125, v45, v125
	v_exp_f32_e32 v49, v49
	v_add_f32_e32 v125, v46, v125
	v_add_f32_e32 v125, v47, v125
	v_add_f32_e32 v125, v48, v125
	v_add3_u32 v126, s0, v117, v77
	v_add_f32_e32 v125, v49, v125
	v_add_f32_e32 v125, v123, v125
	v_add_u32_e32 v123, v126, v116
	v_cvt_pk_bf16_f32 v34, v34, v35
	v_cvt_pk_bf16_f32 v35, v36, v37
	v_cvt_pk_bf16_f32 v36, v38, v39
	v_cvt_pk_bf16_f32 v37, v40, v41
	v_cvt_pk_bf16_f32 v38, v42, v43
	v_cvt_pk_bf16_f32 v39, v44, v45
	v_cvt_pk_bf16_f32 v40, v46, v47
	v_cvt_pk_bf16_f32 v41, v48, v49
	ds_read_b64_tr_b16 v[42:43], v123 offset:26624
	ds_read_b64_tr_b16 v[44:45], v123 offset:27136
	ds_read_b64_tr_b16 v[46:47], v123 offset:27648
	ds_read_b64_tr_b16 v[48:49], v123 offset:28160
	ds_read_b64_tr_b16 v[126:127], v123 offset:28672
	ds_read_b64_tr_b16 v[128:129], v123 offset:29184
	ds_read_b64_tr_b16 v[130:131], v123 offset:29696
	ds_read_b64_tr_b16 v[132:133], v123 offset:30208
	s_waitcnt lgkmcnt(6)
	v_mfma_f32_32x32x16_bf16 v[18:33], v[42:45], v[34:37], v[18:33]
	s_waitcnt lgkmcnt(2)
	v_mfma_f32_32x32x16_bf16 v[2:17], v[126:129], v[34:37], v[2:17]
	ds_read_b128 v[34:37], v122 offset:6656
	ds_read_b128 v[126:129], v122 offset:6688
	v_mfma_f32_32x32x16_bf16 v[18:33], v[46:49], v[38:41], v[18:33]
	s_waitcnt lgkmcnt(2)
	v_mfma_f32_32x32x16_bf16 v[2:17], v[130:133], v[38:41], v[2:17]
	s_waitcnt lgkmcnt(1)
	v_mfma_f32_32x32x16_bf16 v[34:49], v[34:37], v[50:53], 0
	s_waitcnt lgkmcnt(0)
	v_mfma_f32_32x32x16_bf16 v[34:49], v[126:129], v[54:57], v[34:49]
	ds_read_b128 v[126:129], v122 offset:6720
	s_waitcnt lgkmcnt(0)
	v_mfma_f32_32x32x16_bf16 v[34:49], v[126:129], v[58:61], v[34:49]
	ds_read_b128 v[126:129], v122 offset:6752
	s_waitcnt lgkmcnt(0)
	v_mfma_f32_32x32x16_bf16 v[34:49], v[126:129], v[62:65], v[34:49]
	ds_read_b128 v[126:129], v122 offset:6784
	s_waitcnt lgkmcnt(0)
	v_mfma_f32_32x32x16_bf16 v[34:49], v[126:129], v[66:69], v[34:49]
	ds_read_b128 v[126:129], v122 offset:6816
	s_waitcnt lgkmcnt(0)
	v_mfma_f32_32x32x16_bf16 v[34:49], v[126:129], v[70:73], v[34:49]
	s_nop 11
	v_max_f32_e32 v126, v34, v35
	v_max3_f32 v126, v126, v36, v37
	v_max3_f32 v126, v126, v38, v39
	v_max3_f32 v126, v126, v40, v41
	v_max3_f32 v126, v126, v42, v43
	v_max3_f32 v126, v126, v44, v45
	v_max3_f32 v126, v126, v46, v47
	v_max3_f32 v126, v126, v48, v49
	v_mov_b32_e32 v127, v126
	s_nop 1
	v_permlane32_swap_b32 v126, v127
	s_nop 1
	s_nop 0
	v_max_f32_e32 v126, v126, v127
	v_cmp_gt_f32_e32 vcc, v126, v124
	s_cbranch_vccz .LBB0_413
; #define LAS __attribute__((address_space(3)))
; __device__ __forceinline__ unsigned cvtpk(float lo, float hi) { f32x2 v = {lo, hi}; bf16x2_t b = __builtin_convertvector(v, bf16x2_t); return __builtin_bit_cast(unsigned, b); }
; __device__ __forceinline__ float xhalf_max(float v) { float a = v, b = v; xhalf_swap(a, b); return fmaxf(a, b); }
; #define VFRAG(off) ({ const s16x4 lo_ = vtr(vb + (off)); const s16x4 hi_ = vtr(vb + (off) + 512); (bf16x8){lo_[0], lo_[1], lo_[2], lo_[3], hi_[0], hi_[1], hi_[2], hi_[3]}; })
; __device__ __forceinline__ void softmax_pv(WaveAttn& st, f32x16 s, LAS const unsigned char* vb, int lane) {
;     float mx = s[0];
; #pragma unroll
;     for (int r = 1; r < 16; ++r) mx = fmaxf(mx, s[r]);
;     mx = xhalf_max(mx);
;     if (__builtin_amdgcn_ballot_w64(mx > st.m + 8.0f) != 0ull) {
;         const float mn = fmaxf(st.m, mx);
;         const float alpha = __builtin_amdgcn_exp2f(st.m - mn);
;         st.m = mn; st.l *= alpha;
; #pragma unroll
;         for (int r = 0; r < 16; ++r) { st.o0[r] *= alpha; st.o1[r] *= alpha; }
;     }
;     const float mn = st.m;
;     float ps = 0.f;
; #pragma unroll
;     for (int r = 0; r < 16; ++r) { s[r] = __builtin_amdgcn_exp2f(s[r] - mn); ps += s[r]; }
;     st.l += ps;
;     u32x4 p0, p1;
;     p0.x = cvtpk(s[0], s[1]); p0.y = cvtpk(s[2], s[3]); p0.z = cvtpk(s[4], s[5]); p0.w = cvtpk(s[6], s[7]);
;     p1.x = cvtpk(s[8], s[9]); p1.y = cvtpk(s[10], s[11]); p1.z = cvtpk(s[12], s[13]); p1.w = cvtpk(s[14], s[15]);
;     const bf16x8 pb0 = __builtin_bit_cast(bf16x8, p0), pb1 = __builtin_bit_cast(bf16x8, p1);
;     ...
;     { const bf16x8 v00 = VFRAG(0), v01 = VFRAG(1024), v10 = VFRAG(2048), v11 = VFRAG(2048 + 1024);
;       st.o0 = __builtin_amdgcn_mfma_f32_32x32x16_bf16(v00, pb0, st.o0, 0, 0, 0);
;       st.o0 = __builtin_amdgcn_mfma_f32_32x32x16_bf16(v01, pb1, st.o0, 0, 0, 0);
;       st.o1 = __builtin_amdgcn_mfma_f32_32x32x16_bf16(v10, pb0, st.o1, 0, 0, 0);
;       st.o1 = __builtin_amdgcn_mfma_f32_32x32x16_bf16(v11, pb1, st.o1, 0, 0, 0); }
	v_max_f32_e32 v126, v121, v126
	v_sub_f32_e32 v121, v121, v126
	v_exp_f32_e32 v124, v121
	v_mov_b32_e32 v121, v126
	v_mul_f32_e32 v125, v125, v124
	v_pk_mul_f32 v[32:33], v[32:33], v[124:125] op_sel_hi:[1,0]
	v_pk_mul_f32 v[30:31], v[30:31], v[124:125] op_sel_hi:[1,0]
	v_pk_mul_f32 v[28:29], v[28:29], v[124:125] op_sel_hi:[1,0]
	v_pk_mul_f32 v[26:27], v[26:27], v[124:125] op_sel_hi:[1,0]
	v_pk_mul_f32 v[24:25], v[24:25], v[124:125] op_sel_hi:[1,0]
	v_pk_mul_f32 v[22:23], v[22:23], v[124:125] op_sel_hi:[1,0]
	v_pk_mul_f32 v[20:21], v[20:21], v[124:125] op_sel_hi:[1,0]
	v_pk_mul_f32 v[18:19], v[18:19], v[124:125] op_sel_hi:[1,0]
	v_pk_mul_f32 v[16:17], v[16:17], v[124:125] op_sel_hi:[1,0]
	v_pk_mul_f32 v[14:15], v[14:15], v[124:125] op_sel_hi:[1,0]
	v_pk_mul_f32 v[12:13], v[12:13], v[124:125] op_sel_hi:[1,0]
	v_pk_mul_f32 v[10:11], v[10:11], v[124:125] op_sel_hi:[1,0]
	v_pk_mul_f32 v[8:9], v[8:9], v[124:125] op_sel_hi:[1,0]
	v_pk_mul_f32 v[6:7], v[6:7], v[124:125] op_sel_hi:[1,0]
	v_pk_mul_f32 v[4:5], v[4:5], v[124:125] op_sel_hi:[1,0]
	v_pk_mul_f32 v[2:3], v[2:3], v[124:125] op_sel_hi:[1,0]
	v_add_f32_e32 v124, 0x41000000, v126
.LBB0_413:
	v_sub_f32_e32 v34, v34, v121
	v_exp_f32_e32 v34, v34
	v_sub_f32_e32 v35, v35, v121
	v_exp_f32_e32 v35, v35
	v_sub_f32_e32 v36, v36, v121
	v_exp_f32_e32 v36, v36
	v_sub_f32_e32 v37, v37, v121
	v_exp_f32_e32 v37, v37
	v_sub_f32_e32 v38, v38, v121
	v_add_f32_e32 v126, 0, v34
	v_exp_f32_e32 v38, v38
	v_sub_f32_e32 v39, v39, v121
	v_add_f32_e32 v126, v35, v126
	v_exp_f32_e32 v39, v39
	v_sub_f32_e32 v40, v40, v121
	v_add_f32_e32 v126, v36, v126
	v_exp_f32_e32 v40, v40
	v_sub_f32_e32 v41, v41, v121
	v_add_f32_e32 v126, v37, v126
	v_exp_f32_e32 v41, v41
	v_sub_f32_e32 v42, v42, v121
	v_add_f32_e32 v126, v38, v126
	v_exp_f32_e32 v42, v42
	v_sub_f32_e32 v43, v43, v121
	v_add_f32_e32 v126, v39, v126
	v_exp_f32_e32 v43, v43
	v_sub_f32_e32 v44, v44, v121
	v_add_f32_e32 v126, v40, v126
	v_exp_f32_e32 v44, v44
	v_sub_f32_e32 v45, v45, v121
	v_add_f32_e32 v126, v41, v126
	v_exp_f32_e32 v45, v45
	v_sub_f32_e32 v46, v46, v121
	v_add_f32_e32 v126, v42, v126
	v_exp_f32_e32 v46, v46
	v_sub_f32_e32 v47, v47, v121
	v_add_f32_e32 v126, v43, v126
	v_exp_f32_e32 v47, v47
	v_sub_f32_e32 v48, v48, v121
	v_add_f32_e32 v126, v44, v126
	v_exp_f32_e32 v48, v48
	v_sub_f32_e32 v49, v49, v121
	v_add_f32_e32 v126, v45, v126
	v_exp_f32_e32 v49, v49
	v_add_f32_e32 v126, v46, v126
	v_add_f32_e32 v126, v47, v126
	v_add_f32_e32 v126, v48, v126
	v_add_f32_e32 v126, v49, v126
	v_add_f32_e32 v125, v125, v126
	v_cvt_pk_bf16_f32 v34, v34, v35
	v_cvt_pk_bf16_f32 v35, v36, v37
	v_cvt_pk_bf16_f32 v36, v38, v39
	v_cvt_pk_bf16_f32 v37, v40, v41
	v_cvt_pk_bf16_f32 v38, v42, v43
	v_cvt_pk_bf16_f32 v39, v44, v45
	v_cvt_pk_bf16_f32 v40, v46, v47
	v_cvt_pk_bf16_f32 v41, v48, v49
	ds_read_b64_tr_b16 v[42:43], v123 offset:30720
	ds_read_b64_tr_b16 v[44:45], v123 offset:31232
	ds_read_b64_tr_b16 v[46:47], v123 offset:31744
	ds_read_b64_tr_b16 v[48:49], v123 offset:32256
	ds_read_b64_tr_b16 v[126:127], v123 offset:32768
	ds_read_b64_tr_b16 v[128:129], v123 offset:33280
	ds_read_b64_tr_b16 v[130:131], v123 offset:33792
	ds_read_b64_tr_b16 v[132:133], v123 offset:34304
	s_waitcnt lgkmcnt(6)
	v_mfma_f32_32x32x16_bf16 v[18:33], v[42:45], v[34:37], v[18:33]
	s_waitcnt lgkmcnt(2)
	v_mfma_f32_32x32x16_bf16 v[2:17], v[126:129], v[34:37], v[2:17]
	ds_read_b128 v[34:37], v122 offset:13312
	ds_read_b128 v[126:129], v122 offset:13344
	v_mfma_f32_32x32x16_bf16 v[18:33], v[46:49], v[38:41], v[18:33]
	s_waitcnt lgkmcnt(2)
	v_mfma_f32_32x32x16_bf16 v[2:17], v[130:133], v[38:41], v[2:17]
	s_waitcnt lgkmcnt(1)
	v_mfma_f32_32x32x16_bf16 v[34:49], v[34:37], v[50:53], 0
	s_waitcnt lgkmcnt(0)
	v_mfma_f32_32x32x16_bf16 v[34:49], v[126:129], v[54:57], v[34:49]
	ds_read_b128 v[126:129], v122 offset:13376
	s_waitcnt lgkmcnt(0)
	v_mfma_f32_32x32x16_bf16 v[34:49], v[126:129], v[58:61], v[34:49]
	ds_read_b128 v[126:129], v122 offset:13408
	s_waitcnt lgkmcnt(0)
	v_mfma_f32_32x32x16_bf16 v[34:49], v[126:129], v[62:65], v[34:49]
	ds_read_b128 v[126:129], v122 offset:13440
	s_waitcnt lgkmcnt(0)
	v_mfma_f32_32x32x16_bf16 v[34:49], v[126:129], v[66:69], v[34:49]
	ds_read_b128 v[126:129], v122 offset:13472
	s_waitcnt lgkmcnt(0)
	v_mfma_f32_32x32x16_bf16 v[34:49], v[126:129], v[70:73], v[34:49]
	s_nop 11
	v_max_f32_e32 v126, v34, v35
	v_max3_f32 v126, v126, v36, v37
	v_max3_f32 v126, v126, v38, v39
	v_max3_f32 v126, v126, v40, v41
	v_max3_f32 v126, v126, v42, v43
	v_max3_f32 v126, v126, v44, v45
	v_max3_f32 v126, v126, v46, v47
	v_max3_f32 v126, v126, v48, v49
	v_mov_b32_e32 v127, v126
	s_nop 1
	v_permlane32_swap_b32 v126, v127
	s_nop 1
	s_nop 0
	v_max_f32_e32 v126, v126, v127
	v_cmp_gt_f32_e32 vcc, v126, v124
	s_cbranch_vccz .LBB0_415
	v_max_f32_e32 v126, v121, v126
	v_sub_f32_e32 v121, v121, v126
	v_exp_f32_e32 v124, v121
	v_mov_b32_e32 v121, v126
	v_mul_f32_e32 v125, v125, v124
	v_pk_mul_f32 v[32:33], v[32:33], v[124:125] op_sel_hi:[1,0]
	v_pk_mul_f32 v[30:31], v[30:31], v[124:125] op_sel_hi:[1,0]
	v_pk_mul_f32 v[28:29], v[28:29], v[124:125] op_sel_hi:[1,0]
	v_pk_mul_f32 v[26:27], v[26:27], v[124:125] op_sel_hi:[1,0]
	v_pk_mul_f32 v[24:25], v[24:25], v[124:125] op_sel_hi:[1,0]
	v_pk_mul_f32 v[22:23], v[22:23], v[124:125] op_sel_hi:[1,0]
	v_pk_mul_f32 v[20:21], v[20:21], v[124:125] op_sel_hi:[1,0]
	v_pk_mul_f32 v[18:19], v[18:19], v[124:125] op_sel_hi:[1,0]
	v_pk_mul_f32 v[16:17], v[16:17], v[124:125] op_sel_hi:[1,0]
	v_pk_mul_f32 v[14:15], v[14:15], v[124:125] op_sel_hi:[1,0]
	v_pk_mul_f32 v[12:13], v[12:13], v[124:125] op_sel_hi:[1,0]
	v_pk_mul_f32 v[10:11], v[10:11], v[124:125] op_sel_hi:[1,0]
	v_pk_mul_f32 v[8:9], v[8:9], v[124:125] op_sel_hi:[1,0]
	v_pk_mul_f32 v[6:7], v[6:7], v[124:125] op_sel_hi:[1,0]
	v_pk_mul_f32 v[4:5], v[4:5], v[124:125] op_sel_hi:[1,0]
	v_pk_mul_f32 v[2:3], v[2:3], v[124:125] op_sel_hi:[1,0]
	v_add_f32_e32 v124, 0x41000000, v126
; #define LAS __attribute__((address_space(3)))
; __device__ __forceinline__ unsigned cvtpk(float lo, float hi) { f32x2 v = {lo, hi}; bf16x2_t b = __builtin_convertvector(v, bf16x2_t); return __builtin_bit_cast(unsigned, b); }
; __device__ __forceinline__ float xhalf_max(float v) { float a = v, b = v; xhalf_swap(a, b); return fmaxf(a, b); }
; __device__ __forceinline__ void softmax_pv(WaveAttn& st, f32x16 s, LAS const unsigned char* vb, int lane) {
;     float mx = s[0];
; #pragma unroll
;     for (int r = 1; r < 16; ++r) mx = fmaxf(mx, s[r]);
;     mx = xhalf_max(mx);
;     if (__builtin_amdgcn_ballot_w64(mx > st.m + 8.0f) != 0ull) {
;         const float mn = fmaxf(st.m, mx);
;         const float alpha = __builtin_amdgcn_exp2f(st.m - mn);
;         st.m = mn; st.l *= alpha;
; #pragma unroll
;         for (int r = 0; r < 16; ++r) { st.o0[r] *= alpha; st.o1[r] *= alpha; }
;     }
;     const float mn = st.m;
;     float ps = 0.f;
; #pragma unroll
;     for (int r = 0; r < 16; ++r) { s[r] = __builtin_amdgcn_exp2f(s[r] - mn); ps += s[r]; }
;     st.l += ps;
;     u32x4 p0, p1;
;     p0.x = cvtpk(s[0], s[1]); p0.y = cvtpk(s[2], s[3]); p0.z = cvtpk(s[4], s[5]); p0.w = cvtpk(s[6], s[7]);
;     p1.x = cvtpk(s[8], s[9]); p1.y = cvtpk(s[10], s[11]); p1.z = cvtpk(s[12], s[13]); p1.w = cvtpk(s[14], s[15]);
;     const bf16x8 pb0 = __builtin_bit_cast(bf16x8, p0), pb1 = __builtin_bit_cast(bf16x8, p1);
;     ...
;     { const bf16x8 v00 = VFRAG(0), v01 = VFRAG(1024), v10 = VFRAG(2048), v11 = VFRAG(2048 + 1024);
;       st.o0 = __builtin_amdgcn_mfma_f32_32x32x16_bf16(v00, pb0, st.o0, 0, 0, 0);
;       st.o0 = __builtin_amdgcn_mfma_f32_32x32x16_bf16(v01, pb1, st.o0, 0, 0, 0);
;       st.o1 = __builtin_amdgcn_mfma_f32_32x32x16_bf16(v10, pb0, st.o1, 0, 0, 0);
;       st.o1 = __builtin_amdgcn_mfma_f32_32x32x16_bf16(v11, pb1, st.o1, 0, 0, 0); }
; __device__ __forceinline__ void mla_phase(const bf16_t* QKV, bf16_t* O, LAS unsigned char* lds, int nseq, int wv) {
;     ...
;                 LAS const unsigned char* kp = kb + (sub * 32 + r32) * MLA_KP + hi * 16;
; #pragma unroll
;                 for (int ds = 0; ds < 6; ++ds) { const bf16x8 kf = *(LAS const bf16x8*)(kp + ds * 32); s = __builtin_amdgcn_mfma_f32_32x32x16_bf16(kf, q[ds], s, 0, 0, 0); }
;                 softmax_pv(st, s, vbuf + sub * 4096 + voff, lane);
.LBB0_415:
	v_sub_f32_e32 v34, v34, v121
	v_exp_f32_e32 v34, v34
	v_sub_f32_e32 v35, v35, v121
	v_exp_f32_e32 v35, v35
	v_sub_f32_e32 v36, v36, v121
	v_exp_f32_e32 v36, v36
	v_sub_f32_e32 v37, v37, v121
	v_exp_f32_e32 v37, v37
	v_sub_f32_e32 v38, v38, v121
	v_add_f32_e32 v126, 0, v34
	v_exp_f32_e32 v38, v38
	v_sub_f32_e32 v39, v39, v121
	v_add_f32_e32 v126, v35, v126
	v_exp_f32_e32 v39, v39
	v_sub_f32_e32 v40, v40, v121
	v_add_f32_e32 v126, v36, v126
	v_exp_f32_e32 v40, v40
	v_sub_f32_e32 v41, v41, v121
	v_add_f32_e32 v126, v37, v126
	v_exp_f32_e32 v41, v41
	v_sub_f32_e32 v42, v42, v121
	v_add_f32_e32 v126, v38, v126
	v_exp_f32_e32 v42, v42
	v_sub_f32_e32 v43, v43, v121
	v_add_f32_e32 v126, v39, v126
	v_exp_f32_e32 v43, v43
	v_sub_f32_e32 v44, v44, v121
	v_add_f32_e32 v126, v40, v126
	v_exp_f32_e32 v44, v44
	v_sub_f32_e32 v45, v45, v121
	v_add_f32_e32 v126, v41, v126
	v_exp_f32_e32 v45, v45
	v_sub_f32_e32 v46, v46, v121
	v_add_f32_e32 v126, v42, v126
	v_exp_f32_e32 v46, v46
	v_sub_f32_e32 v47, v47, v121
	v_add_f32_e32 v126, v43, v126
	v_exp_f32_e32 v47, v47
	v_sub_f32_e32 v48, v48, v121
	v_add_f32_e32 v126, v44, v126
	v_exp_f32_e32 v48, v48
	v_sub_f32_e32 v49, v49, v121
	v_add_f32_e32 v126, v45, v126
	v_exp_f32_e32 v49, v49
	v_add_f32_e32 v126, v46, v126
	v_add_f32_e32 v126, v47, v126
	v_add_f32_e32 v126, v48, v126
	v_add_f32_e32 v126, v49, v126
	v_add_f32_e32 v125, v125, v126
	v_cvt_pk_bf16_f32 v34, v34, v35
	v_cvt_pk_bf16_f32 v35, v36, v37
	v_cvt_pk_bf16_f32 v36, v38, v39
	v_cvt_pk_bf16_f32 v37, v40, v41
	v_cvt_pk_bf16_f32 v38, v42, v43
	v_cvt_pk_bf16_f32 v39, v44, v45
	v_cvt_pk_bf16_f32 v40, v46, v47
	v_cvt_pk_bf16_f32 v41, v48, v49
	ds_read_b64_tr_b16 v[42:43], v123 offset:34816
	ds_read_b64_tr_b16 v[44:45], v123 offset:35328
	ds_read_b64_tr_b16 v[46:47], v123 offset:35840
	ds_read_b64_tr_b16 v[48:49], v123 offset:36352
	ds_read_b64_tr_b16 v[126:127], v123 offset:36864
	ds_read_b64_tr_b16 v[128:129], v123 offset:37376
	ds_read_b64_tr_b16 v[130:131], v123 offset:37888
	ds_read_b64_tr_b16 v[132:133], v123 offset:38400
	s_waitcnt lgkmcnt(6)
	v_mfma_f32_32x32x16_bf16 v[18:33], v[42:45], v[34:37], v[18:33]
	s_waitcnt lgkmcnt(2)
	v_mfma_f32_32x32x16_bf16 v[2:17], v[126:129], v[34:37], v[2:17]
	ds_read_b128 v[34:37], v122 offset:19968
	ds_read_b128 v[126:129], v122 offset:20000
	v_mfma_f32_32x32x16_bf16 v[18:33], v[46:49], v[38:41], v[18:33]
	s_waitcnt lgkmcnt(2)
	v_mfma_f32_32x32x16_bf16 v[2:17], v[130:133], v[38:41], v[2:17]
	s_waitcnt lgkmcnt(1)
	v_mfma_f32_32x32x16_bf16 v[34:49], v[34:37], v[50:53], 0
	s_waitcnt lgkmcnt(0)
	v_mfma_f32_32x32x16_bf16 v[34:49], v[126:129], v[54:57], v[34:49]
	ds_read_b128 v[126:129], v122 offset:20032
	s_waitcnt lgkmcnt(0)
	v_mfma_f32_32x32x16_bf16 v[34:49], v[126:129], v[58:61], v[34:49]
	ds_read_b128 v[126:129], v122 offset:20064
	s_waitcnt lgkmcnt(0)
	v_mfma_f32_32x32x16_bf16 v[34:49], v[126:129], v[62:65], v[34:49]
	ds_read_b128 v[126:129], v122 offset:20096
	s_waitcnt lgkmcnt(0)
	v_mfma_f32_32x32x16_bf16 v[34:49], v[126:129], v[66:69], v[34:49]
	ds_read_b128 v[126:129], v122 offset:20128
	s_waitcnt lgkmcnt(0)
	v_mfma_f32_32x32x16_bf16 v[34:49], v[126:129], v[70:73], v[34:49]
	s_nop 11
	v_max_f32_e32 v122, v34, v35
	v_max3_f32 v122, v122, v36, v37
	v_max3_f32 v122, v122, v38, v39
	v_max3_f32 v122, v122, v40, v41
	v_max3_f32 v122, v122, v42, v43
	v_max3_f32 v122, v122, v44, v45
	v_max3_f32 v122, v122, v46, v47
	v_max3_f32 v122, v122, v48, v49
	v_mov_b32_e32 v126, v122
	s_nop 1
	v_permlane32_swap_b32 v122, v126
	s_nop 1
	s_nop 0
	v_max_f32_e32 v122, v122, v126
	v_cmp_gt_f32_e32 vcc, v122, v124
	s_cbranch_vccz .LBB0_417
	v_max_f32_e32 v124, v121, v122
	v_sub_f32_e32 v121, v121, v124
	v_exp_f32_e32 v122, v121
	v_mov_b32_e32 v121, v124
	v_mul_f32_e32 v125, v125, v122
	v_pk_mul_f32 v[32:33], v[32:33], v[122:123] op_sel_hi:[1,0]
	v_pk_mul_f32 v[30:31], v[30:31], v[122:123] op_sel_hi:[1,0]
	v_pk_mul_f32 v[28:29], v[28:29], v[122:123] op_sel_hi:[1,0]
	v_pk_mul_f32 v[26:27], v[26:27], v[122:123] op_sel_hi:[1,0]
	v_pk_mul_f32 v[24:25], v[24:25], v[122:123] op_sel_hi:[1,0]
	v_pk_mul_f32 v[22:23], v[22:23], v[122:123] op_sel_hi:[1,0]
	v_pk_mul_f32 v[20:21], v[20:21], v[122:123] op_sel_hi:[1,0]
	v_pk_mul_f32 v[18:19], v[18:19], v[122:123] op_sel_hi:[1,0]
	v_pk_mul_f32 v[16:17], v[16:17], v[122:123] op_sel_hi:[1,0]
	v_pk_mul_f32 v[14:15], v[14:15], v[122:123] op_sel_hi:[1,0]
	v_pk_mul_f32 v[12:13], v[12:13], v[122:123] op_sel_hi:[1,0]
	v_pk_mul_f32 v[10:11], v[10:11], v[122:123] op_sel_hi:[1,0]
	v_pk_mul_f32 v[8:9], v[8:9], v[122:123] op_sel_hi:[1,0]
	v_pk_mul_f32 v[6:7], v[6:7], v[122:123] op_sel_hi:[1,0]
	v_pk_mul_f32 v[4:5], v[4:5], v[122:123] op_sel_hi:[1,0]
	v_pk_mul_f32 v[2:3], v[2:3], v[122:123] op_sel_hi:[1,0]

; __device__ __forceinline__ void softmax_pv_vf(WaveAttn& st, f32x16 s, const bf16x8 (&vf)[4]) {
;     float mx = s[0];
; #pragma unroll
;     for (int r = 1; r < 16; ++r) mx = fmaxf(mx, s[r]);
;     mx = xhalf_max(mx);
;     if (__builtin_amdgcn_ballot_w64(mx > st.m + 8.0f) != 0ull) {
;         const float mn = fmaxf(st.m, mx);
;         const float alpha = __builtin_amdgcn_exp2f(st.m - mn);
;         st.m = mn; st.l *= alpha;
; #pragma unroll
;         for (int r = 0; r < 16; ++r) { st.o0[r] *= alpha; st.o1[r] *= alpha; }
;     }
;     const float mn = st.m;
;     float ps = 0.f;
; #pragma unroll
;     for (int r = 0; r < 16; ++r) { s[r] = __builtin_amdgcn_exp2f(s[r] - mn); ps += s[r]; }
;     st.l += ps;
;     u32x4 p0, p1;
;     p0.x = cvtpk(s[0], s[1]); p0.y = cvtpk(s[2], s[3]); p0.z = cvtpk(s[4], s[5]); p0.w = cvtpk(s[6], s[7]);
;     p1.x = cvtpk(s[8], s[9]); p1.y = cvtpk(s[10], s[11]); p1.z = cvtpk(s[12], s[13]); p1.w = cvtpk(s[14], s[15]);
;     const bf16x8 pb0 = __builtin_bit_cast(bf16x8, p0), pb1 = __builtin_bit_cast(bf16x8, p1);
;     st.o0 = __builtin_amdgcn_mfma_f32_32x32x16_bf16(vf[0], pb0, st.o0, 0, 0, 0);
;     st.o1 = __builtin_amdgcn_mfma_f32_32x32x16_bf16(vf[2], pb0, st.o1, 0, 0, 0);
;     st.o0 = __builtin_amdgcn_mfma_f32_32x32x16_bf16(vf[1], pb1, st.o0, 0, 0, 0);
;     st.o1 = __builtin_amdgcn_mfma_f32_32x32x16_bf16(vf[3], pb1, st.o1, 0, 0, 0);
; __device__ __forceinline__ void mla_phase2(const bf16_t* QKV, bf16_t* O, LAS unsigned char* lds, int nseq, int wv) {
;     ...
;                 LAS const unsigned char* kp = kb + (sub * 32 + r32) * MLA_KP + hi * 16;
;                 __builtin_amdgcn_s_setprio(1);
; #pragma unroll
;                 for (int ds = 0; ds < 6; ++ds) { const bf16x8 kf = *(LAS const bf16x8*)(kp + ds * 32);
;                     sa = __builtin_amdgcn_mfma_f32_32x32x16_bf16(kf, qa[ds], sa, 0, 0, 0); sb = __builtin_amdgcn_mfma_f32_32x32x16_bf16(kf, qb2[ds], sb, 0, 0, 0); }
;                 __builtin_amdgcn_s_setprio(0);
;                 LAS const unsigned char* vb_ = vbuf + sub * 4096 + voff;
;                 bf16x8 vf[4];
; #pragma unroll
;                 for (int i = 0; i < 4; ++i) { const int off = (i >> 1) * 2048 + (i & 1) * 1024; const s16x4 lo_ = vtr(vb_ + off), hi_ = vtr(vb_ + off + 512);
;                     vf[i] = (bf16x8){lo_[0], lo_[1], lo_[2], lo_[3], hi_[0], hi_[1], hi_[2], hi_[3]}; }
.LBB0_442:
	s_bitcmp1_b32 s0, 0
	s_cselect_b32 s0, 0xa800, 0
	s_add_i32 s0, s0, 0
	v_add_u32_e32 v66, s0, v210
	v_add3_u32 v67, s0, v208, v206
	v_add_u32_e32 v214, v67, v207
	v_add_u32_e32 v215, v66, v211
	s_setprio 1
	ds_read_b128 v[66:69], v215
	ds_read_b128 v[146:149], v215 offset:32
	ds_read_b128 v[150:153], v215 offset:64
	ds_read_b128 v[218:221], v215 offset:96
	ds_read_b128 v[232:235], v215 offset:128
	ds_read_b128 v[236:239], v215 offset:160
	s_setprio 0
	s_waitcnt lgkmcnt(0)
	v_mfma_f32_32x32x16_bf16 v[82:97], v[66:69], v[98:101], 0
	v_mfma_f32_32x32x16_bf16 v[82:97], v[146:149], v[102:105], v[82:97]
	v_mfma_f32_32x32x16_bf16 v[66:81], v[66:69], v[106:109], 0
	v_mfma_f32_32x32x16_bf16 v[82:97], v[150:153], v[114:117], v[82:97]
	v_mfma_f32_32x32x16_bf16 v[66:81], v[146:149], v[110:113], v[66:81]
	v_mfma_f32_32x32x16_bf16 v[82:97], v[218:221], v[118:121], v[82:97]
	v_mfma_f32_32x32x16_bf16 v[66:81], v[150:153], v[122:125], v[66:81]
	ds_read_b64_tr_b16 v[158:159], v214 offset:26624
	ds_read_b64_tr_b16 v[160:161], v214 offset:27136
	ds_read_b64_tr_b16 v[150:151], v214 offset:27648
	ds_read_b64_tr_b16 v[152:153], v214 offset:28160
	ds_read_b64_tr_b16 v[154:155], v214 offset:28672
	ds_read_b64_tr_b16 v[156:157], v214 offset:29184
	ds_read_b64_tr_b16 v[146:147], v214 offset:29696
	ds_read_b64_tr_b16 v[148:149], v214 offset:30208
	v_mfma_f32_32x32x16_bf16 v[82:97], v[232:235], v[130:133], v[82:97]
	v_mfma_f32_32x32x16_bf16 v[66:81], v[218:221], v[126:129], v[66:81]
	v_mfma_f32_32x32x16_bf16 v[82:97], v[236:239], v[134:137], v[82:97]
	v_mfma_f32_32x32x16_bf16 v[66:81], v[232:235], v[138:141], v[66:81]
	s_nop 10
	v_max_f32_e32 v222, v83, v83
	v_max_f32_e32 v223, v82, v82
	v_max_f32_e32 v222, v223, v222
	v_max3_f32 v218, v222, v84, v85
	v_max3_f32 v218, v218, v86, v87
	v_max3_f32 v218, v218, v88, v89
	v_max3_f32 v218, v218, v90, v91
	v_max3_f32 v218, v218, v92, v93
	v_mfma_f32_32x32x16_bf16 v[66:81], v[236:239], v[142:145], v[66:81]
	v_max3_f32 v218, v218, v94, v95
	v_max3_f32 v218, v218, v96, v97
	v_mov_b32_e32 v219, v218
	s_nop 1
	v_permlane32_swap_b32 v218, v219
	s_nop 1
	s_nop 0
	v_max_f32_e32 v218, v218, v219
	v_add_f32_e32 v219, 0x41000000, v213
	v_cmp_gt_f32_e32 vcc, v218, v219
	s_cbranch_vccz .LBB0_444
	v_max_f32_e32 v219, v213, v218
	v_sub_f32_e32 v213, v213, v219
	v_exp_f32_e32 v218, v213
	v_mov_b32_e32 v213, v219
	v_mul_f32_e32 v217, v217, v218
	v_pk_mul_f32 v[64:65], v[64:65], v[218:219] op_sel_hi:[1,0]
	v_pk_mul_f32 v[62:63], v[62:63], v[218:219] op_sel_hi:[1,0]
	v_pk_mul_f32 v[60:61], v[60:61], v[218:219] op_sel_hi:[1,0]
	v_pk_mul_f32 v[58:59], v[58:59], v[218:219] op_sel_hi:[1,0]
	v_pk_mul_f32 v[56:57], v[56:57], v[218:219] op_sel_hi:[1,0]
	v_pk_mul_f32 v[54:55], v[54:55], v[218:219] op_sel_hi:[1,0]
	v_pk_mul_f32 v[52:53], v[52:53], v[218:219] op_sel_hi:[1,0]
	v_pk_mul_f32 v[50:51], v[50:51], v[218:219] op_sel_hi:[1,0]
	v_pk_mul_f32 v[48:49], v[48:49], v[218:219] op_sel_hi:[1,0]
	v_pk_mul_f32 v[46:47], v[46:47], v[218:219] op_sel_hi:[1,0]
	v_pk_mul_f32 v[44:45], v[44:45], v[218:219] op_sel_hi:[1,0]
	v_pk_mul_f32 v[42:43], v[42:43], v[218:219] op_sel_hi:[1,0]
	v_pk_mul_f32 v[40:41], v[40:41], v[218:219] op_sel_hi:[1,0]
	v_pk_mul_f32 v[38:39], v[38:39], v[218:219] op_sel_hi:[1,0]
	v_pk_mul_f32 v[36:37], v[36:37], v[218:219] op_sel_hi:[1,0]
	v_pk_mul_f32 v[34:35], v[34:35], v[218:219] op_sel_hi:[1,0]
.LBB0_444:
	v_sub_f32_e32 v82, v82, v213
	v_sub_f32_e32 v83, v83, v213
	v_sub_f32_e32 v84, v84, v213
	v_sub_f32_e32 v85, v85, v213
	v_sub_f32_e32 v86, v86, v213
	v_sub_f32_e32 v87, v87, v213
	v_sub_f32_e32 v88, v88, v213
	v_sub_f32_e32 v89, v89, v213
	v_exp_f32_e32 v82, v82
	v_exp_f32_e32 v83, v83
	v_exp_f32_e32 v84, v84
	v_exp_f32_e32 v85, v85
	v_exp_f32_e32 v86, v86
	v_exp_f32_e32 v87, v87
	v_exp_f32_e32 v88, v88
	v_exp_f32_e32 v89, v89
	v_cvt_pk_bf16_f32 v218, v82, v83
	v_cvt_pk_bf16_f32 v219, v84, v85
	v_cvt_pk_bf16_f32 v220, v86, v87
	v_cvt_pk_bf16_f32 v221, v88, v89
	v_sub_f32_e32 v90, v90, v213
	v_sub_f32_e32 v91, v91, v213
	s_waitcnt lgkmcnt(6)
	v_mfma_f32_32x32x16_bf16 v[50:65], v[158:161], v[218:221], v[50:65]
	v_sub_f32_e32 v92, v92, v213
	v_sub_f32_e32 v93, v93, v213
	v_sub_f32_e32 v94, v94, v213
	v_sub_f32_e32 v95, v95, v213
	v_sub_f32_e32 v96, v96, v213
	v_sub_f32_e32 v97, v97, v213
	v_exp_f32_e32 v90, v90
	s_waitcnt lgkmcnt(2)
	v_mfma_f32_32x32x16_bf16 v[34:49], v[154:157], v[218:221], v[34:49]
	v_exp_f32_e32 v91, v91
	v_exp_f32_e32 v92, v92
	v_exp_f32_e32 v93, v93
	v_exp_f32_e32 v94, v94
	v_exp_f32_e32 v95, v95
	v_exp_f32_e32 v96, v96
	v_exp_f32_e32 v97, v97
	v_max_f32_e32 v218, v66, v67
	v_max3_f32 v218, v218, v68, v69
	v_max3_f32 v218, v218, v70, v71
	v_max3_f32 v218, v218, v72, v73
	v_cvt_pk_bf16_f32 v232, v90, v91
	v_cvt_pk_bf16_f32 v233, v92, v93
	v_cvt_pk_bf16_f32 v234, v94, v95
	v_cvt_pk_bf16_f32 v235, v96, v97
	v_max3_f32 v218, v218, v74, v75
	v_max3_f32 v218, v218, v76, v77
	v_mfma_f32_32x32x16_bf16 v[50:65], v[150:153], v[232:235], v[50:65]
	v_max3_f32 v218, v218, v78, v79
	v_max3_f32 v218, v218, v80, v81
	v_mov_b32_e32 v219, v218
	s_nop 1
	v_permlane32_swap_b32 v218, v219
	s_nop 1
	s_nop 0
	s_waitcnt lgkmcnt(0)
	v_mfma_f32_32x32x16_bf16 v[34:49], v[146:149], v[232:235], v[34:49]
	v_max_f32_e32 v218, v218, v219
	v_add_f32_e32 v219, 0x41000000, v212
	v_cmp_gt_f32_e32 vcc, v218, v219
	s_cbranch_vccz .LBB0_446
	v_max_f32_e32 v218, v212, v218
	v_sub_f32_e32 v212, v212, v218
	v_exp_f32_e32 v212, v212
	s_nop 0
	v_mul_f32_e32 v216, v216, v212
	v_pk_mul_f32 v[32:33], v[32:33], v[212:213] op_sel_hi:[1,0]
	v_pk_mul_f32 v[30:31], v[30:31], v[212:213] op_sel_hi:[1,0]
	v_pk_mul_f32 v[28:29], v[28:29], v[212:213] op_sel_hi:[1,0]
	v_pk_mul_f32 v[26:27], v[26:27], v[212:213] op_sel_hi:[1,0]
	v_pk_mul_f32 v[24:25], v[24:25], v[212:213] op_sel_hi:[1,0]
	v_pk_mul_f32 v[22:23], v[22:23], v[212:213] op_sel_hi:[1,0]
	v_pk_mul_f32 v[20:21], v[20:21], v[212:213] op_sel_hi:[1,0]
	v_pk_mul_f32 v[18:19], v[18:19], v[212:213] op_sel_hi:[1,0]
	v_pk_mul_f32 v[16:17], v[16:17], v[212:213] op_sel_hi:[1,0]
	v_pk_mul_f32 v[14:15], v[14:15], v[212:213] op_sel_hi:[1,0]
	v_pk_mul_f32 v[12:13], v[12:13], v[212:213] op_sel_hi:[1,0]
	v_pk_mul_f32 v[10:11], v[10:11], v[212:213] op_sel_hi:[1,0]
	v_pk_mul_f32 v[8:9], v[8:9], v[212:213] op_sel_hi:[1,0]
	v_pk_mul_f32 v[6:7], v[6:7], v[212:213] op_sel_hi:[1,0]
	v_pk_mul_f32 v[4:5], v[4:5], v[212:213] op_sel_hi:[1,0]
	v_pk_mul_f32 v[2:3], v[2:3], v[212:213] op_sel_hi:[1,0]
	v_mov_b32_e32 v212, v218
; __device__ __forceinline__ void softmax_pv_vf(WaveAttn& st, f32x16 s, const bf16x8 (&vf)[4]) {
;     float mx = s[0];
; #pragma unroll
;     for (int r = 1; r < 16; ++r) mx = fmaxf(mx, s[r]);
;     mx = xhalf_max(mx);
;     if (__builtin_amdgcn_ballot_w64(mx > st.m + 8.0f) != 0ull) {
;         const float mn = fmaxf(st.m, mx);
;         const float alpha = __builtin_amdgcn_exp2f(st.m - mn);
;         st.m = mn; st.l *= alpha;
; #pragma unroll
;         for (int r = 0; r < 16; ++r) { st.o0[r] *= alpha; st.o1[r] *= alpha; }
;     }
;     const float mn = st.m;
;     float ps = 0.f;
; #pragma unroll
;     for (int r = 0; r < 16; ++r) { s[r] = __builtin_amdgcn_exp2f(s[r] - mn); ps += s[r]; }
;     st.l += ps;
;     u32x4 p0, p1;
;     p0.x = cvtpk(s[0], s[1]); p0.y = cvtpk(s[2], s[3]); p0.z = cvtpk(s[4], s[5]); p0.w = cvtpk(s[6], s[7]);
;     p1.x = cvtpk(s[8], s[9]); p1.y = cvtpk(s[10], s[11]); p1.z = cvtpk(s[12], s[13]); p1.w = cvtpk(s[14], s[15]);
;     const bf16x8 pb0 = __builtin_bit_cast(bf16x8, p0), pb1 = __builtin_bit_cast(bf16x8, p1);
;     st.o0 = __builtin_amdgcn_mfma_f32_32x32x16_bf16(vf[0], pb0, st.o0, 0, 0, 0);
;     st.o1 = __builtin_amdgcn_mfma_f32_32x32x16_bf16(vf[2], pb0, st.o1, 0, 0, 0);
;     st.o0 = __builtin_amdgcn_mfma_f32_32x32x16_bf16(vf[1], pb1, st.o0, 0, 0, 0);
;     st.o1 = __builtin_amdgcn_mfma_f32_32x32x16_bf16(vf[3], pb1, st.o1, 0, 0, 0);
; __device__ __forceinline__ void mla_phase2(const bf16_t* QKV, bf16_t* O, LAS unsigned char* lds, int nseq, int wv) {
;     ...
;                 LAS const unsigned char* kp = kb + (sub * 32 + r32) * MLA_KP + hi * 16;
;                 __builtin_amdgcn_s_setprio(1);
; #pragma unroll
;                 for (int ds = 0; ds < 6; ++ds) { const bf16x8 kf = *(LAS const bf16x8*)(kp + ds * 32);
;                     sa = __builtin_amdgcn_mfma_f32_32x32x16_bf16(kf, qa[ds], sa, 0, 0, 0); sb = __builtin_amdgcn_mfma_f32_32x32x16_bf16(kf, qb2[ds], sb, 0, 0, 0); }
;                 __builtin_amdgcn_s_setprio(0);
;                 LAS const unsigned char* vb_ = vbuf + sub * 4096 + voff;
;                 bf16x8 vf[4];
; #pragma unroll
;                 for (int i = 0; i < 4; ++i) { const int off = (i >> 1) * 2048 + (i & 1) * 1024; const s16x4 lo_ = vtr(vb_ + off), hi_ = vtr(vb_ + off + 512);
;                     vf[i] = (bf16x8){lo_[0], lo_[1], lo_[2], lo_[3], hi_[0], hi_[1], hi_[2], hi_[3]}; }
.LBB0_446:
	v_sub_f32_e32 v66, v66, v212
	v_exp_f32_e32 v218, v66
	v_sub_f32_e32 v66, v67, v212
	v_exp_f32_e32 v219, v66
	v_sub_f32_e32 v66, v68, v212
	v_exp_f32_e32 v220, v66
	v_sub_f32_e32 v66, v69, v212
	v_exp_f32_e32 v221, v66
	v_sub_f32_e32 v66, v70, v212
	v_exp_f32_e32 v222, v66
	v_sub_f32_e32 v66, v71, v212
	v_exp_f32_e32 v223, v66
	v_sub_f32_e32 v66, v72, v212
	v_exp_f32_e32 v231, v66
	v_sub_f32_e32 v66, v73, v212
	v_exp_f32_e32 v232, v66
	v_sub_f32_e32 v66, v74, v212
	v_exp_f32_e32 v233, v66
	v_sub_f32_e32 v66, v75, v212
	v_exp_f32_e32 v234, v66
	v_sub_f32_e32 v66, v76, v212
	v_exp_f32_e32 v235, v66
	v_sub_f32_e32 v66, v77, v212
	v_exp_f32_e32 v236, v66
	v_sub_f32_e32 v66, v78, v212
	v_exp_f32_e32 v237, v66
	v_sub_f32_e32 v66, v79, v212
	v_exp_f32_e32 v238, v66
	v_sub_f32_e32 v66, v80, v212
	v_exp_f32_e32 v239, v66
	v_sub_f32_e32 v66, v81, v212
	v_exp_f32_e32 v240, v66
	v_cvt_pk_bf16_f32 v66, v218, v219
	v_cvt_pk_bf16_f32 v67, v220, v221
	v_cvt_pk_bf16_f32 v68, v222, v223
	v_cvt_pk_bf16_f32 v69, v231, v232
	v_add_f32_e32 v82, v83, v82
	v_add_f32_e32 v82, v84, v82
	v_mfma_f32_32x32x16_bf16 v[18:33], v[158:161], v[66:69], v[18:33]
	v_add_f32_e32 v82, v85, v82
	v_add_f32_e32 v82, v86, v82
	v_add_f32_e32 v82, v87, v82
	v_add_f32_e32 v82, v88, v82
	v_add_f32_e32 v82, v89, v82
	v_add_f32_e32 v82, v90, v82
	v_cvt_pk_bf16_f32 v70, v233, v234
	v_mfma_f32_32x32x16_bf16 v[2:17], v[154:157], v[66:69], v[2:17]
	v_cvt_pk_bf16_f32 v71, v235, v236
	v_cvt_pk_bf16_f32 v72, v237, v238
	v_cvt_pk_bf16_f32 v73, v239, v240
	v_add_f32_e32 v82, v91, v82
	v_add_f32_e32 v82, v92, v82
	v_add_f32_e32 v82, v93, v82
	v_add_f32_e32 v82, v94, v82
	v_mfma_f32_32x32x16_bf16 v[18:33], v[150:153], v[70:73], v[18:33]
	v_add_f32_e32 v82, v95, v82
	v_add_f32_e32 v82, v96, v82
	v_add_f32_e32 v82, v97, v82
	v_add_f32_e32 v217, v217, v82
	v_mfma_f32_32x32x16_bf16 v[2:17], v[146:149], v[70:73], v[2:17]
	s_setprio 1
	ds_read_b128 v[66:69], v215 offset:6656
	ds_read_b128 v[146:149], v215 offset:6688
	ds_read_b128 v[150:153], v215 offset:6720
	ds_read_b128 v[242:245], v215 offset:6752
	ds_read_b128 v[246:249], v215 offset:6784
	ds_read_b128 v[250:253], v215 offset:6816
	s_setprio 0
	s_waitcnt lgkmcnt(5)
	v_mfma_f32_32x32x16_bf16 v[82:97], v[66:69], v[98:101], 0
	s_waitcnt lgkmcnt(4)
	v_mfma_f32_32x32x16_bf16 v[82:97], v[146:149], v[102:105], v[82:97]
	v_mfma_f32_32x32x16_bf16 v[66:81], v[66:69], v[106:109], 0
	s_waitcnt lgkmcnt(3)
	v_mfma_f32_32x32x16_bf16 v[82:97], v[150:153], v[114:117], v[82:97]
	v_mfma_f32_32x32x16_bf16 v[66:81], v[146:149], v[110:113], v[66:81]
	s_waitcnt lgkmcnt(2)
	v_mfma_f32_32x32x16_bf16 v[82:97], v[242:245], v[118:121], v[82:97]
	v_mfma_f32_32x32x16_bf16 v[66:81], v[150:153], v[122:125], v[66:81]
	ds_read_b64_tr_b16 v[158:159], v214 offset:30720
	ds_read_b64_tr_b16 v[160:161], v214 offset:31232
	ds_read_b64_tr_b16 v[150:151], v214 offset:31744
	ds_read_b64_tr_b16 v[152:153], v214 offset:32256
	ds_read_b64_tr_b16 v[154:155], v214 offset:32768
	ds_read_b64_tr_b16 v[156:157], v214 offset:33280
	ds_read_b64_tr_b16 v[146:147], v214 offset:33792
	ds_read_b64_tr_b16 v[148:149], v214 offset:34304
	s_waitcnt lgkmcnt(9)
	v_mfma_f32_32x32x16_bf16 v[82:97], v[246:249], v[130:133], v[82:97]
	v_mfma_f32_32x32x16_bf16 v[66:81], v[242:245], v[126:129], v[66:81]
	s_waitcnt lgkmcnt(8)
	v_mfma_f32_32x32x16_bf16 v[82:97], v[250:253], v[134:137], v[82:97]
	v_mfma_f32_32x32x16_bf16 v[66:81], v[246:249], v[138:141], v[66:81]
	s_nop 10
	v_max_f32_e32 v224, v82, v83
	v_max3_f32 v224, v224, v84, v85
	v_max3_f32 v224, v224, v86, v87
	v_max3_f32 v224, v224, v88, v89
	v_max3_f32 v224, v224, v90, v91
	v_max3_f32 v224, v224, v92, v93
	v_mfma_f32_32x32x16_bf16 v[66:81], v[250:253], v[142:145], v[66:81]
	v_max3_f32 v224, v224, v94, v95
	v_max3_f32 v224, v224, v96, v97
	v_mov_b32_e32 v225, v224
	s_nop 1
	v_permlane32_swap_b32 v224, v225
	s_nop 1
	s_nop 0
	v_max_f32_e32 v225, v225, v225
	v_max_f32_e32 v224, v224, v224
	v_max_f32_e32 v241, v224, v225
	v_add_f32_e32 v224, 0x41000000, v213
	v_cmp_gt_f32_e32 vcc, v241, v224
	s_cbranch_vccz .LBB0_448
	v_max_f32_e32 v225, v213, v241
	v_sub_f32_e32 v213, v213, v225
	v_exp_f32_e32 v224, v213
	v_mov_b32_e32 v213, v225
	v_mul_f32_e32 v217, v217, v224
	v_pk_mul_f32 v[64:65], v[64:65], v[224:225] op_sel_hi:[1,0]
	v_pk_mul_f32 v[62:63], v[62:63], v[224:225] op_sel_hi:[1,0]
	v_pk_mul_f32 v[60:61], v[60:61], v[224:225] op_sel_hi:[1,0]
	v_pk_mul_f32 v[58:59], v[58:59], v[224:225] op_sel_hi:[1,0]
	v_pk_mul_f32 v[56:57], v[56:57], v[224:225] op_sel_hi:[1,0]
	v_pk_mul_f32 v[54:55], v[54:55], v[224:225] op_sel_hi:[1,0]
	v_pk_mul_f32 v[52:53], v[52:53], v[224:225] op_sel_hi:[1,0]
	v_pk_mul_f32 v[50:51], v[50:51], v[224:225] op_sel_hi:[1,0]
	v_pk_mul_f32 v[48:49], v[48:49], v[224:225] op_sel_hi:[1,0]
	v_pk_mul_f32 v[46:47], v[46:47], v[224:225] op_sel_hi:[1,0]
	v_pk_mul_f32 v[44:45], v[44:45], v[224:225] op_sel_hi:[1,0]
	v_pk_mul_f32 v[42:43], v[42:43], v[224:225] op_sel_hi:[1,0]
	v_pk_mul_f32 v[40:41], v[40:41], v[224:225] op_sel_hi:[1,0]
	v_pk_mul_f32 v[38:39], v[38:39], v[224:225] op_sel_hi:[1,0]
	v_pk_mul_f32 v[36:37], v[36:37], v[224:225] op_sel_hi:[1,0]
	v_pk_mul_f32 v[34:35], v[34:35], v[224:225] op_sel_hi:[1,0]
; __device__ __forceinline__ unsigned cvtpk(float lo, float hi) { f32x2 v = {lo, hi}; bf16x2_t b = __builtin_convertvector(v, bf16x2_t); return __builtin_bit_cast(unsigned, b); }
; __device__ __forceinline__ float xhalf_max(float v) { float a = v, b = v; xhalf_swap(a, b); return fmaxf(a, b); }
; __device__ __forceinline__ void softmax_pv_vf(WaveAttn& st, f32x16 s, const bf16x8 (&vf)[4]) {
;     float mx = s[0];
; #pragma unroll
;     for (int r = 1; r < 16; ++r) mx = fmaxf(mx, s[r]);
;     mx = xhalf_max(mx);
;     if (__builtin_amdgcn_ballot_w64(mx > st.m + 8.0f) != 0ull) {
;         const float mn = fmaxf(st.m, mx);
;         const float alpha = __builtin_amdgcn_exp2f(st.m - mn);
;         st.m = mn; st.l *= alpha;
; #pragma unroll
;         for (int r = 0; r < 16; ++r) { st.o0[r] *= alpha; st.o1[r] *= alpha; }
;     }
;     const float mn = st.m;
;     float ps = 0.f;
; #pragma unroll
;     for (int r = 0; r < 16; ++r) { s[r] = __builtin_amdgcn_exp2f(s[r] - mn); ps += s[r]; }
;     st.l += ps;
;     u32x4 p0, p1;
;     p0.x = cvtpk(s[0], s[1]); p0.y = cvtpk(s[2], s[3]); p0.z = cvtpk(s[4], s[5]); p0.w = cvtpk(s[6], s[7]);
;     p1.x = cvtpk(s[8], s[9]); p1.y = cvtpk(s[10], s[11]); p1.z = cvtpk(s[12], s[13]); p1.w = cvtpk(s[14], s[15]);
;     const bf16x8 pb0 = __builtin_bit_cast(bf16x8, p0), pb1 = __builtin_bit_cast(bf16x8, p1);
;     st.o0 = __builtin_amdgcn_mfma_f32_32x32x16_bf16(vf[0], pb0, st.o0, 0, 0, 0);
;     st.o1 = __builtin_amdgcn_mfma_f32_32x32x16_bf16(vf[2], pb0, st.o1, 0, 0, 0);
;     st.o0 = __builtin_amdgcn_mfma_f32_32x32x16_bf16(vf[1], pb1, st.o0, 0, 0, 0);
;     st.o1 = __builtin_amdgcn_mfma_f32_32x32x16_bf16(vf[3], pb1, st.o1, 0, 0, 0);
.LBB0_448:
	v_add_f32_e32 v218, v219, v218
	v_add_f32_e32 v218, v220, v218
	v_add_f32_e32 v218, v221, v218
	v_add_f32_e32 v218, v222, v218
	v_add_f32_e32 v218, v223, v218
	v_add_f32_e32 v218, v231, v218
	v_add_f32_e32 v218, v232, v218
	v_add_f32_e32 v218, v233, v218
	v_add_f32_e32 v218, v234, v218
	v_add_f32_e32 v218, v235, v218
	v_add_f32_e32 v218, v236, v218
	v_sub_f32_e32 v82, v82, v213
	v_sub_f32_e32 v83, v83, v213
	v_sub_f32_e32 v84, v84, v213
	v_sub_f32_e32 v85, v85, v213
	v_sub_f32_e32 v86, v86, v213
	v_sub_f32_e32 v87, v87, v213
	v_sub_f32_e32 v88, v88, v213
	v_sub_f32_e32 v89, v89, v213
	v_add_f32_e32 v218, v237, v218
	v_exp_f32_e32 v82, v82
	v_exp_f32_e32 v83, v83
	v_exp_f32_e32 v84, v84
	v_exp_f32_e32 v85, v85
	v_exp_f32_e32 v86, v86
	v_exp_f32_e32 v87, v87
	v_exp_f32_e32 v88, v88
	v_exp_f32_e32 v89, v89
	v_add_f32_e32 v218, v238, v218
	v_add_f32_e32 v218, v239, v218
	v_add_f32_e32 v218, v240, v218
	v_add_f32_e32 v216, v216, v218
	v_cvt_pk_bf16_f32 v218, v82, v83
	v_cvt_pk_bf16_f32 v219, v84, v85
	v_cvt_pk_bf16_f32 v220, v86, v87
	v_cvt_pk_bf16_f32 v221, v88, v89
	v_sub_f32_e32 v90, v90, v213
	v_sub_f32_e32 v91, v91, v213
	s_waitcnt lgkmcnt(6)
	v_mfma_f32_32x32x16_bf16 v[50:65], v[158:161], v[218:221], v[50:65]
	v_sub_f32_e32 v92, v92, v213
	v_sub_f32_e32 v93, v93, v213
	v_sub_f32_e32 v94, v94, v213
	v_sub_f32_e32 v95, v95, v213
	v_sub_f32_e32 v96, v96, v213
	v_sub_f32_e32 v97, v97, v213
	v_exp_f32_e32 v90, v90
	s_waitcnt lgkmcnt(2)
	v_mfma_f32_32x32x16_bf16 v[34:49], v[154:157], v[218:221], v[34:49]
	v_exp_f32_e32 v91, v91
	v_exp_f32_e32 v92, v92
	v_exp_f32_e32 v93, v93
	v_exp_f32_e32 v94, v94
	v_exp_f32_e32 v95, v95
	v_exp_f32_e32 v96, v96
	v_exp_f32_e32 v97, v97
	v_max_f32_e32 v218, v66, v67
	v_max3_f32 v218, v218, v68, v69
	v_max3_f32 v218, v218, v70, v71
	v_max3_f32 v218, v218, v72, v73
	v_cvt_pk_bf16_f32 v232, v90, v91
	v_cvt_pk_bf16_f32 v233, v92, v93
	v_cvt_pk_bf16_f32 v234, v94, v95
	v_cvt_pk_bf16_f32 v235, v96, v97
	v_max3_f32 v218, v218, v74, v75
	v_max3_f32 v218, v218, v76, v77
	v_mfma_f32_32x32x16_bf16 v[50:65], v[150:153], v[232:235], v[50:65]
	v_max3_f32 v218, v218, v78, v79
	v_max3_f32 v218, v218, v80, v81
	v_mov_b32_e32 v219, v218
	s_nop 1
	v_permlane32_swap_b32 v218, v219
	s_nop 1
	s_nop 0
	s_waitcnt lgkmcnt(0)
	v_mfma_f32_32x32x16_bf16 v[34:49], v[146:149], v[232:235], v[34:49]
	v_max_f32_e32 v218, v218, v219
	v_add_f32_e32 v219, 0x41000000, v212
	v_cmp_gt_f32_e32 vcc, v218, v219
	s_cbranch_vccz .LBB0_450
	v_max_f32_e32 v218, v212, v218
	v_sub_f32_e32 v212, v212, v218
	v_exp_f32_e32 v212, v212
	s_nop 0
	v_mul_f32_e32 v216, v216, v212
	v_pk_mul_f32 v[32:33], v[32:33], v[212:213] op_sel_hi:[1,0]
	v_pk_mul_f32 v[30:31], v[30:31], v[212:213] op_sel_hi:[1,0]
	v_pk_mul_f32 v[28:29], v[28:29], v[212:213] op_sel_hi:[1,0]
	v_pk_mul_f32 v[26:27], v[26:27], v[212:213] op_sel_hi:[1,0]
	v_pk_mul_f32 v[24:25], v[24:25], v[212:213] op_sel_hi:[1,0]
	v_pk_mul_f32 v[22:23], v[22:23], v[212:213] op_sel_hi:[1,0]
	v_pk_mul_f32 v[20:21], v[20:21], v[212:213] op_sel_hi:[1,0]
	v_pk_mul_f32 v[18:19], v[18:19], v[212:213] op_sel_hi:[1,0]
	v_pk_mul_f32 v[16:17], v[16:17], v[212:213] op_sel_hi:[1,0]
	v_pk_mul_f32 v[14:15], v[14:15], v[212:213] op_sel_hi:[1,0]
	v_pk_mul_f32 v[12:13], v[12:13], v[212:213] op_sel_hi:[1,0]
	v_pk_mul_f32 v[10:11], v[10:11], v[212:213] op_sel_hi:[1,0]
	v_pk_mul_f32 v[8:9], v[8:9], v[212:213] op_sel_hi:[1,0]
	v_pk_mul_f32 v[6:7], v[6:7], v[212:213] op_sel_hi:[1,0]
	v_pk_mul_f32 v[4:5], v[4:5], v[212:213] op_sel_hi:[1,0]
	v_pk_mul_f32 v[2:3], v[2:3], v[212:213] op_sel_hi:[1,0]
	v_mov_b32_e32 v212, v218
; __device__ __forceinline__ void softmax_pv_vf(WaveAttn& st, f32x16 s, const bf16x8 (&vf)[4]) {
;     float mx = s[0];
; #pragma unroll
;     for (int r = 1; r < 16; ++r) mx = fmaxf(mx, s[r]);
;     mx = xhalf_max(mx);
;     if (__builtin_amdgcn_ballot_w64(mx > st.m + 8.0f) != 0ull) {
;         const float mn = fmaxf(st.m, mx);
;         const float alpha = __builtin_amdgcn_exp2f(st.m - mn);
;         st.m = mn; st.l *= alpha;
; #pragma unroll
;         for (int r = 0; r < 16; ++r) { st.o0[r] *= alpha; st.o1[r] *= alpha; }
;     }
;     const float mn = st.m;
;     float ps = 0.f;
; #pragma unroll
;     for (int r = 0; r < 16; ++r) { s[r] = __builtin_amdgcn_exp2f(s[r] - mn); ps += s[r]; }
;     st.l += ps;
;     u32x4 p0, p1;
;     p0.x = cvtpk(s[0], s[1]); p0.y = cvtpk(s[2], s[3]); p0.z = cvtpk(s[4], s[5]); p0.w = cvtpk(s[6], s[7]);
;     p1.x = cvtpk(s[8], s[9]); p1.y = cvtpk(s[10], s[11]); p1.z = cvtpk(s[12], s[13]); p1.w = cvtpk(s[14], s[15]);
;     const bf16x8 pb0 = __builtin_bit_cast(bf16x8, p0), pb1 = __builtin_bit_cast(bf16x8, p1);
;     st.o0 = __builtin_amdgcn_mfma_f32_32x32x16_bf16(vf[0], pb0, st.o0, 0, 0, 0);
;     st.o1 = __builtin_amdgcn_mfma_f32_32x32x16_bf16(vf[2], pb0, st.o1, 0, 0, 0);
;     st.o0 = __builtin_amdgcn_mfma_f32_32x32x16_bf16(vf[1], pb1, st.o0, 0, 0, 0);
;     st.o1 = __builtin_amdgcn_mfma_f32_32x32x16_bf16(vf[3], pb1, st.o1, 0, 0, 0);
; __device__ __forceinline__ void mla_phase2(const bf16_t* QKV, bf16_t* O, LAS unsigned char* lds, int nseq, int wv) {
;     ...
;                 LAS const unsigned char* kp = kb + (sub * 32 + r32) * MLA_KP + hi * 16;
;                 __builtin_amdgcn_s_setprio(1);
; #pragma unroll
;                 for (int ds = 0; ds < 6; ++ds) { const bf16x8 kf = *(LAS const bf16x8*)(kp + ds * 32);
;                     sa = __builtin_amdgcn_mfma_f32_32x32x16_bf16(kf, qa[ds], sa, 0, 0, 0); sb = __builtin_amdgcn_mfma_f32_32x32x16_bf16(kf, qb2[ds], sb, 0, 0, 0); }
;                 __builtin_amdgcn_s_setprio(0);
;                 LAS const unsigned char* vb_ = vbuf + sub * 4096 + voff;
;                 bf16x8 vf[4];
; #pragma unroll
;                 for (int i = 0; i < 4; ++i) { const int off = (i >> 1) * 2048 + (i & 1) * 1024; const s16x4 lo_ = vtr(vb_ + off), hi_ = vtr(vb_ + off + 512);
;                     vf[i] = (bf16x8){lo_[0], lo_[1], lo_[2], lo_[3], hi_[0], hi_[1], hi_[2], hi_[3]}; }
.LBB0_450:
	v_sub_f32_e32 v66, v66, v212
	v_exp_f32_e32 v218, v66
	v_sub_f32_e32 v66, v67, v212
	v_exp_f32_e32 v219, v66
	v_sub_f32_e32 v66, v68, v212
	v_exp_f32_e32 v220, v66
	v_sub_f32_e32 v66, v69, v212
	v_exp_f32_e32 v221, v66
	v_sub_f32_e32 v66, v70, v212
	v_exp_f32_e32 v222, v66
	v_sub_f32_e32 v66, v71, v212
	v_exp_f32_e32 v223, v66
	v_sub_f32_e32 v66, v72, v212
	v_exp_f32_e32 v231, v66
	v_sub_f32_e32 v66, v73, v212
	v_exp_f32_e32 v232, v66
	v_sub_f32_e32 v66, v74, v212
	v_exp_f32_e32 v233, v66
	v_sub_f32_e32 v66, v75, v212
	v_exp_f32_e32 v234, v66
	v_sub_f32_e32 v66, v76, v212
	v_exp_f32_e32 v235, v66
	v_sub_f32_e32 v66, v77, v212
	v_exp_f32_e32 v236, v66
	v_sub_f32_e32 v66, v78, v212
	v_exp_f32_e32 v237, v66
	v_sub_f32_e32 v66, v79, v212
	v_exp_f32_e32 v238, v66
	v_sub_f32_e32 v66, v80, v212
	v_exp_f32_e32 v239, v66
	v_sub_f32_e32 v66, v81, v212
	v_exp_f32_e32 v240, v66
	v_cvt_pk_bf16_f32 v66, v218, v219
	v_cvt_pk_bf16_f32 v67, v220, v221
	v_cvt_pk_bf16_f32 v68, v222, v223
	v_cvt_pk_bf16_f32 v69, v231, v232
	v_add_f32_e32 v82, v83, v82
	v_add_f32_e32 v82, v84, v82
	v_mfma_f32_32x32x16_bf16 v[18:33], v[158:161], v[66:69], v[18:33]
	v_add_f32_e32 v82, v85, v82
	v_add_f32_e32 v82, v86, v82
	v_add_f32_e32 v82, v87, v82
	v_add_f32_e32 v82, v88, v82
	v_add_f32_e32 v82, v89, v82
	v_add_f32_e32 v82, v90, v82
	v_cvt_pk_bf16_f32 v70, v233, v234
	v_mfma_f32_32x32x16_bf16 v[2:17], v[154:157], v[66:69], v[2:17]
	v_cvt_pk_bf16_f32 v71, v235, v236
	v_cvt_pk_bf16_f32 v72, v237, v238
	v_cvt_pk_bf16_f32 v73, v239, v240
	v_add_f32_e32 v82, v91, v82
	v_add_f32_e32 v82, v92, v82
	v_add_f32_e32 v82, v93, v82
	v_add_f32_e32 v82, v94, v82
	v_mfma_f32_32x32x16_bf16 v[18:33], v[150:153], v[70:73], v[18:33]
	v_add_f32_e32 v82, v95, v82
	v_add_f32_e32 v82, v96, v82
	v_add_f32_e32 v82, v97, v82
	v_add_f32_e32 v217, v217, v82
	v_mfma_f32_32x32x16_bf16 v[2:17], v[146:149], v[70:73], v[2:17]
	s_setprio 1
	ds_read_b128 v[66:69], v215 offset:13312
	ds_read_b128 v[146:149], v215 offset:13344
	ds_read_b128 v[150:153], v215 offset:13376
	ds_read_b128 v[242:245], v215 offset:13408
	ds_read_b128 v[246:249], v215 offset:13440
	ds_read_b128 v[250:253], v215 offset:13472
	s_setprio 0
	s_waitcnt lgkmcnt(5)
	v_mfma_f32_32x32x16_bf16 v[82:97], v[66:69], v[98:101], 0
	s_waitcnt lgkmcnt(4)
	v_mfma_f32_32x32x16_bf16 v[82:97], v[146:149], v[102:105], v[82:97]
	v_mfma_f32_32x32x16_bf16 v[66:81], v[66:69], v[106:109], 0
	s_waitcnt lgkmcnt(3)
	v_mfma_f32_32x32x16_bf16 v[82:97], v[150:153], v[114:117], v[82:97]
	v_mfma_f32_32x32x16_bf16 v[66:81], v[146:149], v[110:113], v[66:81]
	s_waitcnt lgkmcnt(2)
	v_mfma_f32_32x32x16_bf16 v[82:97], v[242:245], v[118:121], v[82:97]
	v_mfma_f32_32x32x16_bf16 v[66:81], v[150:153], v[122:125], v[66:81]
	ds_read_b64_tr_b16 v[158:159], v214 offset:34816
	ds_read_b64_tr_b16 v[160:161], v214 offset:35328
	ds_read_b64_tr_b16 v[150:151], v214 offset:35840
	ds_read_b64_tr_b16 v[152:153], v214 offset:36352
	ds_read_b64_tr_b16 v[154:155], v214 offset:36864
	ds_read_b64_tr_b16 v[156:157], v214 offset:37376
	ds_read_b64_tr_b16 v[146:147], v214 offset:37888
	ds_read_b64_tr_b16 v[148:149], v214 offset:38400
	s_waitcnt lgkmcnt(9)
	v_mfma_f32_32x32x16_bf16 v[82:97], v[246:249], v[130:133], v[82:97]
	v_mfma_f32_32x32x16_bf16 v[66:81], v[242:245], v[126:129], v[66:81]
	s_waitcnt lgkmcnt(8)
	v_mfma_f32_32x32x16_bf16 v[82:97], v[250:253], v[134:137], v[82:97]
	v_mfma_f32_32x32x16_bf16 v[66:81], v[246:249], v[138:141], v[66:81]
	s_nop 10
	v_max_f32_e32 v224, v82, v83
	v_max3_f32 v224, v224, v84, v85
	v_max3_f32 v224, v224, v86, v87
	v_max3_f32 v224, v224, v88, v89
	v_max3_f32 v224, v224, v90, v91
	v_max3_f32 v224, v224, v92, v93
	v_mfma_f32_32x32x16_bf16 v[66:81], v[250:253], v[142:145], v[66:81]
	v_max3_f32 v224, v224, v94, v95
	v_max3_f32 v224, v224, v96, v97
	v_mov_b32_e32 v225, v224
	s_nop 1
	v_permlane32_swap_b32 v224, v225
	s_nop 1
	s_nop 0
	v_max_f32_e32 v225, v225, v225
	v_max_f32_e32 v224, v224, v224
	v_max_f32_e32 v241, v224, v225
	v_add_f32_e32 v224, 0x41000000, v213
	v_cmp_gt_f32_e32 vcc, v241, v224
	s_cbranch_vccz .LBB0_452
	v_max_f32_e32 v225, v213, v241
	v_sub_f32_e32 v213, v213, v225
	v_exp_f32_e32 v224, v213
	v_mov_b32_e32 v213, v225
	v_mul_f32_e32 v217, v217, v224
	v_pk_mul_f32 v[64:65], v[64:65], v[224:225] op_sel_hi:[1,0]
	v_pk_mul_f32 v[62:63], v[62:63], v[224:225] op_sel_hi:[1,0]
	v_pk_mul_f32 v[60:61], v[60:61], v[224:225] op_sel_hi:[1,0]
	v_pk_mul_f32 v[58:59], v[58:59], v[224:225] op_sel_hi:[1,0]
	v_pk_mul_f32 v[56:57], v[56:57], v[224:225] op_sel_hi:[1,0]
	v_pk_mul_f32 v[54:55], v[54:55], v[224:225] op_sel_hi:[1,0]
	v_pk_mul_f32 v[52:53], v[52:53], v[224:225] op_sel_hi:[1,0]
	v_pk_mul_f32 v[50:51], v[50:51], v[224:225] op_sel_hi:[1,0]
	v_pk_mul_f32 v[48:49], v[48:49], v[224:225] op_sel_hi:[1,0]
	v_pk_mul_f32 v[46:47], v[46:47], v[224:225] op_sel_hi:[1,0]
	v_pk_mul_f32 v[44:45], v[44:45], v[224:225] op_sel_hi:[1,0]
	v_pk_mul_f32 v[42:43], v[42:43], v[224:225] op_sel_hi:[1,0]
	v_pk_mul_f32 v[40:41], v[40:41], v[224:225] op_sel_hi:[1,0]
	v_pk_mul_f32 v[38:39], v[38:39], v[224:225] op_sel_hi:[1,0]
	v_pk_mul_f32 v[36:37], v[36:37], v[224:225] op_sel_hi:[1,0]
	v_pk_mul_f32 v[34:35], v[34:35], v[224:225] op_sel_hi:[1,0]

; __device__ __forceinline__ void softmax_pv_vf(WaveAttn& st, f32x16 s, const bf16x8 (&vf)[4]) {
;     float mx = s[0];
; #pragma unroll
;     for (int r = 1; r < 16; ++r) mx = fmaxf(mx, s[r]);
;     mx = xhalf_max(mx);
;     if (__builtin_amdgcn_ballot_w64(mx > st.m + 8.0f) != 0ull) {
;         const float mn = fmaxf(st.m, mx);
;         const float alpha = __builtin_amdgcn_exp2f(st.m - mn);
;         st.m = mn; st.l *= alpha;
; #pragma unroll
;         for (int r = 0; r < 16; ++r) { st.o0[r] *= alpha; st.o1[r] *= alpha; }
;     }
;     const float mn = st.m;
;     float ps = 0.f;
; #pragma unroll
;     for (int r = 0; r < 16; ++r) { s[r] = __builtin_amdgcn_exp2f(s[r] - mn); ps += s[r]; }
;     st.l += ps;
;     u32x4 p0, p1;
;     p0.x = cvtpk(s[0], s[1]); p0.y = cvtpk(s[2], s[3]); p0.z = cvtpk(s[4], s[5]); p0.w = cvtpk(s[6], s[7]);
;     p1.x = cvtpk(s[8], s[9]); p1.y = cvtpk(s[10], s[11]); p1.z = cvtpk(s[12], s[13]); p1.w = cvtpk(s[14], s[15]);
;     const bf16x8 pb0 = __builtin_bit_cast(bf16x8, p0), pb1 = __builtin_bit_cast(bf16x8, p1);
;     st.o0 = __builtin_amdgcn_mfma_f32_32x32x16_bf16(vf[0], pb0, st.o0, 0, 0, 0);
;     st.o1 = __builtin_amdgcn_mfma_f32_32x32x16_bf16(vf[2], pb0, st.o1, 0, 0, 0);
;     st.o0 = __builtin_amdgcn_mfma_f32_32x32x16_bf16(vf[1], pb1, st.o0, 0, 0, 0);
;     st.o1 = __builtin_amdgcn_mfma_f32_32x32x16_bf16(vf[3], pb1, st.o1, 0, 0, 0);
; __device__ __forceinline__ void mla_phase2(const bf16_t* QKV, bf16_t* O, LAS unsigned char* lds, int nseq, int wv) {
;     ...
;                 LAS const unsigned char* kp = kb + (sub * 32 + r32) * MLA_KP + hi * 16;
;                 __builtin_amdgcn_s_setprio(1);
; #pragma unroll
;                 for (int ds = 0; ds < 6; ++ds) { const bf16x8 kf = *(LAS const bf16x8*)(kp + ds * 32);
;                     sa = __builtin_amdgcn_mfma_f32_32x32x16_bf16(kf, qa[ds], sa, 0, 0, 0); sb = __builtin_amdgcn_mfma_f32_32x32x16_bf16(kf, qb2[ds], sb, 0, 0, 0); }
;                 __builtin_amdgcn_s_setprio(0);
;                 LAS const unsigned char* vb_ = vbuf + sub * 4096 + voff;
;                 bf16x8 vf[4];
; #pragma unroll
;                 for (int i = 0; i < 4; ++i) { const int off = (i >> 1) * 2048 + (i & 1) * 1024; const s16x4 lo_ = vtr(vb_ + off), hi_ = vtr(vb_ + off + 512);
;                     vf[i] = (bf16x8){lo_[0], lo_[1], lo_[2], lo_[3], hi_[0], hi_[1], hi_[2], hi_[3]}; }
.LBB0_454:
	v_sub_f32_e32 v66, v66, v212
	v_exp_f32_e32 v218, v66
	v_sub_f32_e32 v66, v67, v212
	v_exp_f32_e32 v219, v66
	v_sub_f32_e32 v66, v68, v212
	v_exp_f32_e32 v220, v66
	v_sub_f32_e32 v66, v69, v212
	v_exp_f32_e32 v221, v66
	v_sub_f32_e32 v66, v70, v212
	v_exp_f32_e32 v222, v66
	v_sub_f32_e32 v66, v71, v212
	v_exp_f32_e32 v223, v66
	v_sub_f32_e32 v66, v72, v212
	v_exp_f32_e32 v231, v66
	v_sub_f32_e32 v66, v73, v212
	v_exp_f32_e32 v232, v66
	v_sub_f32_e32 v66, v74, v212
	v_exp_f32_e32 v233, v66
	v_sub_f32_e32 v66, v75, v212
	v_exp_f32_e32 v234, v66
	v_sub_f32_e32 v66, v76, v212
	v_exp_f32_e32 v235, v66
	v_sub_f32_e32 v66, v77, v212
	v_exp_f32_e32 v236, v66
	v_sub_f32_e32 v66, v78, v212
	v_exp_f32_e32 v237, v66
	v_sub_f32_e32 v66, v79, v212
	v_exp_f32_e32 v238, v66
	v_sub_f32_e32 v66, v80, v212
	v_exp_f32_e32 v239, v66
	v_sub_f32_e32 v66, v81, v212
	v_exp_f32_e32 v240, v66
	v_cvt_pk_bf16_f32 v66, v218, v219
	v_cvt_pk_bf16_f32 v67, v220, v221
	v_cvt_pk_bf16_f32 v68, v222, v223
	v_cvt_pk_bf16_f32 v69, v231, v232
	v_add_f32_e32 v82, v83, v82
	v_add_f32_e32 v82, v84, v82
	v_mfma_f32_32x32x16_bf16 v[18:33], v[158:161], v[66:69], v[18:33]
	v_add_f32_e32 v82, v85, v82
	v_add_f32_e32 v82, v86, v82
	v_add_f32_e32 v82, v87, v82
	v_add_f32_e32 v82, v88, v82
	v_add_f32_e32 v82, v89, v82
	v_add_f32_e32 v82, v90, v82
	v_cvt_pk_bf16_f32 v70, v233, v234
	v_mfma_f32_32x32x16_bf16 v[2:17], v[154:157], v[66:69], v[2:17]
	v_cvt_pk_bf16_f32 v71, v235, v236
	v_cvt_pk_bf16_f32 v72, v237, v238
	v_cvt_pk_bf16_f32 v73, v239, v240
	v_add_f32_e32 v82, v91, v82
	v_add_f32_e32 v82, v92, v82
	v_add_f32_e32 v82, v93, v82
	v_add_f32_e32 v82, v94, v82
	v_mfma_f32_32x32x16_bf16 v[18:33], v[150:153], v[70:73], v[18:33]
	v_add_f32_e32 v82, v95, v82
	v_add_f32_e32 v82, v96, v82
	v_add_f32_e32 v82, v97, v82
	v_add_f32_e32 v217, v217, v82
	v_mfma_f32_32x32x16_bf16 v[2:17], v[146:149], v[70:73], v[2:17]
	s_setprio 1
	ds_read_b128 v[66:69], v215 offset:19968
	ds_read_b128 v[146:149], v215 offset:20000
	ds_read_b128 v[150:153], v215 offset:20032
	ds_read_b128 v[242:245], v215 offset:20064
	ds_read_b128 v[246:249], v215 offset:20096
	ds_read_b128 v[250:253], v215 offset:20128
	s_setprio 0
	s_waitcnt lgkmcnt(5)
	v_mfma_f32_32x32x16_bf16 v[82:97], v[66:69], v[98:101], 0
	s_waitcnt lgkmcnt(4)
	v_mfma_f32_32x32x16_bf16 v[82:97], v[146:149], v[102:105], v[82:97]
	v_mfma_f32_32x32x16_bf16 v[66:81], v[66:69], v[106:109], 0
	s_waitcnt lgkmcnt(3)
	v_mfma_f32_32x32x16_bf16 v[82:97], v[150:153], v[114:117], v[82:97]
	v_mfma_f32_32x32x16_bf16 v[66:81], v[146:149], v[110:113], v[66:81]
	s_waitcnt lgkmcnt(2)
	v_mfma_f32_32x32x16_bf16 v[82:97], v[242:245], v[118:121], v[82:97]
	v_mfma_f32_32x32x16_bf16 v[66:81], v[150:153], v[122:125], v[66:81]
	ds_read_b64_tr_b16 v[158:159], v214 offset:38912
	ds_read_b64_tr_b16 v[160:161], v214 offset:39424
	ds_read_b64_tr_b16 v[150:151], v214 offset:39936
	ds_read_b64_tr_b16 v[152:153], v214 offset:40448
	ds_read_b64_tr_b16 v[154:155], v214 offset:40960
	ds_read_b64_tr_b16 v[156:157], v214 offset:41472
	ds_read_b64_tr_b16 v[146:147], v214 offset:41984
	ds_read_b64_tr_b16 v[148:149], v214 offset:42496
	s_waitcnt lgkmcnt(9)
	v_mfma_f32_32x32x16_bf16 v[82:97], v[246:249], v[130:133], v[82:97]
	v_mfma_f32_32x32x16_bf16 v[66:81], v[242:245], v[126:129], v[66:81]
	s_waitcnt lgkmcnt(8)
	v_mfma_f32_32x32x16_bf16 v[82:97], v[250:253], v[134:137], v[82:97]
	v_mfma_f32_32x32x16_bf16 v[66:81], v[246:249], v[138:141], v[66:81]
	s_nop 10
	v_max_f32_e32 v214, v82, v83
	v_max3_f32 v214, v214, v84, v85
	v_max3_f32 v214, v214, v86, v87
	v_max3_f32 v214, v214, v88, v89
	v_max3_f32 v214, v214, v90, v91
	v_max3_f32 v214, v214, v92, v93
	v_mfma_f32_32x32x16_bf16 v[66:81], v[250:253], v[142:145], v[66:81]
	v_max3_f32 v214, v214, v94, v95
	v_max3_f32 v214, v214, v96, v97
	v_mov_b32_e32 v215, v214
	s_nop 1
	v_permlane32_swap_b32 v214, v215
	s_nop 1
	s_nop 0
	v_max_f32_e32 v214, v214, v215
	v_add_f32_e32 v215, 0x41000000, v213
	v_cmp_gt_f32_e32 vcc, v214, v215
	s_cbranch_vccz .LBB0_456
	v_max_f32_e32 v215, v213, v214
	v_sub_f32_e32 v213, v213, v215
	v_exp_f32_e32 v214, v213
	v_mov_b32_e32 v213, v215
	v_mul_f32_e32 v217, v217, v214
	v_pk_mul_f32 v[64:65], v[64:65], v[214:215] op_sel_hi:[1,0]
	v_pk_mul_f32 v[62:63], v[62:63], v[214:215] op_sel_hi:[1,0]
	v_pk_mul_f32 v[60:61], v[60:61], v[214:215] op_sel_hi:[1,0]
	v_pk_mul_f32 v[58:59], v[58:59], v[214:215] op_sel_hi:[1,0]
	v_pk_mul_f32 v[56:57], v[56:57], v[214:215] op_sel_hi:[1,0]
	v_pk_mul_f32 v[54:55], v[54:55], v[214:215] op_sel_hi:[1,0]
	v_pk_mul_f32 v[52:53], v[52:53], v[214:215] op_sel_hi:[1,0]
	v_pk_mul_f32 v[50:51], v[50:51], v[214:215] op_sel_hi:[1,0]
	v_pk_mul_f32 v[48:49], v[48:49], v[214:215] op_sel_hi:[1,0]
	v_pk_mul_f32 v[46:47], v[46:47], v[214:215] op_sel_hi:[1,0]
	v_pk_mul_f32 v[44:45], v[44:45], v[214:215] op_sel_hi:[1,0]
	v_pk_mul_f32 v[42:43], v[42:43], v[214:215] op_sel_hi:[1,0]
	v_pk_mul_f32 v[40:41], v[40:41], v[214:215] op_sel_hi:[1,0]
	v_pk_mul_f32 v[38:39], v[38:39], v[214:215] op_sel_hi:[1,0]
	v_pk_mul_f32 v[36:37], v[36:37], v[214:215] op_sel_hi:[1,0]
	v_pk_mul_f32 v[34:35], v[34:35], v[214:215] op_sel_hi:[1,0]
; __device__ __forceinline__ unsigned cvtpk(float lo, float hi) { f32x2 v = {lo, hi}; bf16x2_t b = __builtin_convertvector(v, bf16x2_t); return __builtin_bit_cast(unsigned, b); }
; __device__ __forceinline__ float xhalf_max(float v) { float a = v, b = v; xhalf_swap(a, b); return fmaxf(a, b); }
; __device__ __forceinline__ void softmax_pv_vf(WaveAttn& st, f32x16 s, const bf16x8 (&vf)[4]) {
;     float mx = s[0];
; #pragma unroll
;     for (int r = 1; r < 16; ++r) mx = fmaxf(mx, s[r]);
;     mx = xhalf_max(mx);
;     if (__builtin_amdgcn_ballot_w64(mx > st.m + 8.0f) != 0ull) {
;         const float mn = fmaxf(st.m, mx);
;         const float alpha = __builtin_amdgcn_exp2f(st.m - mn);
;         st.m = mn; st.l *= alpha;
; #pragma unroll
;         for (int r = 0; r < 16; ++r) { st.o0[r] *= alpha; st.o1[r] *= alpha; }
;     }
;     const float mn = st.m;
;     float ps = 0.f;
; #pragma unroll
;     for (int r = 0; r < 16; ++r) { s[r] = __builtin_amdgcn_exp2f(s[r] - mn); ps += s[r]; }
;     st.l += ps;
;     u32x4 p0, p1;
;     p0.x = cvtpk(s[0], s[1]); p0.y = cvtpk(s[2], s[3]); p0.z = cvtpk(s[4], s[5]); p0.w = cvtpk(s[6], s[7]);
;     p1.x = cvtpk(s[8], s[9]); p1.y = cvtpk(s[10], s[11]); p1.z = cvtpk(s[12], s[13]); p1.w = cvtpk(s[14], s[15]);
;     const bf16x8 pb0 = __builtin_bit_cast(bf16x8, p0), pb1 = __builtin_bit_cast(bf16x8, p1);
;     st.o0 = __builtin_amdgcn_mfma_f32_32x32x16_bf16(vf[0], pb0, st.o0, 0, 0, 0);
;     st.o1 = __builtin_amdgcn_mfma_f32_32x32x16_bf16(vf[2], pb0, st.o1, 0, 0, 0);
;     st.o0 = __builtin_amdgcn_mfma_f32_32x32x16_bf16(vf[1], pb1, st.o0, 0, 0, 0);
;     st.o1 = __builtin_amdgcn_mfma_f32_32x32x16_bf16(vf[3], pb1, st.o1, 0, 0, 0);
; __device__ __forceinline__ void mla_phase2(const bf16_t* QKV, bf16_t* O, LAS unsigned char* lds, int nseq, int wv) {
;     ...
;             asm volatile("s_waitcnt vmcnt(0)" ::: "memory"); __syncthreads();
;         }
.LBB0_456:
	v_add_f32_e32 v214, 0, v218
	v_add_f32_e32 v214, v219, v214
	v_add_f32_e32 v214, v220, v214
	v_add_f32_e32 v214, v221, v214
	v_add_f32_e32 v214, v222, v214
	v_add_f32_e32 v214, v223, v214
	v_add_f32_e32 v214, v231, v214
	v_add_f32_e32 v214, v232, v214
	v_add_f32_e32 v214, v233, v214
	v_sub_f32_e32 v82, v82, v213
	v_sub_f32_e32 v83, v83, v213
	v_sub_f32_e32 v84, v84, v213
	v_sub_f32_e32 v85, v85, v213
	v_sub_f32_e32 v86, v86, v213
	v_sub_f32_e32 v87, v87, v213
	v_sub_f32_e32 v88, v88, v213
	v_sub_f32_e32 v89, v89, v213
	v_add_f32_e32 v214, v234, v214
	v_exp_f32_e32 v82, v82
	v_exp_f32_e32 v83, v83
	v_exp_f32_e32 v84, v84
	v_exp_f32_e32 v85, v85
	v_exp_f32_e32 v86, v86
	v_exp_f32_e32 v87, v87
	v_exp_f32_e32 v88, v88
	v_exp_f32_e32 v89, v89
	v_add_f32_e32 v214, v235, v214
	v_add_f32_e32 v214, v236, v214
	v_add_f32_e32 v214, v237, v214
	v_add_f32_e32 v214, v238, v214
	v_cvt_pk_bf16_f32 v218, v82, v83
	v_cvt_pk_bf16_f32 v219, v84, v85
	v_cvt_pk_bf16_f32 v220, v86, v87
	v_cvt_pk_bf16_f32 v221, v88, v89
	v_add_f32_e32 v214, v239, v214
	v_add_f32_e32 v214, v240, v214
	s_waitcnt lgkmcnt(6)
	v_mfma_f32_32x32x16_bf16 v[50:65], v[158:161], v[218:221], v[50:65]
	v_add_f32_e32 v214, v216, v214
	v_sub_f32_e32 v90, v90, v213
	v_sub_f32_e32 v91, v91, v213
	v_sub_f32_e32 v92, v92, v213
	v_sub_f32_e32 v93, v93, v213
	v_sub_f32_e32 v94, v94, v213
	v_sub_f32_e32 v95, v95, v213
	s_waitcnt lgkmcnt(2)
	v_mfma_f32_32x32x16_bf16 v[34:49], v[154:157], v[218:221], v[34:49]
	v_sub_f32_e32 v96, v96, v213
	v_sub_f32_e32 v97, v97, v213
	v_exp_f32_e32 v90, v90
	v_exp_f32_e32 v91, v91
	v_exp_f32_e32 v92, v92
	v_exp_f32_e32 v93, v93
	v_exp_f32_e32 v94, v94
	v_exp_f32_e32 v95, v95
	v_exp_f32_e32 v96, v96
	v_exp_f32_e32 v97, v97
	v_max_f32_e32 v215, v66, v67
	v_max3_f32 v215, v215, v68, v69
	v_max3_f32 v215, v215, v70, v71
	v_max3_f32 v215, v215, v72, v73
	v_cvt_pk_bf16_f32 v232, v90, v91
	v_cvt_pk_bf16_f32 v233, v92, v93
	v_cvt_pk_bf16_f32 v234, v94, v95
	v_cvt_pk_bf16_f32 v235, v96, v97
	v_max3_f32 v215, v215, v74, v75
	v_max3_f32 v215, v215, v76, v77
	v_mfma_f32_32x32x16_bf16 v[50:65], v[150:153], v[232:235], v[50:65]
	v_max3_f32 v215, v215, v78, v79
	v_max3_f32 v215, v215, v80, v81
	v_mov_b32_e32 v216, v215
	s_nop 1
	v_permlane32_swap_b32 v215, v216
	s_nop 1
	s_nop 0
	s_waitcnt lgkmcnt(0)
	v_mfma_f32_32x32x16_bf16 v[34:49], v[146:149], v[232:235], v[34:49]
	v_max_f32_e32 v215, v215, v216
	v_add_f32_e32 v216, 0x41000000, v212
	v_cmp_gt_f32_e32 vcc, v215, v216
	s_cbranch_vccz .LBB0_458
	v_max_f32_e32 v215, v215, v215
	v_max_f32_e32 v216, v212, v212
	v_max_f32_e32 v215, v216, v215
	v_sub_f32_e32 v212, v212, v215
	v_exp_f32_e32 v212, v212
	s_nop 0
	v_mul_f32_e32 v214, v214, v212
	v_pk_mul_f32 v[32:33], v[32:33], v[212:213] op_sel_hi:[1,0]
	v_pk_mul_f32 v[30:31], v[30:31], v[212:213] op_sel_hi:[1,0]
	v_pk_mul_f32 v[28:29], v[28:29], v[212:213] op_sel_hi:[1,0]
	v_pk_mul_f32 v[26:27], v[26:27], v[212:213] op_sel_hi:[1,0]
	v_pk_mul_f32 v[24:25], v[24:25], v[212:213] op_sel_hi:[1,0]
	v_pk_mul_f32 v[22:23], v[22:23], v[212:213] op_sel_hi:[1,0]
	v_pk_mul_f32 v[20:21], v[20:21], v[212:213] op_sel_hi:[1,0]
	v_pk_mul_f32 v[18:19], v[18:19], v[212:213] op_sel_hi:[1,0]
	v_pk_mul_f32 v[16:17], v[16:17], v[212:213] op_sel_hi:[1,0]
	v_pk_mul_f32 v[14:15], v[14:15], v[212:213] op_sel_hi:[1,0]
	v_pk_mul_f32 v[12:13], v[12:13], v[212:213] op_sel_hi:[1,0]
	v_pk_mul_f32 v[10:11], v[10:11], v[212:213] op_sel_hi:[1,0]
	v_pk_mul_f32 v[8:9], v[8:9], v[212:213] op_sel_hi:[1,0]
	v_pk_mul_f32 v[6:7], v[6:7], v[212:213] op_sel_hi:[1,0]
	v_pk_mul_f32 v[4:5], v[4:5], v[212:213] op_sel_hi:[1,0]
	v_pk_mul_f32 v[2:3], v[2:3], v[212:213] op_sel_hi:[1,0]
	v_mov_b32_e32 v212, v215
.LBB0_458:
	v_add_f32_e32 v82, v83, v82
	v_add_f32_e32 v82, v84, v82
	v_add_f32_e32 v82, v85, v82
	v_add_f32_e32 v82, v86, v82
	v_add_f32_e32 v82, v87, v82
	v_add_f32_e32 v82, v88, v82
	v_add_f32_e32 v82, v89, v82
	v_add_f32_e32 v82, v90, v82
	v_add_f32_e32 v82, v91, v82
	v_add_f32_e32 v82, v92, v82
	v_add_f32_e32 v82, v93, v82
	v_sub_f32_e32 v66, v66, v212
	v_add_f32_e32 v82, v94, v82
	v_exp_f32_e32 v66, v66
	v_sub_f32_e32 v67, v67, v212
	v_add_f32_e32 v82, v95, v82
	v_exp_f32_e32 v67, v67
	v_sub_f32_e32 v68, v68, v212
	v_add_f32_e32 v82, v96, v82
	v_exp_f32_e32 v68, v68
	v_sub_f32_e32 v69, v69, v212
	v_sub_f32_e32 v70, v70, v212
	v_sub_f32_e32 v71, v71, v212
	v_sub_f32_e32 v72, v72, v212
	v_sub_f32_e32 v73, v73, v212
	v_add_f32_e32 v82, v97, v82
	v_exp_f32_e32 v69, v69
	v_exp_f32_e32 v70, v70
	v_exp_f32_e32 v71, v71
	v_exp_f32_e32 v72, v72
	v_exp_f32_e32 v73, v73
	v_add_f32_e32 v217, v217, v82
	v_add_f32_e32 v82, 0, v66
	v_add_f32_e32 v82, v67, v82
	v_add_f32_e32 v82, v68, v82
	v_add_f32_e32 v82, v69, v82
	v_cvt_pk_bf16_f32 v66, v66, v67
	v_cvt_pk_bf16_f32 v67, v68, v69
	v_cvt_pk_bf16_f32 v68, v70, v71
	v_cvt_pk_bf16_f32 v69, v72, v73
	v_sub_f32_e32 v74, v74, v212
	v_sub_f32_e32 v75, v75, v212
	v_mfma_f32_32x32x16_bf16 v[18:33], v[158:161], v[66:69], v[18:33]
	v_sub_f32_e32 v76, v76, v212
	v_sub_f32_e32 v77, v77, v212
	v_sub_f32_e32 v78, v78, v212
	v_sub_f32_e32 v79, v79, v212
	v_sub_f32_e32 v80, v80, v212
	v_sub_f32_e32 v81, v81, v212
	v_add_f32_e32 v82, v70, v82
	v_mfma_f32_32x32x16_bf16 v[2:17], v[154:157], v[66:69], v[2:17]
	v_exp_f32_e32 v74, v74
	v_exp_f32_e32 v75, v75
	v_exp_f32_e32 v76, v76
	v_exp_f32_e32 v77, v77
	v_exp_f32_e32 v78, v78
	v_exp_f32_e32 v79, v79
	v_exp_f32_e32 v80, v80
	v_exp_f32_e32 v81, v81
	v_add_f32_e32 v82, v71, v82
	v_add_f32_e32 v82, v72, v82
	v_add_f32_e32 v82, v73, v82
	v_add_f32_e32 v82, v74, v82
	v_cvt_pk_bf16_f32 v70, v74, v75
	v_cvt_pk_bf16_f32 v71, v76, v77
	v_cvt_pk_bf16_f32 v72, v78, v79
	v_cvt_pk_bf16_f32 v73, v80, v81
	v_add_f32_e32 v82, v75, v82
	v_add_f32_e32 v82, v76, v82
	v_mfma_f32_32x32x16_bf16 v[18:33], v[150:153], v[70:73], v[18:33]
	v_add_f32_e32 v82, v77, v82
	v_add_f32_e32 v82, v78, v82
	v_add_f32_e32 v82, v79, v82
	v_add_f32_e32 v82, v80, v82
	s_waitcnt vmcnt(0)
	s_add_u32 s66, s66, 0x40000
	v_add_f32_e32 v82, v81, v82
	v_mfma_f32_32x32x16_bf16 v[2:17], v[146:149], v[70:73], v[2:17]
	s_addc_u32 s67, s67, 0
	v_add_f32_e32 v216, v214, v82
	s_cmp_eq_u32 s66, 0x1000000
	s_barrier
	s_cbranch_scc1 .LBB0_429
	s_mov_b32 s0, s22
	s_add_i32 s22, s0, 1
	s_cmp_eq_u32 s66, 0xfc0000
	s_cbranch_scc0 .LBB0_436
	s_branch .LBB0_442

; #define PG8_STAGE(bufoff, gbase, voff) do { _Pragma("unroll") for (int _i = 0; _i < 2; ++_i) \
;         __builtin_amdgcn_global_load_lds((const unsigned*)((const char*)(gbase) + (voff)[_i]), (LAS unsigned*)(lds + (bufoff) + ldsw + _i * 8192), 16, 0, 0); } while (0)
; #define PG8_LDA(dst, b, h) do { _Pragma("unroll") for (int m = 0; m < 4; ++m) _Pragma("unroll") for (int k = 0; k < 2; ++k) dst[m][k] = *(const LAS bf16x8*)(lds + PG8_SA(b, h) + aoff + m * 2048 + k * 1024); } while (0)
; #define PG8_LDB(dst, b, h) do { _Pragma("unroll") for (int n = 0; n < 2; ++n) _Pragma("unroll") for (int k = 0; k < 2; ++k) dst[n][k] = *(const LAS bf16x8*)(lds + PG8_SB(b, h) + boff + n * 2048 + k * 1024); } while (0)
; #define PG8_MMA(ai, bj, At, Bt) do { __builtin_amdgcn_s_setprio(1); _Pragma("unroll") for (int m = 0; m < 4; ++m) _Pragma("unroll") for (int n = 0; n < 2; ++n) _Pragma("unroll") for (int k = 0; k < 2; ++k) \
;         acc[ai][bj][m][n] = __builtin_amdgcn_mfma_f32_16x16x32_bf16(Bt[n][k], At[m][k], acc[ai][bj][m][n], 0, 0, 0); __builtin_amdgcn_s_setprio(0); } while (0)
; #define PG8_WAIT_V(n) asm volatile("s_waitcnt vmcnt(" #n ")" ::: "memory")
; template <class Epi, class Sched>
; __device__ __forceinline__ void gemm_phase(LAS unsigned char* lds, const Gemm g, const Sched& S, const Epi& E, int wv) {
;     ...
;         const char* nA = has_next ? (const char*)g.A + (size_t)nxt.pm * tstepA + (size_t)nxt.ak * 2 : cA; const char* nB = has_next ? (const char*)g.Bt + (size_t)nxt.pn * tstepB : cB;
;         for (int t = 0; t < nt; t += 2) {
;             const bool last = (t == nt - 2);
;             const char* a1 = cA + (size_t)(t + 1) * kstep;
;             const char* a2 = last ? nA : cA + (size_t)(t + 2) * kstep; const char* b2 = last ? nB : cB + (size_t)(t + 2) * kstep;
;             const char* a3 = a2 + kstep; const char* b3 = b2 + kstep;
;             PG8_LDB(B0, 0, 0); PG8_LDB(B1, 0, 1); PG8_SCHED; PG8_LDA(At, 0, 0); PG8_STAGE(PG8_SA(1, 1), a1 + hstepA, voffA);
;             PG8_WAIT_V(8); PG8_WAIT_L(0); PG8_BAR; PG8_MMA(0, 0, At, B0); PG8_MMA(0, 1, At, B1); PG8_BAR; PG8_SCHED;
;             PG8_LDA(At, 0, 1); PG8_STAGE(PG8_SB(0, 0), b2, voffB); PG8_STAGE(PG8_SB(0, 1), b2 + hstepB, voffB); PG8_STAGE(PG8_SA(0, 0), a2, voffA);
;             PG8_WAIT_V(8); PG8_WAIT_L(0); PG8_BAR; PG8_MMA(1, 0, At, B0); PG8_MMA(1, 1, At, B1); PG8_BAR; PG8_SCHED;
.LBB0_556:
	s_add_u32 s0, s78, 0xfff00080
	s_addc_u32 s1, s79, -1
	s_add_i32 s20, 0, 0x10000
	s_cmp_eq_u32 s34, 4
	s_cselect_b32 s83, s5, s1
	s_cselect_b32 s82, s7, s0
	v_add_u32_e32 v0, s20, v231
	s_cselect_b32 s81, s10, s31
	s_cselect_b32 s80, s11, s21
	s_add_i32 s26, 0, 0x14000
	ds_read_b128 v[114:117], v0
	ds_read_b128 v[118:121], v0 offset:1024
	ds_read_b128 v[130:133], v0 offset:2048
	ds_read_b128 v[134:137], v0 offset:3072
	v_add_u32_e32 v0, s26, v231
	ds_read_b128 v[146:149], v0
	ds_read_b128 v[150:153], v0 offset:1024
	ds_read_b128 v[154:157], v0 offset:2048
	ds_read_b128 v[158:161], v0 offset:3072
	v_lshl_add_u64 v[208:209], s[78:79], 0, v[204:205]
	s_add_i32 m0, s60, 0xc000
	ds_read_b128 v[162:165], v232
	ds_read_b128 v[166:169], v232 offset:1024
	ds_read_b128 v[170:173], v232 offset:2048
	ds_read_b128 v[174:177], v232 offset:3072
	ds_read_b128 v[178:181], v232 offset:4096
	ds_read_b128 v[182:185], v232 offset:5120
	ds_read_b128 v[186:189], v232 offset:6144
	ds_read_b128 v[190:193], v232 offset:7168
	global_load_lds_dwordx4 v[208:209], off
	v_lshl_add_u64 v[208:209], s[78:79], 0, v[206:207]
	s_add_i32 m0, s60, 0xe000
	s_nop 0
	global_load_lds_dwordx4 v[208:209], off
	s_waitcnt vmcnt(8)
	s_waitcnt lgkmcnt(0)
	s_barrier
	s_setprio 1
	v_mfma_f32_16x16x32_bf16 v[142:145], v[114:117], v[162:165], v[142:145]
	v_mfma_f32_16x16x32_bf16 v[138:141], v[130:133], v[162:165], v[138:141]
	v_mfma_f32_16x16x32_bf16 v[126:129], v[114:117], v[170:173], v[126:129]
	v_mfma_f32_16x16x32_bf16 v[122:125], v[130:133], v[170:173], v[122:125]
	v_mfma_f32_16x16x32_bf16 v[110:113], v[114:117], v[178:181], v[110:113]
	v_mfma_f32_16x16x32_bf16 v[106:109], v[130:133], v[178:181], v[106:109]
	v_mfma_f32_16x16x32_bf16 v[102:105], v[114:117], v[186:189], v[102:105]
	v_mfma_f32_16x16x32_bf16 v[98:101], v[130:133], v[186:189], v[98:101]
	v_mfma_f32_16x16x32_bf16 v[142:145], v[118:121], v[166:169], v[142:145]
	v_mfma_f32_16x16x32_bf16 v[138:141], v[134:137], v[166:169], v[138:141]
	v_mfma_f32_16x16x32_bf16 v[126:129], v[118:121], v[174:177], v[126:129]
	v_mfma_f32_16x16x32_bf16 v[122:125], v[134:137], v[174:177], v[122:125]
	v_mfma_f32_16x16x32_bf16 v[110:113], v[118:121], v[182:185], v[110:113]
	v_mfma_f32_16x16x32_bf16 v[106:109], v[134:137], v[182:185], v[106:109]
	v_mfma_f32_16x16x32_bf16 v[102:105], v[118:121], v[190:193], v[102:105]
	v_mfma_f32_16x16x32_bf16 v[98:101], v[134:137], v[190:193], v[98:101]
	v_mfma_f32_16x16x32_bf16 v[62:65], v[146:149], v[162:165], v[62:65]
	v_mfma_f32_16x16x32_bf16 v[58:61], v[154:157], v[162:165], v[58:61]
	v_mfma_f32_16x16x32_bf16 v[54:57], v[146:149], v[170:173], v[54:57]
	v_mfma_f32_16x16x32_bf16 v[50:53], v[154:157], v[170:173], v[50:53]
	v_mfma_f32_16x16x32_bf16 v[46:49], v[146:149], v[178:181], v[46:49]
	v_mfma_f32_16x16x32_bf16 v[42:45], v[154:157], v[178:181], v[42:45]
	v_mfma_f32_16x16x32_bf16 v[38:41], v[146:149], v[186:189], v[38:41]
	v_mfma_f32_16x16x32_bf16 v[34:37], v[154:157], v[186:189], v[34:37]
	v_mfma_f32_16x16x32_bf16 v[62:65], v[150:153], v[166:169], v[62:65]
	v_mfma_f32_16x16x32_bf16 v[58:61], v[158:161], v[166:169], v[58:61]
	v_mfma_f32_16x16x32_bf16 v[54:57], v[150:153], v[174:177], v[54:57]
	v_mfma_f32_16x16x32_bf16 v[50:53], v[158:161], v[174:177], v[50:53]
	v_mfma_f32_16x16x32_bf16 v[46:49], v[150:153], v[182:185], v[46:49]
	v_mfma_f32_16x16x32_bf16 v[42:45], v[158:161], v[182:185], v[42:45]
	v_mfma_f32_16x16x32_bf16 v[38:41], v[150:153], v[190:193], v[38:41]
	v_mfma_f32_16x16x32_bf16 v[34:37], v[158:161], v[190:193], v[34:37]
	s_setprio 0
	s_barrier
	s_add_i32 s0, s20, s50
	v_lshl_add_u64 v[208:209], s[80:81], 0, v[198:199]
	s_mov_b32 m0, s0
	ds_read_b128 v[162:165], v232 offset:16384
	ds_read_b128 v[166:169], v232 offset:17408
	ds_read_b128 v[170:173], v232 offset:18432
	ds_read_b128 v[174:177], v232 offset:19456
	ds_read_b128 v[178:181], v232 offset:20480
	ds_read_b128 v[182:185], v232 offset:21504
	ds_read_b128 v[186:189], v232 offset:22528
	ds_read_b128 v[190:193], v232 offset:23552
	global_load_lds_dwordx4 v[208:209], off
	s_add_i32 m0, s0, 0x2000
	s_add_u32 s0, s80, 0x20000
	v_lshl_add_u64 v[210:211], s[80:81], 0, v[202:203]
	s_addc_u32 s1, s81, 0
	s_add_i32 s20, s26, s50
	global_load_lds_dwordx4 v[210:211], off
	v_lshl_add_u64 v[212:213], s[0:1], 0, v[198:199]
	s_mov_b32 m0, s20
	v_lshl_add_u64 v[214:215], s[82:83], 0, v[200:201]
	global_load_lds_dwordx4 v[212:213], off
	v_lshl_add_u64 v[212:213], s[0:1], 0, v[202:203]
	s_add_i32 m0, s20, 0x2000
	s_nop 0
	global_load_lds_dwordx4 v[212:213], off
	v_lshl_add_u64 v[212:213], s[82:83], 0, v[196:197]
	s_mov_b32 m0, s60
	s_nop 0
	global_load_lds_dwordx4 v[212:213], off
	s_mov_b32 m0, s61
	s_nop 0
	global_load_lds_dwordx4 v[214:215], off
	s_waitcnt vmcnt(8)
	s_waitcnt lgkmcnt(0)
	s_barrier
; #define PG8_STAGE(bufoff, gbase, voff) do { _Pragma("unroll") for (int _i = 0; _i < 2; ++_i) \
;         __builtin_amdgcn_global_load_lds((const unsigned*)((const char*)(gbase) + (voff)[_i]), (LAS unsigned*)(lds + (bufoff) + ldsw + _i * 8192), 16, 0, 0); } while (0)
; #define PG8_LDA(dst, b, h) do { _Pragma("unroll") for (int m = 0; m < 4; ++m) _Pragma("unroll") for (int k = 0; k < 2; ++k) dst[m][k] = *(const LAS bf16x8*)(lds + PG8_SA(b, h) + aoff + m * 2048 + k * 1024); } while (0)
; #define PG8_LDB(dst, b, h) do { _Pragma("unroll") for (int n = 0; n < 2; ++n) _Pragma("unroll") for (int k = 0; k < 2; ++k) dst[n][k] = *(const LAS bf16x8*)(lds + PG8_SB(b, h) + boff + n * 2048 + k * 1024); } while (0)
; #define PG8_MMA(ai, bj, At, Bt) do { __builtin_amdgcn_s_setprio(1); _Pragma("unroll") for (int m = 0; m < 4; ++m) _Pragma("unroll") for (int n = 0; n < 2; ++n) _Pragma("unroll") for (int k = 0; k < 2; ++k) \
;         acc[ai][bj][m][n] = __builtin_amdgcn_mfma_f32_16x16x32_bf16(Bt[n][k], At[m][k], acc[ai][bj][m][n], 0, 0, 0); __builtin_amdgcn_s_setprio(0); } while (0)
; #define PG8_WAIT_V(n) asm volatile("s_waitcnt vmcnt(" #n ")" ::: "memory")
; #define PG8_WAIT_L(n) asm volatile("s_waitcnt lgkmcnt(" #n ")" ::: "memory")
; #define PG8_BAR __builtin_amdgcn_s_barrier()
; #define PG8_SCHED __builtin_amdgcn_sched_barrier(0)
; template <class Epi, class Sched>
; __device__ __forceinline__ void gemm_phase(LAS unsigned char* lds, const Gemm g, const Sched& S, const Epi& E, int wv) {
;     ...
;             PG8_WAIT_V(8); PG8_WAIT_L(0); PG8_BAR; PG8_MMA(1, 0, At, B0); PG8_MMA(1, 1, At, B1); PG8_BAR; PG8_SCHED;
;             PG8_LDB(B0, 1, 0); PG8_LDB(B1, 1, 1); PG8_SCHED; PG8_LDA(At, 1, 0); PG8_STAGE(PG8_SA(0, 1), a2 + hstepA, voffA);
;             PG8_WAIT_V(8); PG8_WAIT_L(0); PG8_BAR; PG8_MMA(0, 0, At, B0); PG8_MMA(0, 1, At, B1); PG8_BAR; PG8_SCHED;
	s_setprio 1
	v_mfma_f32_16x16x32_bf16 v[94:97], v[114:117], v[162:165], v[94:97]
	v_mfma_f32_16x16x32_bf16 v[90:93], v[130:133], v[162:165], v[90:93]
	v_mfma_f32_16x16x32_bf16 v[86:89], v[114:117], v[170:173], v[86:89]
	v_mfma_f32_16x16x32_bf16 v[82:85], v[130:133], v[170:173], v[82:85]
	v_mfma_f32_16x16x32_bf16 v[78:81], v[114:117], v[178:181], v[78:81]
	v_mfma_f32_16x16x32_bf16 v[74:77], v[130:133], v[178:181], v[74:77]
	v_mfma_f32_16x16x32_bf16 v[70:73], v[114:117], v[186:189], v[70:73]
	v_mfma_f32_16x16x32_bf16 v[66:69], v[130:133], v[186:189], v[66:69]
	v_mfma_f32_16x16x32_bf16 v[94:97], v[118:121], v[166:169], v[94:97]
	v_mfma_f32_16x16x32_bf16 v[90:93], v[134:137], v[166:169], v[90:93]
	v_mfma_f32_16x16x32_bf16 v[86:89], v[118:121], v[174:177], v[86:89]
	v_mfma_f32_16x16x32_bf16 v[82:85], v[134:137], v[174:177], v[82:85]
	v_mfma_f32_16x16x32_bf16 v[78:81], v[118:121], v[182:185], v[78:81]
	v_mfma_f32_16x16x32_bf16 v[74:77], v[134:137], v[182:185], v[74:77]
	v_mfma_f32_16x16x32_bf16 v[70:73], v[118:121], v[190:193], v[70:73]
	v_mfma_f32_16x16x32_bf16 v[66:69], v[134:137], v[190:193], v[66:69]
	v_mfma_f32_16x16x32_bf16 v[30:33], v[146:149], v[162:165], v[30:33]
	v_mfma_f32_16x16x32_bf16 v[26:29], v[154:157], v[162:165], v[26:29]
	v_mfma_f32_16x16x32_bf16 v[22:25], v[146:149], v[170:173], v[22:25]
	v_mfma_f32_16x16x32_bf16 v[18:21], v[154:157], v[170:173], v[18:21]
	v_mfma_f32_16x16x32_bf16 v[14:17], v[146:149], v[178:181], v[14:17]
	v_mfma_f32_16x16x32_bf16 v[10:13], v[154:157], v[178:181], v[10:13]
	v_mfma_f32_16x16x32_bf16 v[6:9], v[146:149], v[186:189], v[6:9]
	v_mfma_f32_16x16x32_bf16 v[2:5], v[154:157], v[186:189], v[2:5]
	v_mfma_f32_16x16x32_bf16 v[30:33], v[150:153], v[166:169], v[30:33]
	v_mfma_f32_16x16x32_bf16 v[26:29], v[158:161], v[166:169], v[26:29]
	v_mfma_f32_16x16x32_bf16 v[22:25], v[150:153], v[174:177], v[22:25]
	v_mfma_f32_16x16x32_bf16 v[18:21], v[158:161], v[174:177], v[18:21]
	v_mfma_f32_16x16x32_bf16 v[14:17], v[150:153], v[182:185], v[14:17]
	v_mfma_f32_16x16x32_bf16 v[10:13], v[158:161], v[182:185], v[10:13]
	v_mfma_f32_16x16x32_bf16 v[6:9], v[150:153], v[190:193], v[6:9]
	v_mfma_f32_16x16x32_bf16 v[2:5], v[158:161], v[190:193], v[2:5]
	s_setprio 0
	s_barrier
	s_add_i32 s20, 0, 0x18000
	v_add_u32_e32 v0, s20, v231
	s_add_i32 s26, 0, 0x1c000
	ds_read_b128 v[114:117], v0
	ds_read_b128 v[118:121], v0 offset:1024
	ds_read_b128 v[130:133], v0 offset:2048
	ds_read_b128 v[134:137], v0 offset:3072
	v_add_u32_e32 v0, s26, v231
	ds_read_b128 v[146:149], v0
	ds_read_b128 v[150:153], v0 offset:1024
	ds_read_b128 v[154:157], v0 offset:2048
	ds_read_b128 v[158:161], v0 offset:3072
	s_add_u32 s0, s82, 0x100000
	s_addc_u32 s1, s83, 0
	s_mov_b32 m0, s62
	v_lshl_add_u64 v[216:217], s[0:1], 0, v[196:197]
	ds_read_b128 v[162:165], v232 offset:32768
	ds_read_b128 v[166:169], v232 offset:33792
	ds_read_b128 v[170:173], v232 offset:34816
	ds_read_b128 v[174:177], v232 offset:35840
	ds_read_b128 v[178:181], v232 offset:36864
	ds_read_b128 v[182:185], v232 offset:37888
	ds_read_b128 v[186:189], v232 offset:38912
	ds_read_b128 v[190:193], v232 offset:39936
	global_load_lds_dwordx4 v[216:217], off
	v_lshl_add_u64 v[216:217], s[0:1], 0, v[200:201]
	s_mov_b32 m0, s84
	s_nop 0
	global_load_lds_dwordx4 v[216:217], off
	s_waitcnt vmcnt(8)
	s_waitcnt lgkmcnt(0)
	s_barrier
	s_setprio 1
	v_mfma_f32_16x16x32_bf16 v[142:145], v[114:117], v[162:165], v[142:145]
	v_mfma_f32_16x16x32_bf16 v[138:141], v[130:133], v[162:165], v[138:141]
	v_mfma_f32_16x16x32_bf16 v[126:129], v[114:117], v[170:173], v[126:129]
	v_mfma_f32_16x16x32_bf16 v[122:125], v[130:133], v[170:173], v[122:125]
	v_mfma_f32_16x16x32_bf16 v[110:113], v[114:117], v[178:181], v[110:113]
	v_mfma_f32_16x16x32_bf16 v[106:109], v[130:133], v[178:181], v[106:109]
	v_mfma_f32_16x16x32_bf16 v[102:105], v[114:117], v[186:189], v[102:105]
	v_mfma_f32_16x16x32_bf16 v[98:101], v[130:133], v[186:189], v[98:101]
	v_mfma_f32_16x16x32_bf16 v[142:145], v[118:121], v[166:169], v[142:145]
	v_mfma_f32_16x16x32_bf16 v[138:141], v[134:137], v[166:169], v[138:141]
	v_mfma_f32_16x16x32_bf16 v[126:129], v[118:121], v[174:177], v[126:129]
	v_mfma_f32_16x16x32_bf16 v[122:125], v[134:137], v[174:177], v[122:125]
	v_mfma_f32_16x16x32_bf16 v[110:113], v[118:121], v[182:185], v[110:113]
	v_mfma_f32_16x16x32_bf16 v[106:109], v[134:137], v[182:185], v[106:109]
	v_mfma_f32_16x16x32_bf16 v[102:105], v[118:121], v[190:193], v[102:105]
	v_mfma_f32_16x16x32_bf16 v[98:101], v[134:137], v[190:193], v[98:101]
	v_mfma_f32_16x16x32_bf16 v[62:65], v[146:149], v[162:165], v[62:65]
	v_mfma_f32_16x16x32_bf16 v[58:61], v[154:157], v[162:165], v[58:61]
	v_mfma_f32_16x16x32_bf16 v[54:57], v[146:149], v[170:173], v[54:57]
	v_mfma_f32_16x16x32_bf16 v[50:53], v[154:157], v[170:173], v[50:53]
	v_mfma_f32_16x16x32_bf16 v[46:49], v[146:149], v[178:181], v[46:49]
	v_mfma_f32_16x16x32_bf16 v[42:45], v[154:157], v[178:181], v[42:45]
	v_mfma_f32_16x16x32_bf16 v[38:41], v[146:149], v[186:189], v[38:41]
	v_mfma_f32_16x16x32_bf16 v[34:37], v[154:157], v[186:189], v[34:37]
	v_mfma_f32_16x16x32_bf16 v[62:65], v[150:153], v[166:169], v[62:65]
	v_mfma_f32_16x16x32_bf16 v[58:61], v[158:161], v[166:169], v[58:61]
	v_mfma_f32_16x16x32_bf16 v[54:57], v[150:153], v[174:177], v[54:57]
	v_mfma_f32_16x16x32_bf16 v[50:53], v[158:161], v[174:177], v[50:53]
	v_mfma_f32_16x16x32_bf16 v[46:49], v[150:153], v[182:185], v[46:49]
	v_mfma_f32_16x16x32_bf16 v[42:45], v[158:161], v[182:185], v[42:45]
	v_mfma_f32_16x16x32_bf16 v[38:41], v[150:153], v[190:193], v[38:41]
	v_mfma_f32_16x16x32_bf16 v[34:37], v[158:161], v[190:193], v[34:37]
	s_setprio 0
	s_barrier
; #define PG8_STAGE(bufoff, gbase, voff) do { _Pragma("unroll") for (int _i = 0; _i < 2; ++_i) \
;         __builtin_amdgcn_global_load_lds((const unsigned*)((const char*)(gbase) + (voff)[_i]), (LAS unsigned*)(lds + (bufoff) + ldsw + _i * 8192), 16, 0, 0); } while (0)
; #define PG8_LDA(dst, b, h) do { _Pragma("unroll") for (int m = 0; m < 4; ++m) _Pragma("unroll") for (int k = 0; k < 2; ++k) dst[m][k] = *(const LAS bf16x8*)(lds + PG8_SA(b, h) + aoff + m * 2048 + k * 1024); } while (0)
; #define PG8_MMA(ai, bj, At, Bt) do { __builtin_amdgcn_s_setprio(1); _Pragma("unroll") for (int m = 0; m < 4; ++m) _Pragma("unroll") for (int n = 0; n < 2; ++n) _Pragma("unroll") for (int k = 0; k < 2; ++k) \
;         acc[ai][bj][m][n] = __builtin_amdgcn_mfma_f32_16x16x32_bf16(Bt[n][k], At[m][k], acc[ai][bj][m][n], 0, 0, 0); __builtin_amdgcn_s_setprio(0); } while (0)
; #define PG8_WAIT_V(n) asm volatile("s_waitcnt vmcnt(" #n ")" ::: "memory")
; #define PG8_WAIT_L(n) asm volatile("s_waitcnt lgkmcnt(" #n ")" ::: "memory")
; #define PG8_BAR __builtin_amdgcn_s_barrier()
; #define PG8_SCHED __builtin_amdgcn_sched_barrier(0)
; template <class Epi, class Sched>
; __device__ __forceinline__ void gemm_phase(LAS unsigned char* lds, const Gemm g, const Sched& S, const Epi& E, int wv) {
;     ...
;             PG8_LDA(At, 1, 1); PG8_STAGE(PG8_SB(1, 0), b3, voffB); PG8_STAGE(PG8_SB(1, 1), b3 + hstepB, voffB); PG8_STAGE(PG8_SA(1, 0), a3, voffA);
;             PG8_WAIT_V(8); PG8_WAIT_L(0); PG8_BAR; PG8_MMA(1, 0, At, B0); PG8_MMA(1, 1, At, B1); PG8_BAR; PG8_SCHED;
;         }
;         if (wr == 0) PG8_BAR;
	s_add_i32 s0, s20, s50
	v_lshl_add_u64 v[208:209], v[208:209], 0, s[24:25]
	s_mov_b32 m0, s0
	ds_read_b128 v[162:165], v232 offset:49152
	ds_read_b128 v[166:169], v232 offset:50176
	ds_read_b128 v[170:173], v232 offset:51200
	ds_read_b128 v[174:177], v232 offset:52224
	ds_read_b128 v[178:181], v232 offset:53248
	ds_read_b128 v[182:185], v232 offset:54272
	ds_read_b128 v[186:189], v232 offset:55296
	ds_read_b128 v[190:193], v232 offset:56320
	global_load_lds_dwordx4 v[208:209], off
	s_add_i32 m0, s0, 0x2000
	s_add_u32 s0, s80, 0x20080
	v_lshl_add_u64 v[208:209], v[210:211], 0, s[24:25]
	s_addc_u32 s1, s81, 0
	s_add_i32 s20, s26, s50
	global_load_lds_dwordx4 v[208:209], off
	v_lshl_add_u64 v[208:209], s[0:1], 0, v[198:199]
	s_mov_b32 m0, s20
	s_nop 0
	global_load_lds_dwordx4 v[208:209], off
	v_lshl_add_u64 v[208:209], s[0:1], 0, v[202:203]
	s_add_i32 m0, s20, 0x2000
	s_nop 0
	global_load_lds_dwordx4 v[208:209], off
	v_lshl_add_u64 v[208:209], v[212:213], 0, s[24:25]
	s_mov_b32 m0, s85
	s_nop 0
	global_load_lds_dwordx4 v[208:209], off
	v_lshl_add_u64 v[208:209], v[214:215], 0, s[24:25]
	s_mov_b32 m0, s86
	s_nop 0
	global_load_lds_dwordx4 v[208:209], off
	s_waitcnt vmcnt(8)
	s_waitcnt lgkmcnt(0)
	s_barrier
	s_setprio 1
	v_mfma_f32_16x16x32_bf16 v[94:97], v[114:117], v[162:165], v[94:97]
	v_mfma_f32_16x16x32_bf16 v[90:93], v[130:133], v[162:165], v[90:93]
	v_mfma_f32_16x16x32_bf16 v[86:89], v[114:117], v[170:173], v[86:89]
	v_mfma_f32_16x16x32_bf16 v[82:85], v[130:133], v[170:173], v[82:85]
	v_mfma_f32_16x16x32_bf16 v[78:81], v[114:117], v[178:181], v[78:81]
	v_mfma_f32_16x16x32_bf16 v[74:77], v[130:133], v[178:181], v[74:77]
	v_mfma_f32_16x16x32_bf16 v[70:73], v[114:117], v[186:189], v[70:73]
	v_mfma_f32_16x16x32_bf16 v[66:69], v[130:133], v[186:189], v[66:69]
	v_mfma_f32_16x16x32_bf16 v[94:97], v[118:121], v[166:169], v[94:97]
	v_mfma_f32_16x16x32_bf16 v[90:93], v[134:137], v[166:169], v[90:93]
	v_mfma_f32_16x16x32_bf16 v[86:89], v[118:121], v[174:177], v[86:89]
	v_mfma_f32_16x16x32_bf16 v[82:85], v[134:137], v[174:177], v[82:85]
	v_mfma_f32_16x16x32_bf16 v[78:81], v[118:121], v[182:185], v[78:81]
	v_mfma_f32_16x16x32_bf16 v[74:77], v[134:137], v[182:185], v[74:77]
	v_mfma_f32_16x16x32_bf16 v[70:73], v[118:121], v[190:193], v[70:73]
	v_mfma_f32_16x16x32_bf16 v[66:69], v[134:137], v[190:193], v[66:69]
	v_mfma_f32_16x16x32_bf16 v[30:33], v[146:149], v[162:165], v[30:33]
	v_mfma_f32_16x16x32_bf16 v[26:29], v[154:157], v[162:165], v[26:29]
	v_mfma_f32_16x16x32_bf16 v[22:25], v[146:149], v[170:173], v[22:25]
	v_mfma_f32_16x16x32_bf16 v[18:21], v[154:157], v[170:173], v[18:21]
	v_mfma_f32_16x16x32_bf16 v[14:17], v[146:149], v[178:181], v[14:17]
	v_mfma_f32_16x16x32_bf16 v[10:13], v[154:157], v[178:181], v[10:13]
	v_mfma_f32_16x16x32_bf16 v[6:9], v[146:149], v[186:189], v[6:9]
	v_mfma_f32_16x16x32_bf16 v[2:5], v[154:157], v[186:189], v[2:5]
	v_mfma_f32_16x16x32_bf16 v[30:33], v[150:153], v[166:169], v[30:33]
	v_mfma_f32_16x16x32_bf16 v[26:29], v[158:161], v[166:169], v[26:29]
	v_mfma_f32_16x16x32_bf16 v[22:25], v[150:153], v[174:177], v[22:25]
	v_mfma_f32_16x16x32_bf16 v[18:21], v[158:161], v[174:177], v[18:21]
	v_mfma_f32_16x16x32_bf16 v[14:17], v[150:153], v[182:185], v[14:17]
	v_mfma_f32_16x16x32_bf16 v[10:13], v[158:161], v[182:185], v[10:13]
	v_mfma_f32_16x16x32_bf16 v[6:9], v[150:153], v[190:193], v[6:9]
	v_mfma_f32_16x16x32_bf16 v[2:5], v[158:161], v[190:193], v[2:5]
	s_setprio 0
	s_barrier
	s_add_i32 s34, s34, 2
	s_add_u32 s78, s78, 0x100
	s_addc_u32 s79, s79, 0
	s_add_u32 s21, s21, 0x100
	s_addc_u32 s31, s31, 0
	s_cmp_gt_u32 s34, 5
	s_cbranch_scc0 .LBB0_556
	s_and_b64 vcc, exec, s[68:69]
	s_cbranch_vccz .LBB0_559
	s_barrier

; #define PG8_STAGE(bufoff, gbase, voff) do { _Pragma("unroll") for (int _i = 0; _i < 2; ++_i) \
;         __builtin_amdgcn_global_load_lds((const unsigned*)((const char*)(gbase) + (voff)[_i]), (LAS unsigned*)(lds + (bufoff) + ldsw + _i * 8192), 16, 0, 0); } while (0)
; #define PG8_LDA(dst, b, h) do { _Pragma("unroll") for (int m = 0; m < 4; ++m) _Pragma("unroll") for (int k = 0; k < 2; ++k) dst[m][k] = *(const LAS bf16x8*)(lds + PG8_SA(b, h) + aoff + m * 2048 + k * 1024); } while (0)
; #define PG8_LDB(dst, b, h) do { _Pragma("unroll") for (int n = 0; n < 2; ++n) _Pragma("unroll") for (int k = 0; k < 2; ++k) dst[n][k] = *(const LAS bf16x8*)(lds + PG8_SB(b, h) + boff + n * 2048 + k * 1024); } while (0)
; #define PG8_MMA(ai, bj, At, Bt) do { __builtin_amdgcn_s_setprio(1); _Pragma("unroll") for (int m = 0; m < 4; ++m) _Pragma("unroll") for (int n = 0; n < 2; ++n) _Pragma("unroll") for (int k = 0; k < 2; ++k) \
;         acc[ai][bj][m][n] = __builtin_amdgcn_mfma_f32_16x16x32_bf16(Bt[n][k], At[m][k], acc[ai][bj][m][n], 0, 0, 0); __builtin_amdgcn_s_setprio(0); } while (0)
; #define PG8_WAIT_V(n) asm volatile("s_waitcnt vmcnt(" #n ")" ::: "memory")
; template <class Epi, class Sched>
; __device__ __forceinline__ void gemm_phase(LAS unsigned char* lds, const Gemm g, const Sched& S, const Epi& E, int wv) {
;     ...
;         const char* nA = has_next ? (const char*)g.A + (size_t)nxt.pm * tstepA + (size_t)nxt.ak * 2 : cA; const char* nB = has_next ? (const char*)g.Bt + (size_t)nxt.pn * tstepB : cB;
;         for (int t = 0; t < nt; t += 2) {
;             const bool last = (t == nt - 2);
;             const char* a1 = cA + (size_t)(t + 1) * kstep;
;             const char* a2 = last ? nA : cA + (size_t)(t + 2) * kstep; const char* b2 = last ? nB : cB + (size_t)(t + 2) * kstep;
;             const char* a3 = a2 + kstep; const char* b3 = b2 + kstep;
;             PG8_LDB(B0, 0, 0); PG8_LDB(B1, 0, 1); PG8_SCHED; PG8_LDA(At, 0, 0); PG8_STAGE(PG8_SA(1, 1), a1 + hstepA, voffA);
;             PG8_WAIT_V(8); PG8_WAIT_L(0); PG8_BAR; PG8_MMA(0, 0, At, B0); PG8_MMA(0, 1, At, B1); PG8_BAR; PG8_SCHED;
;             PG8_LDA(At, 0, 1); PG8_STAGE(PG8_SB(0, 0), b2, voffB); PG8_STAGE(PG8_SB(0, 1), b2 + hstepB, voffB); PG8_STAGE(PG8_SA(0, 0), a2, voffA);
;             PG8_WAIT_V(8); PG8_WAIT_L(0); PG8_BAR; PG8_MMA(1, 0, At, B0); PG8_MMA(1, 1, At, B1); PG8_BAR; PG8_SCHED;
.LBB0_717:
	s_add_u32 s0, s8, 0xfffc0080
	s_addc_u32 s1, s9, -1
	s_add_i32 s20, 0, 0x10000
	s_cmp_eq_u32 s35, 12
	s_cselect_b32 s13, s5, s1
	s_cselect_b32 s12, s7, s0
	s_waitcnt lgkmcnt(0)
	v_add_u32_e32 v0, s20, v178
	s_cselect_b32 s11, s21, s34
	s_cselect_b32 s10, s22, s31
	s_add_i32 s26, 0, 0x14000
	ds_read_b128 v[142:145], v0
	ds_read_b128 v[146:149], v0 offset:1024
	ds_read_b128 v[150:153], v0 offset:2048
	ds_read_b128 v[154:157], v0 offset:3072
	v_add_u32_e32 v0, s26, v178
	ds_read_b128 v[158:161], v0
	ds_read_b128 v[162:165], v0 offset:1024
	ds_read_b128 v[166:169], v0 offset:2048
	ds_read_b128 v[170:173], v0 offset:3072
	v_lshl_add_u64 v[192:193], s[8:9], 0, v[138:139]
	s_add_i32 m0, s49, 0xc000
	ds_read_b128 v[174:177], v179
	ds_read_b128 v[180:183], v179 offset:1024
	ds_read_b128 v[184:187], v179 offset:2048
	ds_read_b128 v[188:191], v179 offset:3072
	ds_read_b128 v[196:199], v179 offset:4096
	ds_read_b128 v[200:203], v179 offset:5120
	ds_read_b128 v[204:207], v179 offset:6144
	ds_read_b128 v[208:211], v179 offset:7168
	global_load_lds_dwordx4 v[192:193], off
	v_lshl_add_u64 v[192:193], s[8:9], 0, v[140:141]
	s_add_i32 m0, s49, 0xe000
	s_nop 0
	global_load_lds_dwordx4 v[192:193], off
	s_waitcnt vmcnt(8)
	s_waitcnt lgkmcnt(0)
	s_barrier
	s_setprio 1
	v_mfma_f32_16x16x32_bf16 v[126:129], v[142:145], v[174:177], v[126:129]
	v_mfma_f32_16x16x32_bf16 v[122:125], v[150:153], v[174:177], v[122:125]
	v_mfma_f32_16x16x32_bf16 v[110:113], v[142:145], v[184:187], v[110:113]
	v_mfma_f32_16x16x32_bf16 v[106:109], v[150:153], v[184:187], v[106:109]
	v_mfma_f32_16x16x32_bf16 v[94:97], v[142:145], v[196:199], v[94:97]
	v_mfma_f32_16x16x32_bf16 v[90:93], v[150:153], v[196:199], v[90:93]
	v_mfma_f32_16x16x32_bf16 v[78:81], v[142:145], v[204:207], v[78:81]
	v_mfma_f32_16x16x32_bf16 v[74:77], v[150:153], v[204:207], v[74:77]
	v_mfma_f32_16x16x32_bf16 v[126:129], v[146:149], v[180:183], v[126:129]
	v_mfma_f32_16x16x32_bf16 v[122:125], v[154:157], v[180:183], v[122:125]
	v_mfma_f32_16x16x32_bf16 v[110:113], v[146:149], v[188:191], v[110:113]
	v_mfma_f32_16x16x32_bf16 v[106:109], v[154:157], v[188:191], v[106:109]
	v_mfma_f32_16x16x32_bf16 v[94:97], v[146:149], v[200:203], v[94:97]
	v_mfma_f32_16x16x32_bf16 v[90:93], v[154:157], v[200:203], v[90:93]
	v_mfma_f32_16x16x32_bf16 v[78:81], v[146:149], v[208:211], v[78:81]
	v_mfma_f32_16x16x32_bf16 v[74:77], v[154:157], v[208:211], v[74:77]
	v_mfma_f32_16x16x32_bf16 v[118:121], v[158:161], v[174:177], v[118:121]
	v_mfma_f32_16x16x32_bf16 v[114:117], v[166:169], v[174:177], v[114:117]
	v_mfma_f32_16x16x32_bf16 v[102:105], v[158:161], v[184:187], v[102:105]
	v_mfma_f32_16x16x32_bf16 v[98:101], v[166:169], v[184:187], v[98:101]
	v_mfma_f32_16x16x32_bf16 v[86:89], v[158:161], v[196:199], v[86:89]
	v_mfma_f32_16x16x32_bf16 v[82:85], v[166:169], v[196:199], v[82:85]
	v_mfma_f32_16x16x32_bf16 v[70:73], v[158:161], v[204:207], v[70:73]
	v_mfma_f32_16x16x32_bf16 v[66:69], v[166:169], v[204:207], v[66:69]
	v_mfma_f32_16x16x32_bf16 v[118:121], v[162:165], v[180:183], v[118:121]
	v_mfma_f32_16x16x32_bf16 v[114:117], v[170:173], v[180:183], v[114:117]
	v_mfma_f32_16x16x32_bf16 v[102:105], v[162:165], v[188:191], v[102:105]
	v_mfma_f32_16x16x32_bf16 v[98:101], v[170:173], v[188:191], v[98:101]
	v_mfma_f32_16x16x32_bf16 v[86:89], v[162:165], v[200:203], v[86:89]
	v_mfma_f32_16x16x32_bf16 v[82:85], v[170:173], v[200:203], v[82:85]
	v_mfma_f32_16x16x32_bf16 v[70:73], v[162:165], v[208:211], v[70:73]
	v_mfma_f32_16x16x32_bf16 v[66:69], v[170:173], v[208:211], v[66:69]
	s_setprio 0
	s_barrier
	s_add_i32 s0, s20, s48
	v_lshl_add_u64 v[192:193], s[10:11], 0, v[132:133]
	s_mov_b32 m0, s0
	ds_read_b128 v[174:177], v179 offset:16384
	ds_read_b128 v[180:183], v179 offset:17408
	ds_read_b128 v[184:187], v179 offset:18432
	ds_read_b128 v[188:191], v179 offset:19456
	ds_read_b128 v[196:199], v179 offset:20480
	ds_read_b128 v[200:203], v179 offset:21504
	ds_read_b128 v[204:207], v179 offset:22528
	ds_read_b128 v[208:211], v179 offset:23552
	global_load_lds_dwordx4 v[192:193], off
	s_add_i32 m0, s0, 0x2000
	s_add_u32 s0, s10, 0x40000
	v_lshl_add_u64 v[212:213], s[10:11], 0, v[136:137]
	s_addc_u32 s1, s11, 0
	s_add_i32 s20, s26, s48
	global_load_lds_dwordx4 v[212:213], off
	v_lshl_add_u64 v[214:215], s[0:1], 0, v[132:133]
	s_mov_b32 m0, s20
	v_lshl_add_u64 v[216:217], s[12:13], 0, v[134:135]
	global_load_lds_dwordx4 v[214:215], off
	v_lshl_add_u64 v[214:215], s[0:1], 0, v[136:137]
	s_add_i32 m0, s20, 0x2000
	s_nop 0
	global_load_lds_dwordx4 v[214:215], off
	v_lshl_add_u64 v[214:215], s[12:13], 0, v[130:131]
	s_mov_b32 m0, s49
	s_nop 0
	global_load_lds_dwordx4 v[214:215], off
	s_mov_b32 m0, s50
	s_nop 0
	global_load_lds_dwordx4 v[216:217], off
	s_waitcnt vmcnt(8)
	s_waitcnt lgkmcnt(0)
	s_barrier
; #define PG8_STAGE(bufoff, gbase, voff) do { _Pragma("unroll") for (int _i = 0; _i < 2; ++_i) \
;         __builtin_amdgcn_global_load_lds((const unsigned*)((const char*)(gbase) + (voff)[_i]), (LAS unsigned*)(lds + (bufoff) + ldsw + _i * 8192), 16, 0, 0); } while (0)
; #define PG8_LDA(dst, b, h) do { _Pragma("unroll") for (int m = 0; m < 4; ++m) _Pragma("unroll") for (int k = 0; k < 2; ++k) dst[m][k] = *(const LAS bf16x8*)(lds + PG8_SA(b, h) + aoff + m * 2048 + k * 1024); } while (0)
; #define PG8_LDB(dst, b, h) do { _Pragma("unroll") for (int n = 0; n < 2; ++n) _Pragma("unroll") for (int k = 0; k < 2; ++k) dst[n][k] = *(const LAS bf16x8*)(lds + PG8_SB(b, h) + boff + n * 2048 + k * 1024); } while (0)
; #define PG8_MMA(ai, bj, At, Bt) do { __builtin_amdgcn_s_setprio(1); _Pragma("unroll") for (int m = 0; m < 4; ++m) _Pragma("unroll") for (int n = 0; n < 2; ++n) _Pragma("unroll") for (int k = 0; k < 2; ++k) \
;         acc[ai][bj][m][n] = __builtin_amdgcn_mfma_f32_16x16x32_bf16(Bt[n][k], At[m][k], acc[ai][bj][m][n], 0, 0, 0); __builtin_amdgcn_s_setprio(0); } while (0)
; #define PG8_WAIT_V(n) asm volatile("s_waitcnt vmcnt(" #n ")" ::: "memory")
; #define PG8_WAIT_L(n) asm volatile("s_waitcnt lgkmcnt(" #n ")" ::: "memory")
; #define PG8_BAR __builtin_amdgcn_s_barrier()
; #define PG8_SCHED __builtin_amdgcn_sched_barrier(0)
; template <class Epi, class Sched>
; __device__ __forceinline__ void gemm_phase(LAS unsigned char* lds, const Gemm g, const Sched& S, const Epi& E, int wv) {
;     ...
;             PG8_WAIT_V(8); PG8_WAIT_L(0); PG8_BAR; PG8_MMA(1, 0, At, B0); PG8_MMA(1, 1, At, B1); PG8_BAR; PG8_SCHED;
;             PG8_LDB(B0, 1, 0); PG8_LDB(B1, 1, 1); PG8_SCHED; PG8_LDA(At, 1, 0); PG8_STAGE(PG8_SA(0, 1), a2 + hstepA, voffA);
;             PG8_WAIT_V(8); PG8_WAIT_L(0); PG8_BAR; PG8_MMA(0, 0, At, B0); PG8_MMA(0, 1, At, B1); PG8_BAR; PG8_SCHED;
	s_setprio 1
	v_mfma_f32_16x16x32_bf16 v[62:65], v[142:145], v[174:177], v[62:65]
	v_mfma_f32_16x16x32_bf16 v[58:61], v[150:153], v[174:177], v[58:61]
	v_mfma_f32_16x16x32_bf16 v[46:49], v[142:145], v[184:187], v[46:49]
	v_mfma_f32_16x16x32_bf16 v[42:45], v[150:153], v[184:187], v[42:45]
	v_mfma_f32_16x16x32_bf16 v[30:33], v[142:145], v[196:199], v[30:33]
	v_mfma_f32_16x16x32_bf16 v[26:29], v[150:153], v[196:199], v[26:29]
	v_mfma_f32_16x16x32_bf16 v[14:17], v[142:145], v[204:207], v[14:17]
	v_mfma_f32_16x16x32_bf16 v[10:13], v[150:153], v[204:207], v[10:13]
	v_mfma_f32_16x16x32_bf16 v[62:65], v[146:149], v[180:183], v[62:65]
	v_mfma_f32_16x16x32_bf16 v[58:61], v[154:157], v[180:183], v[58:61]
	v_mfma_f32_16x16x32_bf16 v[46:49], v[146:149], v[188:191], v[46:49]
	v_mfma_f32_16x16x32_bf16 v[42:45], v[154:157], v[188:191], v[42:45]
	v_mfma_f32_16x16x32_bf16 v[30:33], v[146:149], v[200:203], v[30:33]
	v_mfma_f32_16x16x32_bf16 v[26:29], v[154:157], v[200:203], v[26:29]
	v_mfma_f32_16x16x32_bf16 v[14:17], v[146:149], v[208:211], v[14:17]
	v_mfma_f32_16x16x32_bf16 v[10:13], v[154:157], v[208:211], v[10:13]
	v_mfma_f32_16x16x32_bf16 v[54:57], v[158:161], v[174:177], v[54:57]
	v_mfma_f32_16x16x32_bf16 v[50:53], v[166:169], v[174:177], v[50:53]
	v_mfma_f32_16x16x32_bf16 v[38:41], v[158:161], v[184:187], v[38:41]
	v_mfma_f32_16x16x32_bf16 v[34:37], v[166:169], v[184:187], v[34:37]
	v_mfma_f32_16x16x32_bf16 v[22:25], v[158:161], v[196:199], v[22:25]
	v_mfma_f32_16x16x32_bf16 v[18:21], v[166:169], v[196:199], v[18:21]
	v_mfma_f32_16x16x32_bf16 v[6:9], v[158:161], v[204:207], v[6:9]
	v_mfma_f32_16x16x32_bf16 v[2:5], v[166:169], v[204:207], v[2:5]
	v_mfma_f32_16x16x32_bf16 v[54:57], v[162:165], v[180:183], v[54:57]
	v_mfma_f32_16x16x32_bf16 v[50:53], v[170:173], v[180:183], v[50:53]
	v_mfma_f32_16x16x32_bf16 v[38:41], v[162:165], v[188:191], v[38:41]
	v_mfma_f32_16x16x32_bf16 v[34:37], v[170:173], v[188:191], v[34:37]
	v_mfma_f32_16x16x32_bf16 v[22:25], v[162:165], v[200:203], v[22:25]
	v_mfma_f32_16x16x32_bf16 v[18:21], v[170:173], v[200:203], v[18:21]
	v_mfma_f32_16x16x32_bf16 v[6:9], v[162:165], v[208:211], v[6:9]
	v_mfma_f32_16x16x32_bf16 v[2:5], v[170:173], v[208:211], v[2:5]
	s_setprio 0
	s_barrier
	s_add_i32 s20, 0, 0x18000
	v_add_u32_e32 v0, s20, v178
	s_add_i32 s26, 0, 0x1c000
	ds_read_b128 v[142:145], v0
	ds_read_b128 v[146:149], v0 offset:1024
	ds_read_b128 v[150:153], v0 offset:2048
	ds_read_b128 v[154:157], v0 offset:3072
	v_add_u32_e32 v0, s26, v178
	ds_read_b128 v[158:161], v0
	ds_read_b128 v[162:165], v0 offset:1024
	ds_read_b128 v[166:169], v0 offset:2048
	ds_read_b128 v[170:173], v0 offset:3072
	s_add_u32 s0, s12, 0x40000
	s_addc_u32 s1, s13, 0
	s_mov_b32 m0, s60
	v_lshl_add_u64 v[218:219], s[0:1], 0, v[130:131]
	ds_read_b128 v[174:177], v179 offset:32768
	ds_read_b128 v[180:183], v179 offset:33792
	ds_read_b128 v[184:187], v179 offset:34816
	ds_read_b128 v[188:191], v179 offset:35840
	ds_read_b128 v[196:199], v179 offset:36864
	ds_read_b128 v[200:203], v179 offset:37888
	ds_read_b128 v[204:207], v179 offset:38912
	ds_read_b128 v[208:211], v179 offset:39936
	global_load_lds_dwordx4 v[218:219], off
	v_lshl_add_u64 v[218:219], s[0:1], 0, v[134:135]
	s_mov_b32 m0, s61
	s_nop 0
	global_load_lds_dwordx4 v[218:219], off
	s_waitcnt vmcnt(8)
	s_waitcnt lgkmcnt(0)
	s_barrier
	s_setprio 1
	v_mfma_f32_16x16x32_bf16 v[126:129], v[142:145], v[174:177], v[126:129]
	v_mfma_f32_16x16x32_bf16 v[122:125], v[150:153], v[174:177], v[122:125]
	v_mfma_f32_16x16x32_bf16 v[110:113], v[142:145], v[184:187], v[110:113]
	v_mfma_f32_16x16x32_bf16 v[106:109], v[150:153], v[184:187], v[106:109]
	v_mfma_f32_16x16x32_bf16 v[94:97], v[142:145], v[196:199], v[94:97]
	v_mfma_f32_16x16x32_bf16 v[90:93], v[150:153], v[196:199], v[90:93]
	v_mfma_f32_16x16x32_bf16 v[78:81], v[142:145], v[204:207], v[78:81]
	v_mfma_f32_16x16x32_bf16 v[74:77], v[150:153], v[204:207], v[74:77]
	v_mfma_f32_16x16x32_bf16 v[126:129], v[146:149], v[180:183], v[126:129]
	v_mfma_f32_16x16x32_bf16 v[122:125], v[154:157], v[180:183], v[122:125]
	v_mfma_f32_16x16x32_bf16 v[110:113], v[146:149], v[188:191], v[110:113]
	v_mfma_f32_16x16x32_bf16 v[106:109], v[154:157], v[188:191], v[106:109]
	v_mfma_f32_16x16x32_bf16 v[94:97], v[146:149], v[200:203], v[94:97]
	v_mfma_f32_16x16x32_bf16 v[90:93], v[154:157], v[200:203], v[90:93]
	v_mfma_f32_16x16x32_bf16 v[78:81], v[146:149], v[208:211], v[78:81]
	v_mfma_f32_16x16x32_bf16 v[74:77], v[154:157], v[208:211], v[74:77]
	v_mfma_f32_16x16x32_bf16 v[118:121], v[158:161], v[174:177], v[118:121]
	v_mfma_f32_16x16x32_bf16 v[114:117], v[166:169], v[174:177], v[114:117]
	v_mfma_f32_16x16x32_bf16 v[102:105], v[158:161], v[184:187], v[102:105]
	v_mfma_f32_16x16x32_bf16 v[98:101], v[166:169], v[184:187], v[98:101]
	v_mfma_f32_16x16x32_bf16 v[86:89], v[158:161], v[196:199], v[86:89]
	v_mfma_f32_16x16x32_bf16 v[82:85], v[166:169], v[196:199], v[82:85]
	v_mfma_f32_16x16x32_bf16 v[70:73], v[158:161], v[204:207], v[70:73]
	v_mfma_f32_16x16x32_bf16 v[66:69], v[166:169], v[204:207], v[66:69]
	v_mfma_f32_16x16x32_bf16 v[118:121], v[162:165], v[180:183], v[118:121]
	v_mfma_f32_16x16x32_bf16 v[114:117], v[170:173], v[180:183], v[114:117]
	v_mfma_f32_16x16x32_bf16 v[102:105], v[162:165], v[188:191], v[102:105]
	v_mfma_f32_16x16x32_bf16 v[98:101], v[170:173], v[188:191], v[98:101]
	v_mfma_f32_16x16x32_bf16 v[86:89], v[162:165], v[200:203], v[86:89]
	v_mfma_f32_16x16x32_bf16 v[82:85], v[170:173], v[200:203], v[82:85]
	v_mfma_f32_16x16x32_bf16 v[70:73], v[162:165], v[208:211], v[70:73]
	v_mfma_f32_16x16x32_bf16 v[66:69], v[170:173], v[208:211], v[66:69]
	s_setprio 0
	s_barrier
; #define PG8_STAGE(bufoff, gbase, voff) do { _Pragma("unroll") for (int _i = 0; _i < 2; ++_i) \
;         __builtin_amdgcn_global_load_lds((const unsigned*)((const char*)(gbase) + (voff)[_i]), (LAS unsigned*)(lds + (bufoff) + ldsw + _i * 8192), 16, 0, 0); } while (0)
; #define PG8_LDA(dst, b, h) do { _Pragma("unroll") for (int m = 0; m < 4; ++m) _Pragma("unroll") for (int k = 0; k < 2; ++k) dst[m][k] = *(const LAS bf16x8*)(lds + PG8_SA(b, h) + aoff + m * 2048 + k * 1024); } while (0)
; #define PG8_MMA(ai, bj, At, Bt) do { __builtin_amdgcn_s_setprio(1); _Pragma("unroll") for (int m = 0; m < 4; ++m) _Pragma("unroll") for (int n = 0; n < 2; ++n) _Pragma("unroll") for (int k = 0; k < 2; ++k) \
;         acc[ai][bj][m][n] = __builtin_amdgcn_mfma_f32_16x16x32_bf16(Bt[n][k], At[m][k], acc[ai][bj][m][n], 0, 0, 0); __builtin_amdgcn_s_setprio(0); } while (0)
; #define PG8_WAIT_V(n) asm volatile("s_waitcnt vmcnt(" #n ")" ::: "memory")
; #define PG8_WAIT_L(n) asm volatile("s_waitcnt lgkmcnt(" #n ")" ::: "memory")
; #define PG8_BAR __builtin_amdgcn_s_barrier()
; #define PG8_SCHED __builtin_amdgcn_sched_barrier(0)
; template <class Epi, class Sched>
; __device__ __forceinline__ void gemm_phase(LAS unsigned char* lds, const Gemm g, const Sched& S, const Epi& E, int wv) {
;     ...
;             PG8_LDA(At, 1, 1); PG8_STAGE(PG8_SB(1, 0), b3, voffB); PG8_STAGE(PG8_SB(1, 1), b3 + hstepB, voffB); PG8_STAGE(PG8_SA(1, 0), a3, voffA);
;             PG8_WAIT_V(8); PG8_WAIT_L(0); PG8_BAR; PG8_MMA(1, 0, At, B0); PG8_MMA(1, 1, At, B1); PG8_BAR; PG8_SCHED;
	s_add_i32 s0, s20, s48
	v_lshl_add_u64 v[192:193], v[192:193], 0, s[24:25]
	s_mov_b32 m0, s0
	ds_read_b128 v[174:177], v179 offset:49152
	ds_read_b128 v[180:183], v179 offset:50176
	ds_read_b128 v[184:187], v179 offset:51200
	ds_read_b128 v[188:191], v179 offset:52224
	ds_read_b128 v[196:199], v179 offset:53248
	ds_read_b128 v[200:203], v179 offset:54272
	ds_read_b128 v[204:207], v179 offset:55296
	ds_read_b128 v[208:211], v179 offset:56320
	global_load_lds_dwordx4 v[192:193], off
	s_add_i32 m0, s0, 0x2000
	s_add_u32 s0, s10, 0x40080
	v_lshl_add_u64 v[192:193], v[212:213], 0, s[24:25]
	s_addc_u32 s1, s11, 0
	s_add_i32 s10, s26, s48
	global_load_lds_dwordx4 v[192:193], off
	v_lshl_add_u64 v[192:193], s[0:1], 0, v[132:133]
	s_mov_b32 m0, s10
	s_nop 0
	global_load_lds_dwordx4 v[192:193], off
	v_lshl_add_u64 v[192:193], s[0:1], 0, v[136:137]
	s_add_i32 m0, s10, 0x2000
	s_nop 0
	global_load_lds_dwordx4 v[192:193], off
	v_lshl_add_u64 v[192:193], v[214:215], 0, s[24:25]
	s_mov_b32 m0, s62
	s_nop 0
	global_load_lds_dwordx4 v[192:193], off
	v_lshl_add_u64 v[192:193], v[216:217], 0, s[24:25]
	s_mov_b32 m0, s63
	s_nop 0
	global_load_lds_dwordx4 v[192:193], off
	s_waitcnt vmcnt(8)
	s_waitcnt lgkmcnt(0)
	s_barrier
	s_setprio 1
	v_mfma_f32_16x16x32_bf16 v[62:65], v[142:145], v[174:177], v[62:65]
	v_mfma_f32_16x16x32_bf16 v[58:61], v[150:153], v[174:177], v[58:61]
	v_mfma_f32_16x16x32_bf16 v[46:49], v[142:145], v[184:187], v[46:49]
	v_mfma_f32_16x16x32_bf16 v[42:45], v[150:153], v[184:187], v[42:45]
	v_mfma_f32_16x16x32_bf16 v[30:33], v[142:145], v[196:199], v[30:33]
	v_mfma_f32_16x16x32_bf16 v[26:29], v[150:153], v[196:199], v[26:29]
	v_mfma_f32_16x16x32_bf16 v[14:17], v[142:145], v[204:207], v[14:17]
	v_mfma_f32_16x16x32_bf16 v[10:13], v[150:153], v[204:207], v[10:13]
	v_mfma_f32_16x16x32_bf16 v[62:65], v[146:149], v[180:183], v[62:65]
	v_mfma_f32_16x16x32_bf16 v[58:61], v[154:157], v[180:183], v[58:61]
	v_mfma_f32_16x16x32_bf16 v[46:49], v[146:149], v[188:191], v[46:49]
	v_mfma_f32_16x16x32_bf16 v[42:45], v[154:157], v[188:191], v[42:45]
	v_mfma_f32_16x16x32_bf16 v[30:33], v[146:149], v[200:203], v[30:33]
	v_mfma_f32_16x16x32_bf16 v[26:29], v[154:157], v[200:203], v[26:29]
	v_mfma_f32_16x16x32_bf16 v[14:17], v[146:149], v[208:211], v[14:17]
	v_mfma_f32_16x16x32_bf16 v[10:13], v[154:157], v[208:211], v[10:13]
	v_mfma_f32_16x16x32_bf16 v[54:57], v[158:161], v[174:177], v[54:57]
	v_mfma_f32_16x16x32_bf16 v[50:53], v[166:169], v[174:177], v[50:53]
	v_mfma_f32_16x16x32_bf16 v[38:41], v[158:161], v[184:187], v[38:41]
	v_mfma_f32_16x16x32_bf16 v[34:37], v[166:169], v[184:187], v[34:37]
	v_mfma_f32_16x16x32_bf16 v[22:25], v[158:161], v[196:199], v[22:25]
	v_mfma_f32_16x16x32_bf16 v[18:21], v[166:169], v[196:199], v[18:21]
	v_mfma_f32_16x16x32_bf16 v[6:9], v[158:161], v[204:207], v[6:9]
	v_mfma_f32_16x16x32_bf16 v[2:5], v[166:169], v[204:207], v[2:5]
	v_mfma_f32_16x16x32_bf16 v[54:57], v[162:165], v[180:183], v[54:57]
	v_mfma_f32_16x16x32_bf16 v[50:53], v[170:173], v[180:183], v[50:53]
	v_mfma_f32_16x16x32_bf16 v[38:41], v[162:165], v[188:191], v[38:41]
	v_mfma_f32_16x16x32_bf16 v[34:37], v[170:173], v[188:191], v[34:37]
	v_mfma_f32_16x16x32_bf16 v[22:25], v[162:165], v[200:203], v[22:25]
	v_mfma_f32_16x16x32_bf16 v[18:21], v[170:173], v[200:203], v[18:21]
	v_mfma_f32_16x16x32_bf16 v[6:9], v[162:165], v[208:211], v[6:9]
	v_mfma_f32_16x16x32_bf16 v[2:5], v[170:173], v[208:211], v[2:5]
	s_setprio 0
	s_barrier
	s_add_i32 s35, s35, 2
	s_add_u32 s8, s8, 0x100
	s_addc_u32 s9, s9, 0
	s_add_u32 s31, s31, 0x100
	s_addc_u32 s34, s34, 0
	s_cmp_gt_u32 s35, 13
	s_cbranch_scc0 .LBB0_717
	s_and_b64 vcc, exec, s[74:75]
	s_cbranch_vccz .LBB0_720
	s_barrier
